# c11 + every remaining flat load/store converted to global (barrier polls and atomics left as flat)
# speedup vs baseline: 1.0107x; 1.0013x over previous
; DEVI unsigned cvtpk(float lo, float hi) { unsigned r; asm volatile("v_cvt_pk_bf16_f32 %0, %1, %2" : "=v"(r) : "v"(lo), "v"(hi)); return r; }
; DEVI int lbid() { int t = blockIdx.x; asm volatile("" : "+s"(t)); return t; }
; DEVI float wave_sum(float v) { v += dpp<0xB1>(v); v += dpp<0x4E>(v); v += dpp<0x124>(v); v += dpp<0x128>(v); return xrow16_sum(v); }
; DEVI void norm_phase(const float* __restrict__ x, const float* __restrict__ gain, bf16_t* __restrict__ out,
;                      const float* wf_src, const float* bf_src, float* logf, char* lds, int wv) {
;     ...
;     for (int row0 = lbid() * 8 + wave; row0 < T_TOK; row0 += 2 * nw) {
;         f32x4 v[2][4]; float ss[2];
; #pragma unroll
;         for (int q = 0; q < 2; ++q) { const int row = row0 + q * nw < T_TOK ? row0 + q * nw : row0; const float* xr = x + (size_t)row * DM;
; #pragma unroll
;             for (int j = 0; j < 4; ++j) v[q][j] = *(const f32x4*)(xr + j * 256 + lane * 4); }
; #pragma unroll
;         for (int q = 0; q < 2; ++q) { float s_ = 0.f;
; #pragma unroll
;             for (int j = 0; j < 4; ++j) s_ += v[q][j][0] * v[q][j][0] + v[q][j][1] * v[q][j][1] + v[q][j][2] * v[q][j][2] + v[q][j][3] * v[q][j][3];
;             ss[q] = wave_sum(s_); }
; #pragma unroll
;         for (int q = 0; q < 2; ++q) { const int row = row0 + q * nw; if (row >= T_TOK) break;
;             const float rstd = __builtin_amdgcn_rsqf(ss[q] * (1.f / 1024.f) + 1e-6f);
; #pragma unroll
;             for (int j = 0; j < 4; ++j) { v[q][j] = v[q][j] * rstd * g[j]; u32x2 w; w.x = cvtpk(v[q][j][0], v[q][j][1]); w.y = cvtpk(v[q][j][2], v[q][j][3]); *(u32x2*)(out + (size_t)row * DM + j * 256 + lane * 4) = w; }
.LBB0_27:
	v_ashrrev_i32_e32 v41, 31, v40
	v_lshlrev_b64 v[18:19], 12, v[40:41]
	v_add_u32_e32 v38, s10, v40
	v_lshl_add_u64 v[18:19], v[34:35], 0, v[18:19]
	v_cmp_gt_i32_e32 vcc, s33, v38
	global_load_dwordx4 v[42:45], v[18:19], off
	global_load_dwordx4 v[46:49], v[18:19], off offset:1024
	global_load_dwordx4 v[50:53], v[18:19], off offset:2048
	global_load_dwordx4 v[54:57], v[18:19], off offset:3072
	v_cndmask_b32_e32 v18, v40, v38, vcc
	v_ashrrev_i32_e32 v19, 31, v18
	v_lshlrev_b64 v[18:19], 12, v[18:19]
	v_lshl_add_u64 v[18:19], v[34:35], 0, v[18:19]
	global_load_dwordx4 v[30:33], v[18:19], off
	global_load_dwordx4 v[26:29], v[18:19], off offset:1024
	global_load_dwordx4 v[22:25], v[18:19], off offset:2048
	s_nop 0
	global_load_dwordx4 v[18:21], v[18:19], off offset:3072
	v_lshlrev_b64 v[40:41], 11, v[40:41]
	v_lshl_add_u64 v[40:41], v[36:37], 0, v[40:41]
	s_waitcnt vmcnt(0) lgkmcnt(0)
	v_mul_f32_e32 v0, v43, v43
	v_mul_f32_e32 v39, v47, v47
	v_mul_f32_e32 v58, v51, v51
	v_fmac_f32_e32 v0, v42, v42
	v_fmac_f32_e32 v39, v46, v46
	v_mul_f32_e32 v59, v55, v55
	v_fmac_f32_e32 v58, v50, v50
	v_fmac_f32_e32 v0, v44, v44
	v_fmac_f32_e32 v39, v48, v48
	v_fmac_f32_e32 v59, v54, v54
	v_fmac_f32_e32 v58, v52, v52
	v_mul_f32_e32 v60, v31, v31
	v_mul_f32_e32 v61, v27, v27
	v_fmac_f32_e32 v0, v45, v45
	v_fmac_f32_e32 v39, v49, v49
	v_fmac_f32_e32 v59, v56, v56
	v_mul_f32_e32 v62, v23, v23
	v_fmac_f32_e32 v58, v53, v53
	v_fmac_f32_e32 v60, v30, v30
	v_fmac_f32_e32 v61, v26, v26
	v_add_f32_e32 v0, v0, v39
	v_mul_f32_e32 v63, v19, v19
	v_fmac_f32_e32 v59, v57, v57
	v_fmac_f32_e32 v62, v22, v22
	v_fmac_f32_e32 v60, v32, v32
	v_fmac_f32_e32 v61, v28, v28
	v_add_f32_e32 v0, v0, v58
	v_fmac_f32_e32 v63, v18, v18
	v_fmac_f32_e32 v62, v24, v24
	v_fmac_f32_e32 v60, v33, v33
	v_fmac_f32_e32 v61, v29, v29
	v_add_f32_e32 v0, v0, v59
	v_fmac_f32_e32 v63, v20, v20
	v_fmac_f32_e32 v62, v25, v25
	v_add_f32_e32 v39, v60, v61
	v_add_f32_dpp v0, v0, v0 quad_perm:[1,0,3,2] row_mask:0xf bank_mask:0xf bound_ctrl:1
	v_fmac_f32_e32 v63, v21, v21
	v_add_f32_e32 v39, v39, v62
	v_add_f32_dpp v0, v0, v0 quad_perm:[2,3,0,1] row_mask:0xf bank_mask:0xf bound_ctrl:1
	v_add_f32_e32 v39, v39, v63
	s_nop 0
	v_add_f32_dpp v0, v0, v0 row_ror:4 row_mask:0xf bank_mask:0xf bound_ctrl:1
	v_add_f32_dpp v39, v39, v39 quad_perm:[1,0,3,2] row_mask:0xf bank_mask:0xf bound_ctrl:1
	s_nop 0
	v_add_f32_dpp v0, v0, v0 row_ror:8 row_mask:0xf bank_mask:0xf bound_ctrl:1
	v_add_f32_dpp v39, v39, v39 quad_perm:[2,3,0,1] row_mask:0xf bank_mask:0xf bound_ctrl:1
	v_mov_b32_e32 v58, v0
	s_nop 1
	v_permlane16_swap_b32_e32 v0, v58
	v_add_f32_dpp v39, v39, v39 row_ror:4 row_mask:0xf bank_mask:0xf bound_ctrl:1
	v_add_f32_e32 v58, v0, v58
	v_mov_b32_e32 v59, v58
	v_add_f32_dpp v39, v39, v39 row_ror:8 row_mask:0xf bank_mask:0xf bound_ctrl:1
	v_mov_b32_e32 v0, v39
	s_nop 1
	v_permlane16_swap_b32_e32 v39, v0
	v_permlane32_swap_b32_e32 v58, v59
	v_add_f32_e32 v0, v39, v0
	v_add_f32_e32 v39, v58, v59
	v_fmamk_f32 v39, v39, 0x3a800000, v216
	v_rsq_f32_e32 v58, v39
	v_mov_b32_e32 v39, v0
	s_nop 1
	v_permlane32_swap_b32_e32 v0, v39
	v_pk_mul_f32 v[42:43], v[42:43], v[58:59] op_sel_hi:[1,0]
	v_pk_mul_f32 v[44:45], v[44:45], v[58:59] op_sel_hi:[1,0]
	v_pk_mul_f32 v[42:43], v[2:3], v[42:43]
	v_pk_mul_f32 v[46:47], v[46:47], v[58:59] op_sel_hi:[1,0]
	v_pk_mul_f32 v[48:49], v[48:49], v[58:59] op_sel_hi:[1,0]
	v_pk_mul_f32 v[44:45], v[4:5], v[44:45]
	v_cvt_pk_bf16_f32 v42, v42, v43
	v_pk_mul_f32 v[50:51], v[50:51], v[58:59] op_sel_hi:[1,0]
	v_cvt_pk_bf16_f32 v43, v44, v45
	v_pk_mul_f32 v[52:53], v[52:53], v[58:59] op_sel_hi:[1,0]
	v_pk_mul_f32 v[48:49], v[8:9], v[48:49]
	v_pk_mul_f32 v[46:47], v[6:7], v[46:47]
	global_store_dwordx2 v[40:41], v[42:43], off
	v_cvt_pk_bf16_f32 v42, v46, v47
	v_cvt_pk_bf16_f32 v43, v48, v49
	v_pk_mul_f32 v[54:55], v[54:55], v[58:59] op_sel_hi:[1,0]
	v_pk_mul_f32 v[56:57], v[56:57], v[58:59] op_sel_hi:[1,0]
	v_pk_mul_f32 v[52:53], v[12:13], v[52:53]
	v_pk_mul_f32 v[50:51], v[10:11], v[50:51]
	global_store_dwordx2 v[40:41], v[42:43], off offset:512
	v_cvt_pk_bf16_f32 v42, v50, v51
	v_cvt_pk_bf16_f32 v43, v52, v53
	v_pk_mul_f32 v[56:57], v[16:17], v[56:57]
	v_pk_mul_f32 v[54:55], v[14:15], v[54:55]
	global_store_dwordx2 v[40:41], v[42:43], off offset:1024
	v_cvt_pk_bf16_f32 v42, v54, v55
	v_cvt_pk_bf16_f32 v43, v56, v57
	global_store_dwordx2 v[40:41], v[42:43], off offset:1536
	s_and_saveexec_b64 s[8:9], vcc
	s_cbranch_execz .LBB0_26
	v_add_f32_e32 v0, v0, v39
	v_fmamk_f32 v0, v0, 0x3a800000, v216
	v_rsq_f32_e32 v0, v0
	v_ashrrev_i32_e32 v39, 31, v38
	v_lshlrev_b64 v[40:41], 11, v[38:39]
	v_lshl_add_u64 v[40:41], v[36:37], 0, v[40:41]
	v_pk_mul_f32 v[30:31], v[30:31], v[0:1] op_sel_hi:[1,0]
	v_pk_mul_f32 v[26:27], v[26:27], v[0:1] op_sel_hi:[1,0]
	v_pk_mul_f32 v[22:23], v[22:23], v[0:1] op_sel_hi:[1,0]
	v_pk_mul_f32 v[18:19], v[18:19], v[0:1] op_sel_hi:[1,0]
	v_pk_mul_f32 v[32:33], v[32:33], v[0:1] op_sel_hi:[1,0]
	v_pk_mul_f32 v[30:31], v[2:3], v[30:31]
	v_pk_mul_f32 v[28:29], v[28:29], v[0:1] op_sel_hi:[1,0]
	v_pk_mul_f32 v[26:27], v[6:7], v[26:27]
	v_pk_mul_f32 v[24:25], v[24:25], v[0:1] op_sel_hi:[1,0]
	v_pk_mul_f32 v[22:23], v[10:11], v[22:23]
	v_pk_mul_f32 v[20:21], v[20:21], v[0:1] op_sel_hi:[1,0]
	v_pk_mul_f32 v[18:19], v[14:15], v[18:19]
	v_pk_mul_f32 v[32:33], v[4:5], v[32:33]
	v_cvt_pk_bf16_f32 v30, v30, v31
	v_pk_mul_f32 v[28:29], v[8:9], v[28:29]
	v_cvt_pk_bf16_f32 v31, v32, v33
	global_store_dwordx2 v[40:41], v[30:31], off
	v_cvt_pk_bf16_f32 v26, v26, v27
	v_cvt_pk_bf16_f32 v27, v28, v29
	global_store_dwordx2 v[40:41], v[26:27], off offset:512
	v_pk_mul_f32 v[24:25], v[12:13], v[24:25]
	v_cvt_pk_bf16_f32 v22, v22, v23
	v_pk_mul_f32 v[20:21], v[16:17], v[20:21]
	v_cvt_pk_bf16_f32 v23, v24, v25
	global_store_dwordx2 v[40:41], v[22:23], off offset:1024
	v_cvt_pk_bf16_f32 v18, v18, v19
	v_cvt_pk_bf16_f32 v19, v20, v21
	global_store_dwordx2 v[40:41], v[18:19], off offset:1536
	s_branch .LBB0_26

; DEVI unsigned cvtpk(float lo, float hi) { unsigned r; asm volatile("v_cvt_pk_bf16_f32 %0, %1, %2" : "=v"(r) : "v"(lo), "v"(hi)); return r; }
; DEVI float bflo(unsigned w) { return __uint_as_float(w << 16); }
; DEVI float bfhi(unsigned w) { return __uint_as_float(w & 0xffff0000u); }
; DEVI float sigmoidf_(float x) { return __builtin_amdgcn_rcpf(1.f + __expf(-x)); }
;     DEVI void operator()(AccRef acc, const pg8::Unit& u, int wr, int wc, int fr, int fq) const {
;         unsigned o = (unsigned)((u.pm * 256 + wr * 64 + fr) * DM + u.pn * 256 + wc * 32 + 8 * fq) * 2u;
; #pragma unroll
;         for (int ai = 0; ai < 2; ++ai) {
;             asm volatile("" : "+v"(o));
;             u32x4 gr[4][2];
; #pragma unroll
;             for (int m = 0; m < 4; ++m)
; #pragma unroll
;                 for (int bj = 0; bj < 2; ++bj) gr[m][bj] = *(const u32x4*)((const char*)gR + o + (unsigned)(m * 16 * DM * 2 + bj * 256));
; #pragma unroll
;             for (int m = 0; m < 4; ++m)
; #pragma unroll
;                 for (int bj = 0; bj < 2; ++bj) { const u32x4 r = gr[m][bj];
;                     const float rv[8] = {bflo(r.x), bfhi(r.x), bflo(r.y), bfhi(r.y), bflo(r.z), bfhi(r.z), bflo(r.w), bfhi(r.w)}; float v[8];
; #pragma unroll
;                     for (int j = 0; j < 8; ++j) v[j] = acc[ai][bj][m][j >> 2][j & 3] * sigmoidf_(rv[j]);
;                     u32x4 w; w.x = cvtpk(v[0], v[1]); w.y = cvtpk(v[2], v[3]); w.z = cvtpk(v[4], v[5]); w.w = cvtpk(v[6], v[7]); *(u32x4*)((char*)out + o + (unsigned)(m * 16 * DM * 2 + bj * 256)) = w; }
.LBB0_55:
	v_mov_b32_e32 v193, v1
	s_mov_b32 s85, s22
	v_lshl_add_u64 v[2:3], s[10:11], 0, v[192:193]
	global_load_dwordx4 v[160:163], v[2:3], off
	global_load_dwordx4 v[156:159], v[2:3], off offset:256
	v_add_co_u32_e32 v132, vcc, 0x8000, v2
	s_mov_b32 s84, s24
	s_nop 0
	v_addc_co_u32_e32 v133, vcc, 0, v3, vcc
	global_load_dwordx4 v[152:155], v[132:133], off
	global_load_dwordx4 v[148:151], v[132:133], off offset:256
	v_add_co_u32_e32 v132, vcc, 0x10000, v2
	s_mov_b64 s[86:87], s[80:81]
	s_nop 0
	v_addc_co_u32_e32 v133, vcc, 0, v3, vcc
	v_add_co_u32_e32 v2, vcc, 0x18000, v2
	global_load_dwordx4 v[144:147], v[132:133], off
	global_load_dwordx4 v[140:143], v[132:133], off offset:256
	v_addc_co_u32_e32 v3, vcc, 0, v3, vcc
	global_load_dwordx4 v[136:139], v[2:3], off
	global_load_dwordx4 v[132:135], v[2:3], off offset:256
	s_mov_b64 s[82:83], s[78:79]
	s_waitcnt vmcnt(0) lgkmcnt(0)
	v_and_b32_e32 v2, 0xffff0000, v160
	v_mul_f32_e32 v2, 0xbfb8aa3b, v2
	v_exp_f32_e32 v2, v2
	v_lshlrev_b32_e32 v0, 16, v160
	v_lshlrev_b32_e32 v3, 16, v161
	v_and_b32_e32 v160, 0xffff0000, v161
	v_add_f32_e32 v2, 1.0, v2
	v_rcp_f32_e32 v2, v2
	v_lshlrev_b32_e32 v161, 16, v162
	v_and_b32_e32 v162, 0xffff0000, v162
	v_mul_f32_e32 v0, 0xbfb8aa3b, v0
	v_mul_f32_e32 v2, v129, v2
	v_mul_f32_e32 v129, 0xbfb8aa3b, v161
	v_exp_f32_e32 v129, v129
	v_mul_f32_e32 v3, 0xbfb8aa3b, v3
	v_exp_f32_e32 v0, v0
	v_exp_f32_e32 v3, v3
	v_add_f32_e32 v129, 1.0, v129
	v_rcp_f32_e32 v129, v129
	v_add_f32_e32 v0, 1.0, v0
	v_add_f32_e32 v3, 1.0, v3
	v_rcp_f32_e32 v0, v0
	v_mul_f32_e32 v129, v124, v129
	v_mul_f32_e32 v124, 0xbfb8aa3b, v162
	v_exp_f32_e32 v124, v124
	v_rcp_f32_e32 v3, v3
	v_lshlrev_b32_e32 v164, 16, v163
	v_mul_f32_e32 v0, v128, v0
	v_add_f32_e32 v124, 1.0, v124
	v_rcp_f32_e32 v124, v124
	v_mul_f32_e32 v3, v130, v3
	v_mul_f32_e32 v128, 0xbfb8aa3b, v160
	v_exp_f32_e32 v128, v128
	v_mul_f32_e32 v130, v125, v124
	v_mul_f32_e32 v124, 0xbfb8aa3b, v164
	v_exp_f32_e32 v124, v124
	v_add_f32_e32 v128, 1.0, v128
	v_rcp_f32_e32 v128, v128
	v_and_b32_e32 v163, 0xffff0000, v163
	v_add_f32_e32 v124, 1.0, v124
	v_rcp_f32_e32 v124, v124
	v_mul_f32_e32 v128, v131, v128
	v_mul_f32_e32 v131, v126, v124
	v_mul_f32_e32 v124, 0xbfb8aa3b, v163
	v_exp_f32_e32 v124, v124
	s_nop 0
	v_add_f32_e32 v124, 1.0, v124
	v_rcp_f32_e32 v124, v124
	s_nop 0
	v_mul_f32_e32 v127, v127, v124
	v_cvt_pk_bf16_f32 v124, v0, v2
	v_lshlrev_b32_e32 v0, 16, v156
	v_mul_f32_e32 v0, 0xbfb8aa3b, v0
	v_exp_f32_e32 v0, v0
	v_cvt_pk_bf16_f32 v125, v3, v128
	v_lshl_add_u64 v[2:3], s[14:15], 0, v[192:193]
	v_cvt_pk_bf16_f32 v126, v129, v130
	v_add_f32_e32 v0, 1.0, v0
	v_rcp_f32_e32 v0, v0
	v_cvt_pk_bf16_f32 v127, v131, v127
	global_store_dwordx4 v[2:3], v[124:127], off
	v_and_b32_e32 v128, 0xffff0000, v158
	v_mul_f32_e32 v0, v120, v0
	v_and_b32_e32 v124, 0xffff0000, v156
	v_mul_f32_e32 v120, 0xbfb8aa3b, v124
	v_exp_f32_e32 v120, v120
	v_lshlrev_b32_e32 v125, 16, v157
	v_and_b32_e32 v126, 0xffff0000, v157
	v_lshlrev_b32_e32 v127, 16, v158
	v_add_f32_e32 v120, 1.0, v120
	v_rcp_f32_e32 v120, v120
	v_lshlrev_b32_e32 v129, 16, v159
	v_and_b32_e32 v130, 0xffff0000, v159
	v_mul_f32_e32 v120, v121, v120
	v_mul_f32_e32 v121, 0xbfb8aa3b, v125
	v_exp_f32_e32 v121, v121
	s_nop 0
	v_add_f32_e32 v121, 1.0, v121
	v_rcp_f32_e32 v121, v121
	s_nop 0
	v_mul_f32_e32 v121, v122, v121
	v_mul_f32_e32 v122, 0xbfb8aa3b, v126
	v_exp_f32_e32 v122, v122
	s_nop 0
	v_add_f32_e32 v122, 1.0, v122
	v_rcp_f32_e32 v122, v122
	s_nop 0
	v_mul_f32_e32 v122, v123, v122
	v_mul_f32_e32 v123, 0xbfb8aa3b, v127
	v_exp_f32_e32 v123, v123
	s_nop 0
	v_add_f32_e32 v123, 1.0, v123
	v_rcp_f32_e32 v123, v123
	s_nop 0
	v_mul_f32_e32 v123, v116, v123
	v_mul_f32_e32 v116, 0xbfb8aa3b, v128
	v_exp_f32_e32 v116, v116
	s_nop 0
	v_add_f32_e32 v116, 1.0, v116
	v_rcp_f32_e32 v116, v116
	s_nop 0
	v_mul_f32_e32 v124, v117, v116
	v_mul_f32_e32 v116, 0xbfb8aa3b, v129
	v_exp_f32_e32 v116, v116
	s_nop 0
	v_add_f32_e32 v116, 1.0, v116
	v_rcp_f32_e32 v116, v116
	s_nop 0
	v_mul_f32_e32 v125, v118, v116
	v_mul_f32_e32 v116, 0xbfb8aa3b, v130
	v_exp_f32_e32 v116, v116
	s_nop 0
	v_add_f32_e32 v116, 1.0, v116
	v_rcp_f32_e32 v116, v116
	s_nop 0
	v_mul_f32_e32 v119, v119, v116
	v_cvt_pk_bf16_f32 v116, v0, v120
	v_lshlrev_b32_e32 v0, 16, v152
	v_mul_f32_e32 v0, 0xbfb8aa3b, v0
	v_exp_f32_e32 v0, v0
	v_cvt_pk_bf16_f32 v117, v121, v122
	v_cvt_pk_bf16_f32 v118, v123, v124
	v_cvt_pk_bf16_f32 v119, v125, v119
	global_store_dwordx4 v[2:3], v[116:119], off offset:256
	v_add_f32_e32 v0, 1.0, v0
	v_rcp_f32_e32 v0, v0
	v_and_b32_e32 v116, 0xffff0000, v152
	v_lshlrev_b32_e32 v117, 16, v153
	v_and_b32_e32 v118, 0xffff0000, v153
	v_mul_f32_e32 v0, v112, v0
	v_mul_f32_e32 v112, 0xbfb8aa3b, v116
	v_exp_f32_e32 v112, v112
	v_lshlrev_b32_e32 v119, 16, v154
	v_and_b32_e32 v120, 0xffff0000, v154
	v_lshlrev_b32_e32 v121, 16, v155
	v_add_f32_e32 v112, 1.0, v112
	v_rcp_f32_e32 v112, v112
	v_and_b32_e32 v122, 0xffff0000, v155
	v_mul_f32_e32 v112, v113, v112
	v_mul_f32_e32 v113, 0xbfb8aa3b, v117
	v_exp_f32_e32 v113, v113
	s_nop 0
	v_add_f32_e32 v113, 1.0, v113
	v_rcp_f32_e32 v113, v113
	s_nop 0
	v_mul_f32_e32 v113, v114, v113
	v_mul_f32_e32 v114, 0xbfb8aa3b, v118
	v_exp_f32_e32 v114, v114
	s_nop 0
	v_add_f32_e32 v114, 1.0, v114
	v_rcp_f32_e32 v114, v114
	s_nop 0
	v_mul_f32_e32 v114, v115, v114
	v_mul_f32_e32 v115, 0xbfb8aa3b, v119
	v_exp_f32_e32 v115, v115
	s_nop 0
	v_add_f32_e32 v115, 1.0, v115
	v_rcp_f32_e32 v115, v115
	s_nop 0
	v_mul_f32_e32 v115, v108, v115
	v_mul_f32_e32 v108, 0xbfb8aa3b, v120
	v_exp_f32_e32 v108, v108
	s_nop 0
	v_add_f32_e32 v108, 1.0, v108
	v_rcp_f32_e32 v108, v108
	s_nop 0
	v_mul_f32_e32 v116, v109, v108
; DEVI unsigned cvtpk(float lo, float hi) { unsigned r; asm volatile("v_cvt_pk_bf16_f32 %0, %1, %2" : "=v"(r) : "v"(lo), "v"(hi)); return r; }
; DEVI float bflo(unsigned w) { return __uint_as_float(w << 16); }
; DEVI float bfhi(unsigned w) { return __uint_as_float(w & 0xffff0000u); }
; DEVI float sigmoidf_(float x) { return __builtin_amdgcn_rcpf(1.f + __expf(-x)); }
;     DEVI void operator()(AccRef acc, const pg8::Unit& u, int wr, int wc, int fr, int fq) const {
;     ...
;             for (int m = 0; m < 4; ++m)
; #pragma unroll
;                 for (int bj = 0; bj < 2; ++bj) { const u32x4 r = gr[m][bj];
;                     const float rv[8] = {bflo(r.x), bfhi(r.x), bflo(r.y), bfhi(r.y), bflo(r.z), bfhi(r.z), bflo(r.w), bfhi(r.w)}; float v[8];
; #pragma unroll
;                     for (int j = 0; j < 8; ++j) v[j] = acc[ai][bj][m][j >> 2][j & 3] * sigmoidf_(rv[j]);
;                     u32x4 w; w.x = cvtpk(v[0], v[1]); w.y = cvtpk(v[2], v[3]); w.z = cvtpk(v[4], v[5]); w.w = cvtpk(v[6], v[7]); *(u32x4*)((char*)out + o + (unsigned)(m * 16 * DM * 2 + bj * 256)) = w; }
	v_mul_f32_e32 v108, 0xbfb8aa3b, v121
	v_exp_f32_e32 v108, v108
	s_nop 0
	v_add_f32_e32 v108, 1.0, v108
	v_rcp_f32_e32 v108, v108
	s_nop 0
	v_mul_f32_e32 v117, v110, v108
	v_mul_f32_e32 v108, 0xbfb8aa3b, v122
	v_exp_f32_e32 v108, v108
	s_nop 0
	v_add_f32_e32 v108, 1.0, v108
	v_rcp_f32_e32 v108, v108
	s_nop 0
	v_mul_f32_e32 v111, v111, v108
	v_cvt_pk_bf16_f32 v108, v0, v112
	v_lshlrev_b32_e32 v0, 16, v148
	v_mul_f32_e32 v0, 0xbfb8aa3b, v0
	v_exp_f32_e32 v0, v0
	v_add_co_u32_e32 v112, vcc, s33, v2
	v_cvt_pk_bf16_f32 v109, v113, v114
	v_add_f32_e32 v0, 1.0, v0
	v_rcp_f32_e32 v0, v0
	v_addc_co_u32_e32 v113, vcc, 0, v3, vcc
	v_cvt_pk_bf16_f32 v110, v115, v116
	v_cvt_pk_bf16_f32 v111, v117, v111
	global_store_dwordx4 v[112:113], v[108:111], off
	v_mul_f32_e32 v0, v104, v0
	v_and_b32_e32 v114, 0xffff0000, v150
	v_and_b32_e32 v108, 0xffff0000, v148
	v_mul_f32_e32 v104, 0xbfb8aa3b, v108
	v_exp_f32_e32 v104, v104
	v_lshlrev_b32_e32 v109, 16, v149
	v_and_b32_e32 v110, 0xffff0000, v149
	v_lshlrev_b32_e32 v111, 16, v150
	v_add_f32_e32 v104, 1.0, v104
	v_rcp_f32_e32 v104, v104
	v_lshlrev_b32_e32 v115, 16, v151
	v_and_b32_e32 v116, 0xffff0000, v151
	v_mul_f32_e32 v104, v105, v104
	v_mul_f32_e32 v105, 0xbfb8aa3b, v109
	v_exp_f32_e32 v105, v105
	s_nop 0
	v_add_f32_e32 v105, 1.0, v105
	v_rcp_f32_e32 v105, v105
	s_nop 0
	v_mul_f32_e32 v105, v106, v105
	v_mul_f32_e32 v106, 0xbfb8aa3b, v110
	v_exp_f32_e32 v106, v106
	s_nop 0
	v_add_f32_e32 v106, 1.0, v106
	v_rcp_f32_e32 v106, v106
	s_nop 0
	v_mul_f32_e32 v106, v107, v106
	v_mul_f32_e32 v107, 0xbfb8aa3b, v111
	v_exp_f32_e32 v107, v107
	s_nop 0
	v_add_f32_e32 v107, 1.0, v107
	v_rcp_f32_e32 v107, v107
	s_nop 0
	v_mul_f32_e32 v107, v100, v107
	v_mul_f32_e32 v100, 0xbfb8aa3b, v114
	v_exp_f32_e32 v100, v100
	s_nop 0
	v_add_f32_e32 v100, 1.0, v100
	v_rcp_f32_e32 v100, v100
	s_nop 0
	v_mul_f32_e32 v108, v101, v100
	v_mul_f32_e32 v100, 0xbfb8aa3b, v115
	v_exp_f32_e32 v100, v100
	s_nop 0
	v_add_f32_e32 v100, 1.0, v100
	v_rcp_f32_e32 v100, v100
	s_nop 0
	v_mul_f32_e32 v109, v102, v100
	v_mul_f32_e32 v100, 0xbfb8aa3b, v116
	v_exp_f32_e32 v100, v100
	s_nop 0
	v_add_f32_e32 v100, 1.0, v100
	v_rcp_f32_e32 v100, v100
	s_nop 0
	v_mul_f32_e32 v103, v103, v100
	v_cvt_pk_bf16_f32 v100, v0, v104
	v_lshlrev_b32_e32 v0, 16, v144
	v_mul_f32_e32 v0, 0xbfb8aa3b, v0
	v_exp_f32_e32 v0, v0
	v_cvt_pk_bf16_f32 v101, v105, v106
	v_cvt_pk_bf16_f32 v102, v107, v108
	v_cvt_pk_bf16_f32 v103, v109, v103
	global_store_dwordx4 v[112:113], v[100:103], off offset:256
	v_add_f32_e32 v0, 1.0, v0
	v_rcp_f32_e32 v0, v0
	v_and_b32_e32 v100, 0xffff0000, v144
	v_lshlrev_b32_e32 v101, 16, v145
	v_and_b32_e32 v102, 0xffff0000, v145
	v_mul_f32_e32 v0, v96, v0
	v_mul_f32_e32 v96, 0xbfb8aa3b, v100
	v_exp_f32_e32 v96, v96
	v_lshlrev_b32_e32 v103, 16, v146
	v_and_b32_e32 v104, 0xffff0000, v146
	v_lshlrev_b32_e32 v105, 16, v147
	v_add_f32_e32 v96, 1.0, v96
	v_rcp_f32_e32 v96, v96
	v_and_b32_e32 v106, 0xffff0000, v147
	v_mul_f32_e32 v96, v97, v96
	v_mul_f32_e32 v97, 0xbfb8aa3b, v101
	v_exp_f32_e32 v97, v97
	s_nop 0
	v_add_f32_e32 v97, 1.0, v97
	v_rcp_f32_e32 v97, v97
	s_nop 0
	v_mul_f32_e32 v97, v98, v97
	v_mul_f32_e32 v98, 0xbfb8aa3b, v102
	v_exp_f32_e32 v98, v98
	s_nop 0
	v_add_f32_e32 v98, 1.0, v98
	v_rcp_f32_e32 v98, v98
	s_nop 0
	v_mul_f32_e32 v98, v99, v98
	v_mul_f32_e32 v99, 0xbfb8aa3b, v103
	v_exp_f32_e32 v99, v99
	s_nop 0
	v_add_f32_e32 v99, 1.0, v99
	v_rcp_f32_e32 v99, v99
	s_nop 0
	v_mul_f32_e32 v99, v92, v99
	v_mul_f32_e32 v92, 0xbfb8aa3b, v104
	v_exp_f32_e32 v92, v92
	s_nop 0
	v_add_f32_e32 v92, 1.0, v92
	v_rcp_f32_e32 v92, v92
	s_nop 0
	v_mul_f32_e32 v100, v93, v92
	v_mul_f32_e32 v92, 0xbfb8aa3b, v105
	v_exp_f32_e32 v92, v92
	s_nop 0
	v_add_f32_e32 v92, 1.0, v92
	v_rcp_f32_e32 v92, v92
	s_nop 0
	v_mul_f32_e32 v101, v94, v92
	v_mul_f32_e32 v92, 0xbfb8aa3b, v106
	v_exp_f32_e32 v92, v92
	s_nop 0
	v_add_f32_e32 v92, 1.0, v92
	v_rcp_f32_e32 v92, v92
	s_nop 0
	v_mul_f32_e32 v95, v95, v92
	v_cvt_pk_bf16_f32 v92, v0, v96
	v_lshlrev_b32_e32 v0, 16, v140
	v_mul_f32_e32 v0, 0xbfb8aa3b, v0
	v_exp_f32_e32 v0, v0
	v_add_co_u32_e32 v96, vcc, s54, v2
	v_cvt_pk_bf16_f32 v93, v97, v98
	v_add_f32_e32 v0, 1.0, v0
	v_rcp_f32_e32 v0, v0
	v_addc_co_u32_e32 v97, vcc, 0, v3, vcc
	v_cvt_pk_bf16_f32 v94, v99, v100
	v_cvt_pk_bf16_f32 v95, v101, v95
	global_store_dwordx4 v[96:97], v[92:95], off
	v_mul_f32_e32 v0, v88, v0
	v_and_b32_e32 v98, 0xffff0000, v142
	v_and_b32_e32 v92, 0xffff0000, v140
	v_mul_f32_e32 v88, 0xbfb8aa3b, v92
	v_exp_f32_e32 v88, v88
	v_lshlrev_b32_e32 v93, 16, v141
	v_and_b32_e32 v94, 0xffff0000, v141
	v_lshlrev_b32_e32 v95, 16, v142
	v_add_f32_e32 v88, 1.0, v88
	v_rcp_f32_e32 v88, v88
	v_lshlrev_b32_e32 v99, 16, v143
	v_and_b32_e32 v100, 0xffff0000, v143
	v_add_co_u32_e32 v2, vcc, s27, v2
	v_mul_f32_e32 v88, v89, v88
	v_mul_f32_e32 v89, 0xbfb8aa3b, v93
	v_exp_f32_e32 v89, v89
	v_addc_co_u32_e32 v3, vcc, 0, v3, vcc
	v_add_f32_e32 v89, 1.0, v89
	v_rcp_f32_e32 v89, v89
	s_nop 0
	v_mul_f32_e32 v89, v90, v89
	v_mul_f32_e32 v90, 0xbfb8aa3b, v94
	v_exp_f32_e32 v90, v90
	s_nop 0
	v_add_f32_e32 v90, 1.0, v90
	v_rcp_f32_e32 v90, v90
	s_nop 0
	v_mul_f32_e32 v90, v91, v90
	v_mul_f32_e32 v91, 0xbfb8aa3b, v95
	v_exp_f32_e32 v91, v91
	s_nop 0
	v_add_f32_e32 v91, 1.0, v91
	v_rcp_f32_e32 v91, v91
	s_nop 0
	v_mul_f32_e32 v91, v84, v91
	v_mul_f32_e32 v84, 0xbfb8aa3b, v98
	v_exp_f32_e32 v84, v84
	s_nop 0
	v_add_f32_e32 v84, 1.0, v84
	v_rcp_f32_e32 v84, v84
	s_nop 0
	v_mul_f32_e32 v92, v85, v84
	v_mul_f32_e32 v84, 0xbfb8aa3b, v99
	v_exp_f32_e32 v84, v84
	s_nop 0
	v_add_f32_e32 v84, 1.0, v84
	v_rcp_f32_e32 v84, v84
	s_nop 0
	v_mul_f32_e32 v93, v86, v84
	v_mul_f32_e32 v84, 0xbfb8aa3b, v100
; DEVI unsigned cvtpk(float lo, float hi) { unsigned r; asm volatile("v_cvt_pk_bf16_f32 %0, %1, %2" : "=v"(r) : "v"(lo), "v"(hi)); return r; }
; DEVI float bflo(unsigned w) { return __uint_as_float(w << 16); }
; DEVI float bfhi(unsigned w) { return __uint_as_float(w & 0xffff0000u); }
; DEVI float sigmoidf_(float x) { return __builtin_amdgcn_rcpf(1.f + __expf(-x)); }
;     DEVI void operator()(AccRef acc, const pg8::Unit& u, int wr, int wc, int fr, int fq) const {
;     ...
;         for (int ai = 0; ai < 2; ++ai) {
;             asm volatile("" : "+v"(o));
;             u32x4 gr[4][2];
; #pragma unroll
;             for (int m = 0; m < 4; ++m)
; #pragma unroll
;                 for (int bj = 0; bj < 2; ++bj) gr[m][bj] = *(const u32x4*)((const char*)gR + o + (unsigned)(m * 16 * DM * 2 + bj * 256));
; #pragma unroll
;             for (int m = 0; m < 4; ++m)
; #pragma unroll
;                 for (int bj = 0; bj < 2; ++bj) { const u32x4 r = gr[m][bj];
;                     const float rv[8] = {bflo(r.x), bfhi(r.x), bflo(r.y), bfhi(r.y), bflo(r.z), bfhi(r.z), bflo(r.w), bfhi(r.w)}; float v[8];
; #pragma unroll
;                     for (int j = 0; j < 8; ++j) v[j] = acc[ai][bj][m][j >> 2][j & 3] * sigmoidf_(rv[j]);
;                     u32x4 w; w.x = cvtpk(v[0], v[1]); w.y = cvtpk(v[2], v[3]); w.z = cvtpk(v[4], v[5]); w.w = cvtpk(v[6], v[7]); *(u32x4*)((char*)out + o + (unsigned)(m * 16 * DM * 2 + bj * 256)) = w; }
	v_exp_f32_e32 v84, v84
	s_nop 0
	v_add_f32_e32 v84, 1.0, v84
	v_rcp_f32_e32 v84, v84
	s_nop 0
	v_mul_f32_e32 v87, v87, v84
	v_cvt_pk_bf16_f32 v84, v0, v88
	v_lshlrev_b32_e32 v0, 16, v136
	v_mul_f32_e32 v0, 0xbfb8aa3b, v0
	v_exp_f32_e32 v0, v0
	v_cvt_pk_bf16_f32 v85, v89, v90
	v_cvt_pk_bf16_f32 v86, v91, v92
	v_cvt_pk_bf16_f32 v87, v93, v87
	global_store_dwordx4 v[96:97], v[84:87], off offset:256
	v_add_f32_e32 v0, 1.0, v0
	v_rcp_f32_e32 v0, v0
	v_and_b32_e32 v84, 0xffff0000, v136
	v_lshlrev_b32_e32 v85, 16, v137
	v_and_b32_e32 v86, 0xffff0000, v137
	v_mul_f32_e32 v0, v80, v0
	v_mul_f32_e32 v80, 0xbfb8aa3b, v84
	v_exp_f32_e32 v80, v80
	v_lshlrev_b32_e32 v87, 16, v138
	v_and_b32_e32 v88, 0xffff0000, v138
	v_lshlrev_b32_e32 v89, 16, v139
	v_add_f32_e32 v80, 1.0, v80
	v_rcp_f32_e32 v80, v80
	v_and_b32_e32 v90, 0xffff0000, v139
	v_mul_f32_e32 v80, v81, v80
	v_mul_f32_e32 v81, 0xbfb8aa3b, v85
	v_exp_f32_e32 v81, v81
	s_nop 0
	v_add_f32_e32 v81, 1.0, v81
	v_rcp_f32_e32 v81, v81
	s_nop 0
	v_mul_f32_e32 v81, v82, v81
	v_mul_f32_e32 v82, 0xbfb8aa3b, v86
	v_exp_f32_e32 v82, v82
	s_nop 0
	v_add_f32_e32 v82, 1.0, v82
	v_rcp_f32_e32 v82, v82
	s_nop 0
	v_mul_f32_e32 v82, v83, v82
	v_mul_f32_e32 v83, 0xbfb8aa3b, v87
	v_exp_f32_e32 v83, v83
	s_nop 0
	v_add_f32_e32 v83, 1.0, v83
	v_rcp_f32_e32 v83, v83
	s_nop 0
	v_mul_f32_e32 v83, v76, v83
	v_mul_f32_e32 v76, 0xbfb8aa3b, v88
	v_exp_f32_e32 v76, v76
	s_nop 0
	v_add_f32_e32 v76, 1.0, v76
	v_rcp_f32_e32 v76, v76
	s_nop 0
	v_mul_f32_e32 v84, v77, v76
	v_mul_f32_e32 v76, 0xbfb8aa3b, v89
	v_exp_f32_e32 v76, v76
	s_nop 0
	v_add_f32_e32 v76, 1.0, v76
	v_rcp_f32_e32 v76, v76
	s_nop 0
	v_mul_f32_e32 v85, v78, v76
	v_mul_f32_e32 v76, 0xbfb8aa3b, v90
	v_exp_f32_e32 v76, v76
	s_nop 0
	v_add_f32_e32 v76, 1.0, v76
	v_rcp_f32_e32 v76, v76
	s_nop 0
	v_mul_f32_e32 v79, v79, v76
	v_cvt_pk_bf16_f32 v76, v0, v80
	v_lshlrev_b32_e32 v0, 16, v132
	v_mul_f32_e32 v0, 0xbfb8aa3b, v0
	v_exp_f32_e32 v0, v0
	v_cvt_pk_bf16_f32 v77, v81, v82
	v_cvt_pk_bf16_f32 v78, v83, v84
	v_cvt_pk_bf16_f32 v79, v85, v79
	global_store_dwordx4 v[2:3], v[76:79], off
	v_add_f32_e32 v0, 1.0, v0
	v_rcp_f32_e32 v0, v0
	v_and_b32_e32 v76, 0xffff0000, v132
	v_lshlrev_b32_e32 v77, 16, v133
	v_and_b32_e32 v78, 0xffff0000, v133
	v_mul_f32_e32 v0, v72, v0
	v_mul_f32_e32 v72, 0xbfb8aa3b, v76
	v_exp_f32_e32 v72, v72
	v_lshlrev_b32_e32 v79, 16, v134
	v_and_b32_e32 v80, 0xffff0000, v134
	v_lshlrev_b32_e32 v81, 16, v135
	v_add_f32_e32 v72, 1.0, v72
	v_rcp_f32_e32 v72, v72
	v_and_b32_e32 v82, 0xffff0000, v135
	v_mul_f32_e32 v72, v73, v72
	v_mul_f32_e32 v73, 0xbfb8aa3b, v77
	v_exp_f32_e32 v73, v73
	s_nop 0
	v_add_f32_e32 v73, 1.0, v73
	v_rcp_f32_e32 v73, v73
	s_nop 0
	v_mul_f32_e32 v73, v74, v73
	v_mul_f32_e32 v74, 0xbfb8aa3b, v78
	v_exp_f32_e32 v74, v74
	s_nop 0
	v_add_f32_e32 v74, 1.0, v74
	v_rcp_f32_e32 v74, v74
	s_nop 0
	v_mul_f32_e32 v74, v75, v74
	v_mul_f32_e32 v75, 0xbfb8aa3b, v79
	v_exp_f32_e32 v75, v75
	s_nop 0
	v_add_f32_e32 v75, 1.0, v75
	v_rcp_f32_e32 v75, v75
	s_nop 0
	v_mul_f32_e32 v75, v68, v75
	v_mul_f32_e32 v68, 0xbfb8aa3b, v80
	v_exp_f32_e32 v68, v68
	s_nop 0
	v_add_f32_e32 v68, 1.0, v68
	v_rcp_f32_e32 v68, v68
	s_nop 0
	v_mul_f32_e32 v76, v69, v68
	v_mul_f32_e32 v68, 0xbfb8aa3b, v81
	v_exp_f32_e32 v68, v68
	s_nop 0
	v_add_f32_e32 v68, 1.0, v68
	v_rcp_f32_e32 v68, v68
	s_nop 0
	v_mul_f32_e32 v77, v70, v68
	v_mul_f32_e32 v68, 0xbfb8aa3b, v82
	v_exp_f32_e32 v68, v68
	s_nop 0
	v_add_f32_e32 v68, 1.0, v68
	v_rcp_f32_e32 v68, v68
	s_nop 0
	v_mul_f32_e32 v71, v71, v68
	v_cvt_pk_bf16_f32 v68, v0, v72
	v_add_u32_e32 v0, 0x40000, v192
	v_cvt_pk_bf16_f32 v69, v73, v74
	v_cvt_pk_bf16_f32 v70, v75, v76
	v_cvt_pk_bf16_f32 v71, v77, v71
	global_store_dwordx4 v[2:3], v[68:71], off offset:256
	s_nop 0
	v_lshl_add_u64 v[2:3], s[10:11], 0, v[0:1]
	global_load_dwordx4 v[92:95], v[2:3], off
	global_load_dwordx4 v[96:99], v[2:3], off offset:256
	v_add_co_u32_e32 v68, vcc, s33, v2
	s_waitcnt vmcnt(0) lgkmcnt(0)
	v_lshlrev_b32_e32 v100, 16, v94
	v_addc_co_u32_e32 v69, vcc, 0, v3, vcc
	global_load_dwordx4 v[88:91], v[68:69], off
	global_load_dwordx4 v[84:87], v[68:69], off offset:256
	v_add_co_u32_e32 v68, vcc, s54, v2
	v_and_b32_e32 v94, 0xffff0000, v94
	s_nop 0
	v_addc_co_u32_e32 v69, vcc, 0, v3, vcc
	v_add_co_u32_e32 v2, vcc, s27, v2
	global_load_dwordx4 v[80:83], v[68:69], off
	global_load_dwordx4 v[76:79], v[68:69], off offset:256
	v_addc_co_u32_e32 v3, vcc, 0, v3, vcc
	global_load_dwordx4 v[72:75], v[2:3], off
	global_load_dwordx4 v[68:71], v[2:3], off offset:256
	v_lshlrev_b32_e32 v2, 16, v92
	v_mul_f32_e32 v2, 0xbfb8aa3b, v2
	v_exp_f32_e32 v2, v2
	v_and_b32_e32 v3, 0xffff0000, v92
	v_lshlrev_b32_e32 v92, 16, v93
	v_mul_f32_e32 v3, 0xbfb8aa3b, v3
	v_add_f32_e32 v2, 1.0, v2
	v_rcp_f32_e32 v2, v2
	v_exp_f32_e32 v3, v3
	v_and_b32_e32 v93, 0xffff0000, v93
	v_lshlrev_b32_e32 v101, 16, v95
	v_mul_f32_e32 v2, v64, v2
	v_mul_f32_e32 v64, 0xbfb8aa3b, v92
	v_exp_f32_e32 v64, v64
	v_add_f32_e32 v3, 1.0, v3
	v_rcp_f32_e32 v3, v3
	v_and_b32_e32 v95, 0xffff0000, v95
	v_add_f32_e32 v64, 1.0, v64
	v_rcp_f32_e32 v64, v64
	v_mul_f32_e32 v3, v65, v3
	v_mul_f32_e32 v65, 0xbfb8aa3b, v93
	v_exp_f32_e32 v65, v65
	v_mul_f32_e32 v64, v66, v64
	v_mul_f32_e32 v66, 0xbfb8aa3b, v100
	v_exp_f32_e32 v66, v66
	v_add_f32_e32 v65, 1.0, v65
	v_rcp_f32_e32 v65, v65
	v_add_f32_e32 v66, 1.0, v66
	v_rcp_f32_e32 v66, v66
	v_mul_f32_e32 v65, v67, v65
	v_mul_f32_e32 v66, v60, v66
	v_mul_f32_e32 v60, 0xbfb8aa3b, v94
	v_exp_f32_e32 v60, v60
	s_nop 0
	v_add_f32_e32 v60, 1.0, v60
	v_rcp_f32_e32 v60, v60
	s_nop 0
	v_mul_f32_e32 v67, v61, v60
	v_mul_f32_e32 v60, 0xbfb8aa3b, v101
	v_exp_f32_e32 v60, v60
	s_nop 0
; DEVI unsigned cvtpk(float lo, float hi) { unsigned r; asm volatile("v_cvt_pk_bf16_f32 %0, %1, %2" : "=v"(r) : "v"(lo), "v"(hi)); return r; }
; DEVI float bflo(unsigned w) { return __uint_as_float(w << 16); }
; DEVI float bfhi(unsigned w) { return __uint_as_float(w & 0xffff0000u); }
; DEVI float sigmoidf_(float x) { return __builtin_amdgcn_rcpf(1.f + __expf(-x)); }
;     DEVI void operator()(AccRef acc, const pg8::Unit& u, int wr, int wc, int fr, int fq) const {
;     ...
;                 for (int bj = 0; bj < 2; ++bj) gr[m][bj] = *(const u32x4*)((const char*)gR + o + (unsigned)(m * 16 * DM * 2 + bj * 256));
; #pragma unroll
;             for (int m = 0; m < 4; ++m)
; #pragma unroll
;                 for (int bj = 0; bj < 2; ++bj) { const u32x4 r = gr[m][bj];
;                     const float rv[8] = {bflo(r.x), bfhi(r.x), bflo(r.y), bfhi(r.y), bflo(r.z), bfhi(r.z), bflo(r.w), bfhi(r.w)}; float v[8];
; #pragma unroll
;                     for (int j = 0; j < 8; ++j) v[j] = acc[ai][bj][m][j >> 2][j & 3] * sigmoidf_(rv[j]);
;                     u32x4 w; w.x = cvtpk(v[0], v[1]); w.y = cvtpk(v[2], v[3]); w.z = cvtpk(v[4], v[5]); w.w = cvtpk(v[6], v[7]); *(u32x4*)((char*)out + o + (unsigned)(m * 16 * DM * 2 + bj * 256)) = w; }
;             o += 128u * DM * 2u; }
	v_add_f32_e32 v60, 1.0, v60
	v_rcp_f32_e32 v60, v60
	s_nop 0
	v_mul_f32_e32 v92, v62, v60
	v_mul_f32_e32 v60, 0xbfb8aa3b, v95
	v_exp_f32_e32 v60, v60
	s_nop 0
	v_add_f32_e32 v60, 1.0, v60
	v_rcp_f32_e32 v60, v60
	s_nop 0
	v_mul_f32_e32 v63, v63, v60
	v_cvt_pk_bf16_f32 v60, v2, v3
	v_lshl_add_u64 v[2:3], s[14:15], 0, v[0:1]
	v_lshlrev_b32_e32 v0, 16, v96
	v_mul_f32_e32 v0, 0xbfb8aa3b, v0
	v_exp_f32_e32 v0, v0
	v_cvt_pk_bf16_f32 v61, v64, v65
	v_cvt_pk_bf16_f32 v62, v66, v67
	v_cvt_pk_bf16_f32 v63, v92, v63
	global_store_dwordx4 v[2:3], v[60:63], off
	v_add_f32_e32 v0, 1.0, v0
	v_rcp_f32_e32 v0, v0
	v_and_b32_e32 v60, 0xffff0000, v96
	v_lshlrev_b32_e32 v61, 16, v97
	v_and_b32_e32 v62, 0xffff0000, v97
	v_mul_f32_e32 v0, v56, v0
	v_mul_f32_e32 v56, 0xbfb8aa3b, v60
	v_exp_f32_e32 v56, v56
	v_lshlrev_b32_e32 v63, 16, v98
	v_and_b32_e32 v64, 0xffff0000, v98
	v_lshlrev_b32_e32 v65, 16, v99
	v_add_f32_e32 v56, 1.0, v56
	v_rcp_f32_e32 v56, v56
	v_and_b32_e32 v66, 0xffff0000, v99
	v_mul_f32_e32 v56, v57, v56
	v_mul_f32_e32 v57, 0xbfb8aa3b, v61
	v_exp_f32_e32 v57, v57
	s_nop 0
	v_add_f32_e32 v57, 1.0, v57
	v_rcp_f32_e32 v57, v57
	s_nop 0
	v_mul_f32_e32 v57, v58, v57
	v_mul_f32_e32 v58, 0xbfb8aa3b, v62
	v_exp_f32_e32 v58, v58
	s_nop 0
	v_add_f32_e32 v58, 1.0, v58
	v_rcp_f32_e32 v58, v58
	s_nop 0
	v_mul_f32_e32 v58, v59, v58
	v_mul_f32_e32 v59, 0xbfb8aa3b, v63
	v_exp_f32_e32 v59, v59
	s_nop 0
	v_add_f32_e32 v59, 1.0, v59
	v_rcp_f32_e32 v59, v59
	s_nop 0
	v_mul_f32_e32 v59, v52, v59
	v_mul_f32_e32 v52, 0xbfb8aa3b, v64
	v_exp_f32_e32 v52, v52
	s_nop 0
	v_add_f32_e32 v52, 1.0, v52
	v_rcp_f32_e32 v52, v52
	s_nop 0
	v_mul_f32_e32 v60, v53, v52
	v_mul_f32_e32 v52, 0xbfb8aa3b, v65
	v_exp_f32_e32 v52, v52
	s_nop 0
	v_add_f32_e32 v52, 1.0, v52
	v_rcp_f32_e32 v52, v52
	s_nop 0
	v_mul_f32_e32 v61, v54, v52
	v_mul_f32_e32 v52, 0xbfb8aa3b, v66
	v_exp_f32_e32 v52, v52
	s_nop 0
	v_add_f32_e32 v52, 1.0, v52
	v_rcp_f32_e32 v52, v52
	s_nop 0
	v_mul_f32_e32 v55, v55, v52
	v_cvt_pk_bf16_f32 v52, v0, v56
	s_waitcnt vmcnt(0) lgkmcnt(0)
	v_lshlrev_b32_e32 v0, 16, v88
	v_mul_f32_e32 v0, 0xbfb8aa3b, v0
	v_exp_f32_e32 v0, v0
	v_cvt_pk_bf16_f32 v53, v57, v58
	v_cvt_pk_bf16_f32 v54, v59, v60
	v_cvt_pk_bf16_f32 v55, v61, v55
	global_store_dwordx4 v[2:3], v[52:55], off offset:256
	v_add_f32_e32 v0, 1.0, v0
	v_rcp_f32_e32 v0, v0
	v_and_b32_e32 v52, 0xffff0000, v88
	v_lshlrev_b32_e32 v53, 16, v89
	v_and_b32_e32 v54, 0xffff0000, v89
	v_mul_f32_e32 v0, v48, v0
	v_mul_f32_e32 v48, 0xbfb8aa3b, v52
	v_exp_f32_e32 v48, v48
	v_lshlrev_b32_e32 v55, 16, v90
	v_and_b32_e32 v56, 0xffff0000, v90
	v_lshlrev_b32_e32 v57, 16, v91
	v_add_f32_e32 v48, 1.0, v48
	v_rcp_f32_e32 v48, v48
	v_and_b32_e32 v58, 0xffff0000, v91
	v_mul_f32_e32 v48, v49, v48
	v_mul_f32_e32 v49, 0xbfb8aa3b, v53
	v_exp_f32_e32 v49, v49
	s_nop 0
	v_add_f32_e32 v49, 1.0, v49
	v_rcp_f32_e32 v49, v49
	s_nop 0
	v_mul_f32_e32 v49, v50, v49
	v_mul_f32_e32 v50, 0xbfb8aa3b, v54
	v_exp_f32_e32 v50, v50
	s_nop 0
	v_add_f32_e32 v50, 1.0, v50
	v_rcp_f32_e32 v50, v50
	s_nop 0
	v_mul_f32_e32 v50, v51, v50
	v_mul_f32_e32 v51, 0xbfb8aa3b, v55
	v_exp_f32_e32 v51, v51
	s_nop 0
	v_add_f32_e32 v51, 1.0, v51
	v_rcp_f32_e32 v51, v51
	s_nop 0
	v_mul_f32_e32 v51, v44, v51
	v_mul_f32_e32 v44, 0xbfb8aa3b, v56
	v_exp_f32_e32 v44, v44
	s_nop 0
	v_add_f32_e32 v44, 1.0, v44
	v_rcp_f32_e32 v44, v44
	s_nop 0
	v_mul_f32_e32 v52, v45, v44
	v_mul_f32_e32 v44, 0xbfb8aa3b, v57
	v_exp_f32_e32 v44, v44
	s_nop 0
	v_add_f32_e32 v44, 1.0, v44
	v_rcp_f32_e32 v44, v44
	s_nop 0
	v_mul_f32_e32 v53, v46, v44
	v_mul_f32_e32 v44, 0xbfb8aa3b, v58
	v_exp_f32_e32 v44, v44
	s_nop 0
	v_add_f32_e32 v44, 1.0, v44
	v_rcp_f32_e32 v44, v44
	s_nop 0
	v_mul_f32_e32 v47, v47, v44
	v_cvt_pk_bf16_f32 v44, v0, v48
	v_lshlrev_b32_e32 v0, 16, v84
	v_mul_f32_e32 v0, 0xbfb8aa3b, v0
	v_exp_f32_e32 v0, v0
	v_add_co_u32_e32 v48, vcc, s33, v2
	v_cvt_pk_bf16_f32 v45, v49, v50
	v_add_f32_e32 v0, 1.0, v0
	v_rcp_f32_e32 v0, v0
	v_addc_co_u32_e32 v49, vcc, 0, v3, vcc
	v_cvt_pk_bf16_f32 v46, v51, v52
	v_cvt_pk_bf16_f32 v47, v53, v47
	global_store_dwordx4 v[48:49], v[44:47], off
	v_mul_f32_e32 v0, v40, v0
	v_and_b32_e32 v50, 0xffff0000, v86
	v_and_b32_e32 v44, 0xffff0000, v84
	v_mul_f32_e32 v40, 0xbfb8aa3b, v44
	v_exp_f32_e32 v40, v40
	v_lshlrev_b32_e32 v45, 16, v85
	v_and_b32_e32 v46, 0xffff0000, v85
	v_lshlrev_b32_e32 v47, 16, v86
	v_add_f32_e32 v40, 1.0, v40
	v_rcp_f32_e32 v40, v40
	v_lshlrev_b32_e32 v51, 16, v87
	v_and_b32_e32 v52, 0xffff0000, v87
	v_mul_f32_e32 v40, v41, v40
	v_mul_f32_e32 v41, 0xbfb8aa3b, v45
	v_exp_f32_e32 v41, v41
	s_nop 0
	v_add_f32_e32 v41, 1.0, v41
	v_rcp_f32_e32 v41, v41
	s_nop 0
	v_mul_f32_e32 v41, v42, v41
	v_mul_f32_e32 v42, 0xbfb8aa3b, v46
	v_exp_f32_e32 v42, v42
	s_nop 0
	v_add_f32_e32 v42, 1.0, v42
	v_rcp_f32_e32 v42, v42
	s_nop 0
	v_mul_f32_e32 v42, v43, v42
	v_mul_f32_e32 v43, 0xbfb8aa3b, v47
	v_exp_f32_e32 v43, v43
	s_nop 0
	v_add_f32_e32 v43, 1.0, v43
	v_rcp_f32_e32 v43, v43
	s_nop 0
	v_mul_f32_e32 v43, v36, v43
	v_mul_f32_e32 v36, 0xbfb8aa3b, v50
	v_exp_f32_e32 v36, v36
	s_nop 0
	v_add_f32_e32 v36, 1.0, v36
	v_rcp_f32_e32 v36, v36
	s_nop 0
	v_mul_f32_e32 v44, v37, v36
	v_mul_f32_e32 v36, 0xbfb8aa3b, v51
	v_exp_f32_e32 v36, v36
	s_nop 0
	v_add_f32_e32 v36, 1.0, v36
	v_rcp_f32_e32 v36, v36
	s_nop 0
	v_mul_f32_e32 v45, v38, v36
	v_mul_f32_e32 v36, 0xbfb8aa3b, v52
	v_exp_f32_e32 v36, v36
	s_nop 0
	v_add_f32_e32 v36, 1.0, v36
	v_rcp_f32_e32 v36, v36
	s_nop 0
	v_mul_f32_e32 v39, v39, v36
	v_cvt_pk_bf16_f32 v36, v0, v40
	v_lshlrev_b32_e32 v0, 16, v80
	v_mul_f32_e32 v0, 0xbfb8aa3b, v0
	v_exp_f32_e32 v0, v0
	v_cvt_pk_bf16_f32 v37, v41, v42
	v_cvt_pk_bf16_f32 v38, v43, v44
; DEVI unsigned cvtpk(float lo, float hi) { unsigned r; asm volatile("v_cvt_pk_bf16_f32 %0, %1, %2" : "=v"(r) : "v"(lo), "v"(hi)); return r; }
; DEVI float bflo(unsigned w) { return __uint_as_float(w << 16); }
; DEVI float bfhi(unsigned w) { return __uint_as_float(w & 0xffff0000u); }
; DEVI float sigmoidf_(float x) { return __builtin_amdgcn_rcpf(1.f + __expf(-x)); }
;     DEVI void operator()(AccRef acc, const pg8::Unit& u, int wr, int wc, int fr, int fq) const {
;     ...
;                 for (int bj = 0; bj < 2; ++bj) gr[m][bj] = *(const u32x4*)((const char*)gR + o + (unsigned)(m * 16 * DM * 2 + bj * 256));
; #pragma unroll
;             for (int m = 0; m < 4; ++m)
; #pragma unroll
;                 for (int bj = 0; bj < 2; ++bj) { const u32x4 r = gr[m][bj];
;                     const float rv[8] = {bflo(r.x), bfhi(r.x), bflo(r.y), bfhi(r.y), bflo(r.z), bfhi(r.z), bflo(r.w), bfhi(r.w)}; float v[8];
; #pragma unroll
;                     for (int j = 0; j < 8; ++j) v[j] = acc[ai][bj][m][j >> 2][j & 3] * sigmoidf_(rv[j]);
;                     u32x4 w; w.x = cvtpk(v[0], v[1]); w.y = cvtpk(v[2], v[3]); w.z = cvtpk(v[4], v[5]); w.w = cvtpk(v[6], v[7]); *(u32x4*)((char*)out + o + (unsigned)(m * 16 * DM * 2 + bj * 256)) = w; }
;             o += 128u * DM * 2u; }
	v_cvt_pk_bf16_f32 v39, v45, v39
	global_store_dwordx4 v[48:49], v[36:39], off offset:256
	v_add_f32_e32 v0, 1.0, v0
	v_rcp_f32_e32 v0, v0
	v_and_b32_e32 v36, 0xffff0000, v80
	v_lshlrev_b32_e32 v37, 16, v81
	v_and_b32_e32 v38, 0xffff0000, v81
	v_mul_f32_e32 v0, v32, v0
	v_mul_f32_e32 v32, 0xbfb8aa3b, v36
	v_exp_f32_e32 v32, v32
	v_lshlrev_b32_e32 v39, 16, v82
	v_and_b32_e32 v40, 0xffff0000, v82
	v_lshlrev_b32_e32 v41, 16, v83
	v_add_f32_e32 v32, 1.0, v32
	v_rcp_f32_e32 v32, v32
	v_and_b32_e32 v42, 0xffff0000, v83
	v_mul_f32_e32 v32, v33, v32
	v_mul_f32_e32 v33, 0xbfb8aa3b, v37
	v_exp_f32_e32 v33, v33
	s_nop 0
	v_add_f32_e32 v33, 1.0, v33
	v_rcp_f32_e32 v33, v33
	s_nop 0
	v_mul_f32_e32 v33, v34, v33
	v_mul_f32_e32 v34, 0xbfb8aa3b, v38
	v_exp_f32_e32 v34, v34
	s_nop 0
	v_add_f32_e32 v34, 1.0, v34
	v_rcp_f32_e32 v34, v34
	s_nop 0
	v_mul_f32_e32 v34, v35, v34
	v_mul_f32_e32 v35, 0xbfb8aa3b, v39
	v_exp_f32_e32 v35, v35
	s_nop 0
	v_add_f32_e32 v35, 1.0, v35
	v_rcp_f32_e32 v35, v35
	s_nop 0
	v_mul_f32_e32 v35, v28, v35
	v_mul_f32_e32 v28, 0xbfb8aa3b, v40
	v_exp_f32_e32 v28, v28
	s_nop 0
	v_add_f32_e32 v28, 1.0, v28
	v_rcp_f32_e32 v28, v28
	s_nop 0
	v_mul_f32_e32 v36, v29, v28
	v_mul_f32_e32 v28, 0xbfb8aa3b, v41
	v_exp_f32_e32 v28, v28
	s_nop 0
	v_add_f32_e32 v28, 1.0, v28
	v_rcp_f32_e32 v28, v28
	s_nop 0
	v_mul_f32_e32 v37, v30, v28
	v_mul_f32_e32 v28, 0xbfb8aa3b, v42
	v_exp_f32_e32 v28, v28
	s_nop 0
	v_add_f32_e32 v28, 1.0, v28
	v_rcp_f32_e32 v28, v28
	s_nop 0
	v_mul_f32_e32 v31, v31, v28
	v_cvt_pk_bf16_f32 v28, v0, v32
	v_lshlrev_b32_e32 v0, 16, v76
	v_mul_f32_e32 v0, 0xbfb8aa3b, v0
	v_exp_f32_e32 v0, v0
	v_add_co_u32_e32 v32, vcc, s54, v2
	v_cvt_pk_bf16_f32 v29, v33, v34
	v_add_f32_e32 v0, 1.0, v0
	v_rcp_f32_e32 v0, v0
	v_addc_co_u32_e32 v33, vcc, 0, v3, vcc
	v_cvt_pk_bf16_f32 v30, v35, v36
	v_cvt_pk_bf16_f32 v31, v37, v31
	global_store_dwordx4 v[32:33], v[28:31], off
	v_mul_f32_e32 v0, v24, v0
	v_and_b32_e32 v34, 0xffff0000, v78
	v_and_b32_e32 v28, 0xffff0000, v76
	v_mul_f32_e32 v24, 0xbfb8aa3b, v28
	v_exp_f32_e32 v24, v24
	v_lshlrev_b32_e32 v29, 16, v77
	v_and_b32_e32 v30, 0xffff0000, v77
	v_lshlrev_b32_e32 v31, 16, v78
	v_add_f32_e32 v24, 1.0, v24
	v_rcp_f32_e32 v24, v24
	v_lshlrev_b32_e32 v35, 16, v79
	v_and_b32_e32 v36, 0xffff0000, v79
	v_mul_f32_e32 v24, v25, v24
	v_mul_f32_e32 v25, 0xbfb8aa3b, v29
	v_exp_f32_e32 v25, v25
	s_nop 0
	v_add_f32_e32 v25, 1.0, v25
	v_rcp_f32_e32 v25, v25
	s_nop 0
	v_mul_f32_e32 v25, v26, v25
	v_mul_f32_e32 v26, 0xbfb8aa3b, v30
	v_exp_f32_e32 v26, v26
	s_nop 0
	v_add_f32_e32 v26, 1.0, v26
	v_rcp_f32_e32 v26, v26
	s_nop 0
	v_mul_f32_e32 v26, v27, v26
	v_mul_f32_e32 v27, 0xbfb8aa3b, v31
	v_exp_f32_e32 v27, v27
	s_nop 0
	v_add_f32_e32 v27, 1.0, v27
	v_rcp_f32_e32 v27, v27
	s_nop 0
	v_mul_f32_e32 v27, v20, v27
	v_mul_f32_e32 v20, 0xbfb8aa3b, v34
	v_exp_f32_e32 v20, v20
	s_nop 0
	v_add_f32_e32 v20, 1.0, v20
	v_rcp_f32_e32 v20, v20
	s_nop 0
	v_mul_f32_e32 v28, v21, v20
	v_mul_f32_e32 v20, 0xbfb8aa3b, v35
	v_exp_f32_e32 v20, v20
	s_nop 0
	v_add_f32_e32 v20, 1.0, v20
	v_rcp_f32_e32 v20, v20
	s_nop 0
	v_mul_f32_e32 v29, v22, v20
	v_mul_f32_e32 v20, 0xbfb8aa3b, v36
	v_exp_f32_e32 v20, v20
	s_nop 0
	v_add_f32_e32 v20, 1.0, v20
	v_rcp_f32_e32 v20, v20
	s_nop 0
	v_mul_f32_e32 v23, v23, v20
	v_cvt_pk_bf16_f32 v20, v0, v24
	v_lshlrev_b32_e32 v0, 16, v72
	v_mul_f32_e32 v0, 0xbfb8aa3b, v0
	v_exp_f32_e32 v0, v0
	v_cvt_pk_bf16_f32 v21, v25, v26
	v_cvt_pk_bf16_f32 v22, v27, v28
	v_cvt_pk_bf16_f32 v23, v29, v23
	global_store_dwordx4 v[32:33], v[20:23], off offset:256
	v_add_f32_e32 v0, 1.0, v0
	v_rcp_f32_e32 v0, v0
	v_and_b32_e32 v20, 0xffff0000, v72
	v_lshlrev_b32_e32 v21, 16, v73
	v_and_b32_e32 v22, 0xffff0000, v73
	v_mul_f32_e32 v0, v16, v0
	v_mul_f32_e32 v16, 0xbfb8aa3b, v20
	v_exp_f32_e32 v16, v16
	v_lshlrev_b32_e32 v23, 16, v74
	v_and_b32_e32 v24, 0xffff0000, v74
	v_lshlrev_b32_e32 v25, 16, v75
	v_add_f32_e32 v16, 1.0, v16
	v_rcp_f32_e32 v16, v16
	v_and_b32_e32 v26, 0xffff0000, v75
	v_mul_f32_e32 v16, v17, v16
	v_mul_f32_e32 v17, 0xbfb8aa3b, v21
	v_exp_f32_e32 v17, v17
	s_nop 0
	v_add_f32_e32 v17, 1.0, v17
	v_rcp_f32_e32 v17, v17
	s_nop 0
	v_mul_f32_e32 v17, v18, v17
	v_mul_f32_e32 v18, 0xbfb8aa3b, v22
	v_exp_f32_e32 v18, v18
	s_nop 0
	v_add_f32_e32 v18, 1.0, v18
	v_rcp_f32_e32 v18, v18
	s_nop 0
	v_mul_f32_e32 v18, v19, v18
	v_mul_f32_e32 v19, 0xbfb8aa3b, v23
	v_exp_f32_e32 v19, v19
	s_nop 0
	v_add_f32_e32 v19, 1.0, v19
	v_rcp_f32_e32 v19, v19
	s_nop 0
	v_mul_f32_e32 v19, v12, v19
	v_mul_f32_e32 v12, 0xbfb8aa3b, v24
	v_exp_f32_e32 v12, v12
	s_nop 0
	v_add_f32_e32 v12, 1.0, v12
	v_rcp_f32_e32 v12, v12
	s_nop 0
	v_mul_f32_e32 v20, v13, v12
	v_mul_f32_e32 v12, 0xbfb8aa3b, v25
	v_exp_f32_e32 v12, v12
	s_nop 0
	v_add_f32_e32 v12, 1.0, v12
	v_rcp_f32_e32 v12, v12
	s_nop 0
	v_mul_f32_e32 v21, v14, v12
	v_mul_f32_e32 v12, 0xbfb8aa3b, v26
	v_exp_f32_e32 v12, v12
	s_nop 0
	v_add_f32_e32 v12, 1.0, v12
	v_rcp_f32_e32 v12, v12
	s_nop 0
	v_mul_f32_e32 v15, v15, v12
	v_cvt_pk_bf16_f32 v12, v0, v16
	v_add_co_u32_e32 v16, vcc, s27, v2
	v_and_b32_e32 v2, 0xffff0000, v68
	v_mul_f32_e32 v2, 0xbfb8aa3b, v2
	v_exp_f32_e32 v2, v2
	v_cvt_pk_bf16_f32 v13, v17, v18
	v_addc_co_u32_e32 v17, vcc, 0, v3, vcc
	v_add_f32_e32 v2, 1.0, v2
	v_rcp_f32_e32 v2, v2
	v_cvt_pk_bf16_f32 v14, v19, v20
	v_cvt_pk_bf16_f32 v15, v21, v15
	global_store_dwordx4 v[16:17], v[12:15], off
	v_mul_f32_e32 v2, v9, v2
	v_lshlrev_b32_e32 v0, 16, v68
	v_lshlrev_b32_e32 v13, 16, v70
	v_mul_f32_e32 v9, 0xbfb8aa3b, v13
	v_exp_f32_e32 v9, v9
	v_and_b32_e32 v14, 0xffff0000, v70
	v_lshlrev_b32_e32 v15, 16, v71
	v_mul_f32_e32 v0, 0xbfb8aa3b, v0
	v_add_f32_e32 v9, 1.0, v9
	v_rcp_f32_e32 v9, v9
	v_exp_f32_e32 v0, v0
	v_lshlrev_b32_e32 v3, 16, v69
	v_and_b32_e32 v12, 0xffff0000, v69
	v_mul_f32_e32 v4, v4, v9
	v_mul_f32_e32 v9, 0xbfb8aa3b, v14
	v_exp_f32_e32 v9, v9
	v_add_f32_e32 v0, 1.0, v0
	v_rcp_f32_e32 v0, v0
	v_and_b32_e32 v18, 0xffff0000, v71
	v_add_f32_e32 v9, 1.0, v9
	v_rcp_f32_e32 v9, v9
	v_mul_f32_e32 v3, 0xbfb8aa3b, v3
	v_mul_f32_e32 v0, v8, v0
	v_exp_f32_e32 v3, v3
	v_mul_f32_e32 v5, v5, v9
	v_mul_f32_e32 v9, 0xbfb8aa3b, v15
	v_exp_f32_e32 v9, v9
	v_mul_f32_e32 v8, 0xbfb8aa3b, v12
	v_exp_f32_e32 v8, v8
	v_add_f32_e32 v3, 1.0, v3
	v_add_f32_e32 v9, 1.0, v9
	v_rcp_f32_e32 v9, v9
	v_rcp_f32_e32 v3, v3
	v_add_f32_e32 v8, 1.0, v8
	v_rcp_f32_e32 v8, v8
	v_mul_f32_e32 v6, v6, v9
	v_mul_f32_e32 v9, 0xbfb8aa3b, v18
	v_exp_f32_e32 v9, v9
	v_mul_f32_e32 v3, v10, v3
	s_and_b64 vcc, exec, s[4:5]
	v_mul_f32_e32 v8, v11, v8
	v_add_f32_e32 v9, 1.0, v9
	v_rcp_f32_e32 v9, v9
	v_cvt_pk_bf16_f32 v2, v0, v2
	v_cvt_pk_bf16_f32 v3, v3, v8
	v_cvt_pk_bf16_f32 v4, v4, v5
	s_nop 0
	v_mul_f32_e32 v7, v7, v9
	v_cvt_pk_bf16_f32 v5, v6, v7
	global_store_dwordx4 v[16:17], v[2:5], off offset:256
	s_cbranch_vccnz .LBB0_66

; DEVI float bflo(unsigned w) { return __uint_as_float(w << 16); }
; DEVI float bfhi(unsigned w) { return __uint_as_float(w & 0xffff0000u); }
;     DEVI void mid(AccRef acc, const pg8::Unit& u, int wr, int wc, int fr, int fq) const {
;     ...
;         for (int ai = 0; ai < 2; ++ai) {
;             asm volatile("" : "+v"(o));
;             u32x4 ga[4][2], gr[4][2];
; #pragma unroll
;             for (int m = 0; m < 4; ++m)
; #pragma unroll
;                 for (int bj = 0; bj < 2; ++bj) { ga[m][bj] = *(const u32x4*)((const char*)gA + o + (unsigned)(m * 16 * DM * 2 + bj * 256)); gr[m][bj] = *(const u32x4*)((const char*)gR + o + (unsigned)(m * 16 * DM * 2 + bj * 256)); }
; #pragma unroll
;             for (int m = 0; m < 4; ++m)
; #pragma unroll
;                 for (int bj = 0; bj < 2; ++bj) { const u32x4 a = ga[m][bj], r = gr[m][bj];
;                     const float av[8] = {bflo(a.x), bfhi(a.x), bflo(a.y), bfhi(a.y), bflo(a.z), bfhi(a.z), bflo(a.w), bfhi(a.w)};
;                     const float rv[8] = {bflo(r.x), bfhi(r.x), bflo(r.y), bfhi(r.y), bflo(r.z), bfhi(r.z), bflo(r.w), bfhi(r.w)};
; #pragma unroll
;                     for (int j = 0; j < 8; ++j) { const float q = (1.f + __expf(-rv[j])) * __builtin_amdgcn_rcpf(1.f + __expf(-av[j])); acc[ai][bj][m][j >> 2][j & 3] *= q; } }
.LBB0_64:
	s_cmpk_lg_i32 s84, 0x800
	s_cbranch_scc1 .LBB0_63
	v_mov_b32_e32 v0, v192
	s_nop 0
	v_lshl_add_u64 v[2:3], s[8:9], 0, v[0:1]
	global_load_dwordx4 v[196:199], v[2:3], off
	v_lshl_add_u64 v[132:133], s[10:11], 0, v[0:1]
	global_load_dwordx4 v[206:209], v[132:133], off
	global_load_dwordx4 v[210:213], v[2:3], off offset:256
	global_load_dwordx4 v[218:221], v[132:133], off offset:256
	v_add_co_u32_e32 v134, vcc, 0x8000, v2
	v_add_u32_e32 v0, 0x40000, v0
	s_nop 0
	v_addc_co_u32_e32 v135, vcc, 0, v3, vcc
	v_add_co_u32_e32 v136, vcc, 0x8000, v132
	global_load_dwordx4 v[176:179], v[134:135], off
	global_load_dwordx4 v[168:171], v[134:135], off offset:256
	v_addc_co_u32_e32 v137, vcc, 0, v133, vcc
	global_load_dwordx4 v[172:175], v[136:137], off
	global_load_dwordx4 v[164:167], v[136:137], off offset:256
	v_add_co_u32_e32 v134, vcc, 0x10000, v2
	s_waitcnt vmcnt(0) lgkmcnt(0)
	v_lshlrev_b32_e32 v223, 16, v209
	v_addc_co_u32_e32 v135, vcc, 0, v3, vcc
	v_add_co_u32_e32 v136, vcc, 0x10000, v132
	global_load_dwordx4 v[156:159], v[134:135], off
	global_load_dwordx4 v[148:151], v[134:135], off offset:256
	v_addc_co_u32_e32 v137, vcc, 0, v133, vcc
	v_add_co_u32_e32 v2, vcc, 0x18000, v2
	global_load_dwordx4 v[160:163], v[136:137], off
	global_load_dwordx4 v[152:155], v[136:137], off offset:256
	v_addc_co_u32_e32 v3, vcc, 0, v3, vcc
	v_add_co_u32_e32 v132, vcc, 0x18000, v132
	v_lshlrev_b32_e32 v193, 16, v197
	s_nop 0
	v_addc_co_u32_e32 v133, vcc, 0, v133, vcc
	global_load_dwordx4 v[144:147], v[2:3], off
	global_load_dwordx4 v[136:139], v[2:3], off offset:256
	global_load_dwordx4 v[140:143], v[132:133], off
	s_nop 0
	global_load_dwordx4 v[132:135], v[132:133], off offset:256
	v_lshlrev_b32_e32 v2, 16, v196
	v_and_b32_e32 v3, 0xffff0000, v196
	v_and_b32_e32 v196, 0xffff0000, v197
	v_lshlrev_b32_e32 v197, 16, v198
	v_and_b32_e32 v205, 0xffff0000, v198
	v_lshlrev_b32_e32 v214, 16, v199
	v_and_b32_e32 v215, 0xffff0000, v199
	v_lshlrev_b32_e32 v198, 16, v206
	v_and_b32_e32 v199, 0xffff0000, v206
	v_mul_f32_e32 v198, 0xbfb8aa3b, v198
	v_mul_f32_e32 v224, 0xbfb8aa3b, v2
	v_mul_f32_e32 v199, 0xbfb8aa3b, v199
	v_mul_f32_e32 v225, 0xbfb8aa3b, v3
	v_lshlrev_b32_e32 v206, 16, v207
	v_mul_f32_e32 v193, 0xbfb8aa3b, v193
	v_exp_f32_e32 v2, v198
	v_exp_f32_e32 v198, v224
	v_exp_f32_e32 v3, v199
	v_exp_f32_e32 v199, v225
	v_mul_f32_e32 v206, 0xbfb8aa3b, v206
	v_mul_f32_e32 v226, 0xbfb8aa3b, v196
	v_exp_f32_e32 v193, v193
	v_exp_f32_e32 v196, v206
	v_exp_f32_e32 v206, v226
	v_and_b32_e32 v207, 0xffff0000, v207
	v_add_f32_e32 v198, 1.0, v198
	v_add_f32_e32 v199, 1.0, v199
	v_mul_f32_e32 v207, 0xbfb8aa3b, v207
	v_mul_f32_e32 v227, 0xbfb8aa3b, v197
	v_add_f32_e32 v193, 1.0, v193
	v_rcp_f32_e32 v198, v198
	v_rcp_f32_e32 v199, v199
	v_exp_f32_e32 v197, v207
	v_add_f32_e32 v207, 1.0, v206
	v_rcp_f32_e32 v206, v193
	v_exp_f32_e32 v193, v227
	v_rcp_f32_e32 v207, v207
	v_pk_add_f32 v[2:3], v[2:3], 1.0 op_sel_hi:[1,0]
	v_pk_add_f32 v[196:197], v[196:197], 1.0 op_sel_hi:[1,0]
	v_pk_mul_f32 v[2:3], v[2:3], v[198:199]
	v_pk_mul_f32 v[196:197], v[196:197], v[206:207]
	v_pk_mul_f32 v[128:129], v[128:129], v[2:3]
	v_add_f32_e32 v3, 1.0, v193
	v_mul_f32_e32 v193, 0xbfb8aa3b, v205
	v_exp_f32_e32 v193, v193
	v_pk_mul_f32 v[130:131], v[130:131], v[196:197]
	v_mul_f32_e32 v197, 0xbfb8aa3b, v214
	v_exp_f32_e32 v199, v197
	v_add_f32_e32 v193, 1.0, v193
	v_rcp_f32_e32 v197, v193
	v_mul_f32_e32 v193, 0xbfb8aa3b, v223
	v_lshlrev_b32_e32 v222, 16, v208
	v_and_b32_e32 v208, 0xffff0000, v208
	v_exp_f32_e32 v198, v193
	v_add_f32_e32 v193, 1.0, v199
	v_mul_f32_e32 v199, 0xbfb8aa3b, v215
	v_mul_f32_e32 v2, 0xbfb8aa3b, v222
	v_rcp_f32_e32 v196, v3
	v_mul_f32_e32 v3, 0xbfb8aa3b, v208
	v_exp_f32_e32 v205, v199
	v_exp_f32_e32 v2, v2
	v_exp_f32_e32 v3, v3
	v_and_b32_e32 v209, 0xffff0000, v209
	v_mul_f32_e32 v199, 0xbfb8aa3b, v209
	v_exp_f32_e32 v199, v199
	v_rcp_f32_e32 v206, v193
	v_add_f32_e32 v193, 1.0, v205
	v_rcp_f32_e32 v207, v193
	v_pk_add_f32 v[2:3], v[2:3], 1.0 op_sel_hi:[1,0]
	v_pk_add_f32 v[198:199], v[198:199], 1.0 op_sel_hi:[1,0]
	v_pk_mul_f32 v[2:3], v[2:3], v[196:197]
	v_pk_mul_f32 v[196:197], v[198:199], v[206:207]
	v_pk_mul_f32 v[124:125], v[124:125], v[2:3]
	v_lshlrev_b32_e32 v2, 16, v210
	v_mul_f32_e32 v2, 0xbfb8aa3b, v2
	v_exp_f32_e32 v207, v2
	v_and_b32_e32 v3, 0xffff0000, v210
	v_pk_mul_f32 v[126:127], v[126:127], v[196:197]
	v_lshlrev_b32_e32 v196, 16, v218
	v_mul_f32_e32 v3, 0xbfb8aa3b, v3
	v_mul_f32_e32 v2, 0xbfb8aa3b, v196
	v_add_f32_e32 v196, 1.0, v207
	v_exp_f32_e32 v207, v3
	v_lshlrev_b32_e32 v193, 16, v211
	v_and_b32_e32 v199, 0xffff0000, v211
	v_mul_f32_e32 v193, 0xbfb8aa3b, v193
	v_and_b32_e32 v197, 0xffff0000, v218
	v_exp_f32_e32 v193, v193
	v_mul_f32_e32 v199, 0xbfb8aa3b, v199
	v_mul_f32_e32 v3, 0xbfb8aa3b, v197
	v_add_f32_e32 v197, 1.0, v207
	v_exp_f32_e32 v207, v199
	v_and_b32_e32 v206, 0xffff0000, v219
	v_add_f32_e32 v193, 1.0, v193
	v_lshlrev_b32_e32 v205, 16, v212
	v_lshlrev_b32_e32 v198, 16, v219
	v_exp_f32_e32 v2, v2
	v_exp_f32_e32 v3, v3
	v_mul_f32_e32 v199, 0xbfb8aa3b, v206
	v_rcp_f32_e32 v206, v193
	v_add_f32_e32 v193, 1.0, v207
	v_rcp_f32_e32 v196, v196
	v_rcp_f32_e32 v197, v197
	v_mul_f32_e32 v198, 0xbfb8aa3b, v198
	v_rcp_f32_e32 v207, v193
	v_mul_f32_e32 v193, 0xbfb8aa3b, v205
	v_exp_f32_e32 v198, v198
	v_exp_f32_e32 v199, v199
	v_exp_f32_e32 v193, v193
	v_pk_add_f32 v[2:3], v[2:3], 1.0 op_sel_hi:[1,0]
	v_and_b32_e32 v208, 0xffff0000, v212
	v_pk_mul_f32 v[2:3], v[2:3], v[196:197]
	v_pk_add_f32 v[198:199], v[198:199], 1.0 op_sel_hi:[1,0]
	v_pk_mul_f32 v[120:121], v[120:121], v[2:3]
	v_add_f32_e32 v3, 1.0, v193
	v_mul_f32_e32 v193, 0xbfb8aa3b, v208
; DEVI float bflo(unsigned w) { return __uint_as_float(w << 16); }
; DEVI float bfhi(unsigned w) { return __uint_as_float(w & 0xffff0000u); }
;     DEVI void mid(AccRef acc, const pg8::Unit& u, int wr, int wc, int fr, int fq) const {
;     ...
;             for (int m = 0; m < 4; ++m)
; #pragma unroll
;                 for (int bj = 0; bj < 2; ++bj) { const u32x4 a = ga[m][bj], r = gr[m][bj];
;                     const float av[8] = {bflo(a.x), bfhi(a.x), bflo(a.y), bfhi(a.y), bflo(a.z), bfhi(a.z), bflo(a.w), bfhi(a.w)};
;                     const float rv[8] = {bflo(r.x), bfhi(r.x), bflo(r.y), bfhi(r.y), bflo(r.z), bfhi(r.z), bflo(r.w), bfhi(r.w)};
; #pragma unroll
;                     for (int j = 0; j < 8; ++j) { const float q = (1.f + __expf(-rv[j])) * __builtin_amdgcn_rcpf(1.f + __expf(-av[j])); acc[ai][bj][m][j >> 2][j & 3] *= q; } }
	v_lshlrev_b32_e32 v209, 16, v213
	v_pk_mul_f32 v[196:197], v[198:199], v[206:207]
	v_exp_f32_e32 v193, v193
	v_pk_mul_f32 v[122:123], v[122:123], v[196:197]
	v_mul_f32_e32 v197, 0xbfb8aa3b, v209
	v_exp_f32_e32 v199, v197
	v_and_b32_e32 v210, 0xffff0000, v213
	v_lshlrev_b32_e32 v213, 16, v221
	v_add_f32_e32 v193, 1.0, v193
	v_rcp_f32_e32 v197, v193
	v_mul_f32_e32 v193, 0xbfb8aa3b, v213
	v_exp_f32_e32 v198, v193
	v_add_f32_e32 v193, 1.0, v199
	v_mul_f32_e32 v199, 0xbfb8aa3b, v210
	v_lshlrev_b32_e32 v211, 16, v220
	v_and_b32_e32 v212, 0xffff0000, v220
	v_exp_f32_e32 v205, v199
	v_mul_f32_e32 v2, 0xbfb8aa3b, v211
	v_rcp_f32_e32 v196, v3
	v_mul_f32_e32 v3, 0xbfb8aa3b, v212
	v_and_b32_e32 v214, 0xffff0000, v221
	v_exp_f32_e32 v2, v2
	v_exp_f32_e32 v3, v3
	v_mul_f32_e32 v199, 0xbfb8aa3b, v214
	v_exp_f32_e32 v199, v199
	v_rcp_f32_e32 v206, v193
	v_add_f32_e32 v193, 1.0, v205
	v_rcp_f32_e32 v207, v193
	v_pk_add_f32 v[2:3], v[2:3], 1.0 op_sel_hi:[1,0]
	v_pk_add_f32 v[198:199], v[198:199], 1.0 op_sel_hi:[1,0]
	v_pk_mul_f32 v[2:3], v[2:3], v[196:197]
	v_pk_mul_f32 v[196:197], v[198:199], v[206:207]
	v_pk_mul_f32 v[116:117], v[116:117], v[2:3]
	v_lshlrev_b32_e32 v2, 16, v176
	v_and_b32_e32 v3, 0xffff0000, v176
	v_lshlrev_b32_e32 v176, 16, v177
	v_lshlrev_b32_e32 v206, 16, v174
	v_and_b32_e32 v207, 0xffff0000, v174
	v_mul_f32_e32 v174, 0xbfb8aa3b, v176
	v_lshlrev_b32_e32 v208, 16, v175
	v_and_b32_e32 v209, 0xffff0000, v175
	v_exp_f32_e32 v175, v174
	v_and_b32_e32 v177, 0xffff0000, v177
	v_mul_f32_e32 v2, 0xbfb8aa3b, v2
	v_mul_f32_e32 v3, 0xbfb8aa3b, v3
	v_add_f32_e32 v176, 1.0, v175
	v_mul_f32_e32 v175, 0xbfb8aa3b, v177
	v_pk_mul_f32 v[118:119], v[118:119], v[196:197]
	v_lshlrev_b32_e32 v197, 16, v172
	v_and_b32_e32 v198, 0xffff0000, v172
	v_lshlrev_b32_e32 v199, 16, v173
	v_and_b32_e32 v205, 0xffff0000, v173
	v_exp_f32_e32 v172, v2
	v_exp_f32_e32 v173, v3
	v_exp_f32_e32 v177, v175
	v_mul_f32_e32 v2, 0xbfb8aa3b, v197
	v_mul_f32_e32 v3, 0xbfb8aa3b, v198
	v_mul_f32_e32 v174, 0xbfb8aa3b, v199
	v_mul_f32_e32 v175, 0xbfb8aa3b, v205
	v_exp_f32_e32 v2, v2
	v_add_f32_e32 v172, 1.0, v172
	v_exp_f32_e32 v3, v3
	v_add_f32_e32 v173, 1.0, v173
	v_exp_f32_e32 v174, v174
	v_exp_f32_e32 v175, v175
	v_add_f32_e32 v177, 1.0, v177
	v_rcp_f32_e32 v172, v172
	v_rcp_f32_e32 v173, v173
	v_rcp_f32_e32 v176, v176
	v_rcp_f32_e32 v177, v177
	v_pk_add_f32 v[174:175], v[174:175], 1.0 op_sel_hi:[1,0]
	v_pk_add_f32 v[2:3], v[2:3], 1.0 op_sel_hi:[1,0]
	v_lshlrev_b32_e32 v193, 16, v178
	v_pk_mul_f32 v[2:3], v[2:3], v[172:173]
	v_pk_mul_f32 v[172:173], v[174:175], v[176:177]
	v_and_b32_e32 v178, 0xffff0000, v178
	v_pk_mul_f32 v[114:115], v[114:115], v[172:173]
	v_mul_f32_e32 v172, 0xbfb8aa3b, v193
	v_exp_f32_e32 v172, v172
	v_pk_mul_f32 v[112:113], v[112:113], v[2:3]
	v_lshlrev_b32_e32 v196, 16, v179
	v_mul_f32_e32 v174, 0xbfb8aa3b, v196
	v_add_f32_e32 v3, 1.0, v172
	v_mul_f32_e32 v172, 0xbfb8aa3b, v178
	v_exp_f32_e32 v173, v172
	v_mul_f32_e32 v2, 0xbfb8aa3b, v206
	v_rcp_f32_e32 v172, v3
	v_mul_f32_e32 v3, 0xbfb8aa3b, v207
	v_exp_f32_e32 v175, v174
	v_exp_f32_e32 v2, v2
	v_exp_f32_e32 v3, v3
	v_add_f32_e32 v173, 1.0, v173
	v_rcp_f32_e32 v173, v173
	v_and_b32_e32 v179, 0xffff0000, v179
	v_add_f32_e32 v176, 1.0, v175
	v_mul_f32_e32 v175, 0xbfb8aa3b, v179
	v_exp_f32_e32 v177, v175
	v_pk_add_f32 v[2:3], v[2:3], 1.0 op_sel_hi:[1,0]
	v_mul_f32_e32 v174, 0xbfb8aa3b, v208
	v_pk_mul_f32 v[2:3], v[2:3], v[172:173]
	v_mul_f32_e32 v175, 0xbfb8aa3b, v209
	v_pk_mul_f32 v[108:109], v[108:109], v[2:3]
	v_lshlrev_b32_e32 v2, 16, v168
	v_and_b32_e32 v3, 0xffff0000, v168
	v_lshlrev_b32_e32 v168, 16, v169
	v_lshlrev_b32_e32 v178, 16, v166
	v_and_b32_e32 v179, 0xffff0000, v166
	v_mul_f32_e32 v166, 0xbfb8aa3b, v168
	v_exp_f32_e32 v174, v174
	v_exp_f32_e32 v175, v175
	v_add_f32_e32 v177, 1.0, v177
	v_lshlrev_b32_e32 v193, 16, v167
	v_and_b32_e32 v196, 0xffff0000, v167
	v_exp_f32_e32 v167, v166
	v_rcp_f32_e32 v176, v176
	v_rcp_f32_e32 v177, v177
	v_and_b32_e32 v169, 0xffff0000, v169
	v_pk_add_f32 v[174:175], v[174:175], 1.0 op_sel_hi:[1,0]
	v_mul_f32_e32 v2, 0xbfb8aa3b, v2
	v_mul_f32_e32 v3, 0xbfb8aa3b, v3
	v_add_f32_e32 v168, 1.0, v167
	v_mul_f32_e32 v167, 0xbfb8aa3b, v169
	v_pk_mul_f32 v[172:173], v[174:175], v[176:177]
	v_lshlrev_b32_e32 v174, 16, v164
	v_and_b32_e32 v175, 0xffff0000, v164
	v_lshlrev_b32_e32 v176, 16, v165
	v_and_b32_e32 v177, 0xffff0000, v165
	v_exp_f32_e32 v164, v2
	v_exp_f32_e32 v165, v3
	v_exp_f32_e32 v169, v167
	v_mul_f32_e32 v2, 0xbfb8aa3b, v174
	v_mul_f32_e32 v3, 0xbfb8aa3b, v175
	v_mul_f32_e32 v166, 0xbfb8aa3b, v176
	v_mul_f32_e32 v167, 0xbfb8aa3b, v177
	v_exp_f32_e32 v2, v2
	v_add_f32_e32 v164, 1.0, v164
	v_exp_f32_e32 v3, v3
	v_add_f32_e32 v165, 1.0, v165
	v_exp_f32_e32 v166, v166
	v_exp_f32_e32 v167, v167
	v_add_f32_e32 v169, 1.0, v169
	v_rcp_f32_e32 v164, v164
	v_rcp_f32_e32 v165, v165
	v_rcp_f32_e32 v168, v168
	v_rcp_f32_e32 v169, v169
	v_pk_add_f32 v[166:167], v[166:167], 1.0 op_sel_hi:[1,0]
	v_pk_add_f32 v[2:3], v[2:3], 1.0 op_sel_hi:[1,0]
	v_pk_mul_f32 v[110:111], v[110:111], v[172:173]
	v_lshlrev_b32_e32 v172, 16, v170
	v_pk_mul_f32 v[2:3], v[2:3], v[164:165]
	v_pk_mul_f32 v[164:165], v[166:167], v[168:169]
	v_lshlrev_b32_e32 v173, 16, v171
	v_pk_mul_f32 v[106:107], v[106:107], v[164:165]
	v_mul_f32_e32 v164, 0xbfb8aa3b, v172
	v_exp_f32_e32 v164, v164
	v_mul_f32_e32 v166, 0xbfb8aa3b, v173
	v_exp_f32_e32 v167, v166
	v_and_b32_e32 v170, 0xffff0000, v170
	v_pk_mul_f32 v[104:105], v[104:105], v[2:3]
	v_add_f32_e32 v3, 1.0, v164
	v_mul_f32_e32 v164, 0xbfb8aa3b, v170
	v_and_b32_e32 v171, 0xffff0000, v171
	v_exp_f32_e32 v165, v164
	v_add_f32_e32 v168, 1.0, v167
	v_mul_f32_e32 v167, 0xbfb8aa3b, v171
	v_exp_f32_e32 v169, v167
	v_mul_f32_e32 v2, 0xbfb8aa3b, v178
	v_rcp_f32_e32 v164, v3
	v_mul_f32_e32 v3, 0xbfb8aa3b, v179
	v_exp_f32_e32 v2, v2
	v_exp_f32_e32 v3, v3
	v_add_f32_e32 v165, 1.0, v165
	v_rcp_f32_e32 v165, v165
	v_mul_f32_e32 v166, 0xbfb8aa3b, v193
	v_mul_f32_e32 v167, 0xbfb8aa3b, v196
	v_exp_f32_e32 v166, v166
	v_exp_f32_e32 v167, v167
	v_add_f32_e32 v169, 1.0, v169
	v_rcp_f32_e32 v168, v168
	v_rcp_f32_e32 v169, v169
	v_pk_add_f32 v[2:3], v[2:3], 1.0 op_sel_hi:[1,0]
	v_pk_add_f32 v[166:167], v[166:167], 1.0 op_sel_hi:[1,0]
	v_pk_mul_f32 v[2:3], v[2:3], v[164:165]
	v_pk_mul_f32 v[164:165], v[166:167], v[168:169]
	v_pk_mul_f32 v[100:101], v[100:101], v[2:3]
	s_waitcnt vmcnt(0) lgkmcnt(0)
; DEVI float bflo(unsigned w) { return __uint_as_float(w << 16); }
; DEVI float bfhi(unsigned w) { return __uint_as_float(w & 0xffff0000u); }
;     DEVI void mid(AccRef acc, const pg8::Unit& u, int wr, int wc, int fr, int fq) const {
;     ...
;             for (int m = 0; m < 4; ++m)
; #pragma unroll
;                 for (int bj = 0; bj < 2; ++bj) { const u32x4 a = ga[m][bj], r = gr[m][bj];
;                     const float av[8] = {bflo(a.x), bfhi(a.x), bflo(a.y), bfhi(a.y), bflo(a.z), bfhi(a.z), bflo(a.w), bfhi(a.w)};
;                     const float rv[8] = {bflo(r.x), bfhi(r.x), bflo(r.y), bfhi(r.y), bflo(r.z), bfhi(r.z), bflo(r.w), bfhi(r.w)};
; #pragma unroll
;                     for (int j = 0; j < 8; ++j) { const float q = (1.f + __expf(-rv[j])) * __builtin_amdgcn_rcpf(1.f + __expf(-av[j])); acc[ai][bj][m][j >> 2][j & 3] *= q; } }
	v_lshlrev_b32_e32 v2, 16, v156
	v_mul_f32_e32 v2, 0xbfb8aa3b, v2
	v_pk_mul_f32 v[102:103], v[102:103], v[164:165]
	v_and_b32_e32 v3, 0xffff0000, v156
	v_lshlrev_b32_e32 v164, 16, v157
	v_and_b32_e32 v165, 0xffff0000, v157
	v_lshlrev_b32_e32 v156, 16, v160
	v_and_b32_e32 v157, 0xffff0000, v160
	v_exp_f32_e32 v160, v2
	v_mul_f32_e32 v3, 0xbfb8aa3b, v3
	v_mul_f32_e32 v2, 0xbfb8aa3b, v156
	v_lshlrev_b32_e32 v166, 16, v158
	v_add_f32_e32 v156, 1.0, v160
	v_exp_f32_e32 v160, v3
	v_and_b32_e32 v167, 0xffff0000, v158
	v_lshlrev_b32_e32 v168, 16, v159
	v_and_b32_e32 v169, 0xffff0000, v159
	v_lshlrev_b32_e32 v158, 16, v161
	v_and_b32_e32 v159, 0xffff0000, v161
	v_mul_f32_e32 v3, 0xbfb8aa3b, v157
	v_add_f32_e32 v157, 1.0, v160
	v_mul_f32_e32 v160, 0xbfb8aa3b, v164
	v_mul_f32_e32 v161, 0xbfb8aa3b, v165
	v_exp_f32_e32 v160, v160
	v_exp_f32_e32 v161, v161
	v_mul_f32_e32 v158, 0xbfb8aa3b, v158
	v_mul_f32_e32 v159, 0xbfb8aa3b, v159
	v_exp_f32_e32 v2, v2
	v_exp_f32_e32 v3, v3
	v_exp_f32_e32 v158, v158
	v_add_f32_e32 v160, 1.0, v160
	v_exp_f32_e32 v159, v159
	v_add_f32_e32 v161, 1.0, v161
	v_rcp_f32_e32 v156, v156
	v_rcp_f32_e32 v157, v157
	v_rcp_f32_e32 v160, v160
	v_rcp_f32_e32 v161, v161
	v_pk_add_f32 v[158:159], v[158:159], 1.0 op_sel_hi:[1,0]
	v_pk_add_f32 v[2:3], v[2:3], 1.0 op_sel_hi:[1,0]
	v_lshlrev_b32_e32 v170, 16, v162
	v_pk_mul_f32 v[2:3], v[2:3], v[156:157]
	v_pk_mul_f32 v[156:157], v[158:159], v[160:161]
	v_mul_f32_e32 v158, 0xbfb8aa3b, v168
	v_pk_mul_f32 v[98:99], v[98:99], v[156:157]
	v_mul_f32_e32 v156, 0xbfb8aa3b, v166
	v_exp_f32_e32 v156, v156
	v_exp_f32_e32 v159, v158
	v_pk_mul_f32 v[96:97], v[96:97], v[2:3]
	v_and_b32_e32 v162, 0xffff0000, v162
	v_add_f32_e32 v3, 1.0, v156
	v_mul_f32_e32 v156, 0xbfb8aa3b, v167
	v_exp_f32_e32 v157, v156
	v_add_f32_e32 v160, 1.0, v159
	v_mul_f32_e32 v159, 0xbfb8aa3b, v169
	v_exp_f32_e32 v161, v159
	v_mul_f32_e32 v2, 0xbfb8aa3b, v170
	v_rcp_f32_e32 v156, v3
	v_mul_f32_e32 v3, 0xbfb8aa3b, v162
	v_lshlrev_b32_e32 v171, 16, v163
	v_and_b32_e32 v163, 0xffff0000, v163
	v_exp_f32_e32 v2, v2
	v_exp_f32_e32 v3, v3
	v_add_f32_e32 v157, 1.0, v157
	v_rcp_f32_e32 v157, v157
	v_mul_f32_e32 v158, 0xbfb8aa3b, v171
	v_mul_f32_e32 v159, 0xbfb8aa3b, v163
	v_exp_f32_e32 v158, v158
	v_exp_f32_e32 v159, v159
	v_add_f32_e32 v161, 1.0, v161
	v_rcp_f32_e32 v160, v160
	v_rcp_f32_e32 v161, v161
	v_pk_add_f32 v[2:3], v[2:3], 1.0 op_sel_hi:[1,0]
	v_pk_add_f32 v[158:159], v[158:159], 1.0 op_sel_hi:[1,0]
	v_pk_mul_f32 v[2:3], v[2:3], v[156:157]
	v_pk_mul_f32 v[156:157], v[158:159], v[160:161]
	v_pk_mul_f32 v[92:93], v[92:93], v[2:3]
	v_lshlrev_b32_e32 v2, 16, v148
	v_mul_f32_e32 v2, 0xbfb8aa3b, v2
	v_pk_mul_f32 v[94:95], v[94:95], v[156:157]
	v_and_b32_e32 v3, 0xffff0000, v148
	v_lshlrev_b32_e32 v156, 16, v149
	v_and_b32_e32 v157, 0xffff0000, v149
	v_lshlrev_b32_e32 v148, 16, v152
	v_and_b32_e32 v149, 0xffff0000, v152
	v_exp_f32_e32 v152, v2
	v_mul_f32_e32 v3, 0xbfb8aa3b, v3
	v_mul_f32_e32 v2, 0xbfb8aa3b, v148
	v_lshlrev_b32_e32 v158, 16, v150
	v_add_f32_e32 v148, 1.0, v152
	v_exp_f32_e32 v152, v3
	v_and_b32_e32 v159, 0xffff0000, v150
	v_lshlrev_b32_e32 v160, 16, v151
	v_and_b32_e32 v161, 0xffff0000, v151
	v_lshlrev_b32_e32 v150, 16, v153
	v_and_b32_e32 v151, 0xffff0000, v153
	v_mul_f32_e32 v3, 0xbfb8aa3b, v149
	v_add_f32_e32 v149, 1.0, v152
	v_mul_f32_e32 v152, 0xbfb8aa3b, v156
	v_mul_f32_e32 v153, 0xbfb8aa3b, v157
	v_exp_f32_e32 v152, v152
	v_exp_f32_e32 v153, v153
	v_mul_f32_e32 v150, 0xbfb8aa3b, v150
	v_mul_f32_e32 v151, 0xbfb8aa3b, v151
	v_exp_f32_e32 v2, v2
	v_exp_f32_e32 v3, v3
	v_exp_f32_e32 v150, v150
	v_add_f32_e32 v152, 1.0, v152
	v_exp_f32_e32 v151, v151
	v_add_f32_e32 v153, 1.0, v153
	v_rcp_f32_e32 v148, v148
	v_rcp_f32_e32 v149, v149
	v_rcp_f32_e32 v152, v152
	v_rcp_f32_e32 v153, v153
	v_pk_add_f32 v[150:151], v[150:151], 1.0 op_sel_hi:[1,0]
	v_pk_add_f32 v[2:3], v[2:3], 1.0 op_sel_hi:[1,0]
	v_lshlrev_b32_e32 v162, 16, v154
	v_pk_mul_f32 v[2:3], v[2:3], v[148:149]
	v_pk_mul_f32 v[148:149], v[150:151], v[152:153]
	v_pk_mul_f32 v[88:89], v[88:89], v[2:3]
	v_pk_mul_f32 v[90:91], v[90:91], v[148:149]
	v_mul_f32_e32 v148, 0xbfb8aa3b, v158
	v_exp_f32_e32 v148, v148
	v_and_b32_e32 v154, 0xffff0000, v154
	v_mul_f32_e32 v150, 0xbfb8aa3b, v160
	v_mul_f32_e32 v2, 0xbfb8aa3b, v162
	v_add_f32_e32 v3, 1.0, v148
	v_mul_f32_e32 v148, 0xbfb8aa3b, v159
	v_exp_f32_e32 v149, v148
	v_rcp_f32_e32 v148, v3
	v_mul_f32_e32 v3, 0xbfb8aa3b, v154
	v_exp_f32_e32 v151, v150
	v_exp_f32_e32 v2, v2
	v_exp_f32_e32 v3, v3
	v_add_f32_e32 v149, 1.0, v149
	v_rcp_f32_e32 v149, v149
	v_add_f32_e32 v152, 1.0, v151
	v_mul_f32_e32 v151, 0xbfb8aa3b, v161
	v_exp_f32_e32 v153, v151
	v_pk_add_f32 v[2:3], v[2:3], 1.0 op_sel_hi:[1,0]
	v_lshlrev_b32_e32 v163, 16, v155
	v_pk_mul_f32 v[2:3], v[2:3], v[148:149]
	v_and_b32_e32 v155, 0xffff0000, v155
	v_pk_mul_f32 v[84:85], v[84:85], v[2:3]
	v_lshlrev_b32_e32 v2, 16, v144
	v_and_b32_e32 v3, 0xffff0000, v144
	v_lshlrev_b32_e32 v144, 16, v145
	v_mul_f32_e32 v150, 0xbfb8aa3b, v163
	v_mul_f32_e32 v151, 0xbfb8aa3b, v155
	v_lshlrev_b32_e32 v154, 16, v142
	v_and_b32_e32 v155, 0xffff0000, v142
	v_mul_f32_e32 v142, 0xbfb8aa3b, v144
	v_exp_f32_e32 v150, v150
	v_exp_f32_e32 v151, v151
	v_add_f32_e32 v153, 1.0, v153
	v_lshlrev_b32_e32 v156, 16, v143
	v_and_b32_e32 v157, 0xffff0000, v143
	v_exp_f32_e32 v143, v142
	v_rcp_f32_e32 v152, v152
	v_rcp_f32_e32 v153, v153
	v_and_b32_e32 v145, 0xffff0000, v145
	v_pk_add_f32 v[150:151], v[150:151], 1.0 op_sel_hi:[1,0]
	v_mul_f32_e32 v2, 0xbfb8aa3b, v2
	v_mul_f32_e32 v3, 0xbfb8aa3b, v3
	v_add_f32_e32 v144, 1.0, v143
	v_mul_f32_e32 v143, 0xbfb8aa3b, v145
	v_pk_mul_f32 v[148:149], v[150:151], v[152:153]
; DEVI float bflo(unsigned w) { return __uint_as_float(w << 16); }
; DEVI float bfhi(unsigned w) { return __uint_as_float(w & 0xffff0000u); }
;     DEVI void mid(AccRef acc, const pg8::Unit& u, int wr, int wc, int fr, int fq) const {
;     ...
;             for (int m = 0; m < 4; ++m)
; #pragma unroll
;                 for (int bj = 0; bj < 2; ++bj) { ga[m][bj] = *(const u32x4*)((const char*)gA + o + (unsigned)(m * 16 * DM * 2 + bj * 256)); gr[m][bj] = *(const u32x4*)((const char*)gR + o + (unsigned)(m * 16 * DM * 2 + bj * 256)); }
; #pragma unroll
;             for (int m = 0; m < 4; ++m)
; #pragma unroll
;                 for (int bj = 0; bj < 2; ++bj) { const u32x4 a = ga[m][bj], r = gr[m][bj];
;                     const float av[8] = {bflo(a.x), bfhi(a.x), bflo(a.y), bfhi(a.y), bflo(a.z), bfhi(a.z), bflo(a.w), bfhi(a.w)};
;                     const float rv[8] = {bflo(r.x), bfhi(r.x), bflo(r.y), bfhi(r.y), bflo(r.z), bfhi(r.z), bflo(r.w), bfhi(r.w)};
; #pragma unroll
;                     for (int j = 0; j < 8; ++j) { const float q = (1.f + __expf(-rv[j])) * __builtin_amdgcn_rcpf(1.f + __expf(-av[j])); acc[ai][bj][m][j >> 2][j & 3] *= q; } }
;             o += 128u * DM * 2u; }
	v_lshlrev_b32_e32 v150, 16, v140
	v_and_b32_e32 v151, 0xffff0000, v140
	v_lshlrev_b32_e32 v152, 16, v141
	v_and_b32_e32 v153, 0xffff0000, v141
	v_exp_f32_e32 v140, v2
	v_exp_f32_e32 v141, v3
	v_exp_f32_e32 v145, v143
	v_mul_f32_e32 v2, 0xbfb8aa3b, v150
	v_mul_f32_e32 v3, 0xbfb8aa3b, v151
	v_mul_f32_e32 v142, 0xbfb8aa3b, v152
	v_mul_f32_e32 v143, 0xbfb8aa3b, v153
	v_exp_f32_e32 v2, v2
	v_add_f32_e32 v140, 1.0, v140
	v_exp_f32_e32 v3, v3
	v_add_f32_e32 v141, 1.0, v141
	v_exp_f32_e32 v142, v142
	v_exp_f32_e32 v143, v143
	v_add_f32_e32 v145, 1.0, v145
	v_rcp_f32_e32 v140, v140
	v_rcp_f32_e32 v141, v141
	v_rcp_f32_e32 v144, v144
	v_rcp_f32_e32 v145, v145
	v_pk_add_f32 v[142:143], v[142:143], 1.0 op_sel_hi:[1,0]
	v_pk_add_f32 v[2:3], v[2:3], 1.0 op_sel_hi:[1,0]
	v_pk_mul_f32 v[86:87], v[86:87], v[148:149]
	v_lshlrev_b32_e32 v148, 16, v146
	v_pk_mul_f32 v[2:3], v[2:3], v[140:141]
	v_pk_mul_f32 v[140:141], v[142:143], v[144:145]
	v_lshlrev_b32_e32 v149, 16, v147
	v_pk_mul_f32 v[82:83], v[82:83], v[140:141]
	v_mul_f32_e32 v140, 0xbfb8aa3b, v148
	v_exp_f32_e32 v140, v140
	v_mul_f32_e32 v142, 0xbfb8aa3b, v149
	v_exp_f32_e32 v143, v142
	v_and_b32_e32 v146, 0xffff0000, v146
	v_pk_mul_f32 v[80:81], v[80:81], v[2:3]
	v_add_f32_e32 v3, 1.0, v140
	v_mul_f32_e32 v140, 0xbfb8aa3b, v146
	v_and_b32_e32 v147, 0xffff0000, v147
	v_exp_f32_e32 v141, v140
	v_add_f32_e32 v144, 1.0, v143
	v_mul_f32_e32 v143, 0xbfb8aa3b, v147
	v_exp_f32_e32 v145, v143
	v_mul_f32_e32 v2, 0xbfb8aa3b, v154
	v_rcp_f32_e32 v140, v3
	v_mul_f32_e32 v3, 0xbfb8aa3b, v155
	v_exp_f32_e32 v2, v2
	v_exp_f32_e32 v3, v3
	v_add_f32_e32 v141, 1.0, v141
	v_rcp_f32_e32 v141, v141
	v_mul_f32_e32 v142, 0xbfb8aa3b, v156
	v_mul_f32_e32 v143, 0xbfb8aa3b, v157
	v_exp_f32_e32 v142, v142
	v_exp_f32_e32 v143, v143
	v_add_f32_e32 v145, 1.0, v145
	v_rcp_f32_e32 v144, v144
	v_rcp_f32_e32 v145, v145
	v_pk_add_f32 v[2:3], v[2:3], 1.0 op_sel_hi:[1,0]
	v_pk_add_f32 v[142:143], v[142:143], 1.0 op_sel_hi:[1,0]
	v_pk_mul_f32 v[2:3], v[2:3], v[140:141]
	v_pk_mul_f32 v[140:141], v[142:143], v[144:145]
	v_pk_mul_f32 v[76:77], v[76:77], v[2:3]
	v_lshlrev_b32_e32 v2, 16, v136
	v_and_b32_e32 v3, 0xffff0000, v136
	v_mul_f32_e32 v2, 0xbfb8aa3b, v2
	v_mul_f32_e32 v3, 0xbfb8aa3b, v3
	v_pk_mul_f32 v[78:79], v[78:79], v[140:141]
	v_lshlrev_b32_e32 v140, 16, v138
	v_and_b32_e32 v141, 0xffff0000, v138
	v_lshlrev_b32_e32 v142, 16, v139
	v_and_b32_e32 v143, 0xffff0000, v139
	v_lshlrev_b32_e32 v138, 16, v132
	v_and_b32_e32 v139, 0xffff0000, v132
	v_lshlrev_b32_e32 v144, 16, v133
	v_and_b32_e32 v145, 0xffff0000, v133
	v_exp_f32_e32 v132, v2
	v_exp_f32_e32 v133, v3
	v_lshlrev_b32_e32 v136, 16, v137
	v_and_b32_e32 v137, 0xffff0000, v137
	v_mul_f32_e32 v2, 0xbfb8aa3b, v138
	v_mul_f32_e32 v3, 0xbfb8aa3b, v139
	v_lshlrev_b32_e32 v146, 16, v134
	v_and_b32_e32 v147, 0xffff0000, v134
	v_exp_f32_e32 v2, v2
	v_add_f32_e32 v132, 1.0, v132
	v_exp_f32_e32 v3, v3
	v_add_f32_e32 v133, 1.0, v133
	v_mul_f32_e32 v134, 0xbfb8aa3b, v136
	v_mul_f32_e32 v136, 0xbfb8aa3b, v137
	v_rcp_f32_e32 v132, v132
	v_rcp_f32_e32 v133, v133
	v_exp_f32_e32 v139, v136
	v_pk_add_f32 v[2:3], v[2:3], 1.0 op_sel_hi:[1,0]
	v_lshl_add_u64 v[136:137], s[8:9], 0, v[0:1]
	global_load_dwordx4 v[196:199], v[136:137], off
	v_pk_mul_f32 v[2:3], v[2:3], v[132:133]
	v_lshl_add_u64 v[132:133], s[10:11], 0, v[0:1]
	global_load_dwordx4 v[206:209], v[132:133], off
	global_load_dwordx4 v[210:213], v[136:137], off offset:256
	global_load_dwordx4 v[218:221], v[132:133], off offset:256
	v_lshlrev_b32_e32 v148, 16, v135
	v_and_b32_e32 v149, 0xffff0000, v135
	v_exp_f32_e32 v135, v134
	v_mul_f32_e32 v134, 0xbfb8aa3b, v144
	v_exp_f32_e32 v134, v134
	v_add_f32_e32 v139, 1.0, v139
	v_add_f32_e32 v138, 1.0, v135
	v_mul_f32_e32 v135, 0xbfb8aa3b, v145
	v_exp_f32_e32 v135, v135
	v_rcp_f32_e32 v138, v138
	v_rcp_f32_e32 v139, v139
	v_mul_f32_e32 v0, 0xbfb8aa3b, v140
	v_pk_add_f32 v[134:135], v[134:135], 1.0 op_sel_hi:[1,0]
	v_exp_f32_e32 v0, v0
	v_pk_mul_f32 v[134:135], v[134:135], v[138:139]
	v_pk_mul_f32 v[72:73], v[72:73], v[2:3]
	v_mul_f32_e32 v3, 0xbfb8aa3b, v141
	v_pk_mul_f32 v[74:75], v[74:75], v[134:135]
	v_exp_f32_e32 v135, v3
	v_add_f32_e32 v0, 1.0, v0
	v_rcp_f32_e32 v134, v0
	v_mul_f32_e32 v0, 0xbfb8aa3b, v147
	v_exp_f32_e32 v3, v0
	v_add_f32_e32 v0, 1.0, v135
	v_mul_f32_e32 v135, 0xbfb8aa3b, v142
	v_exp_f32_e32 v139, v135
	v_rcp_f32_e32 v135, v0
	v_mul_f32_e32 v0, 0xbfb8aa3b, v148
	v_exp_f32_e32 v138, v0
	v_add_f32_e32 v0, 1.0, v139
	v_mul_f32_e32 v139, 0xbfb8aa3b, v143
	v_exp_f32_e32 v141, v139
	v_mul_f32_e32 v2, 0xbfb8aa3b, v146
	v_exp_f32_e32 v2, v2
	v_mul_f32_e32 v139, 0xbfb8aa3b, v149
	v_exp_f32_e32 v139, v139
	v_rcp_f32_e32 v140, v0
	v_add_f32_e32 v0, 1.0, v141
	v_rcp_f32_e32 v141, v0
	v_pk_add_f32 v[2:3], v[2:3], 1.0 op_sel_hi:[1,0]
	v_pk_add_f32 v[138:139], v[138:139], 1.0 op_sel_hi:[1,0]
	v_pk_mul_f32 v[2:3], v[2:3], v[134:135]
	v_pk_mul_f32 v[134:135], v[138:139], v[140:141]
	v_pk_mul_f32 v[68:69], v[68:69], v[2:3]
	v_add_co_u32_e32 v2, vcc, s33, v136
	v_pk_mul_f32 v[70:71], v[70:71], v[134:135]
	s_nop 0
	v_addc_co_u32_e32 v3, vcc, 0, v137, vcc
	v_add_co_u32_e32 v134, vcc, s33, v132
	s_waitcnt vmcnt(0) lgkmcnt(0)
; DEVI float bflo(unsigned w) { return __uint_as_float(w << 16); }
; DEVI float bfhi(unsigned w) { return __uint_as_float(w & 0xffff0000u); }
;     DEVI void mid(AccRef acc, const pg8::Unit& u, int wr, int wc, int fr, int fq) const {
;     ...
;             for (int m = 0; m < 4; ++m)
; #pragma unroll
;                 for (int bj = 0; bj < 2; ++bj) { ga[m][bj] = *(const u32x4*)((const char*)gA + o + (unsigned)(m * 16 * DM * 2 + bj * 256)); gr[m][bj] = *(const u32x4*)((const char*)gR + o + (unsigned)(m * 16 * DM * 2 + bj * 256)); }
; #pragma unroll
;             for (int m = 0; m < 4; ++m)
; #pragma unroll
;                 for (int bj = 0; bj < 2; ++bj) { const u32x4 a = ga[m][bj], r = gr[m][bj];
;                     const float av[8] = {bflo(a.x), bfhi(a.x), bflo(a.y), bfhi(a.y), bflo(a.z), bfhi(a.z), bflo(a.w), bfhi(a.w)};
;                     const float rv[8] = {bflo(r.x), bfhi(r.x), bflo(r.y), bfhi(r.y), bflo(r.z), bfhi(r.z), bflo(r.w), bfhi(r.w)};
; #pragma unroll
;                     for (int j = 0; j < 8; ++j) { const float q = (1.f + __expf(-rv[j])) * __builtin_amdgcn_rcpf(1.f + __expf(-av[j])); acc[ai][bj][m][j >> 2][j & 3] *= q; } }
	v_lshlrev_b32_e32 v0, 16, v196
	v_addc_co_u32_e32 v135, vcc, 0, v133, vcc
	global_load_dwordx4 v[176:179], v[2:3], off
	global_load_dwordx4 v[168:171], v[2:3], off offset:256
	global_load_dwordx4 v[172:175], v[134:135], off
	global_load_dwordx4 v[164:167], v[134:135], off offset:256
	v_add_co_u32_e32 v2, vcc, s54, v136
	v_mul_f32_e32 v0, 0xbfb8aa3b, v0
	s_nop 0
	v_addc_co_u32_e32 v3, vcc, 0, v137, vcc
	v_add_co_u32_e32 v134, vcc, s54, v132
	v_exp_f32_e32 v0, v0
	s_nop 0
	v_addc_co_u32_e32 v135, vcc, 0, v133, vcc
	global_load_dwordx4 v[160:163], v[2:3], off
	global_load_dwordx4 v[152:155], v[2:3], off offset:256
	global_load_dwordx4 v[156:159], v[134:135], off
	global_load_dwordx4 v[148:151], v[134:135], off offset:256
	v_add_co_u32_e32 v2, vcc, s27, v136
	v_lshlrev_b32_e32 v193, 16, v197
	s_nop 0
	v_addc_co_u32_e32 v3, vcc, 0, v137, vcc
	v_add_co_u32_e32 v132, vcc, s27, v132
	v_and_b32_e32 v205, 0xffff0000, v197
	s_nop 0
	v_addc_co_u32_e32 v133, vcc, 0, v133, vcc
	global_load_dwordx4 v[144:147], v[2:3], off
	global_load_dwordx4 v[136:139], v[2:3], off offset:256
	global_load_dwordx4 v[140:143], v[132:133], off
	s_nop 0
	global_load_dwordx4 v[132:135], v[132:133], off offset:256
	v_and_b32_e32 v3, 0xffff0000, v196
	v_mul_f32_e32 v3, 0xbfb8aa3b, v3
	v_lshlrev_b32_e32 v2, 16, v206
	v_and_b32_e32 v197, 0xffff0000, v206
	v_exp_f32_e32 v206, v3
	v_mul_f32_e32 v193, 0xbfb8aa3b, v193
	v_add_f32_e32 v0, 1.0, v0
	v_exp_f32_e32 v193, v193
	v_rcp_f32_e32 v196, v0
	v_mul_f32_e32 v0, 0xbfb8aa3b, v197
	v_lshlrev_b32_e32 v214, 16, v198
	v_and_b32_e32 v215, 0xffff0000, v198
	v_lshlrev_b32_e32 v198, 16, v207
	v_exp_f32_e32 v3, v0
	v_add_f32_e32 v0, 1.0, v206
	v_rcp_f32_e32 v197, v0
	v_mul_f32_e32 v0, 0xbfb8aa3b, v198
	v_exp_f32_e32 v198, v0
	v_add_f32_e32 v0, 1.0, v193
	v_mul_f32_e32 v193, 0xbfb8aa3b, v205
	v_mul_f32_e32 v2, 0xbfb8aa3b, v2
	v_exp_f32_e32 v193, v193
	v_exp_f32_e32 v2, v2
	v_lshlrev_b32_e32 v222, 16, v199
	v_and_b32_e32 v223, 0xffff0000, v199
	v_and_b32_e32 v199, 0xffff0000, v207
	v_mul_f32_e32 v199, 0xbfb8aa3b, v199
	v_rcp_f32_e32 v206, v0
	v_add_f32_e32 v0, 1.0, v193
	v_exp_f32_e32 v199, v199
	v_rcp_f32_e32 v207, v0
	v_pk_add_f32 v[2:3], v[2:3], 1.0 op_sel_hi:[1,0]
	v_mul_f32_e32 v0, 0xbfb8aa3b, v214
	v_pk_mul_f32 v[2:3], v[2:3], v[196:197]
	v_exp_f32_e32 v0, v0
	v_pk_mul_f32 v[64:65], v[64:65], v[2:3]
	v_mul_f32_e32 v3, 0xbfb8aa3b, v215
	v_exp_f32_e32 v193, v3
	v_pk_add_f32 v[198:199], v[198:199], 1.0 op_sel_hi:[1,0]
	v_lshlrev_b32_e32 v224, 16, v208
	v_and_b32_e32 v208, 0xffff0000, v208
	v_pk_mul_f32 v[196:197], v[198:199], v[206:207]
	v_add_f32_e32 v0, 1.0, v0
	v_pk_mul_f32 v[66:67], v[66:67], v[196:197]
	v_rcp_f32_e32 v196, v0
	v_mul_f32_e32 v0, 0xbfb8aa3b, v208
	v_exp_f32_e32 v3, v0
	v_add_f32_e32 v0, 1.0, v193
	v_mul_f32_e32 v193, 0xbfb8aa3b, v222
	v_exp_f32_e32 v193, v193
	v_lshlrev_b32_e32 v225, 16, v209
	v_rcp_f32_e32 v197, v0
	v_mul_f32_e32 v0, 0xbfb8aa3b, v225
	v_exp_f32_e32 v198, v0
	v_add_f32_e32 v0, 1.0, v193
	v_mul_f32_e32 v193, 0xbfb8aa3b, v223
	v_mul_f32_e32 v2, 0xbfb8aa3b, v224
	v_exp_f32_e32 v193, v193
	v_exp_f32_e32 v2, v2
	v_and_b32_e32 v209, 0xffff0000, v209
	v_mul_f32_e32 v199, 0xbfb8aa3b, v209
	v_exp_f32_e32 v199, v199
	v_rcp_f32_e32 v206, v0
	v_add_f32_e32 v0, 1.0, v193
	v_rcp_f32_e32 v207, v0
	v_pk_add_f32 v[2:3], v[2:3], 1.0 op_sel_hi:[1,0]
	v_lshlrev_b32_e32 v0, 16, v210
	v_pk_mul_f32 v[2:3], v[2:3], v[196:197]
	v_mul_f32_e32 v0, 0xbfb8aa3b, v0
	v_pk_mul_f32 v[60:61], v[60:61], v[2:3]
	v_and_b32_e32 v3, 0xffff0000, v210
	v_exp_f32_e32 v0, v0
	v_pk_add_f32 v[198:199], v[198:199], 1.0 op_sel_hi:[1,0]
	v_mul_f32_e32 v3, 0xbfb8aa3b, v3
	v_pk_mul_f32 v[196:197], v[198:199], v[206:207]
	v_lshlrev_b32_e32 v193, 16, v211
	v_exp_f32_e32 v207, v3
	v_mul_f32_e32 v193, 0xbfb8aa3b, v193
	v_pk_mul_f32 v[62:63], v[62:63], v[196:197]
	v_and_b32_e32 v197, 0xffff0000, v218
	v_add_f32_e32 v0, 1.0, v0
	v_exp_f32_e32 v193, v193
	v_rcp_f32_e32 v196, v0
	v_mul_f32_e32 v0, 0xbfb8aa3b, v197
	v_lshlrev_b32_e32 v198, 16, v219
	v_exp_f32_e32 v3, v0
	v_add_f32_e32 v0, 1.0, v207
	v_and_b32_e32 v199, 0xffff0000, v211
	v_rcp_f32_e32 v197, v0
	v_mul_f32_e32 v0, 0xbfb8aa3b, v198
	v_lshlrev_b32_e32 v2, 16, v218
	v_exp_f32_e32 v198, v0
	v_add_f32_e32 v0, 1.0, v193
	v_mul_f32_e32 v193, 0xbfb8aa3b, v199
	v_mul_f32_e32 v2, 0xbfb8aa3b, v2
	v_exp_f32_e32 v193, v193
	v_exp_f32_e32 v2, v2
	v_and_b32_e32 v206, 0xffff0000, v219
	v_lshlrev_b32_e32 v205, 16, v212
	v_mul_f32_e32 v199, 0xbfb8aa3b, v206
	v_rcp_f32_e32 v206, v0
	v_add_f32_e32 v0, 1.0, v193
	v_exp_f32_e32 v199, v199
	v_rcp_f32_e32 v207, v0
	v_pk_add_f32 v[2:3], v[2:3], 1.0 op_sel_hi:[1,0]
	v_mul_f32_e32 v0, 0xbfb8aa3b, v205
	v_and_b32_e32 v208, 0xffff0000, v212
	v_pk_mul_f32 v[2:3], v[2:3], v[196:197]
	v_exp_f32_e32 v0, v0
	v_pk_mul_f32 v[56:57], v[56:57], v[2:3]
	v_mul_f32_e32 v3, 0xbfb8aa3b, v208
	v_exp_f32_e32 v193, v3
	v_pk_add_f32 v[198:199], v[198:199], 1.0 op_sel_hi:[1,0]
	v_and_b32_e32 v212, 0xffff0000, v220
	v_pk_mul_f32 v[196:197], v[198:199], v[206:207]
	v_add_f32_e32 v0, 1.0, v0
	v_lshlrev_b32_e32 v209, 16, v213
	v_pk_mul_f32 v[58:59], v[58:59], v[196:197]
	v_rcp_f32_e32 v196, v0
	v_mul_f32_e32 v0, 0xbfb8aa3b, v212
	v_exp_f32_e32 v3, v0
	v_add_f32_e32 v0, 1.0, v193
	v_mul_f32_e32 v193, 0xbfb8aa3b, v209
	v_exp_f32_e32 v193, v193
	v_and_b32_e32 v210, 0xffff0000, v213
	v_lshlrev_b32_e32 v213, 16, v221
	v_rcp_f32_e32 v197, v0
	v_mul_f32_e32 v0, 0xbfb8aa3b, v213
	v_lshlrev_b32_e32 v211, 16, v220
	v_exp_f32_e32 v198, v0
	v_add_f32_e32 v0, 1.0, v193
	v_mul_f32_e32 v193, 0xbfb8aa3b, v210
	v_mul_f32_e32 v2, 0xbfb8aa3b, v211
	v_exp_f32_e32 v193, v193
	v_exp_f32_e32 v2, v2
	v_and_b32_e32 v214, 0xffff0000, v221
	v_mul_f32_e32 v199, 0xbfb8aa3b, v214
	v_exp_f32_e32 v199, v199
	v_rcp_f32_e32 v206, v0
	v_add_f32_e32 v0, 1.0, v193
	v_rcp_f32_e32 v207, v0
	v_pk_add_f32 v[2:3], v[2:3], 1.0 op_sel_hi:[1,0]
	s_waitcnt vmcnt(0) lgkmcnt(0)
; DEVI float bflo(unsigned w) { return __uint_as_float(w << 16); }
; DEVI float bfhi(unsigned w) { return __uint_as_float(w & 0xffff0000u); }
;     DEVI void mid(AccRef acc, const pg8::Unit& u, int wr, int wc, int fr, int fq) const {
;     ...
;             for (int m = 0; m < 4; ++m)
; #pragma unroll
;                 for (int bj = 0; bj < 2; ++bj) { const u32x4 a = ga[m][bj], r = gr[m][bj];
;                     const float av[8] = {bflo(a.x), bfhi(a.x), bflo(a.y), bfhi(a.y), bflo(a.z), bfhi(a.z), bflo(a.w), bfhi(a.w)};
;                     const float rv[8] = {bflo(r.x), bfhi(r.x), bflo(r.y), bfhi(r.y), bflo(r.z), bfhi(r.z), bflo(r.w), bfhi(r.w)};
; #pragma unroll
;                     for (int j = 0; j < 8; ++j) { const float q = (1.f + __expf(-rv[j])) * __builtin_amdgcn_rcpf(1.f + __expf(-av[j])); acc[ai][bj][m][j >> 2][j & 3] *= q; } }
	v_lshlrev_b32_e32 v0, 16, v176
	v_pk_mul_f32 v[2:3], v[2:3], v[196:197]
	v_mul_f32_e32 v0, 0xbfb8aa3b, v0
	v_pk_mul_f32 v[52:53], v[52:53], v[2:3]
	v_and_b32_e32 v3, 0xffff0000, v176
	v_exp_f32_e32 v0, v0
	v_pk_add_f32 v[198:199], v[198:199], 1.0 op_sel_hi:[1,0]
	v_mul_f32_e32 v3, 0xbfb8aa3b, v3
	v_pk_mul_f32 v[196:197], v[198:199], v[206:207]
	v_lshlrev_b32_e32 v198, 16, v173
	v_and_b32_e32 v199, 0xffff0000, v173
	v_exp_f32_e32 v173, v3
	v_pk_mul_f32 v[54:55], v[54:55], v[196:197]
	v_and_b32_e32 v197, 0xffff0000, v172
	v_add_f32_e32 v0, 1.0, v0
	v_lshlrev_b32_e32 v176, 16, v177
	v_lshlrev_b32_e32 v2, 16, v172
	v_rcp_f32_e32 v172, v0
	v_mul_f32_e32 v0, 0xbfb8aa3b, v197
	v_exp_f32_e32 v3, v0
	v_add_f32_e32 v0, 1.0, v173
	v_mul_f32_e32 v173, 0xbfb8aa3b, v176
	v_lshlrev_b32_e32 v207, 16, v175
	v_and_b32_e32 v208, 0xffff0000, v175
	v_exp_f32_e32 v175, v173
	v_and_b32_e32 v177, 0xffff0000, v177
	v_rcp_f32_e32 v173, v0
	v_mul_f32_e32 v0, 0xbfb8aa3b, v198
	v_lshlrev_b32_e32 v205, 16, v174
	v_and_b32_e32 v206, 0xffff0000, v174
	v_exp_f32_e32 v174, v0
	v_add_f32_e32 v0, 1.0, v175
	v_mul_f32_e32 v175, 0xbfb8aa3b, v177
	v_exp_f32_e32 v177, v175
	v_mul_f32_e32 v2, 0xbfb8aa3b, v2
	v_exp_f32_e32 v2, v2
	v_mul_f32_e32 v175, 0xbfb8aa3b, v199
	v_exp_f32_e32 v175, v175
	v_rcp_f32_e32 v176, v0
	v_add_f32_e32 v0, 1.0, v177
	v_rcp_f32_e32 v177, v0
	v_lshlrev_b32_e32 v193, 16, v178
	v_pk_add_f32 v[2:3], v[2:3], 1.0 op_sel_hi:[1,0]
	v_mul_f32_e32 v0, 0xbfb8aa3b, v193
	v_and_b32_e32 v178, 0xffff0000, v178
	v_pk_add_f32 v[174:175], v[174:175], 1.0 op_sel_hi:[1,0]
	v_pk_mul_f32 v[2:3], v[2:3], v[172:173]
	v_exp_f32_e32 v0, v0
	v_pk_mul_f32 v[172:173], v[174:175], v[176:177]
	v_pk_mul_f32 v[48:49], v[48:49], v[2:3]
	v_mul_f32_e32 v3, 0xbfb8aa3b, v178
	v_pk_mul_f32 v[50:51], v[50:51], v[172:173]
	v_exp_f32_e32 v173, v3
	v_add_f32_e32 v0, 1.0, v0
	v_lshlrev_b32_e32 v196, 16, v179
	v_rcp_f32_e32 v172, v0
	v_mul_f32_e32 v0, 0xbfb8aa3b, v206
	v_exp_f32_e32 v3, v0
	v_add_f32_e32 v0, 1.0, v173
	v_mul_f32_e32 v173, 0xbfb8aa3b, v196
	v_exp_f32_e32 v175, v173
	v_and_b32_e32 v179, 0xffff0000, v179
	v_rcp_f32_e32 v173, v0
	v_mul_f32_e32 v0, 0xbfb8aa3b, v207
	v_exp_f32_e32 v174, v0
	v_add_f32_e32 v0, 1.0, v175
	v_mul_f32_e32 v175, 0xbfb8aa3b, v179
	v_mul_f32_e32 v2, 0xbfb8aa3b, v205
	v_exp_f32_e32 v177, v175
	v_exp_f32_e32 v2, v2
	v_mul_f32_e32 v175, 0xbfb8aa3b, v208
	v_exp_f32_e32 v175, v175
	v_rcp_f32_e32 v176, v0
	v_add_f32_e32 v0, 1.0, v177
	v_rcp_f32_e32 v177, v0
	v_pk_add_f32 v[2:3], v[2:3], 1.0 op_sel_hi:[1,0]
	v_lshlrev_b32_e32 v0, 16, v168
	v_pk_mul_f32 v[2:3], v[2:3], v[172:173]
	v_mul_f32_e32 v0, 0xbfb8aa3b, v0
	v_pk_mul_f32 v[44:45], v[44:45], v[2:3]
	v_and_b32_e32 v3, 0xffff0000, v168
	v_exp_f32_e32 v0, v0
	v_pk_add_f32 v[174:175], v[174:175], 1.0 op_sel_hi:[1,0]
	v_mul_f32_e32 v3, 0xbfb8aa3b, v3
	v_pk_mul_f32 v[172:173], v[174:175], v[176:177]
	v_lshlrev_b32_e32 v175, 16, v165
	v_and_b32_e32 v176, 0xffff0000, v165
	v_exp_f32_e32 v165, v3
	v_and_b32_e32 v174, 0xffff0000, v164
	v_add_f32_e32 v0, 1.0, v0
	v_lshlrev_b32_e32 v168, 16, v169
	v_lshlrev_b32_e32 v2, 16, v164
	v_rcp_f32_e32 v164, v0
	v_mul_f32_e32 v0, 0xbfb8aa3b, v174
	v_exp_f32_e32 v3, v0
	v_add_f32_e32 v0, 1.0, v165
	v_mul_f32_e32 v165, 0xbfb8aa3b, v168
	v_lshlrev_b32_e32 v179, 16, v167
	v_and_b32_e32 v193, 0xffff0000, v167
	v_exp_f32_e32 v167, v165
	v_and_b32_e32 v169, 0xffff0000, v169
	v_rcp_f32_e32 v165, v0
	v_mul_f32_e32 v0, 0xbfb8aa3b, v175
	v_lshlrev_b32_e32 v177, 16, v166
	v_and_b32_e32 v178, 0xffff0000, v166
	v_exp_f32_e32 v166, v0
	v_add_f32_e32 v0, 1.0, v167
	v_mul_f32_e32 v167, 0xbfb8aa3b, v169
	v_exp_f32_e32 v169, v167
	v_mul_f32_e32 v2, 0xbfb8aa3b, v2
	v_exp_f32_e32 v2, v2
	v_mul_f32_e32 v167, 0xbfb8aa3b, v176
	v_exp_f32_e32 v167, v167
	v_rcp_f32_e32 v168, v0
	v_add_f32_e32 v0, 1.0, v169
	v_rcp_f32_e32 v169, v0
	v_pk_mul_f32 v[46:47], v[46:47], v[172:173]
	v_lshlrev_b32_e32 v172, 16, v170
	v_pk_add_f32 v[2:3], v[2:3], 1.0 op_sel_hi:[1,0]
	v_mul_f32_e32 v0, 0xbfb8aa3b, v172
	v_and_b32_e32 v170, 0xffff0000, v170
	v_pk_add_f32 v[166:167], v[166:167], 1.0 op_sel_hi:[1,0]
	v_pk_mul_f32 v[2:3], v[2:3], v[164:165]
	v_exp_f32_e32 v0, v0
	v_pk_mul_f32 v[164:165], v[166:167], v[168:169]
	v_pk_mul_f32 v[40:41], v[40:41], v[2:3]
	v_mul_f32_e32 v3, 0xbfb8aa3b, v170
	v_pk_mul_f32 v[42:43], v[42:43], v[164:165]
	v_exp_f32_e32 v165, v3
	v_add_f32_e32 v0, 1.0, v0
	v_lshlrev_b32_e32 v173, 16, v171
	v_rcp_f32_e32 v164, v0
	v_mul_f32_e32 v0, 0xbfb8aa3b, v178
	v_exp_f32_e32 v3, v0
	v_add_f32_e32 v0, 1.0, v165
	v_mul_f32_e32 v165, 0xbfb8aa3b, v173
	v_exp_f32_e32 v167, v165
	v_and_b32_e32 v171, 0xffff0000, v171
	v_rcp_f32_e32 v165, v0
	v_mul_f32_e32 v0, 0xbfb8aa3b, v179
	v_exp_f32_e32 v166, v0
	v_add_f32_e32 v0, 1.0, v167
	v_mul_f32_e32 v167, 0xbfb8aa3b, v171
	v_mul_f32_e32 v2, 0xbfb8aa3b, v177
	v_exp_f32_e32 v169, v167
	v_exp_f32_e32 v2, v2
	v_mul_f32_e32 v167, 0xbfb8aa3b, v193
	v_exp_f32_e32 v167, v167
	v_rcp_f32_e32 v168, v0
	v_add_f32_e32 v0, 1.0, v169
	v_rcp_f32_e32 v169, v0
	v_pk_add_f32 v[2:3], v[2:3], 1.0 op_sel_hi:[1,0]
	v_lshlrev_b32_e32 v0, 16, v160
	v_pk_mul_f32 v[2:3], v[2:3], v[164:165]
	v_mul_f32_e32 v0, 0xbfb8aa3b, v0
	v_pk_mul_f32 v[36:37], v[36:37], v[2:3]
	v_and_b32_e32 v3, 0xffff0000, v160
	v_exp_f32_e32 v0, v0
	v_pk_add_f32 v[166:167], v[166:167], 1.0 op_sel_hi:[1,0]
	v_mul_f32_e32 v3, 0xbfb8aa3b, v3
	v_pk_mul_f32 v[164:165], v[166:167], v[168:169]
	v_lshlrev_b32_e32 v167, 16, v157
	v_and_b32_e32 v168, 0xffff0000, v157
	v_exp_f32_e32 v157, v3
	v_and_b32_e32 v166, 0xffff0000, v156
	v_add_f32_e32 v0, 1.0, v0
	v_lshlrev_b32_e32 v160, 16, v161
	v_lshlrev_b32_e32 v2, 16, v156
	v_rcp_f32_e32 v156, v0
; DEVI float bflo(unsigned w) { return __uint_as_float(w << 16); }
; DEVI float bfhi(unsigned w) { return __uint_as_float(w & 0xffff0000u); }
;     DEVI void mid(AccRef acc, const pg8::Unit& u, int wr, int wc, int fr, int fq) const {
;     ...
;             for (int m = 0; m < 4; ++m)
; #pragma unroll
;                 for (int bj = 0; bj < 2; ++bj) { const u32x4 a = ga[m][bj], r = gr[m][bj];
;                     const float av[8] = {bflo(a.x), bfhi(a.x), bflo(a.y), bfhi(a.y), bflo(a.z), bfhi(a.z), bflo(a.w), bfhi(a.w)};
;                     const float rv[8] = {bflo(r.x), bfhi(r.x), bflo(r.y), bfhi(r.y), bflo(r.z), bfhi(r.z), bflo(r.w), bfhi(r.w)};
; #pragma unroll
;                     for (int j = 0; j < 8; ++j) { const float q = (1.f + __expf(-rv[j])) * __builtin_amdgcn_rcpf(1.f + __expf(-av[j])); acc[ai][bj][m][j >> 2][j & 3] *= q; } }
	v_mul_f32_e32 v0, 0xbfb8aa3b, v166
	v_exp_f32_e32 v3, v0
	v_add_f32_e32 v0, 1.0, v157
	v_mul_f32_e32 v157, 0xbfb8aa3b, v160
	v_lshlrev_b32_e32 v171, 16, v159
	v_and_b32_e32 v172, 0xffff0000, v159
	v_exp_f32_e32 v159, v157
	v_and_b32_e32 v161, 0xffff0000, v161
	v_rcp_f32_e32 v157, v0
	v_mul_f32_e32 v0, 0xbfb8aa3b, v167
	v_lshlrev_b32_e32 v169, 16, v158
	v_and_b32_e32 v170, 0xffff0000, v158
	v_exp_f32_e32 v158, v0
	v_add_f32_e32 v0, 1.0, v159
	v_mul_f32_e32 v159, 0xbfb8aa3b, v161
	v_exp_f32_e32 v161, v159
	v_mul_f32_e32 v2, 0xbfb8aa3b, v2
	v_exp_f32_e32 v2, v2
	v_mul_f32_e32 v159, 0xbfb8aa3b, v168
	v_exp_f32_e32 v159, v159
	v_rcp_f32_e32 v160, v0
	v_add_f32_e32 v0, 1.0, v161
	v_rcp_f32_e32 v161, v0
	v_pk_mul_f32 v[38:39], v[38:39], v[164:165]
	v_lshlrev_b32_e32 v164, 16, v162
	v_pk_add_f32 v[2:3], v[2:3], 1.0 op_sel_hi:[1,0]
	v_mul_f32_e32 v0, 0xbfb8aa3b, v164
	v_and_b32_e32 v162, 0xffff0000, v162
	v_pk_add_f32 v[158:159], v[158:159], 1.0 op_sel_hi:[1,0]
	v_pk_mul_f32 v[2:3], v[2:3], v[156:157]
	v_exp_f32_e32 v0, v0
	v_pk_mul_f32 v[156:157], v[158:159], v[160:161]
	v_pk_mul_f32 v[32:33], v[32:33], v[2:3]
	v_mul_f32_e32 v3, 0xbfb8aa3b, v162
	v_pk_mul_f32 v[34:35], v[34:35], v[156:157]
	v_exp_f32_e32 v157, v3
	v_add_f32_e32 v0, 1.0, v0
	v_lshlrev_b32_e32 v165, 16, v163
	v_rcp_f32_e32 v156, v0
	v_mul_f32_e32 v0, 0xbfb8aa3b, v170
	v_exp_f32_e32 v3, v0
	v_add_f32_e32 v0, 1.0, v157
	v_mul_f32_e32 v157, 0xbfb8aa3b, v165
	v_exp_f32_e32 v159, v157
	v_and_b32_e32 v163, 0xffff0000, v163
	v_rcp_f32_e32 v157, v0
	v_mul_f32_e32 v0, 0xbfb8aa3b, v171
	v_exp_f32_e32 v158, v0
	v_add_f32_e32 v0, 1.0, v159
	v_mul_f32_e32 v159, 0xbfb8aa3b, v163
	v_mul_f32_e32 v2, 0xbfb8aa3b, v169
	v_exp_f32_e32 v161, v159
	v_exp_f32_e32 v2, v2
	v_mul_f32_e32 v159, 0xbfb8aa3b, v172
	v_exp_f32_e32 v159, v159
	v_rcp_f32_e32 v160, v0
	v_add_f32_e32 v0, 1.0, v161
	v_rcp_f32_e32 v161, v0
	v_pk_add_f32 v[2:3], v[2:3], 1.0 op_sel_hi:[1,0]
	v_lshlrev_b32_e32 v0, 16, v152
	v_pk_mul_f32 v[2:3], v[2:3], v[156:157]
	v_mul_f32_e32 v0, 0xbfb8aa3b, v0
	v_pk_mul_f32 v[28:29], v[28:29], v[2:3]
	v_and_b32_e32 v3, 0xffff0000, v152
	v_exp_f32_e32 v0, v0
	v_pk_add_f32 v[158:159], v[158:159], 1.0 op_sel_hi:[1,0]
	v_mul_f32_e32 v3, 0xbfb8aa3b, v3
	v_pk_mul_f32 v[156:157], v[158:159], v[160:161]
	v_lshlrev_b32_e32 v159, 16, v149
	v_and_b32_e32 v160, 0xffff0000, v149
	v_exp_f32_e32 v149, v3
	v_and_b32_e32 v158, 0xffff0000, v148
	v_add_f32_e32 v0, 1.0, v0
	v_lshlrev_b32_e32 v152, 16, v153
	v_lshlrev_b32_e32 v2, 16, v148
	v_rcp_f32_e32 v148, v0
	v_mul_f32_e32 v0, 0xbfb8aa3b, v158
	v_exp_f32_e32 v3, v0
	v_add_f32_e32 v0, 1.0, v149
	v_mul_f32_e32 v149, 0xbfb8aa3b, v152
	v_lshlrev_b32_e32 v163, 16, v151
	v_and_b32_e32 v164, 0xffff0000, v151
	v_exp_f32_e32 v151, v149
	v_and_b32_e32 v153, 0xffff0000, v153
	v_rcp_f32_e32 v149, v0
	v_mul_f32_e32 v0, 0xbfb8aa3b, v159
	v_lshlrev_b32_e32 v161, 16, v150
	v_and_b32_e32 v162, 0xffff0000, v150
	v_exp_f32_e32 v150, v0
	v_add_f32_e32 v0, 1.0, v151
	v_mul_f32_e32 v151, 0xbfb8aa3b, v153
	v_exp_f32_e32 v153, v151
	v_mul_f32_e32 v2, 0xbfb8aa3b, v2
	v_exp_f32_e32 v2, v2
	v_mul_f32_e32 v151, 0xbfb8aa3b, v160
	v_exp_f32_e32 v151, v151
	v_rcp_f32_e32 v152, v0
	v_add_f32_e32 v0, 1.0, v153
	v_rcp_f32_e32 v153, v0
	v_pk_mul_f32 v[30:31], v[30:31], v[156:157]
	v_lshlrev_b32_e32 v156, 16, v154
	v_pk_add_f32 v[2:3], v[2:3], 1.0 op_sel_hi:[1,0]
	v_mul_f32_e32 v0, 0xbfb8aa3b, v156
	v_and_b32_e32 v154, 0xffff0000, v154
	v_pk_add_f32 v[150:151], v[150:151], 1.0 op_sel_hi:[1,0]
	v_pk_mul_f32 v[2:3], v[2:3], v[148:149]
	v_exp_f32_e32 v0, v0
	v_pk_mul_f32 v[148:149], v[150:151], v[152:153]
	v_pk_mul_f32 v[24:25], v[24:25], v[2:3]
	v_mul_f32_e32 v3, 0xbfb8aa3b, v154
	v_pk_mul_f32 v[26:27], v[26:27], v[148:149]
	v_exp_f32_e32 v149, v3
	v_add_f32_e32 v0, 1.0, v0
	v_lshlrev_b32_e32 v157, 16, v155
	v_rcp_f32_e32 v148, v0
	v_mul_f32_e32 v0, 0xbfb8aa3b, v162
	v_exp_f32_e32 v3, v0
	v_add_f32_e32 v0, 1.0, v149
	v_mul_f32_e32 v149, 0xbfb8aa3b, v157
	v_exp_f32_e32 v151, v149
	v_and_b32_e32 v155, 0xffff0000, v155
	v_rcp_f32_e32 v149, v0
	v_mul_f32_e32 v0, 0xbfb8aa3b, v163
	v_exp_f32_e32 v150, v0
	v_add_f32_e32 v0, 1.0, v151
	v_mul_f32_e32 v151, 0xbfb8aa3b, v155
	v_mul_f32_e32 v2, 0xbfb8aa3b, v161
	v_exp_f32_e32 v153, v151
	v_exp_f32_e32 v2, v2
	v_mul_f32_e32 v151, 0xbfb8aa3b, v164
	v_exp_f32_e32 v151, v151
	v_rcp_f32_e32 v152, v0
	v_add_f32_e32 v0, 1.0, v153
	v_rcp_f32_e32 v153, v0
	v_pk_add_f32 v[2:3], v[2:3], 1.0 op_sel_hi:[1,0]
	v_lshlrev_b32_e32 v0, 16, v144
	v_pk_mul_f32 v[2:3], v[2:3], v[148:149]
	v_mul_f32_e32 v0, 0xbfb8aa3b, v0
	v_pk_mul_f32 v[20:21], v[20:21], v[2:3]
	v_and_b32_e32 v3, 0xffff0000, v144
	v_exp_f32_e32 v0, v0
	v_pk_add_f32 v[150:151], v[150:151], 1.0 op_sel_hi:[1,0]
	v_mul_f32_e32 v3, 0xbfb8aa3b, v3
	v_pk_mul_f32 v[148:149], v[150:151], v[152:153]
	v_lshlrev_b32_e32 v151, 16, v141
	v_and_b32_e32 v152, 0xffff0000, v141
; DEVI float bflo(unsigned w) { return __uint_as_float(w << 16); }
; DEVI float bfhi(unsigned w) { return __uint_as_float(w & 0xffff0000u); }
;     DEVI void mid(AccRef acc, const pg8::Unit& u, int wr, int wc, int fr, int fq) const {
;     ...
;             for (int m = 0; m < 4; ++m)
; #pragma unroll
;                 for (int bj = 0; bj < 2; ++bj) { const u32x4 a = ga[m][bj], r = gr[m][bj];
;                     const float av[8] = {bflo(a.x), bfhi(a.x), bflo(a.y), bfhi(a.y), bflo(a.z), bfhi(a.z), bflo(a.w), bfhi(a.w)};
;                     const float rv[8] = {bflo(r.x), bfhi(r.x), bflo(r.y), bfhi(r.y), bflo(r.z), bfhi(r.z), bflo(r.w), bfhi(r.w)};
; #pragma unroll
;                     for (int j = 0; j < 8; ++j) { const float q = (1.f + __expf(-rv[j])) * __builtin_amdgcn_rcpf(1.f + __expf(-av[j])); acc[ai][bj][m][j >> 2][j & 3] *= q; } }
	v_exp_f32_e32 v141, v3
	v_and_b32_e32 v150, 0xffff0000, v140
	v_add_f32_e32 v0, 1.0, v0
	v_lshlrev_b32_e32 v144, 16, v145
	v_lshlrev_b32_e32 v2, 16, v140
	v_rcp_f32_e32 v140, v0
	v_mul_f32_e32 v0, 0xbfb8aa3b, v150
	v_exp_f32_e32 v3, v0
	v_add_f32_e32 v0, 1.0, v141
	v_mul_f32_e32 v141, 0xbfb8aa3b, v144
	v_lshlrev_b32_e32 v155, 16, v143
	v_and_b32_e32 v156, 0xffff0000, v143
	v_exp_f32_e32 v143, v141
	v_and_b32_e32 v145, 0xffff0000, v145
	v_rcp_f32_e32 v141, v0
	v_mul_f32_e32 v0, 0xbfb8aa3b, v151
	v_lshlrev_b32_e32 v153, 16, v142
	v_and_b32_e32 v154, 0xffff0000, v142
	v_exp_f32_e32 v142, v0
	v_add_f32_e32 v0, 1.0, v143
	v_mul_f32_e32 v143, 0xbfb8aa3b, v145
	v_exp_f32_e32 v145, v143
	v_mul_f32_e32 v2, 0xbfb8aa3b, v2
	v_exp_f32_e32 v2, v2
	v_mul_f32_e32 v143, 0xbfb8aa3b, v152
	v_exp_f32_e32 v143, v143
	v_rcp_f32_e32 v144, v0
	v_add_f32_e32 v0, 1.0, v145
	v_rcp_f32_e32 v145, v0
	v_pk_mul_f32 v[22:23], v[22:23], v[148:149]
	v_lshlrev_b32_e32 v148, 16, v146
	v_pk_add_f32 v[2:3], v[2:3], 1.0 op_sel_hi:[1,0]
	v_mul_f32_e32 v0, 0xbfb8aa3b, v148
	v_and_b32_e32 v146, 0xffff0000, v146
	v_pk_add_f32 v[142:143], v[142:143], 1.0 op_sel_hi:[1,0]
	v_pk_mul_f32 v[2:3], v[2:3], v[140:141]
	v_exp_f32_e32 v0, v0
	v_pk_mul_f32 v[140:141], v[142:143], v[144:145]
	v_pk_mul_f32 v[16:17], v[16:17], v[2:3]
	v_mul_f32_e32 v3, 0xbfb8aa3b, v146
	v_pk_mul_f32 v[18:19], v[18:19], v[140:141]
	v_exp_f32_e32 v141, v3
	v_add_f32_e32 v0, 1.0, v0
	v_lshlrev_b32_e32 v149, 16, v147
	v_rcp_f32_e32 v140, v0
	v_mul_f32_e32 v0, 0xbfb8aa3b, v154
	v_exp_f32_e32 v3, v0
	v_add_f32_e32 v0, 1.0, v141
	v_mul_f32_e32 v141, 0xbfb8aa3b, v149
	v_exp_f32_e32 v143, v141
	v_and_b32_e32 v147, 0xffff0000, v147
	v_rcp_f32_e32 v141, v0
	v_mul_f32_e32 v0, 0xbfb8aa3b, v155
	v_exp_f32_e32 v142, v0
	v_add_f32_e32 v0, 1.0, v143
	v_mul_f32_e32 v143, 0xbfb8aa3b, v147
	v_mul_f32_e32 v2, 0xbfb8aa3b, v153
	v_exp_f32_e32 v145, v143
	v_exp_f32_e32 v2, v2
	v_mul_f32_e32 v143, 0xbfb8aa3b, v156
	v_exp_f32_e32 v143, v143
	v_rcp_f32_e32 v144, v0
	v_add_f32_e32 v0, 1.0, v145
	v_rcp_f32_e32 v145, v0
	v_pk_add_f32 v[2:3], v[2:3], 1.0 op_sel_hi:[1,0]
	v_lshlrev_b32_e32 v0, 16, v136
	v_pk_mul_f32 v[2:3], v[2:3], v[140:141]
	v_mul_f32_e32 v0, 0xbfb8aa3b, v0
	v_pk_mul_f32 v[12:13], v[12:13], v[2:3]
	v_and_b32_e32 v3, 0xffff0000, v136
	v_exp_f32_e32 v0, v0
	v_pk_add_f32 v[142:143], v[142:143], 1.0 op_sel_hi:[1,0]
	v_mul_f32_e32 v3, 0xbfb8aa3b, v3
	v_pk_mul_f32 v[140:141], v[142:143], v[144:145]
	v_lshlrev_b32_e32 v143, 16, v133
	v_and_b32_e32 v144, 0xffff0000, v133
	v_exp_f32_e32 v133, v3
	v_and_b32_e32 v142, 0xffff0000, v132
	v_add_f32_e32 v0, 1.0, v0
	v_lshlrev_b32_e32 v136, 16, v137
	v_lshlrev_b32_e32 v2, 16, v132
	v_rcp_f32_e32 v132, v0
	v_mul_f32_e32 v0, 0xbfb8aa3b, v142
	v_exp_f32_e32 v3, v0
	v_add_f32_e32 v0, 1.0, v133
	v_mul_f32_e32 v133, 0xbfb8aa3b, v136
	v_lshlrev_b32_e32 v147, 16, v135
	v_and_b32_e32 v148, 0xffff0000, v135
	v_exp_f32_e32 v135, v133
	v_and_b32_e32 v137, 0xffff0000, v137
	v_rcp_f32_e32 v133, v0
	v_mul_f32_e32 v0, 0xbfb8aa3b, v143
	v_lshlrev_b32_e32 v145, 16, v134
	v_and_b32_e32 v146, 0xffff0000, v134
	v_exp_f32_e32 v134, v0
	v_add_f32_e32 v0, 1.0, v135
	v_mul_f32_e32 v135, 0xbfb8aa3b, v137
	v_exp_f32_e32 v137, v135
	v_mul_f32_e32 v2, 0xbfb8aa3b, v2
	v_exp_f32_e32 v2, v2
	v_mul_f32_e32 v135, 0xbfb8aa3b, v144
	v_exp_f32_e32 v135, v135
	v_rcp_f32_e32 v136, v0
	v_add_f32_e32 v0, 1.0, v137
	v_rcp_f32_e32 v137, v0
	v_pk_mul_f32 v[14:15], v[14:15], v[140:141]
	v_lshlrev_b32_e32 v140, 16, v138
	v_pk_add_f32 v[2:3], v[2:3], 1.0 op_sel_hi:[1,0]
	v_mul_f32_e32 v0, 0xbfb8aa3b, v140
	v_and_b32_e32 v138, 0xffff0000, v138
	v_pk_add_f32 v[134:135], v[134:135], 1.0 op_sel_hi:[1,0]
	v_pk_mul_f32 v[2:3], v[2:3], v[132:133]
	v_exp_f32_e32 v0, v0
	v_pk_mul_f32 v[132:133], v[134:135], v[136:137]
	v_pk_mul_f32 v[8:9], v[8:9], v[2:3]
	v_mul_f32_e32 v3, 0xbfb8aa3b, v138
	v_pk_mul_f32 v[10:11], v[10:11], v[132:133]
	v_exp_f32_e32 v133, v3
	v_add_f32_e32 v0, 1.0, v0
	v_lshlrev_b32_e32 v141, 16, v139
	v_rcp_f32_e32 v132, v0
	v_mul_f32_e32 v0, 0xbfb8aa3b, v146
	v_exp_f32_e32 v3, v0
	v_add_f32_e32 v0, 1.0, v133
	v_mul_f32_e32 v133, 0xbfb8aa3b, v141
	v_exp_f32_e32 v135, v133
	v_and_b32_e32 v139, 0xffff0000, v139
	v_rcp_f32_e32 v133, v0
	v_mul_f32_e32 v0, 0xbfb8aa3b, v147
	v_exp_f32_e32 v134, v0
	v_add_f32_e32 v0, 1.0, v135
	v_mul_f32_e32 v135, 0xbfb8aa3b, v139
	v_exp_f32_e32 v137, v135
	v_mul_f32_e32 v2, 0xbfb8aa3b, v145
	v_mul_f32_e32 v135, 0xbfb8aa3b, v148
	v_exp_f32_e32 v2, v2
	v_exp_f32_e32 v135, v135
	v_rcp_f32_e32 v136, v0
	v_add_f32_e32 v0, 1.0, v137
	v_rcp_f32_e32 v137, v0
	v_pk_add_f32 v[134:135], v[134:135], 1.0 op_sel_hi:[1,0]
	v_pk_add_f32 v[2:3], v[2:3], 1.0 op_sel_hi:[1,0]
	s_nop 0
	v_pk_mul_f32 v[2:3], v[2:3], v[132:133]
	v_pk_mul_f32 v[132:133], v[134:135], v[136:137]
	v_pk_mul_f32 v[4:5], v[4:5], v[2:3]
	v_pk_mul_f32 v[6:7], v[6:7], v[132:133]
	s_branch .LBB0_63

; DEVI unsigned cvtpk(float lo, float hi) { unsigned r; asm volatile("v_cvt_pk_bf16_f32 %0, %1, %2" : "=v"(r) : "v"(lo), "v"(hi)); return r; }
; DEVI float bflo(unsigned w) { return __uint_as_float(w << 16); }
; DEVI float bfhi(unsigned w) { return __uint_as_float(w & 0xffff0000u); }
; DEVI float sigmoidf_(float x) { return __builtin_amdgcn_rcpf(1.f + __expf(-x)); }
; DEVI int ltid(int wv) { int t = (wv << 6) | (int)__builtin_amdgcn_mbcnt_hi(~0u, __builtin_amdgcn_mbcnt_lo(~0u, 0u)); asm volatile("" : "+v"(t)); return t; }
; DEVI void rnn_fix_phase(const bf16_t* hloc, const bf16_t* pcum, const float* carry, bf16_t* gr_yr, int wv) {
;     ...
;     for (size_t idx0 = (size_t)lbid() * 512 + ltid(wv); idx0 < nvec; idx0 += 2 * stride) {
;         u32x4 hw[2], pw[2], gw[2]; f32x4 c0[2], c1[2];
; #pragma unroll
;         for (int q = 0; q < 2; ++q) { const size_t idx = idx0 + q * stride; if (idx >= nvec) break; const size_t row = idx >> 7; const int c8 = (int)(idx & 127) * 8; const int b = (int)(row >> 14), chunk = (int)((row & 16383) >> 7);
;             hw[q] = *(const u32x4*)(hloc + idx * 8); pw[q] = *(const u32x4*)(pcum + idx * 8); gw[q] = *(const u32x4*)(gr_yr + idx * 8);
;             const float* cp = carry + ((size_t)b * 128 + chunk) * 1024 + c8; c0[q] = *(const f32x4*)cp; c1[q] = *(const f32x4*)(cp + 4); }
; #pragma unroll
;         for (int q = 0; q < 2; ++q) { const size_t idx = idx0 + q * stride; if (idx >= nvec) break;
;             const float hv[8] = {bflo(hw[q].x), bfhi(hw[q].x), bflo(hw[q].y), bfhi(hw[q].y), bflo(hw[q].z), bfhi(hw[q].z), bflo(hw[q].w), bfhi(hw[q].w)};
;             const float pv[8] = {bflo(pw[q].x), bfhi(pw[q].x), bflo(pw[q].y), bfhi(pw[q].y), bflo(pw[q].z), bfhi(pw[q].z), bflo(pw[q].w), bfhi(pw[q].w)};
;             const float gv[8] = {bflo(gw[q].x), bfhi(gw[q].x), bflo(gw[q].y), bfhi(gw[q].y), bflo(gw[q].z), bfhi(gw[q].z), bflo(gw[q].w), bfhi(gw[q].w)};
;             const float cv[8] = {c0[q][0], c0[q][1], c0[q][2], c0[q][3], c1[q][0], c1[q][1], c1[q][2], c1[q][3]};
;             float y[8];
; #pragma unroll
;             for (int i = 0; i < 8; ++i) { const float x = gv[i], z = 1.5957691216f * (x + 0.044715f * x * x * x); y[i] = (hv[i] + pv[i] * cv[i]) * x * sigmoidf_(z); }
;             u32x4 o = {cvtpk(y[0], y[1]), cvtpk(y[2], y[3]), cvtpk(y[4], y[5]), cvtpk(y[6], y[7])};
;             *(u32x4*)(gr_yr + idx * 8) = o; }
.LBB0_74:
	v_lshl_add_u64 v[52:53], s[80:81], 0, v[44:45]
	v_add_co_u32_e32 v22, vcc, 0x8000000, v52
	v_and_b32_e32 v0, 0x3f8, v46
	s_nop 0
	v_addc_co_u32_e32 v23, vcc, 0, v53, vcc
	v_add_co_u32_e32 v24, vcc, 0xc000000, v52
	v_lshlrev_b32_e32 v0, 2, v0
	s_nop 0
	v_addc_co_u32_e32 v25, vcc, 0, v53, vcc
	v_lshl_add_u64 v[54:55], s[6:7], 0, v[0:1]
	global_load_dwordx4 v[38:41], v[22:23], off
	global_load_dwordx4 v[34:37], v[24:25], off
	v_add_co_u32_e32 v22, vcc, 0x14000000, v52
	v_lshrrev_b32_e32 v0, 2, v48
	s_nop 0
	v_addc_co_u32_e32 v23, vcc, 0, v53, vcc
	v_and_b32_e32 v0, 0xff000, v0
	global_load_dwordx4 v[30:33], v[22:23], off
	v_lshl_add_u64 v[22:23], v[54:55], 0, v[0:1]
	global_load_dwordx4 v[26:29], v[22:23], off
	s_nop 0
	global_load_dwordx4 v[22:25], v[22:23], off offset:16
	v_lshl_add_u64 v[48:49], v[48:49], 0, s[10:11]
	s_mov_b64 s[4:5], 0x400000
	v_cmp_gt_u64_e64 s[4:5], s[4:5], v[48:49]
	v_lshl_add_u64 v[50:51], s[80:81], 0, v[42:43]
	s_and_saveexec_b64 s[60:61], s[4:5]
	s_cbranch_execz .LBB0_76
	v_add_co_u32_e32 v2, vcc, 0x8000000, v50
	v_lshrrev_b32_e32 v0, 2, v48
	s_nop 0
	v_addc_co_u32_e32 v3, vcc, 0, v51, vcc
	v_add_co_u32_e32 v6, vcc, 0xc000000, v50
	v_and_b32_e32 v0, 0xff000, v0
	s_nop 0
	v_addc_co_u32_e32 v7, vcc, 0, v51, vcc
	v_add_co_u32_e32 v10, vcc, 0x14000000, v50
	v_lshl_add_u64 v[18:19], v[54:55], 0, v[0:1]
	s_nop 0
	v_addc_co_u32_e32 v11, vcc, 0, v51, vcc
	global_load_dwordx4 v[2:5], v[2:3], off
	s_nop 0
	global_load_dwordx4 v[6:9], v[6:7], off
	s_nop 0
	global_load_dwordx4 v[10:13], v[10:11], off
	s_nop 0
	global_load_dwordx4 v[14:17], v[18:19], off
	s_nop 0
	global_load_dwordx4 v[18:21], v[18:19], off offset:16
.LBB0_76:
	s_or_b64 exec, exec, s[60:61]
	s_waitcnt vmcnt(0) lgkmcnt(0)
	v_lshlrev_b32_e32 v54, 16, v39
	v_lshlrev_b32_e32 v58, 16, v35
	v_lshlrev_b32_e32 v62, 16, v31
	v_and_b32_e32 v31, 0xffff0000, v31
	v_fmac_f32_e32 v54, v28, v58
	v_mul_f32_e32 v28, 0x3d372713, v31
	v_mul_f32_e32 v28, v28, v31
	v_fma_f32 v28, v28, v31, v31
	v_mul_f32_e32 v28, 0x3fcc422a, v28
	v_mul_f32_e32 v28, 0xbfb8aa3b, v28
	v_exp_f32_e32 v28, v28
	v_and_b32_e32 v39, 0xffff0000, v39
	v_and_b32_e32 v35, 0xffff0000, v35
	v_fmac_f32_e32 v39, v29, v35
	v_add_f32_e32 v28, 1.0, v28
	v_rcp_f32_e32 v28, v28
	v_lshlrev_b32_e32 v63, 16, v32
	v_mul_f32_e32 v29, v39, v31
	v_lshlrev_b32_e32 v61, 16, v30
	v_mul_f32_e32 v28, v29, v28
	v_mul_f32_e32 v29, 0x3d372713, v63
	v_lshlrev_b32_e32 v0, 16, v38
	v_and_b32_e32 v38, 0xffff0000, v38
	v_lshlrev_b32_e32 v57, 16, v34
	v_and_b32_e32 v34, 0xffff0000, v34
	v_mul_f32_e32 v65, 0x3d372713, v61
	v_mul_f32_e32 v29, v29, v63
	v_mul_f32_e32 v65, v65, v61
	v_fmac_f32_e32 v38, v27, v34
	v_mul_f32_e32 v27, 0x3d372713, v62
	v_fma_f32 v29, v29, v63, v63
	v_lshlrev_b32_e32 v55, 16, v40
	v_lshlrev_b32_e32 v59, 16, v36
	v_and_b32_e32 v32, 0xffff0000, v32
	v_fma_f32 v65, v65, v61, v61
	v_mul_f32_e32 v27, v27, v62
	v_mul_f32_e32 v29, 0x3fcc422a, v29
	v_mul_f32_e32 v65, 0x3fcc422a, v65
	v_fma_f32 v27, v27, v62, v62
	v_fmac_f32_e32 v55, v22, v59
	v_mul_f32_e32 v22, 0xbfb8aa3b, v29
	v_mul_f32_e32 v29, 0x3d372713, v32
	v_fmac_f32_e32 v0, v26, v57
	v_mul_f32_e32 v26, 0xbfb8aa3b, v65
	v_mul_f32_e32 v27, 0x3fcc422a, v27
	v_mul_f32_e32 v29, v29, v32
	v_exp_f32_e32 v26, v26
	v_mul_f32_e32 v27, 0xbfb8aa3b, v27
	v_fma_f32 v29, v29, v32, v32
	v_exp_f32_e32 v27, v27
	v_mul_f32_e32 v29, 0x3fcc422a, v29
	v_exp_f32_e32 v22, v22
	v_mul_f32_e32 v29, 0xbfb8aa3b, v29
	v_exp_f32_e32 v29, v29
	v_add_f32_e32 v26, 1.0, v26
	v_rcp_f32_e32 v26, v26
	v_add_f32_e32 v27, 1.0, v27
	v_and_b32_e32 v30, 0xffff0000, v30
	v_rcp_f32_e32 v27, v27
	v_add_f32_e32 v22, 1.0, v22
	v_mul_f32_e32 v57, 0x3d372713, v30
	v_rcp_f32_e32 v22, v22
	v_add_f32_e32 v29, 1.0, v29
	v_mul_f32_e32 v57, v57, v30
	v_mul_f32_e32 v0, v0, v61
	v_rcp_f32_e32 v29, v29
	v_and_b32_e32 v40, 0xffff0000, v40
	v_and_b32_e32 v36, 0xffff0000, v36
	v_fma_f32 v57, v57, v30, v30
	v_mul_f32_e32 v0, v0, v26
	v_mul_f32_e32 v26, v38, v30
	v_mul_f32_e32 v30, v54, v62
	v_mul_f32_e32 v27, v30, v27
	v_mul_f32_e32 v30, v55, v63
	v_fmac_f32_e32 v40, v23, v36
	v_lshlrev_b32_e32 v64, 16, v33
	v_mul_f32_e32 v30, v30, v22
	v_mul_f32_e32 v22, v40, v32
	v_and_b32_e32 v33, 0xffff0000, v33
	v_mul_f32_e32 v29, v22, v29
	v_mul_f32_e32 v22, 0x3d372713, v64
	v_mul_f32_e32 v22, v22, v64
	v_mul_f32_e32 v23, 0x3d372713, v33
	v_fma_f32 v22, v22, v64, v64
	v_mul_f32_e32 v23, v23, v33
	v_mul_f32_e32 v22, 0x3fcc422a, v22
	v_fma_f32 v23, v23, v33, v33
	v_mul_f32_e32 v22, 0xbfb8aa3b, v22
	v_mul_f32_e32 v23, 0x3fcc422a, v23
	v_mul_f32_e32 v57, 0x3fcc422a, v57
	v_exp_f32_e32 v22, v22
	v_mul_f32_e32 v23, 0xbfb8aa3b, v23
	v_mul_f32_e32 v57, 0xbfb8aa3b, v57
	v_exp_f32_e32 v23, v23
	v_exp_f32_e32 v57, v57
	v_add_f32_e32 v22, 1.0, v22
	v_rcp_f32_e32 v22, v22
	v_add_f32_e32 v23, 1.0, v23
	v_lshlrev_b32_e32 v56, 16, v41
	v_lshlrev_b32_e32 v60, 16, v37
	v_add_f32_e32 v57, 1.0, v57
	v_rcp_f32_e32 v23, v23
	v_and_b32_e32 v41, 0xffff0000, v41
	v_and_b32_e32 v37, 0xffff0000, v37
	v_rcp_f32_e32 v57, v57
	v_fmac_f32_e32 v56, v24, v60
	v_mul_f32_e32 v24, v56, v64
	v_fmac_f32_e32 v41, v25, v37
	s_mov_b64 s[60:61], 0x14000000
	v_mul_f32_e32 v31, v24, v22
	v_mul_f32_e32 v22, v41, v33
	v_lshl_add_u64 v[52:53], v[52:53], 0, s[60:61]
	v_mul_f32_e32 v25, v22, v23
	v_mul_f32_e32 v26, v26, v57
	v_cvt_pk_bf16_f32 v22, v0, v26
	v_cvt_pk_bf16_f32 v23, v27, v28
	v_cvt_pk_bf16_f32 v24, v30, v29
	v_cvt_pk_bf16_f32 v25, v31, v25
	global_store_dwordx4 v[52:53], v[22:25], off
	s_and_saveexec_b64 s[82:83], s[4:5]
	s_cbranch_execz .LBB0_73
; DEVI unsigned cvtpk(float lo, float hi) { unsigned r; asm volatile("v_cvt_pk_bf16_f32 %0, %1, %2" : "=v"(r) : "v"(lo), "v"(hi)); return r; }
; DEVI float bflo(unsigned w) { return __uint_as_float(w << 16); }
; DEVI float bfhi(unsigned w) { return __uint_as_float(w & 0xffff0000u); }
; DEVI float sigmoidf_(float x) { return __builtin_amdgcn_rcpf(1.f + __expf(-x)); }
; DEVI void rnn_fix_phase(const bf16_t* hloc, const bf16_t* pcum, const float* carry, bf16_t* gr_yr, int wv) {
;     ...
;         for (int q = 0; q < 2; ++q) { const size_t idx = idx0 + q * stride; if (idx >= nvec) break;
;             const float hv[8] = {bflo(hw[q].x), bfhi(hw[q].x), bflo(hw[q].y), bfhi(hw[q].y), bflo(hw[q].z), bfhi(hw[q].z), bflo(hw[q].w), bfhi(hw[q].w)};
;             const float pv[8] = {bflo(pw[q].x), bfhi(pw[q].x), bflo(pw[q].y), bfhi(pw[q].y), bflo(pw[q].z), bfhi(pw[q].z), bflo(pw[q].w), bfhi(pw[q].w)};
;             const float gv[8] = {bflo(gw[q].x), bfhi(gw[q].x), bflo(gw[q].y), bfhi(gw[q].y), bflo(gw[q].z), bfhi(gw[q].z), bflo(gw[q].w), bfhi(gw[q].w)};
;             const float cv[8] = {c0[q][0], c0[q][1], c0[q][2], c0[q][3], c1[q][0], c1[q][1], c1[q][2], c1[q][3]};
;             float y[8];
; #pragma unroll
;             for (int i = 0; i < 8; ++i) { const float x = gv[i], z = 1.5957691216f * (x + 0.044715f * x * x * x); y[i] = (hv[i] + pv[i] * cv[i]) * x * sigmoidf_(z); }
;             u32x4 o = {cvtpk(y[0], y[1]), cvtpk(y[2], y[3]), cvtpk(y[4], y[5]), cvtpk(y[6], y[7])};
;             *(u32x4*)(gr_yr + idx * 8) = o; }
	v_lshlrev_b32_e32 v37, 16, v10
	v_mul_f32_e32 v55, 0x3d372713, v37
	v_mul_f32_e32 v55, v55, v37
	v_fma_f32 v55, v55, v37, v37
	v_lshlrev_b32_e32 v0, 16, v2
	v_lshlrev_b32_e32 v29, 16, v6
	v_mul_f32_e32 v55, 0x3fcc422a, v55
	v_fmac_f32_e32 v0, v14, v29
	v_mul_f32_e32 v29, 0xbfb8aa3b, v55
	v_exp_f32_e32 v29, v29
	v_lshlrev_b32_e32 v39, 16, v11
	v_mul_f32_e32 v0, v0, v37
	v_and_b32_e32 v22, 0xffff0000, v2
	v_add_f32_e32 v29, 1.0, v29
	v_rcp_f32_e32 v29, v29
	v_and_b32_e32 v30, 0xffff0000, v6
	v_and_b32_e32 v40, 0xffff0000, v11
	v_fmac_f32_e32 v22, v15, v30
	v_mul_f32_e32 v0, v0, v29
	v_mul_f32_e32 v29, 0x3d372713, v39
	v_mul_f32_e32 v29, v29, v39
	v_mul_f32_e32 v30, 0x3d372713, v40
	v_fma_f32 v29, v29, v39, v39
	v_mul_f32_e32 v30, v30, v40
	v_mul_f32_e32 v29, 0x3fcc422a, v29
	v_fma_f32 v30, v30, v40, v40
	v_mul_f32_e32 v29, 0xbfb8aa3b, v29
	v_mul_f32_e32 v30, 0x3fcc422a, v30
	v_exp_f32_e32 v29, v29
	v_mul_f32_e32 v30, 0xbfb8aa3b, v30
	v_exp_f32_e32 v30, v30
	v_lshlrev_b32_e32 v23, 16, v3
	v_add_f32_e32 v29, 1.0, v29
	v_rcp_f32_e32 v29, v29
	v_add_f32_e32 v30, 1.0, v30
	v_lshlrev_b32_e32 v31, 16, v7
	v_rcp_f32_e32 v30, v30
	v_and_b32_e32 v24, 0xffff0000, v3
	v_and_b32_e32 v32, 0xffff0000, v7
	v_fmac_f32_e32 v23, v16, v31
	v_lshlrev_b32_e32 v41, 16, v12
	v_mul_f32_e32 v23, v23, v39
	v_fmac_f32_e32 v24, v17, v32
	v_and_b32_e32 v52, 0xffff0000, v12
	v_mul_f32_e32 v23, v23, v29
	v_mul_f32_e32 v24, v24, v40
	v_mul_f32_e32 v29, 0x3d372713, v41
	v_mul_f32_e32 v24, v24, v30
	v_mul_f32_e32 v29, v29, v41
	v_mul_f32_e32 v30, 0x3d372713, v52
	v_fma_f32 v29, v29, v41, v41
	v_mul_f32_e32 v30, v30, v52
	v_mul_f32_e32 v29, 0x3fcc422a, v29
	v_fma_f32 v30, v30, v52, v52
	v_mul_f32_e32 v29, 0xbfb8aa3b, v29
	v_mul_f32_e32 v30, 0x3fcc422a, v30
	v_exp_f32_e32 v29, v29
	v_mul_f32_e32 v30, 0xbfb8aa3b, v30
	v_exp_f32_e32 v30, v30
	v_lshlrev_b32_e32 v25, 16, v4
	v_add_f32_e32 v29, 1.0, v29
	v_rcp_f32_e32 v29, v29
	v_add_f32_e32 v30, 1.0, v30
	v_lshlrev_b32_e32 v33, 16, v8
	v_rcp_f32_e32 v30, v30
	v_and_b32_e32 v26, 0xffff0000, v4
	v_and_b32_e32 v34, 0xffff0000, v8
	v_and_b32_e32 v38, 0xffff0000, v10
	v_fmac_f32_e32 v25, v18, v33
	v_lshlrev_b32_e32 v53, 16, v13
	v_mul_f32_e32 v55, 0x3d372713, v38
	v_mul_f32_e32 v25, v25, v41
	v_fmac_f32_e32 v26, v19, v34
	v_and_b32_e32 v54, 0xffff0000, v13
	v_mul_f32_e32 v55, v55, v38
	v_mul_f32_e32 v25, v25, v29
	v_mul_f32_e32 v26, v26, v52
	v_mul_f32_e32 v29, 0x3d372713, v53
	v_fma_f32 v55, v55, v38, v38
	v_mul_f32_e32 v26, v26, v30
	v_mul_f32_e32 v29, v29, v53
	v_mul_f32_e32 v30, 0x3d372713, v54
	v_mul_f32_e32 v55, 0x3fcc422a, v55
	v_fma_f32 v29, v29, v53, v53
	v_mul_f32_e32 v30, v30, v54
	v_mul_f32_e32 v55, 0xbfb8aa3b, v55
	v_mul_f32_e32 v29, 0x3fcc422a, v29
	v_fma_f32 v30, v30, v54, v54
	v_exp_f32_e32 v55, v55
	v_mul_f32_e32 v29, 0xbfb8aa3b, v29
	v_mul_f32_e32 v30, 0x3fcc422a, v30
	v_exp_f32_e32 v29, v29
	v_mul_f32_e32 v30, 0xbfb8aa3b, v30
	v_exp_f32_e32 v30, v30
	v_add_f32_e32 v37, 1.0, v55
	v_rcp_f32_e32 v37, v37
	v_add_f32_e32 v29, 1.0, v29
	v_rcp_f32_e32 v29, v29
	v_add_f32_e32 v30, 1.0, v30
	v_lshlrev_b32_e32 v27, 16, v5
	v_lshlrev_b32_e32 v35, 16, v9
	v_rcp_f32_e32 v30, v30
	v_and_b32_e32 v28, 0xffff0000, v5
	v_and_b32_e32 v36, 0xffff0000, v9
	v_mul_f32_e32 v22, v22, v38
	v_fmac_f32_e32 v27, v20, v35
	v_mul_f32_e32 v22, v22, v37
	v_mul_f32_e32 v27, v27, v53
	v_fmac_f32_e32 v28, v21, v36
	v_mul_f32_e32 v27, v27, v29
	v_mul_f32_e32 v28, v28, v54
	v_cvt_pk_bf16_f32 v22, v0, v22
	v_cvt_pk_bf16_f32 v23, v23, v24
	v_cvt_pk_bf16_f32 v24, v25, v26
	v_add_co_u32_e32 v26, vcc, 0x14000000, v50
	v_mul_f32_e32 v28, v28, v30
	v_cvt_pk_bf16_f32 v25, v27, v28
	s_nop 0
	v_addc_co_u32_e32 v27, vcc, 0, v51, vcc
	global_store_dwordx4 v[26:27], v[22:25], off
	s_branch .LBB0_73

; DEVI void rnn_carry_phase(const float* aggA, const float* aggH, float* carry, int wv) {
;     ...
;     if (g < 2048) { const int b = g >> 10, ch = g & 1023; float H = 0.f;
;         for (int c0 = 0; c0 < 128; c0 += 64) { float A[64], Hh[64];
; #pragma unroll
;             for (int i = 0; i < 64; ++i) { const size_t o = ((size_t)b * 128 + c0 + i) * 1024 + ch; A[i] = aggA[o]; Hh[i] = aggH[o]; }
.LBB0_86:
	v_or_b32_e32 v7, s11, v3
	v_or_b32_e32 v6, s10, v2
	v_lshlrev_b64 v[6:7], 12, v[6:7]
	v_or_b32_e32 v10, v6, v0
	v_mov_b32_e32 v11, v7
	v_lshl_add_u64 v[12:13], s[18:19], 0, v[10:11]
	v_lshl_add_u64 v[10:11], s[20:21], 0, v[10:11]
	v_or_b32_e32 v8, 0x1000, v6
	global_load_dword v15, v[12:13], off
	v_or_b32_e32 v14, 0x4000, v6
	global_load_dword v11, v[10:11], off
	v_or_b32_e32 v12, v8, v0
	v_mov_b32_e32 v13, v7
	v_lshl_add_u64 v[16:17], s[18:19], 0, v[12:13]
	v_lshl_add_u64 v[12:13], s[20:21], 0, v[12:13]
	v_or_b32_e32 v10, 0x2000, v6
	global_load_dword v19, v[16:17], off
	v_or_b32_e32 v18, 0x6000, v6
	global_load_dword v13, v[12:13], off
	v_or_b32_e32 v16, v10, v0
	v_mov_b32_e32 v17, v7
	v_lshl_add_u64 v[20:21], s[18:19], 0, v[16:17]
	v_lshl_add_u64 v[16:17], s[20:21], 0, v[16:17]
	v_or_b32_e32 v12, 0x3000, v6
	global_load_dword v23, v[20:21], off
	v_or_b32_e32 v22, 0x8000, v6
	global_load_dword v17, v[16:17], off
	v_or_b32_e32 v20, v12, v0
	v_mov_b32_e32 v21, v7
	v_lshl_add_u64 v[24:25], s[18:19], 0, v[20:21]
	v_lshl_add_u64 v[20:21], s[20:21], 0, v[20:21]
	global_load_dword v27, v[24:25], off
	v_or_b32_e32 v16, 0x5000, v6
	global_load_dword v21, v[20:21], off
	v_or_b32_e32 v24, v14, v0
	v_mov_b32_e32 v25, v7
	v_lshl_add_u64 v[28:29], s[18:19], 0, v[24:25]
	v_lshl_add_u64 v[24:25], s[20:21], 0, v[24:25]
	global_load_dword v31, v[28:29], off
	v_or_b32_e32 v20, 0x7000, v6
	global_load_dword v25, v[24:25], off
	v_or_b32_e32 v28, v16, v0
	v_mov_b32_e32 v29, v7
	v_lshl_add_u64 v[32:33], s[18:19], 0, v[28:29]
	v_lshl_add_u64 v[28:29], s[20:21], 0, v[28:29]
	s_waitcnt vmcnt(0)
	global_load_dword v35, v[32:33], off
	v_or_b32_e32 v24, 0x9000, v6
	global_load_dword v29, v[28:29], off
	v_or_b32_e32 v32, v18, v0
	v_mov_b32_e32 v33, v7
	v_lshl_add_u64 v[36:37], s[18:19], 0, v[32:33]
	v_lshl_add_u64 v[32:33], s[20:21], 0, v[32:33]
	global_load_dword v39, v[36:37], off
	v_or_b32_e32 v26, 0xa000, v6
	global_load_dword v33, v[32:33], off
	v_or_b32_e32 v36, v20, v0
	v_mov_b32_e32 v37, v7
	v_lshl_add_u64 v[40:41], s[18:19], 0, v[36:37]
	v_lshl_add_u64 v[36:37], s[20:21], 0, v[36:37]
	global_load_dword v43, v[40:41], off
	v_or_b32_e32 v28, 0xb000, v6
	global_load_dword v37, v[36:37], off
	v_or_b32_e32 v40, v22, v0
	v_mov_b32_e32 v41, v7
	v_lshl_add_u64 v[44:45], s[18:19], 0, v[40:41]
	v_lshl_add_u64 v[40:41], s[20:21], 0, v[40:41]
	global_load_dword v47, v[44:45], off
	v_or_b32_e32 v30, 0xc000, v6
	global_load_dword v41, v[40:41], off
	v_or_b32_e32 v44, v24, v0
	v_mov_b32_e32 v45, v7
	v_lshl_add_u64 v[48:49], s[18:19], 0, v[44:45]
	v_lshl_add_u64 v[44:45], s[20:21], 0, v[44:45]
	global_load_dword v51, v[48:49], off
	v_or_b32_e32 v32, 0xd000, v6
	global_load_dword v45, v[44:45], off
	v_or_b32_e32 v48, v26, v0
	v_mov_b32_e32 v49, v7
	v_lshl_add_u64 v[52:53], s[18:19], 0, v[48:49]
	v_lshl_add_u64 v[48:49], s[20:21], 0, v[48:49]
	global_load_dword v55, v[52:53], off
	v_or_b32_e32 v34, 0xe000, v6
	global_load_dword v49, v[48:49], off
	v_or_b32_e32 v52, v28, v0
	v_mov_b32_e32 v53, v7
	v_lshl_add_u64 v[56:57], s[18:19], 0, v[52:53]
	v_lshl_add_u64 v[52:53], s[20:21], 0, v[52:53]
	global_load_dword v59, v[56:57], off
	v_or_b32_e32 v36, 0xf000, v6
	global_load_dword v53, v[52:53], off
	v_or_b32_e32 v56, v30, v0
	v_mov_b32_e32 v57, v7
	v_lshl_add_u64 v[60:61], s[18:19], 0, v[56:57]
	v_lshl_add_u64 v[56:57], s[20:21], 0, v[56:57]
	global_load_dword v63, v[60:61], off
	v_or_b32_e32 v38, 0x10000, v6
	global_load_dword v57, v[56:57], off
	v_or_b32_e32 v60, v32, v0
	v_mov_b32_e32 v61, v7
	v_lshl_add_u64 v[64:65], s[18:19], 0, v[60:61]
	v_lshl_add_u64 v[60:61], s[20:21], 0, v[60:61]
	global_load_dword v67, v[64:65], off
	v_or_b32_e32 v40, 0x11000, v6
	global_load_dword v61, v[60:61], off
	v_or_b32_e32 v64, v34, v0
	v_mov_b32_e32 v65, v7
	v_lshl_add_u64 v[68:69], s[18:19], 0, v[64:65]
	v_lshl_add_u64 v[64:65], s[20:21], 0, v[64:65]
	global_load_dword v71, v[68:69], off
	v_or_b32_e32 v42, 0x12000, v6
	global_load_dword v65, v[64:65], off
	v_or_b32_e32 v68, v36, v0
	v_mov_b32_e32 v69, v7
	v_lshl_add_u64 v[72:73], s[18:19], 0, v[68:69]
	v_lshl_add_u64 v[68:69], s[20:21], 0, v[68:69]
	global_load_dword v75, v[72:73], off
	v_or_b32_e32 v44, 0x13000, v6
	global_load_dword v69, v[68:69], off
	v_or_b32_e32 v72, v38, v0
	v_mov_b32_e32 v73, v7
	v_lshl_add_u64 v[76:77], s[18:19], 0, v[72:73]
	v_lshl_add_u64 v[72:73], s[20:21], 0, v[72:73]
	global_load_dword v79, v[76:77], off
	v_or_b32_e32 v46, 0x14000, v6
	global_load_dword v73, v[72:73], off
	v_or_b32_e32 v76, v40, v0
	v_mov_b32_e32 v77, v7
	v_lshl_add_u64 v[80:81], s[18:19], 0, v[76:77]
	v_lshl_add_u64 v[76:77], s[20:21], 0, v[76:77]
	global_load_dword v83, v[80:81], off
	v_or_b32_e32 v48, 0x15000, v6
	global_load_dword v77, v[76:77], off
	v_or_b32_e32 v80, v42, v0
	v_mov_b32_e32 v81, v7
	v_lshl_add_u64 v[84:85], s[18:19], 0, v[80:81]
	v_lshl_add_u64 v[80:81], s[20:21], 0, v[80:81]
	global_load_dword v87, v[84:85], off
	v_or_b32_e32 v50, 0x16000, v6
	global_load_dword v81, v[80:81], off
	v_or_b32_e32 v84, v44, v0
	v_mov_b32_e32 v85, v7
	v_lshl_add_u64 v[88:89], s[18:19], 0, v[84:85]
	v_lshl_add_u64 v[84:85], s[20:21], 0, v[84:85]
	global_load_dword v91, v[88:89], off
	v_or_b32_e32 v52, 0x17000, v6
	global_load_dword v85, v[84:85], off
	v_or_b32_e32 v88, v46, v0
	v_mov_b32_e32 v89, v7
	v_lshl_add_u64 v[92:93], s[18:19], 0, v[88:89]
	v_lshl_add_u64 v[88:89], s[20:21], 0, v[88:89]
	global_load_dword v95, v[92:93], off
	v_or_b32_e32 v54, 0x18000, v6
	global_load_dword v89, v[88:89], off
	v_or_b32_e32 v92, v48, v0
	v_mov_b32_e32 v93, v7
	v_lshl_add_u64 v[96:97], s[18:19], 0, v[92:93]
	v_lshl_add_u64 v[92:93], s[20:21], 0, v[92:93]
; DEVI void rnn_carry_phase(const float* aggA, const float* aggH, float* carry, int wv) {
;     ...
;     if (g < 2048) { const int b = g >> 10, ch = g & 1023; float H = 0.f;
;         for (int c0 = 0; c0 < 128; c0 += 64) { float A[64], Hh[64];
; #pragma unroll
;             for (int i = 0; i < 64; ++i) { const size_t o = ((size_t)b * 128 + c0 + i) * 1024 + ch; A[i] = aggA[o]; Hh[i] = aggH[o]; }
	global_load_dword v99, v[96:97], off
	v_or_b32_e32 v56, 0x19000, v6
	global_load_dword v93, v[92:93], off
	v_or_b32_e32 v96, v50, v0
	v_mov_b32_e32 v97, v7
	v_lshl_add_u64 v[100:101], s[18:19], 0, v[96:97]
	v_lshl_add_u64 v[96:97], s[20:21], 0, v[96:97]
	global_load_dword v103, v[100:101], off
	v_or_b32_e32 v58, 0x1a000, v6
	global_load_dword v97, v[96:97], off
	v_or_b32_e32 v100, v52, v0
	v_mov_b32_e32 v101, v7
	v_lshl_add_u64 v[104:105], s[18:19], 0, v[100:101]
	v_lshl_add_u64 v[100:101], s[20:21], 0, v[100:101]
	global_load_dword v107, v[104:105], off
	v_or_b32_e32 v60, 0x1b000, v6
	global_load_dword v101, v[100:101], off
	v_or_b32_e32 v104, v54, v0
	v_mov_b32_e32 v105, v7
	v_lshl_add_u64 v[108:109], s[18:19], 0, v[104:105]
	v_lshl_add_u64 v[104:105], s[20:21], 0, v[104:105]
	global_load_dword v111, v[108:109], off
	v_or_b32_e32 v62, 0x1c000, v6
	global_load_dword v105, v[104:105], off
	v_or_b32_e32 v108, v56, v0
	v_mov_b32_e32 v109, v7
	v_lshl_add_u64 v[112:113], s[18:19], 0, v[108:109]
	v_lshl_add_u64 v[108:109], s[20:21], 0, v[108:109]
	global_load_dword v115, v[112:113], off
	v_or_b32_e32 v64, 0x1d000, v6
	global_load_dword v109, v[108:109], off
	v_or_b32_e32 v112, v58, v0
	v_mov_b32_e32 v113, v7
	v_lshl_add_u64 v[116:117], s[18:19], 0, v[112:113]
	v_lshl_add_u64 v[112:113], s[20:21], 0, v[112:113]
	global_load_dword v119, v[116:117], off
	v_or_b32_e32 v66, 0x1e000, v6
	global_load_dword v113, v[112:113], off
	v_or_b32_e32 v116, v60, v0
	v_mov_b32_e32 v117, v7
	v_lshl_add_u64 v[120:121], s[18:19], 0, v[116:117]
	v_lshl_add_u64 v[116:117], s[20:21], 0, v[116:117]
	global_load_dword v123, v[120:121], off
	v_or_b32_e32 v68, 0x1f000, v6
	global_load_dword v117, v[116:117], off
	v_or_b32_e32 v120, v62, v0
	v_mov_b32_e32 v121, v7
	v_lshl_add_u64 v[124:125], s[18:19], 0, v[120:121]
	v_lshl_add_u64 v[120:121], s[20:21], 0, v[120:121]
	global_load_dword v127, v[124:125], off
	v_or_b32_e32 v70, 0x20000, v6
	global_load_dword v121, v[120:121], off
	v_or_b32_e32 v124, v64, v0
	v_mov_b32_e32 v125, v7
	v_lshl_add_u64 v[128:129], s[18:19], 0, v[124:125]
	v_lshl_add_u64 v[124:125], s[20:21], 0, v[124:125]
	global_load_dword v133, v[128:129], off
	v_or_b32_e32 v72, 0x21000, v6
	global_load_dword v125, v[124:125], off
	v_or_b32_e32 v128, v66, v0
	v_mov_b32_e32 v129, v7
	v_lshl_add_u64 v[130:131], s[18:19], 0, v[128:129]
	v_lshl_add_u64 v[128:129], s[20:21], 0, v[128:129]
	global_load_dword v135, v[130:131], off
	v_or_b32_e32 v74, 0x22000, v6
	global_load_dword v131, v[128:129], off
	v_or_b32_e32 v128, v68, v0
	v_mov_b32_e32 v129, v7
	v_lshl_add_u64 v[136:137], s[18:19], 0, v[128:129]
	v_lshl_add_u64 v[128:129], s[20:21], 0, v[128:129]
	global_load_dword v137, v[136:137], off
	v_or_b32_e32 v76, 0x23000, v6
	global_load_dword v134, v[128:129], off
	v_or_b32_e32 v128, v70, v0
	v_mov_b32_e32 v129, v7
	v_lshl_add_u64 v[138:139], s[18:19], 0, v[128:129]
	v_lshl_add_u64 v[128:129], s[20:21], 0, v[128:129]
	global_load_dword v139, v[138:139], off
	v_or_b32_e32 v78, 0x24000, v6
	global_load_dword v136, v[128:129], off
	v_or_b32_e32 v128, v72, v0
	v_mov_b32_e32 v129, v7
	v_lshl_add_u64 v[140:141], s[18:19], 0, v[128:129]
	v_lshl_add_u64 v[128:129], s[20:21], 0, v[128:129]
	global_load_dword v141, v[140:141], off
	v_or_b32_e32 v80, 0x25000, v6
	global_load_dword v138, v[128:129], off
	v_or_b32_e32 v128, v74, v0
	v_mov_b32_e32 v129, v7
	v_lshl_add_u64 v[142:143], s[18:19], 0, v[128:129]
	v_lshl_add_u64 v[128:129], s[20:21], 0, v[128:129]
	global_load_dword v143, v[142:143], off
	v_or_b32_e32 v82, 0x26000, v6
	global_load_dword v140, v[128:129], off
	v_or_b32_e32 v128, v76, v0
	v_mov_b32_e32 v129, v7
	v_lshl_add_u64 v[144:145], s[18:19], 0, v[128:129]
	v_lshl_add_u64 v[128:129], s[20:21], 0, v[128:129]
	global_load_dword v145, v[144:145], off
	v_or_b32_e32 v84, 0x27000, v6
	global_load_dword v142, v[128:129], off
	v_or_b32_e32 v128, v78, v0
	v_mov_b32_e32 v129, v7
	v_lshl_add_u64 v[146:147], s[18:19], 0, v[128:129]
	v_lshl_add_u64 v[128:129], s[20:21], 0, v[128:129]
	global_load_dword v147, v[146:147], off
	v_or_b32_e32 v86, 0x28000, v6
	global_load_dword v144, v[128:129], off
	v_or_b32_e32 v128, v80, v0
	v_mov_b32_e32 v129, v7
	v_lshl_add_u64 v[148:149], s[18:19], 0, v[128:129]
	v_lshl_add_u64 v[128:129], s[20:21], 0, v[128:129]
	global_load_dword v149, v[148:149], off
	v_or_b32_e32 v88, 0x29000, v6
	global_load_dword v146, v[128:129], off
	v_or_b32_e32 v128, v82, v0
	v_mov_b32_e32 v129, v7
	v_lshl_add_u64 v[150:151], s[18:19], 0, v[128:129]
	v_lshl_add_u64 v[128:129], s[20:21], 0, v[128:129]
	global_load_dword v151, v[150:151], off
	v_or_b32_e32 v90, 0x2a000, v6
	global_load_dword v148, v[128:129], off
	v_or_b32_e32 v128, v84, v0
	v_mov_b32_e32 v129, v7
	v_lshl_add_u64 v[152:153], s[18:19], 0, v[128:129]
	v_lshl_add_u64 v[128:129], s[20:21], 0, v[128:129]
	global_load_dword v153, v[152:153], off
	v_or_b32_e32 v92, 0x2b000, v6
	global_load_dword v150, v[128:129], off
	v_or_b32_e32 v128, v86, v0
	v_mov_b32_e32 v129, v7
	v_lshl_add_u64 v[154:155], s[18:19], 0, v[128:129]
	v_lshl_add_u64 v[128:129], s[20:21], 0, v[128:129]
	global_load_dword v155, v[154:155], off
	v_or_b32_e32 v94, 0x2c000, v6
	global_load_dword v152, v[128:129], off
	v_or_b32_e32 v128, v88, v0
	v_mov_b32_e32 v129, v7
	v_lshl_add_u64 v[156:157], s[18:19], 0, v[128:129]
	v_lshl_add_u64 v[128:129], s[20:21], 0, v[128:129]
	global_load_dword v157, v[156:157], off
	v_or_b32_e32 v96, 0x2d000, v6
	global_load_dword v154, v[128:129], off
	v_or_b32_e32 v128, v90, v0
	v_mov_b32_e32 v129, v7
	v_lshl_add_u64 v[158:159], s[18:19], 0, v[128:129]
	v_lshl_add_u64 v[128:129], s[20:21], 0, v[128:129]
; DEVI void rnn_carry_phase(const float* aggA, const float* aggH, float* carry, int wv) {
;     ...
;     if (g < 2048) { const int b = g >> 10, ch = g & 1023; float H = 0.f;
;         for (int c0 = 0; c0 < 128; c0 += 64) { float A[64], Hh[64];
; #pragma unroll
;             for (int i = 0; i < 64; ++i) { const size_t o = ((size_t)b * 128 + c0 + i) * 1024 + ch; A[i] = aggA[o]; Hh[i] = aggH[o]; }
	global_load_dword v159, v[158:159], off
	v_or_b32_e32 v98, 0x2e000, v6
	global_load_dword v156, v[128:129], off
	v_or_b32_e32 v128, v92, v0
	v_mov_b32_e32 v129, v7
	v_lshl_add_u64 v[160:161], s[18:19], 0, v[128:129]
	v_lshl_add_u64 v[128:129], s[20:21], 0, v[128:129]
	global_load_dword v161, v[160:161], off
	v_or_b32_e32 v100, 0x2f000, v6
	global_load_dword v158, v[128:129], off
	v_or_b32_e32 v128, v94, v0
	v_mov_b32_e32 v129, v7
	v_lshl_add_u64 v[162:163], s[18:19], 0, v[128:129]
	v_lshl_add_u64 v[128:129], s[20:21], 0, v[128:129]
	global_load_dword v163, v[162:163], off
	v_or_b32_e32 v102, 0x30000, v6
	global_load_dword v160, v[128:129], off
	v_or_b32_e32 v128, v96, v0
	v_mov_b32_e32 v129, v7
	v_lshl_add_u64 v[164:165], s[18:19], 0, v[128:129]
	v_lshl_add_u64 v[128:129], s[20:21], 0, v[128:129]
	global_load_dword v165, v[164:165], off
	v_or_b32_e32 v104, 0x31000, v6
	global_load_dword v162, v[128:129], off
	v_or_b32_e32 v128, v98, v0
	v_mov_b32_e32 v129, v7
	v_lshl_add_u64 v[166:167], s[18:19], 0, v[128:129]
	v_lshl_add_u64 v[128:129], s[20:21], 0, v[128:129]
	global_load_dword v167, v[166:167], off
	v_or_b32_e32 v106, 0x32000, v6
	global_load_dword v164, v[128:129], off
	v_or_b32_e32 v128, v100, v0
	v_mov_b32_e32 v129, v7
	v_lshl_add_u64 v[168:169], s[18:19], 0, v[128:129]
	v_lshl_add_u64 v[128:129], s[20:21], 0, v[128:129]
	global_load_dword v169, v[168:169], off
	v_or_b32_e32 v108, 0x33000, v6
	global_load_dword v166, v[128:129], off
	v_or_b32_e32 v128, v102, v0
	v_mov_b32_e32 v129, v7
	v_lshl_add_u64 v[170:171], s[18:19], 0, v[128:129]
	v_lshl_add_u64 v[128:129], s[20:21], 0, v[128:129]
	global_load_dword v171, v[170:171], off
	v_or_b32_e32 v110, 0x34000, v6
	global_load_dword v168, v[128:129], off
	v_or_b32_e32 v128, v104, v0
	v_mov_b32_e32 v129, v7
	v_lshl_add_u64 v[172:173], s[18:19], 0, v[128:129]
	v_lshl_add_u64 v[128:129], s[20:21], 0, v[128:129]
	global_load_dword v173, v[172:173], off
	v_or_b32_e32 v112, 0x35000, v6
	global_load_dword v170, v[128:129], off
	v_or_b32_e32 v128, v106, v0
	v_mov_b32_e32 v129, v7
	v_lshl_add_u64 v[174:175], s[18:19], 0, v[128:129]
	v_lshl_add_u64 v[128:129], s[20:21], 0, v[128:129]
	global_load_dword v175, v[174:175], off
	v_or_b32_e32 v114, 0x36000, v6
	global_load_dword v172, v[128:129], off
	v_or_b32_e32 v128, v108, v0
	v_mov_b32_e32 v129, v7
	v_lshl_add_u64 v[176:177], s[18:19], 0, v[128:129]
	v_lshl_add_u64 v[128:129], s[20:21], 0, v[128:129]
	global_load_dword v177, v[176:177], off
	v_or_b32_e32 v116, 0x37000, v6
	global_load_dword v174, v[128:129], off
	v_or_b32_e32 v128, v110, v0
	v_mov_b32_e32 v129, v7
	v_lshl_add_u64 v[178:179], s[18:19], 0, v[128:129]
	v_lshl_add_u64 v[128:129], s[20:21], 0, v[128:129]
	global_load_dword v179, v[178:179], off
	v_or_b32_e32 v118, 0x38000, v6
	global_load_dword v176, v[128:129], off
	v_or_b32_e32 v128, v112, v0
	v_mov_b32_e32 v129, v7
	v_lshl_add_u64 v[180:181], s[18:19], 0, v[128:129]
	v_lshl_add_u64 v[128:129], s[20:21], 0, v[128:129]
	global_load_dword v181, v[180:181], off
	v_or_b32_e32 v120, 0x39000, v6
	global_load_dword v178, v[128:129], off
	v_or_b32_e32 v128, v114, v0
	v_mov_b32_e32 v129, v7
	v_lshl_add_u64 v[182:183], s[18:19], 0, v[128:129]
	v_lshl_add_u64 v[128:129], s[20:21], 0, v[128:129]
	global_load_dword v183, v[182:183], off
	v_or_b32_e32 v122, 0x3a000, v6
	global_load_dword v180, v[128:129], off
	v_or_b32_e32 v128, v116, v0
	v_mov_b32_e32 v129, v7
	v_lshl_add_u64 v[184:185], s[18:19], 0, v[128:129]
	v_lshl_add_u64 v[128:129], s[20:21], 0, v[128:129]
	global_load_dword v185, v[184:185], off
	v_or_b32_e32 v124, 0x3b000, v6
	global_load_dword v182, v[128:129], off
	v_or_b32_e32 v128, v118, v0
	v_mov_b32_e32 v129, v7
	v_lshl_add_u64 v[186:187], s[18:19], 0, v[128:129]
	v_lshl_add_u64 v[128:129], s[20:21], 0, v[128:129]
	global_load_dword v187, v[186:187], off
	v_or_b32_e32 v126, 0x3c000, v6
	global_load_dword v184, v[128:129], off
	v_or_b32_e32 v128, v120, v0
	v_mov_b32_e32 v129, v7
	v_lshl_add_u64 v[188:189], s[18:19], 0, v[128:129]
	v_lshl_add_u64 v[128:129], s[20:21], 0, v[128:129]
	global_load_dword v189, v[188:189], off
	v_or_b32_e32 v132, 0x3d000, v6
	global_load_dword v186, v[128:129], off
	v_or_b32_e32 v128, v122, v0
	v_mov_b32_e32 v129, v7
	v_lshl_add_u64 v[190:191], s[18:19], 0, v[128:129]
	v_lshl_add_u64 v[128:129], s[20:21], 0, v[128:129]
	global_load_dword v190, v[190:191], off
	v_or_b32_e32 v130, 0x3e000, v6
	global_load_dword v188, v[128:129], off
	v_or_b32_e32 v128, v124, v0
	v_mov_b32_e32 v129, v7
	v_lshl_add_u64 v[192:193], s[18:19], 0, v[128:129]
	v_lshl_add_u64 v[128:129], s[20:21], 0, v[128:129]
	global_load_dword v192, v[192:193], off
	s_waitcnt vmcnt(0) lgkmcnt(0)
; DEVI void rnn_carry_phase(const float* aggA, const float* aggH, float* carry, int wv) {
;     ...
;         for (int c0 = 0; c0 < 128; c0 += 64) { float A[64], Hh[64];
; #pragma unroll
;             for (int i = 0; i < 64; ++i) { const size_t o = ((size_t)b * 128 + c0 + i) * 1024 + ch; A[i] = aggA[o]; Hh[i] = aggH[o]; }
; #pragma unroll
;             for (int i = 0; i < 64; ++i) { carry[((size_t)b * 128 + c0 + i) * 1024 + ch] = H; H = A[i] * H + Hh[i]; } } }
	v_fmac_f32_e32 v11, v9, v15
	global_load_dword v191, v[128:129], off
	v_or_b32_e32 v128, v126, v0
	v_mov_b32_e32 v129, v7
	v_lshl_add_u64 v[194:195], s[18:19], 0, v[128:129]
	v_lshl_add_u64 v[128:129], s[20:21], 0, v[128:129]
	global_load_dword v200, v[194:195], off
	v_fmac_f32_e32 v13, v11, v19
	global_load_dword v195, v[128:129], off
	v_or_b32_e32 v128, v132, v0
	v_mov_b32_e32 v129, v7
	v_lshl_add_u64 v[196:197], s[18:19], 0, v[128:129]
	v_lshl_add_u64 v[128:129], s[20:21], 0, v[128:129]
	global_load_dword v203, v[196:197], off
	v_fmac_f32_e32 v17, v13, v23
	global_load_dword v129, v[128:129], off
	v_or_b32_e32 v196, v130, v0
	v_mov_b32_e32 v197, v7
	v_lshl_add_u64 v[198:199], s[18:19], 0, v[196:197]
	v_lshl_add_u64 v[196:197], s[20:21], 0, v[196:197]
	v_or_b32_e32 v128, 0x3f000, v6
	global_load_dword v202, v[198:199], off
	global_load_dword v194, v[196:197], off
	v_or_b32_e32 v196, v128, v0
	v_mov_b32_e32 v197, v7
	v_lshl_add_u64 v[198:199], s[18:19], 0, v[196:197]
	v_lshl_add_u64 v[196:197], s[20:21], 0, v[196:197]
	global_load_dword v201, v[198:199], off
	global_load_dword v193, v[196:197], off
	v_lshl_add_u64 v[196:197], v[4:5], 0, v[6:7]
	global_store_dword v[196:197], v9, off
	v_mov_b32_e32 v9, v7
	v_lshl_add_u64 v[8:9], v[4:5], 0, v[8:9]
	global_store_dword v[8:9], v11, off
	v_mov_b32_e32 v11, v7
	v_lshl_add_u64 v[8:9], v[4:5], 0, v[10:11]
	global_store_dword v[8:9], v13, off
	v_mov_b32_e32 v13, v7
	v_lshl_add_u64 v[8:9], v[4:5], 0, v[12:13]
	v_fmac_f32_e32 v21, v17, v27
	v_mov_b32_e32 v15, v7
	global_store_dword v[8:9], v17, off
	v_lshl_add_u64 v[8:9], v[4:5], 0, v[14:15]
	v_fmac_f32_e32 v25, v21, v31
	v_mov_b32_e32 v17, v7
	global_store_dword v[8:9], v21, off
	v_lshl_add_u64 v[8:9], v[4:5], 0, v[16:17]
	v_fmac_f32_e32 v29, v25, v35
	v_mov_b32_e32 v19, v7
	global_store_dword v[8:9], v25, off
	v_lshl_add_u64 v[8:9], v[4:5], 0, v[18:19]
	v_fmac_f32_e32 v33, v29, v39
	v_mov_b32_e32 v21, v7
	global_store_dword v[8:9], v29, off
	v_lshl_add_u64 v[8:9], v[4:5], 0, v[20:21]
	v_fmac_f32_e32 v37, v33, v43
	v_mov_b32_e32 v23, v7
	global_store_dword v[8:9], v33, off
	v_lshl_add_u64 v[8:9], v[4:5], 0, v[22:23]
	v_fmac_f32_e32 v41, v37, v47
	v_mov_b32_e32 v25, v7
	global_store_dword v[8:9], v37, off
	v_lshl_add_u64 v[8:9], v[4:5], 0, v[24:25]
	v_fmac_f32_e32 v45, v41, v51
	v_mov_b32_e32 v27, v7
	global_store_dword v[8:9], v41, off
	v_lshl_add_u64 v[8:9], v[4:5], 0, v[26:27]
	v_fmac_f32_e32 v49, v45, v55
	v_mov_b32_e32 v29, v7
	global_store_dword v[8:9], v45, off
	v_lshl_add_u64 v[8:9], v[4:5], 0, v[28:29]
	v_fmac_f32_e32 v53, v49, v59
	v_mov_b32_e32 v31, v7
	global_store_dword v[8:9], v49, off
	v_lshl_add_u64 v[8:9], v[4:5], 0, v[30:31]
	v_fmac_f32_e32 v57, v53, v63
	v_mov_b32_e32 v33, v7
	global_store_dword v[8:9], v53, off
	v_lshl_add_u64 v[8:9], v[4:5], 0, v[32:33]
	v_fmac_f32_e32 v61, v57, v67
	v_mov_b32_e32 v35, v7
	global_store_dword v[8:9], v57, off
	v_lshl_add_u64 v[8:9], v[4:5], 0, v[34:35]
	v_fmac_f32_e32 v65, v61, v71
	v_mov_b32_e32 v37, v7
	global_store_dword v[8:9], v61, off
	v_lshl_add_u64 v[8:9], v[4:5], 0, v[36:37]
	v_fmac_f32_e32 v69, v65, v75
	v_mov_b32_e32 v39, v7
	global_store_dword v[8:9], v65, off
	v_lshl_add_u64 v[8:9], v[4:5], 0, v[38:39]
	v_fmac_f32_e32 v73, v69, v79
	v_mov_b32_e32 v41, v7
	global_store_dword v[8:9], v69, off
	v_lshl_add_u64 v[8:9], v[4:5], 0, v[40:41]
	v_fmac_f32_e32 v77, v73, v83
	v_mov_b32_e32 v43, v7
	global_store_dword v[8:9], v73, off
	v_lshl_add_u64 v[8:9], v[4:5], 0, v[42:43]
	v_fmac_f32_e32 v81, v77, v87
	v_mov_b32_e32 v45, v7
	global_store_dword v[8:9], v77, off
	v_lshl_add_u64 v[8:9], v[4:5], 0, v[44:45]
	v_fmac_f32_e32 v85, v81, v91
	v_mov_b32_e32 v47, v7
	global_store_dword v[8:9], v81, off
	v_lshl_add_u64 v[8:9], v[4:5], 0, v[46:47]
	v_fmac_f32_e32 v89, v85, v95
	v_mov_b32_e32 v49, v7
	global_store_dword v[8:9], v85, off
	v_lshl_add_u64 v[8:9], v[4:5], 0, v[48:49]
	v_fmac_f32_e32 v93, v89, v99
	v_mov_b32_e32 v51, v7
	global_store_dword v[8:9], v89, off
	v_lshl_add_u64 v[8:9], v[4:5], 0, v[50:51]
	v_fmac_f32_e32 v97, v93, v103
	v_mov_b32_e32 v53, v7
	global_store_dword v[8:9], v93, off
	v_lshl_add_u64 v[8:9], v[4:5], 0, v[52:53]
	v_fmac_f32_e32 v101, v97, v107
	v_mov_b32_e32 v55, v7
	global_store_dword v[8:9], v97, off
	v_lshl_add_u64 v[8:9], v[4:5], 0, v[54:55]
	v_fmac_f32_e32 v105, v101, v111
	v_mov_b32_e32 v57, v7
	global_store_dword v[8:9], v101, off
	v_lshl_add_u64 v[8:9], v[4:5], 0, v[56:57]
	v_fmac_f32_e32 v109, v105, v115
	v_mov_b32_e32 v59, v7
	global_store_dword v[8:9], v105, off
	v_lshl_add_u64 v[8:9], v[4:5], 0, v[58:59]
	v_fmac_f32_e32 v113, v109, v119
	v_mov_b32_e32 v61, v7
	global_store_dword v[8:9], v109, off
	v_lshl_add_u64 v[8:9], v[4:5], 0, v[60:61]
	v_fmac_f32_e32 v117, v113, v123
	v_mov_b32_e32 v63, v7
	global_store_dword v[8:9], v113, off
	v_lshl_add_u64 v[8:9], v[4:5], 0, v[62:63]
	v_fmac_f32_e32 v121, v117, v127
	v_mov_b32_e32 v65, v7
	global_store_dword v[8:9], v117, off
	v_lshl_add_u64 v[8:9], v[4:5], 0, v[64:65]
; DEVI void rnn_carry_phase(const float* aggA, const float* aggH, float* carry, int wv) {
;     ...
;         for (int c0 = 0; c0 < 128; c0 += 64) { float A[64], Hh[64];
; #pragma unroll
;             for (int i = 0; i < 64; ++i) { const size_t o = ((size_t)b * 128 + c0 + i) * 1024 + ch; A[i] = aggA[o]; Hh[i] = aggH[o]; }
; #pragma unroll
;             for (int i = 0; i < 64; ++i) { carry[((size_t)b * 128 + c0 + i) * 1024 + ch] = H; H = A[i] * H + Hh[i]; } } }
	v_fmac_f32_e32 v125, v121, v133
	v_mov_b32_e32 v67, v7
	global_store_dword v[8:9], v121, off
	v_lshl_add_u64 v[8:9], v[4:5], 0, v[66:67]
	v_fmac_f32_e32 v131, v125, v135
	v_mov_b32_e32 v69, v7
	global_store_dword v[8:9], v125, off
	v_lshl_add_u64 v[8:9], v[4:5], 0, v[68:69]
	v_fmac_f32_e32 v134, v131, v137
	v_mov_b32_e32 v71, v7
	global_store_dword v[8:9], v131, off
	v_lshl_add_u64 v[8:9], v[4:5], 0, v[70:71]
	v_fmac_f32_e32 v136, v134, v139
	v_mov_b32_e32 v73, v7
	global_store_dword v[8:9], v134, off
	v_lshl_add_u64 v[8:9], v[4:5], 0, v[72:73]
	v_fmac_f32_e32 v138, v136, v141
	v_mov_b32_e32 v75, v7
	global_store_dword v[8:9], v136, off
	v_lshl_add_u64 v[8:9], v[4:5], 0, v[74:75]
	v_fmac_f32_e32 v140, v138, v143
	v_mov_b32_e32 v77, v7
	global_store_dword v[8:9], v138, off
	v_lshl_add_u64 v[8:9], v[4:5], 0, v[76:77]
	v_fmac_f32_e32 v142, v140, v145
	v_mov_b32_e32 v79, v7
	global_store_dword v[8:9], v140, off
	v_lshl_add_u64 v[8:9], v[4:5], 0, v[78:79]
	v_fmac_f32_e32 v144, v142, v147
	v_mov_b32_e32 v81, v7
	global_store_dword v[8:9], v142, off
	v_lshl_add_u64 v[8:9], v[4:5], 0, v[80:81]
	v_fmac_f32_e32 v146, v144, v149
	v_mov_b32_e32 v83, v7
	global_store_dword v[8:9], v144, off
	v_lshl_add_u64 v[8:9], v[4:5], 0, v[82:83]
	v_fmac_f32_e32 v148, v146, v151
	v_mov_b32_e32 v85, v7
	global_store_dword v[8:9], v146, off
	v_lshl_add_u64 v[8:9], v[4:5], 0, v[84:85]
	v_fmac_f32_e32 v150, v148, v153
	v_mov_b32_e32 v87, v7
	global_store_dword v[8:9], v148, off
	v_lshl_add_u64 v[8:9], v[4:5], 0, v[86:87]
	v_fmac_f32_e32 v152, v150, v155
	v_mov_b32_e32 v89, v7
	global_store_dword v[8:9], v150, off
	v_lshl_add_u64 v[8:9], v[4:5], 0, v[88:89]
	v_fmac_f32_e32 v154, v152, v157
	v_mov_b32_e32 v91, v7
	global_store_dword v[8:9], v152, off
	v_lshl_add_u64 v[8:9], v[4:5], 0, v[90:91]
	v_fmac_f32_e32 v156, v154, v159
	v_mov_b32_e32 v93, v7
	global_store_dword v[8:9], v154, off
	v_lshl_add_u64 v[8:9], v[4:5], 0, v[92:93]
	v_fmac_f32_e32 v158, v156, v161
	v_mov_b32_e32 v95, v7
	global_store_dword v[8:9], v156, off
	v_lshl_add_u64 v[8:9], v[4:5], 0, v[94:95]
	v_fmac_f32_e32 v160, v158, v163
	v_mov_b32_e32 v97, v7
	global_store_dword v[8:9], v158, off
	v_lshl_add_u64 v[8:9], v[4:5], 0, v[96:97]
	v_fmac_f32_e32 v162, v160, v165
	v_mov_b32_e32 v99, v7
	global_store_dword v[8:9], v160, off
	v_lshl_add_u64 v[8:9], v[4:5], 0, v[98:99]
	v_fmac_f32_e32 v164, v162, v167
	v_mov_b32_e32 v101, v7
	global_store_dword v[8:9], v162, off
	v_lshl_add_u64 v[8:9], v[4:5], 0, v[100:101]
	v_fmac_f32_e32 v166, v164, v169
	v_mov_b32_e32 v103, v7
	global_store_dword v[8:9], v164, off
	v_lshl_add_u64 v[8:9], v[4:5], 0, v[102:103]
	v_fmac_f32_e32 v168, v166, v171
	v_mov_b32_e32 v105, v7
	global_store_dword v[8:9], v166, off
	v_lshl_add_u64 v[8:9], v[4:5], 0, v[104:105]
	v_fmac_f32_e32 v170, v168, v173
	v_mov_b32_e32 v107, v7
	global_store_dword v[8:9], v168, off
	v_lshl_add_u64 v[8:9], v[4:5], 0, v[106:107]
	v_fmac_f32_e32 v172, v170, v175
	v_mov_b32_e32 v109, v7
	global_store_dword v[8:9], v170, off
	v_lshl_add_u64 v[8:9], v[4:5], 0, v[108:109]
	v_fmac_f32_e32 v174, v172, v177
	v_mov_b32_e32 v111, v7
	global_store_dword v[8:9], v172, off
	v_lshl_add_u64 v[8:9], v[4:5], 0, v[110:111]
	v_fmac_f32_e32 v176, v174, v179
	v_mov_b32_e32 v113, v7
	global_store_dword v[8:9], v174, off
	v_lshl_add_u64 v[8:9], v[4:5], 0, v[112:113]
	v_fmac_f32_e32 v178, v176, v181
	v_mov_b32_e32 v115, v7
	global_store_dword v[8:9], v176, off
	v_lshl_add_u64 v[8:9], v[4:5], 0, v[114:115]
	v_fmac_f32_e32 v180, v178, v183
	v_mov_b32_e32 v117, v7
	global_store_dword v[8:9], v178, off
	v_lshl_add_u64 v[8:9], v[4:5], 0, v[116:117]
	v_fmac_f32_e32 v182, v180, v185
	v_mov_b32_e32 v119, v7
	global_store_dword v[8:9], v180, off
	v_lshl_add_u64 v[8:9], v[4:5], 0, v[118:119]
	v_fmac_f32_e32 v184, v182, v187
	v_mov_b32_e32 v121, v7
	global_store_dword v[8:9], v182, off
	v_lshl_add_u64 v[8:9], v[4:5], 0, v[120:121]
	v_fmac_f32_e32 v186, v184, v189
	v_mov_b32_e32 v123, v7
	global_store_dword v[8:9], v184, off
	v_lshl_add_u64 v[8:9], v[4:5], 0, v[122:123]
	v_fmac_f32_e32 v188, v186, v190
	v_mov_b32_e32 v125, v7
	global_store_dword v[8:9], v186, off
	v_lshl_add_u64 v[8:9], v[4:5], 0, v[124:125]
	s_waitcnt vmcnt(0) lgkmcnt(0)
	v_fmac_f32_e32 v191, v188, v192
	v_mov_b32_e32 v127, v7
	global_store_dword v[8:9], v188, off
	v_lshl_add_u64 v[8:9], v[4:5], 0, v[126:127]
	v_fmac_f32_e32 v195, v191, v200
	v_mov_b32_e32 v133, v7
	global_store_dword v[8:9], v191, off
	v_lshl_add_u64 v[8:9], v[4:5], 0, v[132:133]
	v_fmac_f32_e32 v129, v195, v203
	v_mov_b32_e32 v131, v7
	global_store_dword v[8:9], v195, off
	v_lshl_add_u64 v[8:9], v[4:5], 0, v[130:131]
	v_fmac_f32_e32 v194, v129, v202
	global_store_dword v[8:9], v129, off
	v_mov_b32_e32 v129, v7
	v_fmac_f32_e32 v193, v194, v201
	v_lshl_add_u64 v[6:7], v[4:5], 0, v[128:129]
	s_mov_b64 s[10:11], 64
	s_and_b64 vcc, exec, s[6:7]
	v_mov_b32_e32 v9, v193
	s_mov_b64 s[6:7], 0
	global_store_dword v[6:7], v194, off
	s_cbranch_vccnz .LBB0_86

; DEVI unsigned cvtpk(float lo, float hi) { unsigned r; asm volatile("v_cvt_pk_bf16_f32 %0, %1, %2" : "=v"(r) : "v"(lo), "v"(hi)); return r; }
; DEVI int ltid(int wv) { int t = (wv << 6) | (int)__builtin_amdgcn_mbcnt_hi(~0u, __builtin_amdgcn_mbcnt_lo(~0u, 0u)); asm volatile("" : "+v"(t)); return t; }
; template <int KT, class F> DEVI void cvt_tile(F colptr, int ldsrc, int k0, bf16_t* out, int ldo, int v0, float* tile, int wv) {
;     const int tid = ltid(wv);
;     constexpr int PITCH = KT * 64 + 1;
;     { const int vc = tid & 63, kk = tid >> 6; const float* cp = colptr(v0 + vc) + (size_t)k0 * ldsrc; float v[8 * KT];
; #pragma unroll
;       for (int r = 0; r < 8 * KT; ++r) v[r] = cp[(size_t)(r * 8 + kk) * ldsrc];
; #pragma unroll
;       for (int r = 0; r < 8 * KT; ++r) tile[vc * PITCH + r * 8 + kk] = v[r]; }
;     __syncthreads();
;     { const int vc = tid >> 3, k8 = (tid & 7) * 8;
; #pragma unroll
;       for (int q = 0; q < KT; ++q) { const float* tp = tile + vc * PITCH + q * 64 + k8;
;         u32x4 w = {cvtpk(tp[0], tp[1]), cvtpk(tp[2], tp[3]), cvtpk(tp[4], tp[5]), cvtpk(tp[6], tp[7])};
;         *(u32x4*)(out + (size_t)(v0 + vc) * ldo + k0 + q * 64 + k8) = w; } }
;     __syncthreads();
; }
; DEVI void cvt_ffn_phase(const float* wg, const float* wu, const float* wd, unsigned char* ws, char* lds, int j0, int jstride, int wv) {
;     float* tile = (float*)(lds + 32768);
;     bf16_t* Wgu = (bf16_t*)(ws + FFW_GU); bf16_t* Wd = (bf16_t*)(ws + FFW_D);
;     for (int job = j0; job < 352 + 176; job += jstride) {
;         if (job < 352) { const int vt = job >> 2, kg = job & 3; cvt_tile<4>(ColGU{wg, (long)((const char*)wu - (const char*)wg)}, DFF, kg * 256, Wgu, DM, vt * 64, tile, wv); }
;         else { const int j = job - 352, vt = j / 11, kg = j % 11; cvt_tile<4>(ColLin{wd}, DM, kg * 256, Wd, DFF, vt * 64, tile, wv); }
.LBB0_92:
	s_cmpk_gt_i32 s8, 0x15f
	s_mov_b64 s[6:7], -1
	s_cbranch_scc0 .LBB0_94
	s_add_i32 s6, s8, 0xffa0
	s_and_b32 s7, s6, 0xff
	s_mulk_i32 s7, 0x75
	s_lshr_b32 s46, s7, 8
	s_sub_i32 s46, s6, s46
	s_bfe_u32 s46, s46, 0x70001
	s_bfe_u32 s7, s7, 0x80008
	s_add_i32 s46, s46, s7
	s_bfe_u32 s7, s46, 0x50003
	s_mul_i32 s46, s7, 11
	v_mov_b32_e32 v8, v217
	s_sub_i32 s46, s6, s46
	s_lshl_b32 s6, s7, 6
	s_and_b32 s7, s46, 0xff
	v_and_b32_e32 v9, 63, v8
	v_or_b32_e32 v0, s6, v9
	v_ashrrev_i32_e32 v2, 6, v8
	v_lshlrev_b32_e32 v0, 2, v0
	v_lshl_add_u64 v[4:5], s[4:5], 0, v[0:1]
	s_lshl_b32 s46, s7, 20
	v_ashrrev_i32_e32 v3, 31, v2
	v_lshl_add_u64 v[4:5], v[4:5], 0, s[46:47]
	v_lshlrev_b64 v[6:7], 12, v[2:3]
	v_lshl_add_u64 v[4:5], v[4:5], 0, v[6:7]
	v_add_co_u32_e32 v6, vcc, s33, v4
	global_load_dword v0, v[4:5], off
	s_nop 0
	v_addc_co_u32_e32 v7, vcc, 0, v5, vcc
	global_load_dword v3, v[6:7], off
	v_add_co_u32_e32 v6, vcc, s54, v4
	s_mov_b32 s46, 0x28000
	s_nop 0
	v_addc_co_u32_e32 v7, vcc, 0, v5, vcc
	global_load_dword v10, v[6:7], off
	v_add_co_u32_e32 v6, vcc, s27, v4
	v_lshlrev_b32_e32 v2, 2, v2
	s_nop 0
	v_addc_co_u32_e32 v7, vcc, 0, v5, vcc
	global_load_dword v11, v[6:7], off
	v_add_co_u32_e32 v6, vcc, s38, v4
	s_lshl_b32 s7, s7, 9
	s_nop 0
	v_addc_co_u32_e32 v7, vcc, 0, v5, vcc
	global_load_dword v12, v[6:7], off
	v_add_co_u32_e32 v6, vcc, s46, v4
	s_mov_b32 s46, 0x38000
	s_nop 0
	v_addc_co_u32_e32 v7, vcc, 0, v5, vcc
	global_load_dword v13, v[6:7], off
	v_add_co_u32_e32 v6, vcc, s39, v4
	s_add_u32 s76, s70, s7
	s_nop 0
	v_addc_co_u32_e32 v7, vcc, 0, v5, vcc
	global_load_dword v14, v[6:7], off
	v_add_co_u32_e32 v6, vcc, s46, v4
	s_mov_b32 s46, 0x40000
	s_nop 0
	v_addc_co_u32_e32 v7, vcc, 0, v5, vcc
	global_load_dword v15, v[6:7], off
	v_add_co_u32_e32 v6, vcc, s46, v4
	s_mov_b32 s46, 0x48000
	s_nop 0
	v_addc_co_u32_e32 v7, vcc, 0, v5, vcc
	global_load_dword v16, v[6:7], off
	v_add_co_u32_e32 v6, vcc, s46, v4
	s_mov_b32 s46, 0x50000
	s_nop 0
	v_addc_co_u32_e32 v7, vcc, 0, v5, vcc
	global_load_dword v17, v[6:7], off
	v_add_co_u32_e32 v6, vcc, s46, v4
	s_mov_b32 s46, 0x58000
	s_nop 0
	v_addc_co_u32_e32 v7, vcc, 0, v5, vcc
	global_load_dword v18, v[6:7], off
	v_add_co_u32_e32 v6, vcc, s46, v4
	s_mov_b32 s46, 0x60000
	s_nop 0
	v_addc_co_u32_e32 v7, vcc, 0, v5, vcc
	global_load_dword v19, v[6:7], off
	v_add_co_u32_e32 v6, vcc, s46, v4
	s_mov_b32 s46, 0x68000
	s_nop 0
	v_addc_co_u32_e32 v7, vcc, 0, v5, vcc
	global_load_dword v20, v[6:7], off
	v_add_co_u32_e32 v6, vcc, s46, v4
	s_mov_b32 s46, 0x70000
	s_nop 0
	v_addc_co_u32_e32 v7, vcc, 0, v5, vcc
	global_load_dword v21, v[6:7], off
	v_add_co_u32_e32 v6, vcc, s46, v4
	s_mov_b32 s46, 0x78000
	s_nop 0
	v_addc_co_u32_e32 v7, vcc, 0, v5, vcc
	global_load_dword v22, v[6:7], off
	v_add_co_u32_e32 v6, vcc, s46, v4
	s_mov_b32 s46, 0x80000
	s_nop 0
	v_addc_co_u32_e32 v7, vcc, 0, v5, vcc
	global_load_dword v23, v[6:7], off
	v_add_co_u32_e32 v6, vcc, s46, v4
	s_mov_b32 s46, 0x88000
	s_nop 0
	v_addc_co_u32_e32 v7, vcc, 0, v5, vcc
	global_load_dword v24, v[6:7], off
	v_add_co_u32_e32 v6, vcc, s46, v4
	s_mov_b32 s46, 0x90000
	s_nop 0
	v_addc_co_u32_e32 v7, vcc, 0, v5, vcc
	global_load_dword v25, v[6:7], off
	v_add_co_u32_e32 v6, vcc, s46, v4
	s_mov_b32 s46, 0x98000
	s_nop 0
	v_addc_co_u32_e32 v7, vcc, 0, v5, vcc
	global_load_dword v26, v[6:7], off
	v_add_co_u32_e32 v6, vcc, s46, v4
	s_mov_b32 s46, 0xa0000
	s_nop 0
	v_addc_co_u32_e32 v7, vcc, 0, v5, vcc
	global_load_dword v27, v[6:7], off
	v_add_co_u32_e32 v6, vcc, s46, v4
	s_mov_b32 s46, 0xa8000
	s_nop 0
	v_addc_co_u32_e32 v7, vcc, 0, v5, vcc
	global_load_dword v28, v[6:7], off
	v_add_co_u32_e32 v6, vcc, s46, v4
	s_mov_b32 s46, 0xb0000
	s_nop 0
	v_addc_co_u32_e32 v7, vcc, 0, v5, vcc
	global_load_dword v29, v[6:7], off
	v_add_co_u32_e32 v6, vcc, s46, v4
	s_mov_b32 s46, 0xb8000
	s_nop 0
	v_addc_co_u32_e32 v7, vcc, 0, v5, vcc
	global_load_dword v30, v[6:7], off
	v_add_co_u32_e32 v6, vcc, s46, v4
	s_mov_b32 s46, 0xc0000
	s_nop 0
	v_addc_co_u32_e32 v7, vcc, 0, v5, vcc
	global_load_dword v31, v[6:7], off
	v_add_co_u32_e32 v6, vcc, s46, v4
	s_mov_b32 s46, 0xc8000
	s_nop 0
	v_addc_co_u32_e32 v7, vcc, 0, v5, vcc
	global_load_dword v32, v[6:7], off
	v_add_co_u32_e32 v6, vcc, s46, v4
	s_mov_b32 s46, 0xd0000
	s_nop 0
	v_addc_co_u32_e32 v7, vcc, 0, v5, vcc
	global_load_dword v33, v[6:7], off
	v_add_co_u32_e32 v6, vcc, s46, v4
	s_mov_b32 s46, 0xd8000
	s_nop 0
	v_addc_co_u32_e32 v7, vcc, 0, v5, vcc
	global_load_dword v34, v[6:7], off
	v_add_co_u32_e32 v6, vcc, s46, v4
	s_mov_b32 s46, 0xe0000
	s_nop 0
	v_addc_co_u32_e32 v7, vcc, 0, v5, vcc
	global_load_dword v35, v[6:7], off
	v_add_co_u32_e32 v6, vcc, s46, v4
	s_mov_b32 s46, 0xe8000
	s_nop 0
	v_addc_co_u32_e32 v7, vcc, 0, v5, vcc
	global_load_dword v36, v[6:7], off
	v_add_co_u32_e32 v6, vcc, s46, v4
	s_mov_b32 s46, 0xf0000
	s_nop 0
	v_addc_co_u32_e32 v7, vcc, 0, v5, vcc
	global_load_dword v37, v[6:7], off
	v_add_co_u32_e32 v6, vcc, s46, v4
	s_mov_b32 s46, 0xf8000
	s_nop 0
	v_addc_co_u32_e32 v7, vcc, 0, v5, vcc
	v_add_co_u32_e32 v4, vcc, s46, v4
	global_load_dword v6, v[6:7], off
	s_nop 0
	v_addc_co_u32_e32 v5, vcc, 0, v5, vcc
	global_load_dword v4, v[4:5], off
	v_mul_u32_u24_e32 v5, 0x404, v9
	v_add3_u32 v2, 0, v5, v2
	v_add_u32_e32 v2, 0x8000, v2
	s_waitcnt vmcnt(0)
	ds_write2_b32 v2, v0, v3 offset1:8
	ds_write2_b32 v2, v10, v11 offset0:16 offset1:24
	ds_write2_b32 v2, v12, v13 offset0:32 offset1:40
	ds_write2_b32 v2, v14, v15 offset0:48 offset1:56
	ds_write2_b32 v2, v16, v17 offset0:64 offset1:72
	ds_write2_b32 v2, v18, v19 offset0:80 offset1:88
	ds_write2_b32 v2, v20, v21 offset0:96 offset1:104
	ds_write2_b32 v2, v22, v23 offset0:112 offset1:120
	ds_write2_b32 v2, v24, v25 offset0:128 offset1:136
	ds_write2_b32 v2, v26, v27 offset0:144 offset1:152
	ds_write2_b32 v2, v28, v29 offset0:160 offset1:168
	ds_write2_b32 v2, v30, v31 offset0:176 offset1:184
	ds_write2_b32 v2, v32, v33 offset0:192 offset1:200
	ds_write2_b32 v2, v34, v35 offset0:208 offset1:216
	ds_write2_b32 v2, v36, v37 offset0:224 offset1:232
	ds_write2_b32 v2, v6, v4 offset0:240 offset1:248
	v_lshlrev_b32_e32 v2, 3, v8
	v_ashrrev_i32_e32 v0, 3, v8
	v_and_b32_e32 v4, 56, v2
	v_mul_lo_u32 v2, v0, s43
	v_lshlrev_b32_e32 v3, 2, v4
	s_addc_u32 s77, s71, 0
	v_add3_u32 v10, 0, v2, v3
	v_add_u32_e32 v0, s6, v0
	v_mov_b64_e32 v[2:3], s[76:77]
	v_add_u32_e32 v5, 0x8000, v10
	v_mad_i64_i32 v[2:3], s[6:7], v0, s3, v[2:3]
	v_lshlrev_b32_e32 v0, 1, v4
	s_waitcnt lgkmcnt(0)
	s_barrier
; DEVI unsigned cvtpk(float lo, float hi) { unsigned r; asm volatile("v_cvt_pk_bf16_f32 %0, %1, %2" : "=v"(r) : "v"(lo), "v"(hi)); return r; }
; DEVI int ltid(int wv) { int t = (wv << 6) | (int)__builtin_amdgcn_mbcnt_hi(~0u, __builtin_amdgcn_mbcnt_lo(~0u, 0u)); asm volatile("" : "+v"(t)); return t; }
; template <int KT, class F> DEVI void cvt_tile(F colptr, int ldsrc, int k0, bf16_t* out, int ldo, int v0, float* tile, int wv) {
;     const int tid = ltid(wv);
;     constexpr int PITCH = KT * 64 + 1;
;     { const int vc = tid & 63, kk = tid >> 6; const float* cp = colptr(v0 + vc) + (size_t)k0 * ldsrc; float v[8 * KT];
; #pragma unroll
;       for (int r = 0; r < 8 * KT; ++r) v[r] = cp[(size_t)(r * 8 + kk) * ldsrc];
; #pragma unroll
;       for (int r = 0; r < 8 * KT; ++r) tile[vc * PITCH + r * 8 + kk] = v[r]; }
;     ...
;     { const int vc = tid >> 3, k8 = (tid & 7) * 8;
; #pragma unroll
;       for (int q = 0; q < KT; ++q) { const float* tp = tile + vc * PITCH + q * 64 + k8;
;         u32x4 w = {cvtpk(tp[0], tp[1]), cvtpk(tp[2], tp[3]), cvtpk(tp[4], tp[5]), cvtpk(tp[6], tp[7])};
;         *(u32x4*)(out + (size_t)(v0 + vc) * ldo + k0 + q * 64 + k8) = w; } }
;     __syncthreads();
	v_lshl_add_u64 v[6:7], v[2:3], 0, v[0:1]
	ds_read2_b32 v[2:3], v5 offset1:1
	v_add_u32_e32 v0, 0x8008, v10
	s_waitcnt lgkmcnt(0)
	v_cvt_pk_bf16_f32 v2, v2, v3
	ds_read2_b32 v[4:5], v0 offset1:1
	v_add_u32_e32 v0, 0x8010, v10
	s_waitcnt lgkmcnt(0)
	v_cvt_pk_bf16_f32 v3, v4, v5
	ds_read2_b32 v[4:5], v0 offset1:1
	v_add_u32_e32 v0, 0x8018, v10
	s_waitcnt lgkmcnt(0)
	v_cvt_pk_bf16_f32 v4, v4, v5
	ds_read2_b32 v[8:9], v0 offset1:1
	s_waitcnt lgkmcnt(0)
	v_cvt_pk_bf16_f32 v5, v8, v9
	global_store_dwordx4 v[6:7], v[2:5], off
	v_add_u32_e32 v0, 0x8100, v10
	ds_read2_b32 v[2:3], v0 offset1:1
	v_add_u32_e32 v0, 0x8108, v10
	s_waitcnt lgkmcnt(0)
	v_cvt_pk_bf16_f32 v2, v2, v3
	ds_read2_b32 v[4:5], v0 offset1:1
	v_add_u32_e32 v0, 0x8110, v10
	s_waitcnt lgkmcnt(0)
	v_cvt_pk_bf16_f32 v3, v4, v5
	ds_read2_b32 v[4:5], v0 offset1:1
	v_add_u32_e32 v0, 0x8118, v10
	s_waitcnt lgkmcnt(0)
	v_cvt_pk_bf16_f32 v4, v4, v5
	ds_read2_b32 v[8:9], v0 offset1:1
	s_waitcnt lgkmcnt(0)
	v_cvt_pk_bf16_f32 v5, v8, v9
	global_store_dwordx4 v[6:7], v[2:5], off offset:128
	v_add_u32_e32 v0, 0x8200, v10
	ds_read2_b32 v[2:3], v0 offset1:1
	v_add_u32_e32 v0, 0x8208, v10
	s_waitcnt lgkmcnt(0)
	v_cvt_pk_bf16_f32 v2, v2, v3
	ds_read2_b32 v[4:5], v0 offset1:1
	v_add_u32_e32 v0, 0x8210, v10
	s_waitcnt lgkmcnt(0)
	v_cvt_pk_bf16_f32 v3, v4, v5
	ds_read2_b32 v[4:5], v0 offset1:1
	v_add_u32_e32 v0, 0x8218, v10
	s_waitcnt lgkmcnt(0)
	v_cvt_pk_bf16_f32 v4, v4, v5
	ds_read2_b32 v[8:9], v0 offset1:1
	s_waitcnt lgkmcnt(0)
	v_cvt_pk_bf16_f32 v5, v8, v9
	global_store_dwordx4 v[6:7], v[2:5], off offset:256
	v_add_u32_e32 v0, 0x8300, v10
	ds_read2_b32 v[2:3], v0 offset1:1
	v_add_u32_e32 v0, 0x8308, v10
	s_waitcnt lgkmcnt(0)
	v_cvt_pk_bf16_f32 v2, v2, v3
	ds_read2_b32 v[4:5], v0 offset1:1
	v_add_u32_e32 v0, 0x8310, v10
	s_waitcnt lgkmcnt(0)
	v_cvt_pk_bf16_f32 v3, v4, v5
	ds_read2_b32 v[4:5], v0 offset1:1
	v_add_u32_e32 v0, 0x8318, v10
	s_waitcnt lgkmcnt(0)
	v_cvt_pk_bf16_f32 v4, v4, v5
	ds_read2_b32 v[8:9], v0 offset1:1
	s_waitcnt lgkmcnt(0)
	v_cvt_pk_bf16_f32 v5, v8, v9
	global_store_dwordx4 v[6:7], v[2:5], off offset:384
	s_waitcnt lgkmcnt(0)
	s_barrier
	s_mov_b64 s[6:7], 0
.LBB0_94:
	s_andn2_b64 vcc, exec, s[6:7]
	s_cbranch_vccnz .LBB0_91
	s_and_b32 s7, s23, 0x300
	s_and_b32 s6, s25, 0xffffffc0
	s_bitcmp1_b32 s8, 3
	s_cselect_b32 s76, s13, 0
	s_cselect_b32 s46, s22, 0
	s_add_u32 s78, s9, s76
	s_addc_u32 s46, s10, s46
	s_and_b32 s76, s60, 0xffffff80
	v_mov_b32_e32 v6, v217
	s_ashr_i32 s77, s76, 31
	s_lshl_b64 s[76:77], s[76:77], 2
	v_and_b32_e32 v7, 63, v6
	s_add_u32 s76, s78, s76
	v_and_or_b32 v0, s25, 64, v7
	s_addc_u32 s77, s46, s77
	v_lshlrev_b32_e32 v0, 2, v0
	v_lshl_add_u64 v[2:3], s[76:77], 0, v[0:1]
	s_mul_i32 s46, s7, 0x2c00
	v_ashrrev_i32_e32 v8, 6, v6
	v_lshl_add_u64 v[2:3], v[2:3], 0, s[46:47]
	v_mad_i64_i32 v[4:5], s[76:77], v8, s44, v[2:3]
	global_load_dword v0, v[4:5], off
	v_add_u32_e32 v4, 8, v8
	v_mad_i64_i32 v[4:5], s[76:77], v4, s44, v[2:3]
	global_load_dword v9, v[4:5], off
	v_add_u32_e32 v4, 16, v8
	v_mad_i64_i32 v[4:5], s[76:77], v4, s44, v[2:3]
	global_load_dword v10, v[4:5], off
	v_add_u32_e32 v4, 24, v8
	v_mad_i64_i32 v[4:5], s[76:77], v4, s44, v[2:3]
	global_load_dword v11, v[4:5], off
	v_add_u32_e32 v4, 32, v8
	v_mad_i64_i32 v[4:5], s[76:77], v4, s44, v[2:3]
	global_load_dword v12, v[4:5], off
	v_add_u32_e32 v4, 40, v8
	v_mad_i64_i32 v[4:5], s[76:77], v4, s44, v[2:3]
	global_load_dword v13, v[4:5], off
	v_add_u32_e32 v4, 48, v8
	v_mad_i64_i32 v[4:5], s[76:77], v4, s44, v[2:3]
	global_load_dword v14, v[4:5], off
	v_add_u32_e32 v4, 56, v8
	v_mad_i64_i32 v[4:5], s[76:77], v4, s44, v[2:3]
	global_load_dword v15, v[4:5], off
	v_add_u32_e32 v4, 64, v8
	v_mad_i64_i32 v[4:5], s[76:77], v4, s44, v[2:3]
	global_load_dword v16, v[4:5], off
	v_add_u32_e32 v4, 0x48, v8
	v_mad_i64_i32 v[4:5], s[76:77], v4, s44, v[2:3]
	global_load_dword v17, v[4:5], off
	v_add_u32_e32 v4, 0x50, v8
	v_mad_i64_i32 v[4:5], s[76:77], v4, s44, v[2:3]
	global_load_dword v18, v[4:5], off
	v_add_u32_e32 v4, 0x58, v8
	v_mad_i64_i32 v[4:5], s[76:77], v4, s44, v[2:3]
	global_load_dword v19, v[4:5], off
	v_add_u32_e32 v4, 0x60, v8
	v_mad_i64_i32 v[4:5], s[76:77], v4, s44, v[2:3]
	global_load_dword v20, v[4:5], off
	v_add_u32_e32 v4, 0x68, v8
	v_mad_i64_i32 v[4:5], s[76:77], v4, s44, v[2:3]
	global_load_dword v21, v[4:5], off
	v_add_u32_e32 v4, 0x70, v8
	v_mad_i64_i32 v[4:5], s[76:77], v4, s44, v[2:3]
	global_load_dword v22, v[4:5], off
	v_add_u32_e32 v4, 0x78, v8
	v_mad_i64_i32 v[4:5], s[76:77], v4, s44, v[2:3]
	global_load_dword v23, v[4:5], off
	v_add_u32_e32 v4, 0x80, v8
	v_mad_i64_i32 v[4:5], s[76:77], v4, s44, v[2:3]
	global_load_dword v24, v[4:5], off
	v_add_u32_e32 v4, 0x88, v8
	v_mad_i64_i32 v[4:5], s[76:77], v4, s44, v[2:3]
	global_load_dword v25, v[4:5], off
	v_add_u32_e32 v4, 0x90, v8
	v_mad_i64_i32 v[4:5], s[76:77], v4, s44, v[2:3]
	global_load_dword v26, v[4:5], off
	v_add_u32_e32 v4, 0x98, v8
	v_mad_i64_i32 v[4:5], s[76:77], v4, s44, v[2:3]
	global_load_dword v27, v[4:5], off
	v_add_u32_e32 v4, 0xa0, v8
	v_mad_i64_i32 v[4:5], s[76:77], v4, s44, v[2:3]
	global_load_dword v28, v[4:5], off
	v_add_u32_e32 v4, 0xa8, v8
	v_mad_i64_i32 v[4:5], s[76:77], v4, s44, v[2:3]
	global_load_dword v29, v[4:5], off
	v_add_u32_e32 v4, 0xb0, v8
	v_mad_i64_i32 v[4:5], s[76:77], v4, s44, v[2:3]
	global_load_dword v30, v[4:5], off
	v_add_u32_e32 v4, 0xb8, v8
	v_mad_i64_i32 v[4:5], s[76:77], v4, s44, v[2:3]
	global_load_dword v31, v[4:5], off
	v_add_u32_e32 v4, 0xc0, v8
	v_mad_i64_i32 v[4:5], s[76:77], v4, s44, v[2:3]
	global_load_dword v32, v[4:5], off
	v_add_u32_e32 v4, 0xc8, v8
	v_mad_i64_i32 v[4:5], s[76:77], v4, s44, v[2:3]
	global_load_dword v33, v[4:5], off
	v_add_u32_e32 v4, 0xd0, v8
	v_mad_i64_i32 v[4:5], s[76:77], v4, s44, v[2:3]
	global_load_dword v34, v[4:5], off
	v_add_u32_e32 v4, 0xd8, v8
	v_mad_i64_i32 v[4:5], s[76:77], v4, s44, v[2:3]
	global_load_dword v35, v[4:5], off
	v_add_u32_e32 v4, 0xe0, v8
	v_mad_i64_i32 v[4:5], s[76:77], v4, s44, v[2:3]
	global_load_dword v36, v[4:5], off
	v_add_u32_e32 v4, 0xe8, v8
	v_mad_i64_i32 v[4:5], s[76:77], v4, s44, v[2:3]
	global_load_dword v37, v[4:5], off
	v_add_u32_e32 v4, 0xf0, v8
	v_mad_i64_i32 v[4:5], s[76:77], v4, s44, v[2:3]
	global_load_dword v4, v[4:5], off
	v_add_u32_e32 v5, 0xf8, v8
	v_mad_i64_i32 v[2:3], s[76:77], v5, s44, v[2:3]
	global_load_dword v2, v[2:3], off
	v_mul_u32_u24_e32 v3, 0x404, v7
	v_lshlrev_b32_e32 v5, 2, v8
	v_add3_u32 v3, 0, v3, v5
	v_add_u32_e32 v3, 0x8000, v3
	s_waitcnt vmcnt(0)
; DEVI unsigned cvtpk(float lo, float hi) { unsigned r; asm volatile("v_cvt_pk_bf16_f32 %0, %1, %2" : "=v"(r) : "v"(lo), "v"(hi)); return r; }
; DEVI int ltid(int wv) { int t = (wv << 6) | (int)__builtin_amdgcn_mbcnt_hi(~0u, __builtin_amdgcn_mbcnt_lo(~0u, 0u)); asm volatile("" : "+v"(t)); return t; }
; template <int KT, class F> DEVI void cvt_tile(F colptr, int ldsrc, int k0, bf16_t* out, int ldo, int v0, float* tile, int wv) {
;     const int tid = ltid(wv);
;     constexpr int PITCH = KT * 64 + 1;
;     { const int vc = tid & 63, kk = tid >> 6; const float* cp = colptr(v0 + vc) + (size_t)k0 * ldsrc; float v[8 * KT];
; #pragma unroll
;       for (int r = 0; r < 8 * KT; ++r) v[r] = cp[(size_t)(r * 8 + kk) * ldsrc];
; #pragma unroll
;       for (int r = 0; r < 8 * KT; ++r) tile[vc * PITCH + r * 8 + kk] = v[r]; }
;     __syncthreads();
;     { const int vc = tid >> 3, k8 = (tid & 7) * 8;
; #pragma unroll
;       for (int q = 0; q < KT; ++q) { const float* tp = tile + vc * PITCH + q * 64 + k8;
;         u32x4 w = {cvtpk(tp[0], tp[1]), cvtpk(tp[2], tp[3]), cvtpk(tp[4], tp[5]), cvtpk(tp[6], tp[7])};
;         *(u32x4*)(out + (size_t)(v0 + vc) * ldo + k0 + q * 64 + k8) = w; } }
;     __syncthreads();
	ds_write2_b32 v3, v0, v9 offset1:8
	ds_write2_b32 v3, v10, v11 offset0:16 offset1:24
	ds_write2_b32 v3, v12, v13 offset0:32 offset1:40
	ds_write2_b32 v3, v14, v15 offset0:48 offset1:56
	ds_write2_b32 v3, v16, v17 offset0:64 offset1:72
	ds_write2_b32 v3, v18, v19 offset0:80 offset1:88
	ds_write2_b32 v3, v20, v21 offset0:96 offset1:104
	ds_write2_b32 v3, v22, v23 offset0:112 offset1:120
	ds_write2_b32 v3, v24, v25 offset0:128 offset1:136
	ds_write2_b32 v3, v26, v27 offset0:144 offset1:152
	ds_write2_b32 v3, v28, v29 offset0:160 offset1:168
	ds_write2_b32 v3, v30, v31 offset0:176 offset1:184
	ds_write2_b32 v3, v32, v33 offset0:192 offset1:200
	ds_write2_b32 v3, v34, v35 offset0:208 offset1:216
	ds_write2_b32 v3, v36, v37 offset0:224 offset1:232
	ds_write2_b32 v3, v4, v2 offset0:240 offset1:248
	v_lshlrev_b32_e32 v2, 3, v6
	v_ashrrev_i32_e32 v0, 3, v6
	v_and_b32_e32 v4, 56, v2
	v_mul_lo_u32 v2, v0, s43
	v_lshlrev_b32_e32 v3, 2, v4
	v_add3_u32 v10, 0, v2, v3
	s_lshl_b32 s7, s7, 1
	v_add_u32_e32 v2, s6, v0
	s_add_u32 s76, s72, s7
	v_ashrrev_i32_e32 v3, 31, v2
	s_addc_u32 s77, s73, 0
	v_lshlrev_b64 v[2:3], 11, v[2:3]
	v_add_u32_e32 v5, 0x8000, v10
	v_lshl_add_u64 v[2:3], s[76:77], 0, v[2:3]
	v_lshlrev_b32_e32 v0, 1, v4
	s_waitcnt lgkmcnt(0)
	s_barrier
	v_lshl_add_u64 v[6:7], v[2:3], 0, v[0:1]
	ds_read2_b32 v[2:3], v5 offset1:1
	v_add_u32_e32 v0, 0x8008, v10
	s_waitcnt lgkmcnt(0)
	v_cvt_pk_bf16_f32 v2, v2, v3
	ds_read2_b32 v[4:5], v0 offset1:1
	v_add_u32_e32 v0, 0x8010, v10
	s_waitcnt lgkmcnt(0)
	v_cvt_pk_bf16_f32 v3, v4, v5
	ds_read2_b32 v[4:5], v0 offset1:1
	v_add_u32_e32 v0, 0x8018, v10
	s_waitcnt lgkmcnt(0)
	v_cvt_pk_bf16_f32 v4, v4, v5
	ds_read2_b32 v[8:9], v0 offset1:1
	s_waitcnt lgkmcnt(0)
	v_cvt_pk_bf16_f32 v5, v8, v9
	global_store_dwordx4 v[6:7], v[2:5], off
	v_add_u32_e32 v0, 0x8100, v10
	ds_read2_b32 v[2:3], v0 offset1:1
	v_add_u32_e32 v0, 0x8108, v10
	s_waitcnt lgkmcnt(0)
	v_cvt_pk_bf16_f32 v2, v2, v3
	ds_read2_b32 v[4:5], v0 offset1:1
	v_add_u32_e32 v0, 0x8110, v10
	s_waitcnt lgkmcnt(0)
	v_cvt_pk_bf16_f32 v3, v4, v5
	ds_read2_b32 v[4:5], v0 offset1:1
	v_add_u32_e32 v0, 0x8118, v10
	s_waitcnt lgkmcnt(0)
	v_cvt_pk_bf16_f32 v4, v4, v5
	ds_read2_b32 v[8:9], v0 offset1:1
	s_waitcnt lgkmcnt(0)
	v_cvt_pk_bf16_f32 v5, v8, v9
	global_store_dwordx4 v[6:7], v[2:5], off offset:128
	v_add_u32_e32 v0, 0x8200, v10
	ds_read2_b32 v[2:3], v0 offset1:1
	v_add_u32_e32 v0, 0x8208, v10
	s_waitcnt lgkmcnt(0)
	v_cvt_pk_bf16_f32 v2, v2, v3
	ds_read2_b32 v[4:5], v0 offset1:1
	v_add_u32_e32 v0, 0x8210, v10
	s_waitcnt lgkmcnt(0)
	v_cvt_pk_bf16_f32 v3, v4, v5
	ds_read2_b32 v[4:5], v0 offset1:1
	v_add_u32_e32 v0, 0x8218, v10
	s_waitcnt lgkmcnt(0)
	v_cvt_pk_bf16_f32 v4, v4, v5
	ds_read2_b32 v[8:9], v0 offset1:1
	s_waitcnt lgkmcnt(0)
	v_cvt_pk_bf16_f32 v5, v8, v9
	global_store_dwordx4 v[6:7], v[2:5], off offset:256
	v_add_u32_e32 v0, 0x8300, v10
	ds_read2_b32 v[2:3], v0 offset1:1
	v_add_u32_e32 v0, 0x8308, v10
	s_waitcnt lgkmcnt(0)
	v_cvt_pk_bf16_f32 v2, v2, v3
	ds_read2_b32 v[4:5], v0 offset1:1
	v_add_u32_e32 v0, 0x8310, v10
	s_waitcnt lgkmcnt(0)
	v_cvt_pk_bf16_f32 v3, v4, v5
	ds_read2_b32 v[4:5], v0 offset1:1
	v_add_u32_e32 v0, 0x8318, v10
	s_waitcnt lgkmcnt(0)
	v_cvt_pk_bf16_f32 v4, v4, v5
	ds_read2_b32 v[8:9], v0 offset1:1
	s_waitcnt lgkmcnt(0)
	v_cvt_pk_bf16_f32 v5, v8, v9
	global_store_dwordx4 v[6:7], v[2:5], off offset:384
	s_waitcnt lgkmcnt(0)
	s_barrier
	s_branch .LBB0_91

; DEVI int ltid(int wv) { int t = (wv << 6) | (int)__builtin_amdgcn_mbcnt_hi(~0u, __builtin_amdgcn_mbcnt_lo(~0u, 0u)); asm volatile("" : "+v"(t)); return t; }
; template <int KT, class F> DEVI void cvt_tile(F colptr, int ldsrc, int k0, bf16_t* out, int ldo, int v0, float* tile, int wv) {
;     const int tid = ltid(wv);
;     constexpr int PITCH = KT * 64 + 1;
;     { const int vc = tid & 63, kk = tid >> 6; const float* cp = colptr(v0 + vc) + (size_t)k0 * ldsrc; float v[8 * KT];
; #pragma unroll
;       for (int r = 0; r < 8 * KT; ++r) v[r] = cp[(size_t)(r * 8 + kk) * ldsrc];
; #pragma unroll
;       for (int r = 0; r < 8 * KT; ++r) tile[vc * PITCH + r * 8 + kk] = v[r]; }
;     __syncthreads();
; DEVI void cvt_ffn_phase(const float* wg, const float* wu, const float* wd, unsigned char* ws, char* lds, int j0, int jstride, int wv) {
;     ...
;     for (int job = j0; job < 352 + 176; job += jstride) {
;         if (job < 352) { const int vt = job >> 2, kg = job & 3; cvt_tile<4>(ColGU{wg, (long)((const char*)wu - (const char*)wg)}, DFF, kg * 256, Wgu, DM, vt * 64, tile, wv); }
;         else { const int j = job - 352, vt = j / 11, kg = j % 11; cvt_tile<4>(ColLin{wd}, DM, kg * 256, Wd, DFF, vt * 64, tile, wv); }
.LBB0_100:
	s_cmpk_gt_i32 s60, 0x15f
	s_mov_b64 s[6:7], -1
	s_cbranch_scc0 .LBB0_102
	s_add_i32 s6, s60, 0xffa0
	s_and_b32 s7, s6, 0xff
	s_mulk_i32 s7, 0x75
	s_lshr_b32 s46, s7, 8
	s_sub_i32 s46, s6, s46
	s_bfe_u32 s46, s46, 0x70001
	s_bfe_u32 s7, s7, 0x80008
	s_add_i32 s46, s46, s7
	s_bfe_u32 s7, s46, 0x50003
	s_mul_i32 s46, s7, 11
	v_mov_b32_e32 v8, v217
	s_sub_i32 s46, s6, s46
	s_lshl_b32 s6, s7, 6
	s_and_b32 s7, s46, 0xff
	v_and_b32_e32 v9, 63, v8
	v_or_b32_e32 v0, s6, v9
	v_ashrrev_i32_e32 v2, 6, v8
	v_lshlrev_b32_e32 v0, 2, v0
	v_lshl_add_u64 v[4:5], s[4:5], 0, v[0:1]
	s_lshl_b32 s46, s7, 20
	v_ashrrev_i32_e32 v3, 31, v2
	v_lshl_add_u64 v[4:5], v[4:5], 0, s[46:47]
	v_lshlrev_b64 v[6:7], 12, v[2:3]
	v_lshl_add_u64 v[4:5], v[4:5], 0, v[6:7]
	v_add_co_u32_e32 v6, vcc, s33, v4
	global_load_dword v0, v[4:5], off
	s_nop 0
	v_addc_co_u32_e32 v7, vcc, 0, v5, vcc
	global_load_dword v3, v[6:7], off
	v_add_co_u32_e32 v6, vcc, s54, v4
	s_mov_b32 s46, 0x28000
	s_nop 0
	v_addc_co_u32_e32 v7, vcc, 0, v5, vcc
	global_load_dword v10, v[6:7], off
	v_add_co_u32_e32 v6, vcc, s27, v4
	v_lshlrev_b32_e32 v2, 2, v2
	s_nop 0
	v_addc_co_u32_e32 v7, vcc, 0, v5, vcc
	global_load_dword v11, v[6:7], off
	v_add_co_u32_e32 v6, vcc, s38, v4
	s_lshl_b32 s7, s7, 9
	s_nop 0
	v_addc_co_u32_e32 v7, vcc, 0, v5, vcc
	global_load_dword v12, v[6:7], off
	v_add_co_u32_e32 v6, vcc, s46, v4
	s_mov_b32 s46, 0x38000
	s_nop 0
	v_addc_co_u32_e32 v7, vcc, 0, v5, vcc
	global_load_dword v13, v[6:7], off
	v_add_co_u32_e32 v6, vcc, s39, v4
	s_add_u32 s76, s70, s7
	s_nop 0
	v_addc_co_u32_e32 v7, vcc, 0, v5, vcc
	global_load_dword v14, v[6:7], off
	v_add_co_u32_e32 v6, vcc, s46, v4
	s_mov_b32 s46, 0x40000
	s_nop 0
	v_addc_co_u32_e32 v7, vcc, 0, v5, vcc
	global_load_dword v15, v[6:7], off
	v_add_co_u32_e32 v6, vcc, s46, v4
	s_mov_b32 s46, 0x48000
	s_nop 0
	v_addc_co_u32_e32 v7, vcc, 0, v5, vcc
	global_load_dword v16, v[6:7], off
	v_add_co_u32_e32 v6, vcc, s46, v4
	s_mov_b32 s46, 0x50000
	s_nop 0
	v_addc_co_u32_e32 v7, vcc, 0, v5, vcc
	global_load_dword v17, v[6:7], off
	v_add_co_u32_e32 v6, vcc, s46, v4
	s_mov_b32 s46, 0x58000
	s_nop 0
	v_addc_co_u32_e32 v7, vcc, 0, v5, vcc
	global_load_dword v18, v[6:7], off
	v_add_co_u32_e32 v6, vcc, s46, v4
	s_mov_b32 s46, 0x60000
	s_nop 0
	v_addc_co_u32_e32 v7, vcc, 0, v5, vcc
	global_load_dword v19, v[6:7], off
	v_add_co_u32_e32 v6, vcc, s46, v4
	s_mov_b32 s46, 0x68000
	s_nop 0
	v_addc_co_u32_e32 v7, vcc, 0, v5, vcc
	global_load_dword v20, v[6:7], off
	v_add_co_u32_e32 v6, vcc, s46, v4
	s_mov_b32 s46, 0x70000
	s_nop 0
	v_addc_co_u32_e32 v7, vcc, 0, v5, vcc
	global_load_dword v21, v[6:7], off
	v_add_co_u32_e32 v6, vcc, s46, v4
	s_mov_b32 s46, 0x78000
	s_nop 0
	v_addc_co_u32_e32 v7, vcc, 0, v5, vcc
	global_load_dword v22, v[6:7], off
	v_add_co_u32_e32 v6, vcc, s46, v4
	s_mov_b32 s46, 0x80000
	s_nop 0
	v_addc_co_u32_e32 v7, vcc, 0, v5, vcc
	global_load_dword v23, v[6:7], off
	v_add_co_u32_e32 v6, vcc, s46, v4
	s_mov_b32 s46, 0x88000
	s_nop 0
	v_addc_co_u32_e32 v7, vcc, 0, v5, vcc
	global_load_dword v24, v[6:7], off
	v_add_co_u32_e32 v6, vcc, s46, v4
	s_mov_b32 s46, 0x90000
	s_nop 0
	v_addc_co_u32_e32 v7, vcc, 0, v5, vcc
	global_load_dword v25, v[6:7], off
	v_add_co_u32_e32 v6, vcc, s46, v4
	s_mov_b32 s46, 0x98000
	s_nop 0
	v_addc_co_u32_e32 v7, vcc, 0, v5, vcc
	global_load_dword v26, v[6:7], off
	v_add_co_u32_e32 v6, vcc, s46, v4
	s_mov_b32 s46, 0xa0000
	s_nop 0
	v_addc_co_u32_e32 v7, vcc, 0, v5, vcc
	global_load_dword v27, v[6:7], off
	v_add_co_u32_e32 v6, vcc, s46, v4
	s_mov_b32 s46, 0xa8000
	s_nop 0
	v_addc_co_u32_e32 v7, vcc, 0, v5, vcc
	global_load_dword v28, v[6:7], off
	v_add_co_u32_e32 v6, vcc, s46, v4
	s_mov_b32 s46, 0xb0000
	s_nop 0
	v_addc_co_u32_e32 v7, vcc, 0, v5, vcc
	global_load_dword v29, v[6:7], off
	v_add_co_u32_e32 v6, vcc, s46, v4
	s_mov_b32 s46, 0xb8000
	s_nop 0
	v_addc_co_u32_e32 v7, vcc, 0, v5, vcc
	global_load_dword v30, v[6:7], off
	v_add_co_u32_e32 v6, vcc, s46, v4
	s_mov_b32 s46, 0xc0000
	s_nop 0
	v_addc_co_u32_e32 v7, vcc, 0, v5, vcc
	global_load_dword v31, v[6:7], off
	v_add_co_u32_e32 v6, vcc, s46, v4
	s_mov_b32 s46, 0xc8000
	s_nop 0
	v_addc_co_u32_e32 v7, vcc, 0, v5, vcc
	global_load_dword v32, v[6:7], off
	v_add_co_u32_e32 v6, vcc, s46, v4
	s_mov_b32 s46, 0xd0000
	s_nop 0
	v_addc_co_u32_e32 v7, vcc, 0, v5, vcc
	global_load_dword v33, v[6:7], off
	v_add_co_u32_e32 v6, vcc, s46, v4
	s_mov_b32 s46, 0xd8000
	s_nop 0
	v_addc_co_u32_e32 v7, vcc, 0, v5, vcc
	global_load_dword v34, v[6:7], off
	v_add_co_u32_e32 v6, vcc, s46, v4
	s_mov_b32 s46, 0xe0000
	s_nop 0
	v_addc_co_u32_e32 v7, vcc, 0, v5, vcc
	global_load_dword v35, v[6:7], off
	v_add_co_u32_e32 v6, vcc, s46, v4
	s_mov_b32 s46, 0xe8000
	s_nop 0
	v_addc_co_u32_e32 v7, vcc, 0, v5, vcc
	global_load_dword v36, v[6:7], off
	v_add_co_u32_e32 v6, vcc, s46, v4
	s_mov_b32 s46, 0xf0000
	s_nop 0
	v_addc_co_u32_e32 v7, vcc, 0, v5, vcc
	global_load_dword v37, v[6:7], off
	v_add_co_u32_e32 v6, vcc, s46, v4
	s_mov_b32 s46, 0xf8000
	s_nop 0
	v_addc_co_u32_e32 v7, vcc, 0, v5, vcc
	v_add_co_u32_e32 v4, vcc, s46, v4
	global_load_dword v6, v[6:7], off
	s_nop 0
	v_addc_co_u32_e32 v5, vcc, 0, v5, vcc
	global_load_dword v4, v[4:5], off
	v_mul_u32_u24_e32 v5, 0x404, v9
	v_add3_u32 v2, 0, v5, v2
	v_add_u32_e32 v2, 0x8000, v2
	s_waitcnt vmcnt(0)
	ds_write2_b32 v2, v0, v3 offset1:8
	ds_write2_b32 v2, v10, v11 offset0:16 offset1:24
	ds_write2_b32 v2, v12, v13 offset0:32 offset1:40
	ds_write2_b32 v2, v14, v15 offset0:48 offset1:56
	ds_write2_b32 v2, v16, v17 offset0:64 offset1:72
	ds_write2_b32 v2, v18, v19 offset0:80 offset1:88
	ds_write2_b32 v2, v20, v21 offset0:96 offset1:104
	ds_write2_b32 v2, v22, v23 offset0:112 offset1:120
	ds_write2_b32 v2, v24, v25 offset0:128 offset1:136
	ds_write2_b32 v2, v26, v27 offset0:144 offset1:152
	ds_write2_b32 v2, v28, v29 offset0:160 offset1:168
	ds_write2_b32 v2, v30, v31 offset0:176 offset1:184
	ds_write2_b32 v2, v32, v33 offset0:192 offset1:200
	ds_write2_b32 v2, v34, v35 offset0:208 offset1:216
	ds_write2_b32 v2, v36, v37 offset0:224 offset1:232
	ds_write2_b32 v2, v6, v4 offset0:240 offset1:248
	v_lshlrev_b32_e32 v2, 3, v8
	v_ashrrev_i32_e32 v0, 3, v8
	v_and_b32_e32 v4, 56, v2
	v_mul_lo_u32 v2, v0, s43
	v_lshlrev_b32_e32 v3, 2, v4
	s_addc_u32 s77, s71, 0
	v_add3_u32 v10, 0, v2, v3
	v_add_u32_e32 v0, s6, v0
	v_mov_b64_e32 v[2:3], s[76:77]
	v_add_u32_e32 v5, 0x8000, v10
	v_mad_i64_i32 v[2:3], s[6:7], v0, s3, v[2:3]
	v_lshlrev_b32_e32 v0, 1, v4
	s_waitcnt lgkmcnt(0)
	s_barrier
; DEVI unsigned cvtpk(float lo, float hi) { unsigned r; asm volatile("v_cvt_pk_bf16_f32 %0, %1, %2" : "=v"(r) : "v"(lo), "v"(hi)); return r; }
; template <int KT, class F> DEVI void cvt_tile(F colptr, int ldsrc, int k0, bf16_t* out, int ldo, int v0, float* tile, int wv) {
;     ...
;     { const int vc = tid >> 3, k8 = (tid & 7) * 8;
; #pragma unroll
;       for (int q = 0; q < KT; ++q) { const float* tp = tile + vc * PITCH + q * 64 + k8;
;         u32x4 w = {cvtpk(tp[0], tp[1]), cvtpk(tp[2], tp[3]), cvtpk(tp[4], tp[5]), cvtpk(tp[6], tp[7])};
;         *(u32x4*)(out + (size_t)(v0 + vc) * ldo + k0 + q * 64 + k8) = w; } }
; DEVI void cvt_ffn_phase(const float* wg, const float* wu, const float* wd, unsigned char* ws, char* lds, int j0, int jstride, int wv) {
;     ...
;         if (job < 352) { const int vt = job >> 2, kg = job & 3; cvt_tile<4>(ColGU{wg, (long)((const char*)wu - (const char*)wg)}, DFF, kg * 256, Wgu, DM, vt * 64, tile, wv); }
	v_lshl_add_u64 v[6:7], v[2:3], 0, v[0:1]
	ds_read2_b32 v[2:3], v5 offset1:1
	v_add_u32_e32 v0, 0x8008, v10
	s_waitcnt lgkmcnt(0)
	v_cvt_pk_bf16_f32 v2, v2, v3
	ds_read2_b32 v[4:5], v0 offset1:1
	v_add_u32_e32 v0, 0x8010, v10
	s_waitcnt lgkmcnt(0)
	v_cvt_pk_bf16_f32 v3, v4, v5
	ds_read2_b32 v[4:5], v0 offset1:1
	v_add_u32_e32 v0, 0x8018, v10
	s_waitcnt lgkmcnt(0)
	v_cvt_pk_bf16_f32 v4, v4, v5
	ds_read2_b32 v[8:9], v0 offset1:1
	s_waitcnt lgkmcnt(0)
	v_cvt_pk_bf16_f32 v5, v8, v9
	global_store_dwordx4 v[6:7], v[2:5], off
	v_add_u32_e32 v0, 0x8100, v10
	ds_read2_b32 v[2:3], v0 offset1:1
	v_add_u32_e32 v0, 0x8108, v10
	s_waitcnt lgkmcnt(0)
	v_cvt_pk_bf16_f32 v2, v2, v3
	ds_read2_b32 v[4:5], v0 offset1:1
	v_add_u32_e32 v0, 0x8110, v10
	s_waitcnt lgkmcnt(0)
	v_cvt_pk_bf16_f32 v3, v4, v5
	ds_read2_b32 v[4:5], v0 offset1:1
	v_add_u32_e32 v0, 0x8118, v10
	s_waitcnt lgkmcnt(0)
	v_cvt_pk_bf16_f32 v4, v4, v5
	ds_read2_b32 v[8:9], v0 offset1:1
	s_waitcnt lgkmcnt(0)
	v_cvt_pk_bf16_f32 v5, v8, v9
	global_store_dwordx4 v[6:7], v[2:5], off offset:128
	v_add_u32_e32 v0, 0x8200, v10
	ds_read2_b32 v[2:3], v0 offset1:1
	v_add_u32_e32 v0, 0x8208, v10
	s_waitcnt lgkmcnt(0)
	v_cvt_pk_bf16_f32 v2, v2, v3
	ds_read2_b32 v[4:5], v0 offset1:1
	v_add_u32_e32 v0, 0x8210, v10
	s_waitcnt lgkmcnt(0)
	v_cvt_pk_bf16_f32 v3, v4, v5
	ds_read2_b32 v[4:5], v0 offset1:1
	v_add_u32_e32 v0, 0x8218, v10
	s_waitcnt lgkmcnt(0)
	v_cvt_pk_bf16_f32 v4, v4, v5
	ds_read2_b32 v[8:9], v0 offset1:1
	s_waitcnt lgkmcnt(0)
	v_cvt_pk_bf16_f32 v5, v8, v9
	global_store_dwordx4 v[6:7], v[2:5], off offset:256
	v_add_u32_e32 v0, 0x8300, v10
	ds_read2_b32 v[2:3], v0 offset1:1
	v_add_u32_e32 v0, 0x8308, v10
	s_waitcnt lgkmcnt(0)
	v_cvt_pk_bf16_f32 v2, v2, v3
	ds_read2_b32 v[4:5], v0 offset1:1
	v_add_u32_e32 v0, 0x8310, v10
	s_waitcnt lgkmcnt(0)
	v_cvt_pk_bf16_f32 v3, v4, v5
	ds_read2_b32 v[4:5], v0 offset1:1
	v_add_u32_e32 v0, 0x8318, v10
	s_waitcnt lgkmcnt(0)
	v_cvt_pk_bf16_f32 v4, v4, v5
	ds_read2_b32 v[8:9], v0 offset1:1
	s_waitcnt lgkmcnt(0)
	v_cvt_pk_bf16_f32 v5, v8, v9
	global_store_dwordx4 v[6:7], v[2:5], off offset:384
	s_waitcnt lgkmcnt(0)
	s_barrier
	s_mov_b64 s[6:7], 0
.LBB0_102:
	s_andn2_b64 vcc, exec, s[6:7]
	s_cbranch_vccnz .LBB0_99
	s_and_b32 s7, s13, 0x300
	s_and_b32 s6, s23, 0xffffffc0
	s_bitcmp1_b32 s60, 3
	s_cselect_b32 s61, s10, 0
	s_cselect_b32 s46, s11, 0
	s_add_u32 s61, s8, s61
	s_addc_u32 s46, s9, s46
	s_and_b32 s76, s25, 0xffffff80
	v_mov_b32_e32 v6, v217
	s_ashr_i32 s77, s76, 31
	s_lshl_b64 s[76:77], s[76:77], 2
	v_and_b32_e32 v7, 63, v6
	s_add_u32 s76, s61, s76
	v_and_or_b32 v0, s23, 64, v7
	s_addc_u32 s77, s46, s77
	v_lshlrev_b32_e32 v0, 2, v0
	v_lshl_add_u64 v[2:3], s[76:77], 0, v[0:1]
	s_mul_i32 s46, s7, 0x2c00
	v_ashrrev_i32_e32 v8, 6, v6
	v_lshl_add_u64 v[2:3], v[2:3], 0, s[46:47]
	v_mad_i64_i32 v[4:5], s[76:77], v8, s44, v[2:3]
	global_load_dword v0, v[4:5], off
	v_add_u32_e32 v4, 8, v8
	v_mad_i64_i32 v[4:5], s[76:77], v4, s44, v[2:3]
	global_load_dword v9, v[4:5], off
	v_add_u32_e32 v4, 16, v8
	v_mad_i64_i32 v[4:5], s[76:77], v4, s44, v[2:3]
	global_load_dword v10, v[4:5], off
	v_add_u32_e32 v4, 24, v8
	v_mad_i64_i32 v[4:5], s[76:77], v4, s44, v[2:3]
	global_load_dword v11, v[4:5], off
	v_add_u32_e32 v4, 32, v8
	v_mad_i64_i32 v[4:5], s[76:77], v4, s44, v[2:3]
	global_load_dword v12, v[4:5], off
	v_add_u32_e32 v4, 40, v8
	v_mad_i64_i32 v[4:5], s[76:77], v4, s44, v[2:3]
	global_load_dword v13, v[4:5], off
	v_add_u32_e32 v4, 48, v8
	v_mad_i64_i32 v[4:5], s[76:77], v4, s44, v[2:3]
	global_load_dword v14, v[4:5], off
	v_add_u32_e32 v4, 56, v8
	v_mad_i64_i32 v[4:5], s[76:77], v4, s44, v[2:3]
	global_load_dword v15, v[4:5], off
	v_add_u32_e32 v4, 64, v8
	v_mad_i64_i32 v[4:5], s[76:77], v4, s44, v[2:3]
	global_load_dword v16, v[4:5], off
	v_add_u32_e32 v4, 0x48, v8
	v_mad_i64_i32 v[4:5], s[76:77], v4, s44, v[2:3]
	global_load_dword v17, v[4:5], off
	v_add_u32_e32 v4, 0x50, v8
	v_mad_i64_i32 v[4:5], s[76:77], v4, s44, v[2:3]
	global_load_dword v18, v[4:5], off
	v_add_u32_e32 v4, 0x58, v8
	v_mad_i64_i32 v[4:5], s[76:77], v4, s44, v[2:3]
	global_load_dword v19, v[4:5], off
	v_add_u32_e32 v4, 0x60, v8
	v_mad_i64_i32 v[4:5], s[76:77], v4, s44, v[2:3]
	global_load_dword v20, v[4:5], off
	v_add_u32_e32 v4, 0x68, v8
	v_mad_i64_i32 v[4:5], s[76:77], v4, s44, v[2:3]
	global_load_dword v21, v[4:5], off
	v_add_u32_e32 v4, 0x70, v8
	v_mad_i64_i32 v[4:5], s[76:77], v4, s44, v[2:3]
	global_load_dword v22, v[4:5], off
	v_add_u32_e32 v4, 0x78, v8
	v_mad_i64_i32 v[4:5], s[76:77], v4, s44, v[2:3]
	global_load_dword v23, v[4:5], off
	v_add_u32_e32 v4, 0x80, v8
	v_mad_i64_i32 v[4:5], s[76:77], v4, s44, v[2:3]
	global_load_dword v24, v[4:5], off
	v_add_u32_e32 v4, 0x88, v8
	v_mad_i64_i32 v[4:5], s[76:77], v4, s44, v[2:3]
	global_load_dword v25, v[4:5], off
	v_add_u32_e32 v4, 0x90, v8
	v_mad_i64_i32 v[4:5], s[76:77], v4, s44, v[2:3]
	global_load_dword v26, v[4:5], off
	v_add_u32_e32 v4, 0x98, v8
	v_mad_i64_i32 v[4:5], s[76:77], v4, s44, v[2:3]
	global_load_dword v27, v[4:5], off
	v_add_u32_e32 v4, 0xa0, v8
	v_mad_i64_i32 v[4:5], s[76:77], v4, s44, v[2:3]
	global_load_dword v28, v[4:5], off
	v_add_u32_e32 v4, 0xa8, v8
	v_mad_i64_i32 v[4:5], s[76:77], v4, s44, v[2:3]
	global_load_dword v29, v[4:5], off
	v_add_u32_e32 v4, 0xb0, v8
	v_mad_i64_i32 v[4:5], s[76:77], v4, s44, v[2:3]
	global_load_dword v30, v[4:5], off
	v_add_u32_e32 v4, 0xb8, v8
	v_mad_i64_i32 v[4:5], s[76:77], v4, s44, v[2:3]
	global_load_dword v31, v[4:5], off
	v_add_u32_e32 v4, 0xc0, v8
	v_mad_i64_i32 v[4:5], s[76:77], v4, s44, v[2:3]
	global_load_dword v32, v[4:5], off
	v_add_u32_e32 v4, 0xc8, v8
	v_mad_i64_i32 v[4:5], s[76:77], v4, s44, v[2:3]
	global_load_dword v33, v[4:5], off
	v_add_u32_e32 v4, 0xd0, v8
	v_mad_i64_i32 v[4:5], s[76:77], v4, s44, v[2:3]
	global_load_dword v34, v[4:5], off
	v_add_u32_e32 v4, 0xd8, v8
	v_mad_i64_i32 v[4:5], s[76:77], v4, s44, v[2:3]
	global_load_dword v35, v[4:5], off
	v_add_u32_e32 v4, 0xe0, v8
	v_mad_i64_i32 v[4:5], s[76:77], v4, s44, v[2:3]
	global_load_dword v36, v[4:5], off
	v_add_u32_e32 v4, 0xe8, v8
	v_mad_i64_i32 v[4:5], s[76:77], v4, s44, v[2:3]
	global_load_dword v37, v[4:5], off
	v_add_u32_e32 v4, 0xf0, v8
	v_mad_i64_i32 v[4:5], s[76:77], v4, s44, v[2:3]
	global_load_dword v4, v[4:5], off
	v_add_u32_e32 v5, 0xf8, v8
	v_mad_i64_i32 v[2:3], s[76:77], v5, s44, v[2:3]
	global_load_dword v2, v[2:3], off
	v_mul_u32_u24_e32 v3, 0x404, v7
	v_lshlrev_b32_e32 v5, 2, v8
	v_add3_u32 v3, 0, v3, v5
	v_add_u32_e32 v3, 0x8000, v3
	s_waitcnt vmcnt(0)
; DEVI unsigned cvtpk(float lo, float hi) { unsigned r; asm volatile("v_cvt_pk_bf16_f32 %0, %1, %2" : "=v"(r) : "v"(lo), "v"(hi)); return r; }
; template <int KT, class F> DEVI void cvt_tile(F colptr, int ldsrc, int k0, bf16_t* out, int ldo, int v0, float* tile, int wv) {
;     ...
;       for (int r = 0; r < 8 * KT; ++r) tile[vc * PITCH + r * 8 + kk] = v[r]; }
;     __syncthreads();
;     { const int vc = tid >> 3, k8 = (tid & 7) * 8;
; #pragma unroll
;       for (int q = 0; q < KT; ++q) { const float* tp = tile + vc * PITCH + q * 64 + k8;
;         u32x4 w = {cvtpk(tp[0], tp[1]), cvtpk(tp[2], tp[3]), cvtpk(tp[4], tp[5]), cvtpk(tp[6], tp[7])};
;         *(u32x4*)(out + (size_t)(v0 + vc) * ldo + k0 + q * 64 + k8) = w; } }
;     __syncthreads();
	ds_write2_b32 v3, v0, v9 offset1:8
	ds_write2_b32 v3, v10, v11 offset0:16 offset1:24
	ds_write2_b32 v3, v12, v13 offset0:32 offset1:40
	ds_write2_b32 v3, v14, v15 offset0:48 offset1:56
	ds_write2_b32 v3, v16, v17 offset0:64 offset1:72
	ds_write2_b32 v3, v18, v19 offset0:80 offset1:88
	ds_write2_b32 v3, v20, v21 offset0:96 offset1:104
	ds_write2_b32 v3, v22, v23 offset0:112 offset1:120
	ds_write2_b32 v3, v24, v25 offset0:128 offset1:136
	ds_write2_b32 v3, v26, v27 offset0:144 offset1:152
	ds_write2_b32 v3, v28, v29 offset0:160 offset1:168
	ds_write2_b32 v3, v30, v31 offset0:176 offset1:184
	ds_write2_b32 v3, v32, v33 offset0:192 offset1:200
	ds_write2_b32 v3, v34, v35 offset0:208 offset1:216
	ds_write2_b32 v3, v36, v37 offset0:224 offset1:232
	ds_write2_b32 v3, v4, v2 offset0:240 offset1:248
	v_lshlrev_b32_e32 v2, 3, v6
	v_ashrrev_i32_e32 v0, 3, v6
	v_and_b32_e32 v4, 56, v2
	v_mul_lo_u32 v2, v0, s43
	v_lshlrev_b32_e32 v3, 2, v4
	v_add3_u32 v10, 0, v2, v3
	s_lshl_b32 s7, s7, 1
	v_add_u32_e32 v2, s6, v0
	s_add_u32 s76, s72, s7
	v_ashrrev_i32_e32 v3, 31, v2
	s_addc_u32 s77, s73, 0
	v_lshlrev_b64 v[2:3], 11, v[2:3]
	v_add_u32_e32 v5, 0x8000, v10
	v_lshl_add_u64 v[2:3], s[76:77], 0, v[2:3]
	v_lshlrev_b32_e32 v0, 1, v4
	s_waitcnt lgkmcnt(0)
	s_barrier
	v_lshl_add_u64 v[6:7], v[2:3], 0, v[0:1]
	ds_read2_b32 v[2:3], v5 offset1:1
	v_add_u32_e32 v0, 0x8008, v10
	s_waitcnt lgkmcnt(0)
	v_cvt_pk_bf16_f32 v2, v2, v3
	ds_read2_b32 v[4:5], v0 offset1:1
	v_add_u32_e32 v0, 0x8010, v10
	s_waitcnt lgkmcnt(0)
	v_cvt_pk_bf16_f32 v3, v4, v5
	ds_read2_b32 v[4:5], v0 offset1:1
	v_add_u32_e32 v0, 0x8018, v10
	s_waitcnt lgkmcnt(0)
	v_cvt_pk_bf16_f32 v4, v4, v5
	ds_read2_b32 v[8:9], v0 offset1:1
	s_waitcnt lgkmcnt(0)
	v_cvt_pk_bf16_f32 v5, v8, v9
	global_store_dwordx4 v[6:7], v[2:5], off
	v_add_u32_e32 v0, 0x8100, v10
	ds_read2_b32 v[2:3], v0 offset1:1
	v_add_u32_e32 v0, 0x8108, v10
	s_waitcnt lgkmcnt(0)
	v_cvt_pk_bf16_f32 v2, v2, v3
	ds_read2_b32 v[4:5], v0 offset1:1
	v_add_u32_e32 v0, 0x8110, v10
	s_waitcnt lgkmcnt(0)
	v_cvt_pk_bf16_f32 v3, v4, v5
	ds_read2_b32 v[4:5], v0 offset1:1
	v_add_u32_e32 v0, 0x8118, v10
	s_waitcnt lgkmcnt(0)
	v_cvt_pk_bf16_f32 v4, v4, v5
	ds_read2_b32 v[8:9], v0 offset1:1
	s_waitcnt lgkmcnt(0)
	v_cvt_pk_bf16_f32 v5, v8, v9
	global_store_dwordx4 v[6:7], v[2:5], off offset:128
	v_add_u32_e32 v0, 0x8200, v10
	ds_read2_b32 v[2:3], v0 offset1:1
	v_add_u32_e32 v0, 0x8208, v10
	s_waitcnt lgkmcnt(0)
	v_cvt_pk_bf16_f32 v2, v2, v3
	ds_read2_b32 v[4:5], v0 offset1:1
	v_add_u32_e32 v0, 0x8210, v10
	s_waitcnt lgkmcnt(0)
	v_cvt_pk_bf16_f32 v3, v4, v5
	ds_read2_b32 v[4:5], v0 offset1:1
	v_add_u32_e32 v0, 0x8218, v10
	s_waitcnt lgkmcnt(0)
	v_cvt_pk_bf16_f32 v4, v4, v5
	ds_read2_b32 v[8:9], v0 offset1:1
	s_waitcnt lgkmcnt(0)
	v_cvt_pk_bf16_f32 v5, v8, v9
	global_store_dwordx4 v[6:7], v[2:5], off offset:256
	v_add_u32_e32 v0, 0x8300, v10
	ds_read2_b32 v[2:3], v0 offset1:1
	v_add_u32_e32 v0, 0x8308, v10
	s_waitcnt lgkmcnt(0)
	v_cvt_pk_bf16_f32 v2, v2, v3
	ds_read2_b32 v[4:5], v0 offset1:1
	v_add_u32_e32 v0, 0x8310, v10
	s_waitcnt lgkmcnt(0)
	v_cvt_pk_bf16_f32 v3, v4, v5
	ds_read2_b32 v[4:5], v0 offset1:1
	v_add_u32_e32 v0, 0x8318, v10
	s_waitcnt lgkmcnt(0)
	v_cvt_pk_bf16_f32 v4, v4, v5
	ds_read2_b32 v[8:9], v0 offset1:1
	s_waitcnt lgkmcnt(0)
	v_cvt_pk_bf16_f32 v5, v8, v9
	global_store_dwordx4 v[6:7], v[2:5], off offset:384
	s_waitcnt lgkmcnt(0)
	s_barrier
	s_branch .LBB0_99

; #define RNN_LOAD(j_) do { const int b_ = (j_) >> 7, t0_ = ((j_) & 127) * 128; _Pragma("unroll") for (int k = 0; k < 4; ++k) { const int s_ = t0_ + tok - 3 + k; \
;         const bf16_t* p_ = xr + ((size_t)b_ * SEQ + (s_ < 0 ? 0 : s_)) * DM + ch0 + cg4; xw[2 * k] = *(const u32x4*)p_; xw[2 * k + 1] = *(const u32x4*)(p_ + 8); } } while (0)
; DEVI void rnn_local_phase(const bf16_t* xr, const float* convw, const float* convb, const bf16_t* lruT, const float* ba, const float* bx, const float* lam,
;                           bf16_t* hloc, bf16_t* pcum, float* aggA, float* aggH, char* lds, int wv) {
;     ...
;     if (tid < 320) cwL[tid] = tid < 256 ? convw[(tid >> 6) * 1024 + ch0 + (tid & 63)] : convb[ch0 + (tid & 63)];
;     const int l16 = lane & 15, q4 = lane >> 4;
;     bf16_t* WtL = (bf16_t*)(cwL + 320);
;     { const bf16_t* Wt = lruT + cb * 8192;
; #pragma unroll
;       for (int i = 0; i < 2; ++i) { const int e = tid + i * 512, r = e >> 3, c8 = (e & 7) * 8; *(u32x4*)(WtL + r * 72 + c8) = *(const u32x4*)(Wt + r * 64 + c8); } }
;     float bav[4], bxv[4], sp8[4];
; #pragma unroll
;     for (int cg = 0; cg < 4; ++cg) { const int ch = cg * 16 + l16; bav[cg] = ba[ch0 + ch]; bxv[cg] = bx[ch0 + ch]; const float lm = lam[ch0 + ch];
;         sp8[cg] = 8.f * (fmaxf(-lm, 0.f) + __logf(1.f + __expf(-fabsf(lm)))); }
;     const int tok = tid >> 2, cg4 = (tid & 3) * 16;
;     u32x4 xw[8];
;     ...
;     int j = slot;
;     if (j < 256) RNN_LOAD(j);
.LBB0_116:
	s_or_b64 exec, exec, s[78:79]
	s_ashr_i32 s60, s81, 4
	s_lshl_b64 s[8:9], s[34:35], 2
	s_waitcnt lgkmcnt(0)
	s_add_u32 s10, s24, s8
	s_addc_u32 s11, s25, s9
	s_add_u32 s4, s4, s8
	s_addc_u32 s5, s5, s9
	s_add_u32 s6, s6, s8
	s_addc_u32 s7, s7, s9
	s_lshl_b32 s8, s82, 14
	v_readlane_b32 s9, v255, 29
	s_add_u32 s8, s9, s8
	v_readlane_b32 s9, v255, 30
	v_lshlrev_b32_e32 v18, 4, v7
	v_ashrrev_i32_e32 v5, 3, v7
	s_addc_u32 s9, s9, 0
	v_and_b32_e32 v0, 0x70, v18
	v_lshlrev_b32_e32 v2, 6, v5
	v_lshl_add_u64 v[12:13], s[8:9], 0, v[0:1]
	v_ashrrev_i32_e32 v3, 31, v2
	v_lshl_add_u64 v[2:3], v[2:3], 1, v[12:13]
	global_load_dwordx4 v[8:11], v[2:3], off
	v_and_b32_e32 v2, 15, v7
	v_add_u32_e32 v3, 0x200, v7
	v_ashrrev_i32_e32 v19, 3, v3
	v_or_b32_e32 v3, s77, v2
	v_lshlrev_b32_e32 v3, 2, v3
	global_load_dword v149, v3, s[10:11]
	global_load_dword v150, v3, s[10:11] offset:64
	global_load_dword v151, v3, s[10:11] offset:128
	global_load_dword v152, v3, s[4:5]
	global_load_dword v153, v3, s[4:5] offset:64
	global_load_dword v154, v3, s[4:5] offset:128
	global_load_dword v155, v3, s[4:5] offset:192
	global_load_dword v156, v3, s[10:11] offset:192
	v_readlane_b32 s8, v255, 3
	v_lshlrev_b32_e32 v14, 6, v19
	s_movk_i32 s24, 0x90
	v_add_u32_e32 v0, s8, v0
	v_mad_u64_u32 v[16:17], s[8:9], v5, s24, v[0:1]
	v_ashrrev_i32_e32 v15, 31, v14
	v_lshl_add_u64 v[12:13], v[14:15], 1, v[12:13]
	v_mad_u64_u32 v[14:15], s[4:5], v19, s24, v[0:1]
	s_cmpk_lt_i32 s60, 0x100
	v_ashrrev_i32_e32 v157, 2, v7
	s_cselect_b64 s[4:5], -1, 0
	s_cmpk_gt_i32 s60, 0xff
	s_waitcnt vmcnt(0) lgkmcnt(0)
	ds_write_b128 v16, v[8:11]
	global_load_dwordx4 v[10:13], v[12:13], off
	s_nop 0
	global_load_dword v9, v3, s[6:7]
	global_load_dword v8, v3, s[6:7] offset:64
	global_load_dword v6, v3, s[6:7] offset:128
	global_load_dword v5, v3, s[6:7] offset:192
	v_and_b32_e32 v3, 48, v18
	v_lshlrev_b32_e32 v0, 1, v3
	s_waitcnt vmcnt(0) lgkmcnt(0)
	ds_write_b128 v14, v[10:13]
	s_cbranch_scc1 .LBB0_118
	s_lshl_b32 s7, s60, 7
	s_ashr_i32 s6, s81, 11
	s_and_b32 s7, s7, 0x3f80
	v_add_u32_e32 v7, s7, v157
	s_ashr_i32 s7, s6, 31
	s_lshl_b64 s[6:7], s[6:7], 25
	s_add_u32 s6, s72, s6
	s_addc_u32 s7, s73, s7
	s_lshl_b32 s8, s77, 1
	v_add_u32_e32 v14, -3, v7
	s_add_u32 s6, s6, s8
	s_addc_u32 s7, s7, 0
	v_max_i32_e32 v12, 0, v14
	v_mov_b32_e32 v13, v1
	v_lshl_add_u64 v[10:11], s[6:7], 0, v[0:1]
	v_lshlrev_b64 v[12:13], 11, v[12:13]
	v_lshl_add_u64 v[12:13], v[10:11], 0, v[12:13]
	global_load_dwordx4 v[62:65], v[12:13], off
	global_load_dwordx4 v[46:49], v[12:13], off offset:16
	v_max_i32_e32 v12, -1, v14
	v_add_u32_e32 v12, 1, v12
	v_mov_b32_e32 v13, v1
	v_lshlrev_b64 v[12:13], 11, v[12:13]
	v_lshl_add_u64 v[12:13], v[10:11], 0, v[12:13]
	global_load_dwordx4 v[58:61], v[12:13], off
	global_load_dwordx4 v[42:45], v[12:13], off offset:16
	v_max_i32_e32 v12, -2, v14
	v_add_u32_e32 v12, 2, v12
	v_mov_b32_e32 v13, v1
	v_lshlrev_b64 v[12:13], 11, v[12:13]
	v_lshl_add_u64 v[12:13], v[10:11], 0, v[12:13]
	global_load_dwordx4 v[54:57], v[12:13], off
	global_load_dwordx4 v[38:41], v[12:13], off offset:16
	v_max_i32_e32 v12, 0, v7
	v_mov_b32_e32 v13, v1
	v_lshlrev_b64 v[12:13], 11, v[12:13]
	v_lshl_add_u64 v[10:11], v[10:11], 0, v[12:13]
	global_load_dwordx4 v[50:53], v[10:11], off
	global_load_dwordx4 v[34:37], v[10:11], off offset:16

; DEVI int ltid(int wv) { int t = (wv << 6) | (int)__builtin_amdgcn_mbcnt_hi(~0u, __builtin_amdgcn_mbcnt_lo(~0u, 0u)); asm volatile("" : "+v"(t)); return t; }
; DEVI int lbid() { int t = blockIdx.x; asm volatile("" : "+s"(t)); return t; }
; DEVI int lgrid() { int t = gridDim.x; asm volatile("" : "+s"(t)); return t; }
; #define PG8_LAS __attribute__((address_space(3)))
; #define VMW() asm volatile("s_waitcnt vmcnt(0)" ::: "memory")
; #define SWRITE_HK(bf) do { *(bf16x8*)(K_lds + (bf) * SHM_K + kws) = S.st_k0; *(bf16x8*)(K_lds + (bf) * SHM_K + kws + 32 * 256) = S.st_k1; } while (0)
; DEVI void prime(const BlockRef& cur, char* lds, Seam& S, int wv) {
;     const int tid = ltid(wv), wid = __builtin_amdgcn_readfirstlane(tid >> 6), lane = tid & 63, r32 = lane & 31, hi = lane >> 5;
;     const int sr = tid >> 4, sc = (tid & 15) * 8, kws = KSWZ(sr, sc * 2); char* K_lds = lds + 2 * SHM_V; PG8_LAS unsigned char* biasD = (PG8_LAS unsigned char*)(lds + OFF_BIAS);
;     const int kb0 = (cur.P0 / KVBLK + QB / KVBLK - 1) * KVBLK;
;     for (int d0 = 0; d0 < 8; ++d0) S.qr[d0] = ld8(cur.Q + (size_t)(wid * QBLK + r32) * RS + d0 * 16 + hi * 8);
;     SLOAD_H(cur.K, cur.V, cur.C, kb0, 0); VMW(); SWRITE_HK(0);
; DEVI void phase(const bf16_t* Qb, const bf16_t* Kb, const bf16_t* Vb, bf16_t* Ob, const float* cs, const int* jlo, char* lds, int wv) {
;     const int total = 16 * 64, stride = lgrid();
;     const int bid_ = lbid();
;     int L = (stride % 8 == 0) ? (bid_ % 8) * (stride / 8) + bid_ / 8 : bid_; if (L >= total) return;
;     BlockRef cur = mkref(L, Qb, Kb, Vb, Ob, cs, jlo);
;     Seam S;
;     prime(cur, lds, S, wv);
;     for (;;) {
.Lmy_att_prio:
	s_ashr_i32 s4, s10, 9
	s_ashr_i32 s8, s10, 6
	s_ashr_i32 s5, s4, 31
	s_lshl_b32 s6, s10, 8
	s_and_b32 s90, s6, 0x3f00
	s_lshl_b64 s[6:7], s[4:5], 24
	s_lshl_b32 s5, s8, 7
	s_lshl_b32 s4, s90, 10
	s_and_b32 s9, s5, 0x380
	s_or_b32 s4, s9, s4
	s_or_b32 s4, s6, s4
	s_mov_b32 s5, s7
	s_or_b32 s6, s6, s9
	s_lshl_b64 s[4:5], s[4:5], 1
	s_add_u32 s18, s68, s4
	s_addc_u32 s19, s69, s5
	s_lshl_b64 s[20:21], s[6:7], 1
	s_add_u32 s6, s14, s20
	s_addc_u32 s7, s15, s21
	s_add_u32 s94, s22, s20
	s_addc_u32 s95, s23, s21
	s_ashr_i32 s9, s8, 31
	s_lshl_b64 s[8:9], s[8:9], 16
	s_add_u32 s8, s59, s8
	s_addc_u32 s9, s76, s9
	s_ashr_i32 s11, s10, 31
	s_lshl_b64 s[20:21], s[10:11], 2
	s_add_u32 s20, s16, s20
	s_addc_u32 s21, s17, s21
	v_mov_b64_e32 v[2:3], s[20:21]
	global_load_dword v223, v[2:3], off
	v_mov_b32_e32 v2, v217
	s_nop 0
	v_readfirstlane_b32 s11, v2
	s_ashr_i32 s20, s11, 1
	v_mov_b32_e32 v0, s20
	s_movk_i32 s20, 0xffe0
	v_bfi_b32 v4, s20, v0, v2
	v_ashrrev_i32_e32 v5, 31, v4
	v_lshlrev_b64 v[4:5], 11, v[4:5]
	v_lshrrev_b32_e32 v0, 1, v2
	v_lshl_add_u64 v[4:5], s[18:19], 0, v[4:5]
	v_and_b32_e32 v0, 16, v0
	v_lshl_add_u64 v[4:5], v[4:5], 0, v[0:1]
	v_ashrrev_i32_e32 v3, 4, v2
	global_load_dwordx4 v[172:175], v[4:5], off
	global_load_dwordx4 v[168:171], v[4:5], off offset:32
	global_load_dwordx4 v[164:167], v[4:5], off offset:64
	global_load_dwordx4 v[160:163], v[4:5], off offset:96
	global_load_dwordx4 v[156:159], v[4:5], off offset:128
	global_load_dwordx4 v[152:155], v[4:5], off offset:160
	global_load_dwordx4 v[148:151], v[4:5], off offset:192
	global_load_dwordx4 v[144:147], v[4:5], off offset:224
	v_add_u32_e32 v4, s90, v3
	v_add_u32_e32 v4, 0xc0, v4
	v_lshlrev_b32_e32 v6, 3, v2
	v_ashrrev_i32_e32 v5, 31, v4
	v_and_b32_e32 v0, 0x78, v6
	v_lshlrev_b64 v[4:5], 11, v[4:5]
	s_mov_b64 s[20:21], 0x10000
	v_lshl_add_u64 v[6:7], s[94:95], 0, v[4:5]
	v_lshlrev_b32_e32 v0, 1, v0
	v_lshl_add_u64 v[8:9], v[4:5], 0, s[20:21]
	v_lshl_add_u64 v[6:7], v[6:7], 0, v[0:1]
	v_lshl_add_u64 v[10:11], s[94:95], 0, v[8:9]
	v_lshl_add_u64 v[4:5], s[6:7], 0, v[4:5]
	v_lshl_add_u64 v[10:11], v[10:11], 0, v[0:1]
	global_load_dwordx4 v[112:115], v[6:7], off
	global_load_dwordx4 v[116:119], v[10:11], off
	v_lshl_add_u64 v[4:5], v[4:5], 0, v[0:1]
	v_lshl_add_u64 v[6:7], s[6:7], 0, v[8:9]
	v_lshl_add_u64 v[6:7], v[6:7], 0, v[0:1]
	global_load_dwordx4 v[120:123], v[4:5], off
	global_load_dwordx4 v[124:127], v[6:7], off
	s_cmp_gt_u32 s11, 63
	s_cbranch_scc1 .LBB0_200
	s_lshl_b32 s11, s90, 2
	s_add_u32 s20, s8, s11
	v_and_b32_e32 v4, 63, v2
	s_addc_u32 s21, s9, 0
	v_lshlrev_b32_e32 v4, 2, v4
	v_mov_b32_e32 v5, v1
	v_lshl_add_u64 v[4:5], s[20:21], 0, v[4:5]
	s_mov_b64 s[20:21], 0x300
	v_lshl_add_u64 v[4:5], v[4:5], 0, s[20:21]
	s_mov_b64 s[20:21], src_shared_base
	s_cmp_lg_u32 0, -1
	s_cselect_b32 s20, 0, 0
	s_cselect_b32 s11, s21, 0
	s_add_u32 s20, s20, 0x10800
	s_addc_u32 s21, s11, 0
	s_cmp_lg_u64 s[20:21], 0
	s_cselect_b32 m0, s20, -1
	s_nop 0
	global_load_lds_dword v[4:5], off

; DEVI int ltid(int wv) { int t = (wv << 6) | (int)__builtin_amdgcn_mbcnt_hi(~0u, __builtin_amdgcn_mbcnt_lo(~0u, 0u)); asm volatile("" : "+v"(t)); return t; }
; #define PG8_LAS __attribute__((address_space(3)))
; #define SBAR() __builtin_amdgcn_sched_barrier(0)
; DEVI int v_st(int k, int c) { const int kk = (k & ~0xC) | ((k & 4) << 1) | ((k & 8) >> 1); return ((kk >> 3) * 4 + (c >> 5)) * 512 + ((kk & 7) * 32 + (c & 31)) * 2; }
; DEVI int v_rd_base(int lane) { return ((lane & 3) << 3) | (((lane >> 2) & 3) << 6) | (((lane >> 4) & 1) << 5) | (((lane >> 5) & 1) << 8); }
; #define SWRITE_HV(bf) do { *(bf16x8*)(V_lds + (bf) * SHM_V + vst0) = S.st_v0; *(bf16x8*)(V_lds + (bf) * SHM_V + vst1) = S.st_v1; } while (0)
; DEVI void block(const BlockRef& cur, const BlockRef& nxt, char* lds, Seam& S, int wv) {
;     const int tid = ltid(wv), wid = __builtin_amdgcn_readfirstlane(tid >> 6), lane = tid & 63, r32 = lane & 31, hi = lane >> 5;
;     const int j_lo = cur.jlo;
;     const int j_hi = (cur.P0 + QB - 1) / KVBLK + 1;
;     const int NT = j_hi - j_lo;
;     const int kbn = (nxt.P0 / KVBLK + QB / KVBLK - 1) * KVBLK;
;     const int qlo = cur.P0 + wid * QBLK, qm = qlo + r32 - 4 * hi;
;     char* V_lds = lds; char* K_lds = lds + 2 * SHM_V;
;     float* ws = (float*)(lds + OFF_WS) + wid * 64; float* li_l = ws, * al_l = ws + 32;
;     PG8_LAS unsigned char* biasD = (PG8_LAS unsigned char*)(lds + OFF_BIAS); const char* biasb = lds + OFF_BIAS;
;     float m_reg = -1e30f, l_reg = 0; f32x16 o[4] = {};
;     const int sr = tid >> 4, sc = (tid & 15) * 8, vst0 = v_st(sr, sc), vst1 = v_st(32 + sr, sc), kws = KSWZ(sr, sc * 2);
;     const int vb0 = (int)(uintptr_t)V_lds + v_rd_base(lane);
;     const bf16_t* Kh = cur.K; const bf16_t* Vh = cur.V; const float* Ch = cur.C;
;     ...
;     constexpr int NQL = 8;
;     ...
;     f32x16 pA0, pA1, pB0, pB1; float mnA, mnB, alA, alB; bf16x8 pa0, pa1, pa2, pa3;
;     SWRITE_HV(0); SBAR();
;     if (NT > 1) { SLOAD_H(Kh, Vh, Ch, KBASE(1), 1); }
.LBB0_202:
	s_add_i32 s10, s10, s77
	s_cmpk_gt_i32 s10, 0x3ff
	s_cselect_b64 s[82:83], -1, 0
	s_and_b64 vcc, exec, s[82:83]
	s_mov_b32 s84, s90
	s_cbranch_vccnz .LBB0_204
	s_ashr_i32 s4, s10, 6
	s_lshl_b32 s5, s10, 8
	s_ashr_i32 s18, s10, 9
	s_and_b32 s84, s5, 0x3f00
	s_lshl_b32 s11, s4, 7
	s_ashr_i32 s19, s18, 31
	s_lshl_b32 s5, s84, 10
	s_and_b32 s11, s11, 0x380
	s_lshl_b64 s[24:25], s[18:19], 24
	s_or_b32 s5, s11, s5
	s_or_b32 s18, s24, s5
	s_mov_b32 s19, s25
	s_or_b32 s24, s24, s11
	s_lshl_b64 s[20:21], s[18:19], 1
	s_add_u32 s18, s68, s20
	s_addc_u32 s19, s69, s21
	s_add_u32 s20, s64, s20
	s_addc_u32 s21, s65, s21
	s_lshl_b64 s[60:61], s[24:25], 1
	s_add_u32 s24, s14, s60
	s_addc_u32 s25, s15, s61
	s_add_u32 s78, s22, s60
	s_addc_u32 s79, s23, s61
	s_ashr_i32 s5, s4, 31
	s_lshl_b64 s[4:5], s[4:5], 16
	s_add_u32 s80, s59, s4
	s_addc_u32 s81, s76, s5
	s_ashr_i32 s11, s10, 31
	s_lshl_b64 s[4:5], s[10:11], 2
	s_add_u32 s4, s16, s4
	s_addc_u32 s5, s17, s5
	v_mov_b64_e32 v[2:3], s[4:5]
	global_load_dword v218, v[2:3], off
.LBB0_204:
	v_mov_b32_e32 v219, v217
	s_lshr_b32 s4, s90, 6
	v_ashrrev_i32_e32 v201, 4, v219
	v_and_b32_e32 v3, 0xfffff0, v201
	v_lshlrev_b32_e32 v4, 1, v201
	v_and_or_b32 v3, v4, 8, v3
	v_lshrrev_b32_e32 v4, 1, v201
	v_and_b32_e32 v5, 3, v201
	v_add_u32_e32 v229, 32, v201
	v_and_or_b32 v4, v4, 4, v5
	v_and_b32_e32 v5, 0xfffff0, v229
	v_lshlrev_b32_e32 v6, 1, v229
	v_lshlrev_b32_e32 v0, 3, v219
	v_and_or_b32 v5, v6, 8, v5
	v_and_b32_e32 v2, 0x78, v0
	v_lshrrev_b32_e32 v3, 1, v3
	v_bfe_u32 v0, v0, 5, 2
	v_lshrrev_b32_e32 v5, 1, v5
	v_or_b32_e32 v3, v3, v0
	v_lshlrev_b32_e32 v202, 1, v2
	v_or_b32_e32 v0, v5, v0
	s_or_b32 s4, s4, 3
	v_lshlrev_b32_e32 v3, 9, v3
	v_lshlrev_b32_e32 v4, 6, v4
	v_and_b32_e32 v2, 48, v202
	v_lshlrev_b32_e32 v0, 9, v0
	v_sub_u32_e32 v231, s4, v223
	v_or3_b32 v3, v3, v4, v2
	v_or3_b32 v0, v0, v4, v2
	v_readfirstlane_b32 s85, v219
	v_and_b32_e32 v220, 63, v219
	v_add_u32_e32 v235, 1, v231
	v_add_u32_e32 v236, 0, v3
	v_add_u32_e32 v237, 0, v0
	ds_write_b128 v236, v[112:115]
	ds_write_b128 v237, v[116:119]
	v_cmp_lt_i32_e32 vcc, 1, v235
	s_lshl_b32 s60, s4, 6
	s_and_saveexec_b64 s[4:5], vcc
	s_cbranch_execz .LBB0_207
	s_sub_i32 s46, s60, 64
	v_add_u32_e32 v2, s46, v201
	v_ashrrev_i32_e32 v3, 31, v2
	v_add_u32_e32 v6, s46, v229
	v_lshlrev_b64 v[2:3], 11, v[2:3]
	v_ashrrev_i32_e32 v7, 31, v6
	v_lshl_add_u64 v[4:5], s[94:95], 0, v[2:3]
	v_mov_b32_e32 v203, v1
	v_lshlrev_b64 v[6:7], 11, v[6:7]
	v_lshl_add_u64 v[4:5], v[4:5], 0, v[202:203]
	v_lshl_add_u64 v[8:9], s[94:95], 0, v[6:7]
	v_lshl_add_u64 v[2:3], s[6:7], 0, v[2:3]
	v_lshl_add_u64 v[8:9], v[8:9], 0, v[202:203]
	global_load_dwordx4 v[112:115], v[4:5], off
	global_load_dwordx4 v[116:119], v[8:9], off
	v_lshl_add_u64 v[2:3], v[2:3], 0, v[202:203]
	v_lshl_add_u64 v[4:5], s[6:7], 0, v[6:7]
	v_lshl_add_u64 v[4:5], v[4:5], 0, v[202:203]
	global_load_dwordx4 v[120:123], v[2:3], off
	global_load_dwordx4 v[124:127], v[4:5], off
	s_cmp_gt_u32 s85, 63
	s_cbranch_scc1 .LBB0_207
	s_lshl_b64 s[88:89], s[46:47], 2
	s_add_u32 s88, s8, s88
	s_addc_u32 s89, s9, s89
	s_cmp_lg_u32 0, -1
	s_mov_b64 s[92:93], src_shared_base
	s_cselect_b32 s46, 0, 0
	s_cselect_b32 s11, s93, 0
	s_add_u32 s92, s46, 0x10800
	s_addc_u32 s93, s11, 0
	s_cmp_lg_u64 s[92:93], 0
	s_cselect_b32 s11, s92, -1
	v_lshlrev_b32_e32 v0, 2, v220
	s_add_i32 m0, s11, 0x100
	s_nop 0
	global_load_lds_dword v0, s[88:89]

; DEVI void finishSM(f32x16& p0, f32x16& p1, float alpha, float& l_reg, bf16x8& pa0, bf16x8& pa1, bf16x8& pa2, bf16x8& pa3) {
;     for (int r = 0; r < 16; ++r) p1[r] = __builtin_amdgcn_exp2f(p1[r]);
;     float ps = 0; for (int r = 0; r < 16; ++r) ps += p0[r]; for (int r = 0; r < 16; ++r) ps += p1[r];
;     { auto rr = __builtin_amdgcn_permlane32_swap(__float_as_uint(ps), __float_as_uint(ps), false, false);
;       ps = __uint_as_float(rr[0]) + __uint_as_float(rr[1]); }
;     l_reg = l_reg * alpha + ps;
;     ...
;     PK4(p0, 0, pa0); PK4(p0, 8, pa1); PK4(p1, 0, pa2); PK4(p1, 8, pa3);
;     ...
; }
; template <int KB>
; DEVI void qkt(f32x16& p0, f32x16& p1, const char* K_lds, const char* biasb0, int r32, int hi, const bf16x8* qr) {
;     int hb_ = hi * 16; asm volatile("" : "+v"(hb_)); const char* biasb = biasb0 + hb_;
; #pragma unroll
;     for (int g = 0; g < 4; ++g) { const f32x4 b0 = *(const f32x4*)(biasb + KB * 256 + g * 32), b1 = *(const f32x4*)(biasb + KB * 256 + 128 + g * 32);
; #pragma unroll
;         for (int i = 0; i < 4; ++i) { p0[4 * g + i] = b0[i]; p1[4 * g + i] = b1[i]; } }
;     const char* kb[4];
; #pragma unroll
;     for (int dd = 0; dd < 4; ++dd) kb[dd] = K_lds + KB * SHM_K + KSWZ(r32, (dd * 16 + hi * 8) * 2);
; #pragma unroll
;     for (int d0 = 0; d0 < 8; ++d0) { const char* a = kb[d0 & 3] + (d0 >> 2) * 128;
;         bf16x8 b0 = *reinterpret_cast<const bf16x8*>(a);
;         bf16x8 b1 = *reinterpret_cast<const bf16x8*>(a + 32 * 256);
;         p0 = __builtin_amdgcn_mfma_f32_32x32x16_bf16(b0, qr[d0], p0, 0, 0, 0);
;         p1 = __builtin_amdgcn_mfma_f32_32x32x16_bf16(b1, qr[d0], p1, 0, 0, 0); }
.LBB0_215:
	v_mov_b32_e32 v2, v200
	s_add_i32 s6, 0, 0x10800
	v_add_u32_e32 v2, s6, v2
	ds_read_b128 v[100:103], v2 offset:256
	ds_read_b128 v[104:107], v2 offset:288
	ds_read_b128 v[84:87], v2 offset:384
	ds_read_b128 v[88:91], v2 offset:416
	ds_read_b128 v[108:111], v2 offset:320
	ds_read_b128 v[92:95], v2 offset:448
	ds_read_b128 v[112:115], v2 offset:352
	ds_read_b128 v[96:99], v2 offset:480
	ds_read_b128 v[2:5], v233 offset:49152
	ds_read_b128 v[6:9], v233 offset:57344
	v_add_f32_e32 v80, 0, v190
	v_add_f32_e32 v80, v192, v80
	s_waitcnt lgkmcnt(1)
	s_waitcnt lgkmcnt(1)
	v_mfma_f32_32x32x16_bf16 v[100:115], v[2:5], v[172:175], v[100:115]
	ds_read_b128 v[2:5], v234 offset:49152
	v_add_f32_e32 v80, v188, v80
	v_add_f32_e32 v80, v191, v80
	v_add_f32_e32 v80, v187, v80
	v_add_f32_e32 v80, v189, v80
	v_add_f32_e32 v80, v185, v80
	v_add_f32_e32 v80, v186, v80
	v_add_f32_e32 v80, v181, v80
	s_waitcnt lgkmcnt(1)
	v_mfma_f32_32x32x16_bf16 v[84:99], v[6:9], v[172:175], v[84:99]
	ds_read_b128 v[6:9], v234 offset:57344
	v_add_f32_e32 v80, v184, v80
	v_add_f32_e32 v80, v178, v80
	v_add_f32_e32 v80, v182, v80
	v_add_f32_e32 v80, v176, v80
	v_add_f32_e32 v80, v183, v80
	v_add_f32_e32 v80, v177, v80
	s_waitcnt lgkmcnt(1)
	v_mfma_f32_32x32x16_bf16 v[100:115], v[2:5], v[168:171], v[100:115]
	ds_read_b128 v[2:5], v232 offset:49152
	v_add_f32_e32 v80, v179, v80
	v_exp_f32_e32 v10, v134
	v_exp_f32_e32 v11, v135
	v_exp_f32_e32 v12, v132
	v_exp_f32_e32 v13, v133
	v_exp_f32_e32 v126, v130
	v_exp_f32_e32 v127, v131
	s_waitcnt lgkmcnt(1)
	v_mfma_f32_32x32x16_bf16 v[84:99], v[6:9], v[168:171], v[84:99]
	ds_read_b128 v[6:9], v232 offset:57344
	v_exp_f32_e32 v128, v128
	v_exp_f32_e32 v129, v129
	s_waitcnt lgkmcnt(1)
	v_mfma_f32_32x32x16_bf16 v[100:115], v[2:5], v[164:167], v[100:115]
	ds_read_b128 v[2:5], v230 offset:49152
	s_waitcnt lgkmcnt(1)
	v_mfma_f32_32x32x16_bf16 v[84:99], v[6:9], v[164:167], v[84:99]
	ds_read_b128 v[6:9], v230 offset:57344
	s_waitcnt lgkmcnt(1)
	v_mfma_f32_32x32x16_bf16 v[100:115], v[2:5], v[160:163], v[100:115]
	ds_read_b128 v[2:5], v233 offset:49280
	s_waitcnt lgkmcnt(1)
	v_mfma_f32_32x32x16_bf16 v[84:99], v[6:9], v[160:163], v[84:99]
	ds_read_b128 v[6:9], v233 offset:57472
	s_waitcnt lgkmcnt(1)
	v_mfma_f32_32x32x16_bf16 v[100:115], v[2:5], v[156:159], v[100:115]
	ds_read_b128 v[2:5], v234 offset:49280
	s_waitcnt lgkmcnt(1)
	v_mfma_f32_32x32x16_bf16 v[84:99], v[6:9], v[156:159], v[84:99]
	ds_read_b128 v[6:9], v234 offset:57472
	s_waitcnt lgkmcnt(1)
	v_mfma_f32_32x32x16_bf16 v[100:115], v[2:5], v[152:155], v[100:115]
	ds_read_b128 v[2:5], v232 offset:49280
	s_waitcnt lgkmcnt(1)
	v_mfma_f32_32x32x16_bf16 v[84:99], v[6:9], v[152:155], v[84:99]
	ds_read_b128 v[6:9], v232 offset:57472
	s_waitcnt lgkmcnt(1)
	v_mfma_f32_32x32x16_bf16 v[100:115], v[2:5], v[148:151], v[100:115]
	ds_read_b128 v[2:5], v230 offset:49280
	s_waitcnt lgkmcnt(1)
	v_mfma_f32_32x32x16_bf16 v[84:99], v[6:9], v[148:151], v[84:99]
	ds_read_b128 v[6:9], v230 offset:57472
	s_waitcnt lgkmcnt(1)
	v_mfma_f32_32x32x16_bf16 v[100:115], v[2:5], v[144:147], v[100:115]
	v_exp_f32_e32 v2, v142
	v_exp_f32_e32 v3, v143
	v_exp_f32_e32 v4, v140
	v_exp_f32_e32 v5, v141
	v_add_f32_e32 v80, v2, v80
	v_add_f32_e32 v80, v3, v80
	v_add_f32_e32 v80, v4, v80
	s_waitcnt lgkmcnt(0)
	v_mfma_f32_32x32x16_bf16 v[84:99], v[6:9], v[144:147], v[84:99]
	v_exp_f32_e32 v6, v138
	v_exp_f32_e32 v7, v139
	v_exp_f32_e32 v8, v136
	v_exp_f32_e32 v9, v137
	v_add_f32_e32 v80, v5, v80
	v_add_f32_e32 v80, v6, v80
	v_add_f32_e32 v80, v7, v80
	v_add_f32_e32 v80, v8, v80
	v_add_f32_e32 v80, v9, v80
	v_add_f32_e32 v80, v10, v80
	v_add_f32_e32 v80, v11, v80
	v_add_f32_e32 v80, v12, v80
	v_add_f32_e32 v80, v13, v80
	v_add_f32_e32 v80, v126, v80
	v_add_f32_e32 v80, v127, v80
	v_add_f32_e32 v80, v128, v80
	v_add_f32_e32 v205, v129, v80
	v_mov_b32_e32 v239, v205
	v_cvt_pk_bf16_f32 v80, v190, v192
	v_cvt_pk_bf16_f32 v81, v188, v191
	v_cvt_pk_bf16_f32 v82, v187, v189
	v_cvt_pk_bf16_f32 v83, v185, v186
	v_cvt_pk_bf16_f32 v116, v181, v184
	v_cvt_pk_bf16_f32 v117, v178, v182
	v_cvt_pk_bf16_f32 v118, v176, v183
	v_cvt_pk_bf16_f32 v119, v177, v179
	v_cvt_pk_bf16_f32 v120, v2, v3
	v_cvt_pk_bf16_f32 v121, v4, v5
	v_cvt_pk_bf16_f32 v122, v6, v7
	v_cvt_pk_bf16_f32 v123, v8, v9
	v_cvt_pk_bf16_f32 v124, v10, v11
	v_cvt_pk_bf16_f32 v125, v12, v13
	v_cvt_pk_bf16_f32 v126, v126, v127
	v_cvt_pk_bf16_f32 v127, v128, v129
	s_nop 1
	v_permlane32_swap_b32_e32 v205, v239
	v_permlane32_swap_b32_e32 v80, v82
	v_permlane32_swap_b32_e32 v81, v83
	v_permlane32_swap_b32_e32 v116, v118
	v_permlane32_swap_b32_e32 v117, v119
	v_permlane32_swap_b32_e32 v120, v122
	v_permlane32_swap_b32_e32 v121, v123
	v_permlane32_swap_b32_e32 v124, v126
	v_permlane32_swap_b32_e32 v125, v127
	v_add_u32_e32 v210, s90, v201
	v_add_u32_e32 v2, 64, v210
	v_add_u32_e32 v4, 0x60, v210
	v_ashrrev_i32_e32 v3, 31, v2
	v_ashrrev_i32_e32 v5, 31, v4
	v_lshlrev_b64 v[10:11], 11, v[2:3]
	v_lshlrev_b64 v[12:13], 11, v[4:5]
	v_lshl_add_u64 v[2:3], v[14:15], 0, v[10:11]
	v_lshl_add_u64 v[6:7], v[14:15], 0, v[12:13]
	v_lshl_add_u64 v[10:11], v[206:207], 0, v[10:11]
	global_load_dwordx4 v[2:5], v[2:3], off
	s_nop 0
	global_load_dwordx4 v[6:9], v[6:7], off
	v_lshl_add_u64 v[128:129], v[206:207], 0, v[12:13]
	global_load_dwordx4 v[10:13], v[10:11], off
	s_nop 0
	global_load_dwordx4 v[176:179], v[128:129], off
	v_cndmask_b32_e64 v128, 0, 1, s[94:95]
	v_cmp_ne_u32_e64 s[6:7], 1, v128
	s_andn2_b64 vcc, exec, s[94:95]
	s_cbranch_vccnz .LBB0_217
	s_add_i32 s8, s90, 64
	s_ashr_i32 s9, s8, 31
	v_lshl_add_u64 v[128:129], s[8:9], 2, v[208:209]
	s_mov_b64 s[8:9], src_shared_base
	s_cmp_lg_u32 0, -1
	s_cselect_b32 s8, 0, 0
	s_cselect_b32 s9, s9, 0
	s_add_u32 s8, s8, 0x10800
	s_addc_u32 s9, s9, 0
	s_cmp_lg_u64 s[8:9], 0
	s_cselect_b32 m0, s8, -1
	s_nop 0
	global_load_lds_dword v[128:129], off

; DEVI void partialSM(f32x16& p0, f32x16& p1, float& m_reg, float& mn, float& alpha) {
;     float pmax = p0[0]; for (int r = 1; r < 16; ++r) pmax = fmaxf(pmax, p0[r]); for (int r = 0; r < 16; ++r) pmax = fmaxf(pmax, p1[r]);
;     { auto rr = __builtin_amdgcn_permlane32_swap(__float_as_uint(pmax), __float_as_uint(pmax), false, false);
;       pmax = fmaxf(__uint_as_float(rr[0]), __uint_as_float(rr[1])); }
;     constexpr float C2 = 1.4426950408889634f * SCALE;
;     if (__builtin_expect(__all((pmax - m_reg) * SCALE <= THR), 1)) { mn = m_reg; alpha = 1.f; }
;     else { mn = fmaxf(m_reg, pmax); alpha = __builtin_amdgcn_exp2f((m_reg - mn) * C2); m_reg = mn; }
;     const float mnL = -mn * C2;
;     for (int r = 0; r < 16; ++r) p0[r] = fmaf(p0[r], C2, mnL); for (int r = 0; r < 16; ++r) p1[r] = fmaf(p1[r], C2, mnL);
;     for (int r = 0; r < 16; ++r) p0[r] = __builtin_amdgcn_exp2f(p0[r]);
; }
.LBB0_223:
	v_cndmask_b32_e64 v241, v80, v180, s[8:9]
	v_mul_f32_e32 v180, 0xbe0293ee, v241
	v_fmamk_f32 v80, v100, 0x3e0293ee, v180
	v_fmamk_f32 v81, v101, 0x3e0293ee, v180
	v_fmamk_f32 v82, v102, 0x3e0293ee, v180
	v_fmamk_f32 v83, v103, 0x3e0293ee, v180
	v_fmamk_f32 v116, v104, 0x3e0293ee, v180
	v_fmamk_f32 v117, v105, 0x3e0293ee, v180
	v_fmamk_f32 v118, v106, 0x3e0293ee, v180
	v_fmamk_f32 v119, v107, 0x3e0293ee, v180
	v_fmamk_f32 v120, v108, 0x3e0293ee, v180
	v_fmamk_f32 v121, v109, 0x3e0293ee, v180
	v_fmamk_f32 v122, v110, 0x3e0293ee, v180
	v_fmamk_f32 v123, v111, 0x3e0293ee, v180
	v_fmamk_f32 v112, v112, 0x3e0293ee, v180
	v_fmamk_f32 v113, v113, 0x3e0293ee, v180
	v_fmamk_f32 v114, v114, 0x3e0293ee, v180
	v_fmamk_f32 v115, v115, 0x3e0293ee, v180
	v_fmamk_f32 v100, v84, 0x3e0293ee, v180
	v_fmamk_f32 v109, v85, 0x3e0293ee, v180
	v_fmamk_f32 v110, v86, 0x3e0293ee, v180
	v_fmamk_f32 v111, v87, 0x3e0293ee, v180
	v_fmamk_f32 v181, v88, 0x3e0293ee, v180
	v_fmamk_f32 v101, v89, 0x3e0293ee, v180
	v_fmamk_f32 v102, v90, 0x3e0293ee, v180
	v_fmamk_f32 v103, v91, 0x3e0293ee, v180
	v_fmamk_f32 v104, v92, 0x3e0293ee, v180
	v_fmamk_f32 v105, v93, 0x3e0293ee, v180
	v_fmamk_f32 v106, v94, 0x3e0293ee, v180
	v_fmamk_f32 v107, v95, 0x3e0293ee, v180
	v_exp_f32_e32 v80, v80
	v_exp_f32_e32 v81, v81
	v_exp_f32_e32 v82, v82
	v_exp_f32_e32 v83, v83
	v_exp_f32_e32 v84, v116
	v_exp_f32_e32 v85, v117
	v_exp_f32_e32 v86, v118
	v_exp_f32_e32 v87, v119
	v_exp_f32_e32 v88, v120
	v_exp_f32_e32 v89, v121
	v_exp_f32_e32 v90, v122
	v_exp_f32_e32 v91, v123
	v_exp_f32_e32 v92, v112
	v_exp_f32_e32 v93, v113
	v_exp_f32_e32 v94, v114
	v_exp_f32_e32 v95, v115
	v_fmamk_f32 v108, v96, 0x3e0293ee, v180
	v_fmamk_f32 v182, v97, 0x3e0293ee, v180
	v_fmamk_f32 v183, v98, 0x3e0293ee, v180
	v_fmac_f32_e32 v180, 0x3e0293ee, v99
	s_waitcnt lgkmcnt(0)
	s_barrier
; DEVI void finishSM(f32x16& p0, f32x16& p1, float alpha, float& l_reg, bf16x8& pa0, bf16x8& pa1, bf16x8& pa2, bf16x8& pa3) {
;     for (int r = 0; r < 16; ++r) p1[r] = __builtin_amdgcn_exp2f(p1[r]);
;     float ps = 0; for (int r = 0; r < 16; ++r) ps += p0[r]; for (int r = 0; r < 16; ++r) ps += p1[r];
;     { auto rr = __builtin_amdgcn_permlane32_swap(__float_as_uint(ps), __float_as_uint(ps), false, false);
;       ps = __uint_as_float(rr[0]) + __uint_as_float(rr[1]); }
;     l_reg = l_reg * alpha + ps;
;     ...
;     PK4(p0, 0, pa0); PK4(p0, 8, pa1); PK4(p1, 0, pa2); PK4(p1, 8, pa3);
;     ...
; }
; template <int KB>
; DEVI void qkt(f32x16& p0, f32x16& p1, const char* K_lds, const char* biasb0, int r32, int hi, const bf16x8* qr) {
;     int hb_ = hi * 16; asm volatile("" : "+v"(hb_)); const char* biasb = biasb0 + hb_;
; #pragma unroll
;     for (int g = 0; g < 4; ++g) { const f32x4 b0 = *(const f32x4*)(biasb + KB * 256 + g * 32), b1 = *(const f32x4*)(biasb + KB * 256 + 128 + g * 32);
; #pragma unroll
;         for (int i = 0; i < 4; ++i) { p0[4 * g + i] = b0[i]; p1[4 * g + i] = b1[i]; } }
;     const char* kb[4];
; #pragma unroll
;     for (int dd = 0; dd < 4; ++dd) kb[dd] = K_lds + KB * SHM_K + KSWZ(r32, (dd * 16 + hi * 8) * 2);
; #pragma unroll
;     for (int d0 = 0; d0 < 8; ++d0) { const char* a = kb[d0 & 3] + (d0 >> 2) * 128;
;         bf16x8 b0 = *reinterpret_cast<const bf16x8*>(a);
;         bf16x8 b1 = *reinterpret_cast<const bf16x8*>(a + 32 * 256);
;         p0 = __builtin_amdgcn_mfma_f32_32x32x16_bf16(b0, qr[d0], p0, 0, 0, 0);
;         p1 = __builtin_amdgcn_mfma_f32_32x32x16_bf16(b1, qr[d0], p1, 0, 0, 0); }
	v_mov_b32_e32 v96, v200
	v_exp_f32_e32 v101, v101
	v_add_u32_e32 v96, 0, v96
	v_add_u32_e32 v96, 0x10800, v96
	ds_read_b128 v[128:131], v96
	ds_read_b128 v[132:135], v96 offset:32
	ds_read_b128 v[112:115], v96 offset:128
	ds_read_b128 v[116:119], v96 offset:160
	ds_read_b128 v[136:139], v96 offset:64
	ds_read_b128 v[120:123], v96 offset:192
	ds_read_b128 v[140:143], v96 offset:96
	ds_read_b128 v[124:127], v96 offset:224
	ds_read_b128 v[96:99], v233 offset:32768
	ds_read_b128 v[184:187], v233 offset:40960
	v_exp_f32_e32 v102, v102
	v_exp_f32_e32 v103, v103
	s_waitcnt lgkmcnt(1)
	s_waitcnt lgkmcnt(1)
	v_mfma_f32_32x32x16_bf16 v[128:143], v[96:99], v[172:175], v[128:143]
	ds_read_b128 v[96:99], v234 offset:32768
	v_exp_f32_e32 v104, v104
	v_exp_f32_e32 v105, v105
	v_exp_f32_e32 v106, v106
	v_exp_f32_e32 v107, v107
	v_exp_f32_e32 v108, v108
	s_waitcnt lgkmcnt(1)
	v_mfma_f32_32x32x16_bf16 v[112:127], v[184:187], v[172:175], v[112:127]
	ds_read_b128 v[184:187], v234 offset:40960
	s_waitcnt lgkmcnt(1)
	v_mfma_f32_32x32x16_bf16 v[128:143], v[96:99], v[168:171], v[128:143]
	ds_read_b128 v[96:99], v232 offset:32768
	s_waitcnt lgkmcnt(1)
	v_mfma_f32_32x32x16_bf16 v[112:127], v[184:187], v[168:171], v[112:127]
	ds_read_b128 v[184:187], v232 offset:40960
	s_waitcnt lgkmcnt(1)
	v_mfma_f32_32x32x16_bf16 v[128:143], v[96:99], v[164:167], v[128:143]
	ds_read_b128 v[96:99], v230 offset:32768
	s_waitcnt lgkmcnt(1)
	v_mfma_f32_32x32x16_bf16 v[112:127], v[184:187], v[164:167], v[112:127]
	ds_read_b128 v[184:187], v230 offset:40960
	s_waitcnt lgkmcnt(1)
	v_mfma_f32_32x32x16_bf16 v[128:143], v[96:99], v[160:163], v[128:143]
	ds_read_b128 v[96:99], v233 offset:32896
	s_waitcnt lgkmcnt(1)
	v_mfma_f32_32x32x16_bf16 v[112:127], v[184:187], v[160:163], v[112:127]
	ds_read_b128 v[184:187], v233 offset:41088
	s_waitcnt lgkmcnt(1)
	v_mfma_f32_32x32x16_bf16 v[128:143], v[96:99], v[156:159], v[128:143]
	ds_read_b128 v[96:99], v234 offset:32896
	s_waitcnt lgkmcnt(1)
	v_mfma_f32_32x32x16_bf16 v[112:127], v[184:187], v[156:159], v[112:127]
	ds_read_b128 v[184:187], v234 offset:41088
	s_waitcnt lgkmcnt(1)
	v_mfma_f32_32x32x16_bf16 v[128:143], v[96:99], v[152:155], v[128:143]
	ds_read_b128 v[96:99], v232 offset:32896
	s_waitcnt lgkmcnt(1)
	v_mfma_f32_32x32x16_bf16 v[112:127], v[184:187], v[152:155], v[112:127]
	ds_read_b128 v[184:187], v232 offset:41088
	s_waitcnt lgkmcnt(1)
	v_mfma_f32_32x32x16_bf16 v[128:143], v[96:99], v[148:151], v[128:143]
	ds_read_b128 v[96:99], v230 offset:32896
	s_waitcnt lgkmcnt(1)
	v_mfma_f32_32x32x16_bf16 v[112:127], v[184:187], v[148:151], v[112:127]
	ds_read_b128 v[184:187], v230 offset:41088
	s_waitcnt lgkmcnt(1)
	v_mfma_f32_32x32x16_bf16 v[128:143], v[96:99], v[144:147], v[128:143]
	v_exp_f32_e32 v99, v111
	v_exp_f32_e32 v111, v180
	v_add_f32_e32 v180, 0, v80
	v_add_f32_e32 v180, v81, v180
	v_add_f32_e32 v180, v82, v180
	v_add_f32_e32 v180, v83, v180
	v_add_f32_e32 v180, v84, v180
	v_add_f32_e32 v180, v85, v180
	v_add_f32_e32 v180, v86, v180
	v_add_f32_e32 v180, v87, v180
	v_add_f32_e32 v180, v88, v180
	v_add_f32_e32 v180, v89, v180
	v_add_f32_e32 v180, v90, v180
	v_add_f32_e32 v180, v91, v180
	v_exp_f32_e32 v96, v100
	v_add_f32_e32 v180, v92, v180
	v_exp_f32_e32 v97, v109
	v_add_f32_e32 v180, v93, v180
	v_exp_f32_e32 v98, v110
	v_add_f32_e32 v180, v94, v180
	v_add_f32_e32 v180, v95, v180
	v_exp_f32_e32 v100, v181
	v_add_f32_e32 v180, v96, v180
	v_add_f32_e32 v180, v97, v180
	v_add_f32_e32 v180, v98, v180
	v_add_f32_e32 v180, v99, v180
	v_add_f32_e32 v180, v100, v180
	v_add_f32_e32 v180, v101, v180
	v_add_f32_e32 v180, v102, v180
	v_add_f32_e32 v180, v103, v180
	v_add_f32_e32 v180, v104, v180
	v_exp_f32_e32 v109, v182
	v_add_f32_e32 v180, v105, v180
	s_waitcnt lgkmcnt(0)
	v_mfma_f32_32x32x16_bf16 v[112:127], v[184:187], v[144:147], v[112:127]
	v_exp_f32_e32 v110, v183
	v_add_f32_e32 v180, v106, v180
	v_add_f32_e32 v180, v107, v180
	v_add_f32_e32 v180, v108, v180
	v_add_f32_e32 v180, v109, v180
	v_add_f32_e32 v180, v110, v180
	v_add_f32_e32 v242, v111, v180
	v_mov_b32_e32 v243, v242
	v_cvt_pk_bf16_f32 v180, v80, v81
	v_cvt_pk_bf16_f32 v181, v82, v83
	v_cvt_pk_bf16_f32 v182, v84, v85
	v_cvt_pk_bf16_f32 v183, v86, v87
	v_cvt_pk_bf16_f32 v184, v88, v89
	v_cvt_pk_bf16_f32 v185, v90, v91
	v_cvt_pk_bf16_f32 v186, v92, v93
	v_cvt_pk_bf16_f32 v187, v94, v95
	v_cvt_pk_bf16_f32 v188, v96, v97
	v_cvt_pk_bf16_f32 v189, v98, v99
	v_cvt_pk_bf16_f32 v190, v100, v101
	v_cvt_pk_bf16_f32 v191, v102, v103
	v_cvt_pk_bf16_f32 v192, v104, v105
	v_cvt_pk_bf16_f32 v193, v106, v107
	v_cvt_pk_bf16_f32 v194, v108, v109
	v_cvt_pk_bf16_f32 v195, v110, v111
	s_nop 1
	v_permlane32_swap_b32_e32 v242, v243
	v_permlane32_swap_b32_e32 v180, v182
	v_permlane32_swap_b32_e32 v181, v183
	v_permlane32_swap_b32_e32 v184, v186
	v_permlane32_swap_b32_e32 v185, v187
	v_permlane32_swap_b32_e32 v188, v190
	v_permlane32_swap_b32_e32 v189, v191
	v_permlane32_swap_b32_e32 v192, v194
	v_permlane32_swap_b32_e32 v193, v195
	s_add_i32 s8, s46, 1
	v_cmp_lt_i32_e64 s[8:9], s8, v235
	s_and_saveexec_b64 s[60:61], s[8:9]
	s_cbranch_execz .LBB0_227
	v_add_u32_e32 v4, 32, v210
	v_ashrrev_i32_e32 v211, 31, v210
	v_ashrrev_i32_e32 v5, 31, v4
	v_lshlrev_b64 v[10:11], 11, v[210:211]
	v_lshlrev_b64 v[12:13], 11, v[4:5]
	v_lshl_add_u64 v[2:3], v[14:15], 0, v[10:11]
	v_lshl_add_u64 v[6:7], v[14:15], 0, v[12:13]
	v_lshl_add_u64 v[10:11], v[206:207], 0, v[10:11]
	v_lshl_add_u64 v[176:177], v[206:207], 0, v[12:13]
	global_load_dwordx4 v[2:5], v[2:3], off
	s_nop 0
	global_load_dwordx4 v[6:9], v[6:7], off
	s_nop 0
	global_load_dwordx4 v[10:13], v[10:11], off
	s_nop 0
	global_load_dwordx4 v[176:179], v[176:177], off
	s_and_b64 vcc, exec, s[6:7]
	s_cbranch_vccnz .LBB0_226
	s_ashr_i32 s91, s90, 31
	s_mov_b64 s[6:7], src_shared_base
	s_cmp_lg_u32 0, -1
	s_cselect_b32 s6, 0, 0
	s_cselect_b32 s7, s7, 0
	s_add_u32 s6, s6, 0x10800
	s_addc_u32 s7, s7, 0
	s_cmp_lg_u64 s[6:7], 0
	s_cselect_b32 s6, s6, -1
	v_lshl_add_u64 v[196:197], s[90:91], 2, v[208:209]
	s_add_i32 m0, s6, 0x100
	s_nop 0
	global_load_lds_dword v[196:197], off

; #define SBAR() __builtin_amdgcn_sched_barrier(0)
; template <int VB>
; DEVI void pv_tile(f32x16* o, int vb0, bf16x8 pa0, bf16x8 pa1, bf16x8 pa2, bf16x8 pa3) {
;     ...
;     PV_D0(0); PV_D0(1); PV_D0(2); PV_D0(3);
; DEVI void block(const BlockRef& cur, const BlockRef& nxt, char* lds, Seam& S, int wv) {
;     ...
;     const bool even = (NT & 1) == 0;
;     if (even) { SBAR(); qkt<1>(pB0, pB1, K_lds, biasb, r32, hi, S.qr); SBAR(); }
;     SLOAD_H(nxt.K, nxt.V, nxt.C, kbn, 0); SBAR();
; #pragma unroll
;     for (int d0 = 0; d0 < 8; ++d0) S.qr[d0] = ld8(nxt.Q + (size_t)(wid * QBLK + r32) * RS + d0 * 16 + hi * 8);
;     SBAR();
;     finishSM(pA0, pA1, alA, l_reg, pa0, pa1, pa2, pa3); SBAR();
;     pv_tile<0>(o, vb0, pa0, pa1, pa2, pa3);
.LBB0_237:
	s_or_b64 exec, exec, s[4:5]
	s_or_b32 s4, s84, 0xc0
	v_add_u32_e32 v2, s4, v201
	v_ashrrev_i32_e32 v3, 31, v2
	v_add_u32_e32 v6, s4, v229
	v_lshlrev_b64 v[2:3], 11, v[2:3]
	v_ashrrev_i32_e32 v7, 31, v6
	v_lshl_add_u64 v[4:5], s[78:79], 0, v[2:3]
	v_mov_b32_e32 v203, v215
	v_lshlrev_b64 v[6:7], 11, v[6:7]
	v_lshl_add_u64 v[4:5], v[4:5], 0, v[202:203]
	v_lshl_add_u64 v[8:9], s[78:79], 0, v[6:7]
	v_lshl_add_u64 v[2:3], s[24:25], 0, v[2:3]
	v_lshl_add_u64 v[8:9], v[8:9], 0, v[202:203]
	global_load_dwordx4 v[112:115], v[4:5], off
	global_load_dwordx4 v[116:119], v[8:9], off
	v_lshl_add_u64 v[2:3], v[2:3], 0, v[202:203]
	v_lshl_add_u64 v[4:5], s[24:25], 0, v[6:7]
	v_lshl_add_u64 v[4:5], v[4:5], 0, v[202:203]
	global_load_dwordx4 v[120:123], v[2:3], off
	global_load_dwordx4 v[124:127], v[4:5], off
	v_mov_b32_e32 v1, v215
	s_cmp_gt_u32 s85, 63
	s_cbranch_scc1 .LBB0_239
	s_mov_b32 s85, s47
	s_lshl_b64 s[4:5], s[84:85], 2
	s_add_u32 s4, s80, s4
	s_addc_u32 s5, s81, s5
	v_mov_b32_e32 v205, v1
	v_lshl_add_u64 v[2:3], s[4:5], 0, v[204:205]
	s_mov_b64 s[4:5], 0x300
	v_lshl_add_u64 v[2:3], v[2:3], 0, s[4:5]
	s_mov_b64 s[4:5], src_shared_base
	s_cmp_lg_u32 0, -1
	s_cselect_b32 s4, 0, 0
	s_cselect_b32 s5, s5, 0
	s_add_u32 s4, s4, 0x10800
	s_addc_u32 s5, s5, 0
	s_cmp_lg_u64 s[4:5], 0
	s_cselect_b32 m0, s4, -1
	s_nop 0
	global_load_lds_dword v[2:3], off
.LBB0_239:
	v_or_b32_e32 v2, s88, v222
	v_ashrrev_i32_e32 v3, 31, v2
	v_lshlrev_b64 v[2:3], 11, v[2:3]
	v_lshl_add_u64 v[2:3], s[18:19], 0, v[2:3]
	v_mov_b32_e32 v201, v1
	v_lshl_add_u64 v[2:3], v[2:3], 0, v[200:201]
	global_load_dwordx4 v[172:175], v[2:3], off
	global_load_dwordx4 v[168:171], v[2:3], off offset:32
	global_load_dwordx4 v[164:167], v[2:3], off offset:64
	global_load_dwordx4 v[160:163], v[2:3], off offset:96
	global_load_dwordx4 v[156:159], v[2:3], off offset:128
	global_load_dwordx4 v[152:155], v[2:3], off offset:160
	global_load_dwordx4 v[148:151], v[2:3], off offset:192
	global_load_dwordx4 v[144:147], v[2:3], off offset:224
	v_add_f32_e32 v2, 0, v190
	v_add_f32_e32 v2, v192, v2
	v_add_f32_e32 v2, v188, v2
	v_add_f32_e32 v2, v191, v2
	v_add_f32_e32 v2, v187, v2
	v_add_f32_e32 v2, v189, v2
	v_add_f32_e32 v2, v185, v2
	v_add_f32_e32 v2, v186, v2
	v_add_f32_e32 v2, v181, v2
	v_add_f32_e32 v2, v184, v2
	v_add_f32_e32 v2, v178, v2
	v_add_f32_e32 v2, v182, v2
	v_exp_f32_e32 v3, v142
	v_add_f32_e32 v2, v176, v2
	v_exp_f32_e32 v12, v143
	v_add_f32_e32 v2, v183, v2
	v_exp_f32_e32 v13, v140
	v_add_f32_e32 v2, v177, v2
	v_exp_f32_e32 v14, v141
	v_add_f32_e32 v2, v179, v2
	v_exp_f32_e32 v15, v138
	v_add_f32_e32 v2, v3, v2
	v_exp_f32_e32 v138, v139
	v_add_f32_e32 v2, v12, v2
	v_exp_f32_e32 v136, v136
	v_add_f32_e32 v2, v13, v2
	v_exp_f32_e32 v137, v137
	v_add_f32_e32 v2, v14, v2
	v_exp_f32_e32 v134, v134
	v_add_f32_e32 v2, v15, v2
	v_exp_f32_e32 v135, v135
	v_add_f32_e32 v2, v138, v2
	v_exp_f32_e32 v132, v132
	v_add_f32_e32 v2, v136, v2
	v_exp_f32_e32 v133, v133
	v_add_f32_e32 v2, v137, v2
	v_exp_f32_e32 v130, v130
	v_add_f32_e32 v2, v134, v2
	v_exp_f32_e32 v131, v131
	v_add_f32_e32 v2, v135, v2
	v_exp_f32_e32 v139, v128
	v_add_f32_e32 v2, v132, v2
	v_exp_f32_e32 v140, v129
	v_add_f32_e32 v2, v133, v2
	v_add_f32_e32 v2, v130, v2
	v_add_f32_e32 v2, v131, v2
	v_add_f32_e32 v2, v139, v2
	v_add_f32_e32 v2, v140, v2
	v_mov_b32_e32 v4, v2
	s_nop 1
	v_permlane32_swap_b32_e32 v2, v4
	v_add_f32_e32 v2, v2, v4
	v_fmac_f32_e32 v2, v0, v238
	v_cvt_pk_bf16_f32 v4, v190, v192
	v_cvt_pk_bf16_f32 v5, v188, v191
	v_cvt_pk_bf16_f32 v6, v187, v189
	v_cvt_pk_bf16_f32 v7, v185, v186
	v_cvt_pk_bf16_f32 v8, v181, v184
	v_cvt_pk_bf16_f32 v9, v178, v182
	v_cvt_pk_bf16_f32 v10, v176, v183
	v_cvt_pk_bf16_f32 v11, v177, v179
	v_cvt_pk_bf16_f32 v12, v3, v12
	v_cvt_pk_bf16_f32 v13, v13, v14
	v_cvt_pk_bf16_f32 v14, v15, v138
	v_cvt_pk_bf16_f32 v15, v136, v137
	v_cvt_pk_bf16_f32 v128, v134, v135
	v_cvt_pk_bf16_f32 v129, v132, v133
	v_cvt_pk_bf16_f32 v130, v130, v131
	v_cvt_pk_bf16_f32 v131, v139, v140
	s_nop 0
	v_permlane32_swap_b32_e32 v4, v6
	v_permlane32_swap_b32_e32 v5, v7
	v_permlane32_swap_b32_e32 v8, v10
	v_permlane32_swap_b32_e32 v9, v11
	v_permlane32_swap_b32_e32 v12, v14
	v_permlane32_swap_b32_e32 v13, v15
	v_permlane32_swap_b32_e32 v128, v130
	v_permlane32_swap_b32_e32 v129, v131
	ds_read_b64_tr_b16 v[132:133], v227 offset:0
	ds_read_b64_tr_b16 v[134:135], v227 offset:0x800
	ds_read_b64_tr_b16 v[136:137], v227 offset:0x1000
	ds_read_b64_tr_b16 v[138:139], v227 offset:0x1800
	ds_read_b64_tr_b16 v[140:141], v227 offset:0x2000
	ds_read_b64_tr_b16 v[142:143], v227 offset:0x2800
	ds_read_b64_tr_b16 v[176:177], v227 offset:0x3000
	ds_read_b64_tr_b16 v[178:179], v227 offset:0x3800
	s_nop 0
	s_nop 0
	s_waitcnt lgkmcnt(6)
	v_mfma_f32_32x32x16_bf16 v[64:79], v[4:7], v[132:135], v[64:79]
	ds_read_b64_tr_b16 v[132:133], v227 offset:0x200
	ds_read_b64_tr_b16 v[134:135], v227 offset:0xa00
	s_waitcnt lgkmcnt(6)
	v_mfma_f32_32x32x16_bf16 v[64:79], v[8:11], v[136:139], v[64:79]
	ds_read_b64_tr_b16 v[136:137], v227 offset:0x1200
	ds_read_b64_tr_b16 v[138:139], v227 offset:0x1a00
	s_waitcnt lgkmcnt(6)
	v_mfma_f32_32x32x16_bf16 v[64:79], v[12:15], v[140:143], v[64:79]
	ds_read_b64_tr_b16 v[140:141], v227 offset:0x2200
	ds_read_b64_tr_b16 v[142:143], v227 offset:0x2a00
	s_waitcnt lgkmcnt(6)
	v_mfma_f32_32x32x16_bf16 v[64:79], v[128:131], v[176:179], v[64:79]
	ds_read_b64_tr_b16 v[176:177], v227 offset:0x3200
	ds_read_b64_tr_b16 v[178:179], v227 offset:0x3a00
	s_nop 0
	s_waitcnt lgkmcnt(6)
	v_mfma_f32_32x32x16_bf16 v[48:63], v[4:7], v[132:135], v[48:63]
	ds_read_b64_tr_b16 v[132:133], v227 offset:0x400
	ds_read_b64_tr_b16 v[134:135], v227 offset:0xc00
	s_waitcnt lgkmcnt(6)
; #define RESC(a) do { if (__any((a) < 1.f)) { if (hi == 0) al_l[r32] = (a); asm volatile("s_waitcnt lgkmcnt(0)" ::: "memory");              \
;                      for (int d_ = 0; d_ < 4; ++d_) for (int r = 0; r < 16; ++r) o[d_][r] *= al_l[crow(r, hi)]; } } while (0)
; #define MASKT(P0_, P1_, t) do { const int kb_ = KBASE(t); if (kb_ + KVBLK - 1 > qlo) mask_tile(P0_, P1_, qm - kb_, WBIG); } while (0)
; DEVI void mask_tile(f32x16& p0, f32x16& p1, int dq, unsigned W) {
;     const float NEG = -__builtin_inff();
; #pragma unroll
;     for (int r = 0; r < 16; ++r) {
;         const int c = (r & 3) + 8 * (r >> 2);
;         if ((unsigned)(dq - c) >= W) p0[r] = NEG;
;         if ((unsigned)(dq - c - 32) >= W) p1[r] = NEG;
;     }
; }
; template <int VB>
; DEVI void pv_tile(f32x16* o, int vb0, bf16x8 pa0, bf16x8 pa1, bf16x8 pa2, bf16x8 pa3) {
;     ...
;     PV_D0(0); PV_D0(1); PV_D0(2); PV_D0(3);
; DEVI void block(const BlockRef& cur, const BlockRef& nxt, char* lds, Seam& S, int wv) {
;     ...
;     if (even) { MASKT(pB0, pB1, NT - 1); partialSM(pB0, pB1, m_reg, mnB, alB); __syncthreads(); RESC(alB);
	v_mfma_f32_32x32x16_bf16 v[48:63], v[8:11], v[136:139], v[48:63]
	ds_read_b64_tr_b16 v[136:137], v227 offset:0x1400
	ds_read_b64_tr_b16 v[138:139], v227 offset:0x1c00
	s_waitcnt lgkmcnt(6)
	v_mfma_f32_32x32x16_bf16 v[48:63], v[12:15], v[140:143], v[48:63]
	ds_read_b64_tr_b16 v[140:141], v227 offset:0x2400
	ds_read_b64_tr_b16 v[142:143], v227 offset:0x2c00
	s_waitcnt lgkmcnt(6)
	v_mfma_f32_32x32x16_bf16 v[48:63], v[128:131], v[176:179], v[48:63]
	ds_read_b64_tr_b16 v[176:177], v227 offset:0x3400
	ds_read_b64_tr_b16 v[178:179], v227 offset:0x3c00
	s_nop 0
	s_waitcnt lgkmcnt(6)
	v_mfma_f32_32x32x16_bf16 v[32:47], v[4:7], v[132:135], v[32:47]
	ds_read_b64_tr_b16 v[132:133], v227 offset:0x600
	ds_read_b64_tr_b16 v[134:135], v227 offset:0xe00
	s_waitcnt lgkmcnt(6)
	v_mfma_f32_32x32x16_bf16 v[32:47], v[8:11], v[136:139], v[32:47]
	ds_read_b64_tr_b16 v[136:137], v227 offset:0x1600
	ds_read_b64_tr_b16 v[138:139], v227 offset:0x1e00
	s_waitcnt lgkmcnt(6)
	v_mfma_f32_32x32x16_bf16 v[32:47], v[12:15], v[140:143], v[32:47]
	ds_read_b64_tr_b16 v[140:141], v227 offset:0x2600
	ds_read_b64_tr_b16 v[142:143], v227 offset:0x2e00
	s_waitcnt lgkmcnt(6)
	v_mfma_f32_32x32x16_bf16 v[32:47], v[128:131], v[176:179], v[32:47]
	ds_read_b64_tr_b16 v[176:177], v227 offset:0x3600
	ds_read_b64_tr_b16 v[178:179], v227 offset:0x3e00
	s_nop 0
	s_waitcnt lgkmcnt(6)
	v_mfma_f32_32x32x16_bf16 v[16:31], v[4:7], v[132:135], v[16:31]
	s_waitcnt lgkmcnt(4)
	v_mfma_f32_32x32x16_bf16 v[16:31], v[8:11], v[136:139], v[16:31]
	s_waitcnt lgkmcnt(2)
	v_mfma_f32_32x32x16_bf16 v[16:31], v[12:15], v[140:143], v[16:31]
	s_waitcnt lgkmcnt(0)
	v_mfma_f32_32x32x16_bf16 v[16:31], v[128:131], v[176:179], v[16:31]
	s_and_saveexec_b64 s[6:7], vcc
	s_cbranch_execz .LBB0_247
	v_lshlrev_b32_e32 v0, 6, v223
	v_or_b32_e32 v3, 63, v0
	v_cmp_lt_i32_e32 vcc, s11, v3
	s_and_saveexec_b64 s[4:5], vcc
	s_cbranch_execz .LBB0_242
	v_sub_u32_e32 v0, v228, v0
	v_cmp_gt_u32_e32 vcc, 2.0, v0
	v_add_u32_e32 v3, 0xbfffffe0, v0
	s_nop 0
	v_cndmask_b32_e32 v80, v254, v80, vcc
	v_cmp_lt_u32_e32 vcc, s55, v3
	v_add_u32_e32 v3, 0xbfffffff, v0
	s_nop 0
	v_cndmask_b32_e32 v96, v254, v96, vcc
	v_cmp_lt_u32_e32 vcc, s55, v3
	v_add_u32_e32 v3, 0xbfffffdf, v0
	s_nop 0
	v_cndmask_b32_e32 v81, v254, v81, vcc
	v_cmp_lt_u32_e32 vcc, s55, v3
	v_add_u32_e32 v3, 0xbffffffe, v0
	s_nop 0
	v_cndmask_b32_e32 v97, v254, v97, vcc
	v_cmp_lt_u32_e32 vcc, s55, v3
	v_add_u32_e32 v3, 0xbfffffde, v0
	s_nop 0
	v_cndmask_b32_e32 v82, v254, v82, vcc
	v_cmp_lt_u32_e32 vcc, s55, v3
	v_add_u32_e32 v3, 0xbffffffd, v0
	s_nop 0
	v_cndmask_b32_e32 v98, v254, v98, vcc
	v_cmp_lt_u32_e32 vcc, s55, v3
	v_add_u32_e32 v3, 0xbfffffdd, v0
	s_nop 0
	v_cndmask_b32_e32 v83, v254, v83, vcc
	v_cmp_lt_u32_e32 vcc, s55, v3
	v_add_u32_e32 v3, 0xbffffff8, v0
	s_nop 0
	v_cndmask_b32_e32 v99, v254, v99, vcc
	v_cmp_lt_u32_e32 vcc, s55, v3
	v_add_u32_e32 v3, 0xbfffffd8, v0
	s_nop 0
	v_cndmask_b32_e32 v84, v254, v84, vcc
	v_cmp_lt_u32_e32 vcc, s55, v3
	v_add_u32_e32 v3, 0xbffffff7, v0
	s_nop 0
	v_cndmask_b32_e32 v100, v254, v100, vcc
	v_cmp_lt_u32_e32 vcc, s55, v3
	v_add_u32_e32 v3, 0xbfffffd7, v0
	s_nop 0
	v_cndmask_b32_e32 v85, v254, v85, vcc
	v_cmp_lt_u32_e32 vcc, s55, v3
	v_add_u32_e32 v3, 0xbffffff6, v0
	s_nop 0
	v_cndmask_b32_e32 v101, v254, v101, vcc
	v_cmp_lt_u32_e32 vcc, s55, v3
	v_add_u32_e32 v3, 0xbfffffd6, v0
	s_nop 0
	v_cndmask_b32_e32 v86, v254, v86, vcc
	v_cmp_lt_u32_e32 vcc, s55, v3
	v_add_u32_e32 v3, 0xbffffff5, v0
	s_nop 0
	v_cndmask_b32_e32 v102, v254, v102, vcc
	v_cmp_lt_u32_e32 vcc, s55, v3
	v_add_u32_e32 v3, 0xbfffffd5, v0
	s_nop 0
	v_cndmask_b32_e32 v87, v254, v87, vcc
	v_cmp_lt_u32_e32 vcc, s55, v3
	v_add_u32_e32 v3, 0xbffffff0, v0
	s_nop 0
	v_cndmask_b32_e32 v103, v254, v103, vcc
	v_cmp_lt_u32_e32 vcc, s55, v3
	v_add_u32_e32 v3, 0xbfffffd0, v0
	s_nop 0
	v_cndmask_b32_e32 v88, v254, v88, vcc
	v_cmp_lt_u32_e32 vcc, s55, v3
	v_add_u32_e32 v3, 0xbfffffef, v0
	s_nop 0
	v_cndmask_b32_e32 v104, v254, v104, vcc
	v_cmp_lt_u32_e32 vcc, s55, v3
	v_add_u32_e32 v3, 0xbfffffcf, v0
	s_nop 0
	v_cndmask_b32_e32 v89, v254, v89, vcc
	v_cmp_lt_u32_e32 vcc, s55, v3
	v_add_u32_e32 v3, 0xbfffffee, v0
	s_nop 0
	v_cndmask_b32_e32 v105, v254, v105, vcc
	v_cmp_lt_u32_e32 vcc, s55, v3
	v_add_u32_e32 v3, 0xbfffffce, v0
	s_nop 0
	v_cndmask_b32_e32 v90, v254, v90, vcc
	v_cmp_lt_u32_e32 vcc, s55, v3
	v_add_u32_e32 v3, 0xbfffffed, v0
	s_nop 0
	v_cndmask_b32_e32 v106, v254, v106, vcc
	v_cmp_lt_u32_e32 vcc, s55, v3
	v_add_u32_e32 v3, 0xbfffffcd, v0
	s_nop 0
	v_cndmask_b32_e32 v91, v254, v91, vcc
	v_cmp_lt_u32_e32 vcc, s55, v3
	v_add_u32_e32 v3, 0xbfffffe8, v0
	s_nop 0
	v_cndmask_b32_e32 v107, v254, v107, vcc
	v_cmp_lt_u32_e32 vcc, s55, v3
	v_add_u32_e32 v3, 0xbfffffc8, v0
	s_nop 0
	v_cndmask_b32_e32 v92, v254, v92, vcc
	v_cmp_lt_u32_e32 vcc, s55, v3
	v_add_u32_e32 v3, 0xbfffffe7, v0
	s_nop 0
	v_cndmask_b32_e32 v108, v254, v108, vcc
	v_cmp_lt_u32_e32 vcc, s55, v3
	v_add_u32_e32 v3, 0xbfffffc7, v0
	s_nop 0
	v_cndmask_b32_e32 v93, v254, v93, vcc
	v_cmp_lt_u32_e32 vcc, s55, v3
	v_add_u32_e32 v3, 0xbfffffe6, v0
	s_nop 0
	v_cndmask_b32_e32 v109, v254, v109, vcc
	v_cmp_lt_u32_e32 vcc, s55, v3
	v_add_u32_e32 v3, 0xbfffffc6, v0
	s_nop 0
	v_cndmask_b32_e32 v94, v254, v94, vcc
	v_cmp_lt_u32_e32 vcc, s55, v3
	v_add_u32_e32 v3, 0xbfffffe5, v0
	v_add_u32_e32 v0, 0xbfffffc5, v0
	v_cndmask_b32_e32 v110, v254, v110, vcc
	v_cmp_lt_u32_e32 vcc, s55, v3
	s_nop 1
	v_cndmask_b32_e32 v95, v254, v95, vcc
	v_cmp_lt_u32_e32 vcc, s55, v0
	s_nop 1
	v_cndmask_b32_e32 v111, v254, v111, vcc

; DEVI unsigned cvtpk(float lo, float hi) { unsigned r; asm volatile("v_cvt_pk_bf16_f32 %0, %1, %2" : "=v"(r) : "v"(lo), "v"(hi)); return r; }
; template <int CTRL> DEVI float dpp(float x) { return __builtin_bit_cast(float, __builtin_amdgcn_mov_dpp(__builtin_bit_cast(int, x), CTRL, 0xf, 0xf, true)); }
; #define SBAR() __builtin_amdgcn_sched_barrier(0)
; DEVI int crow(int r, int hi) { return (r & 3) + 8 * (r >> 2) + 4 * hi; }
; #define SEAM_K0() do { VMWN(NQL); SWRITE_HK(0); SBAR(); } while (0)
; DEVI void block(const BlockRef& cur, const BlockRef& nxt, char* lds, Seam& S, int wv) {
;     ...
;     SBAR(); SEAM_K0();
;     if (hi == 0) li_l[r32] = l_reg; asm volatile("s_waitcnt lgkmcnt(0)" ::: "memory");
;     float rli[16];
; #pragma unroll
;     for (int r = 0; r < 16; ++r) rli[r] = __builtin_amdgcn_rcpf(li_l[crow(r, hi)]);
;     bf16_t* Ow = cur.O + (size_t)(wid * QBLK) * RS;
; #pragma unroll
;     for (int r = 0; r < 16; ++r) { const int orow = crow(r, hi);
; #pragma unroll
;         for (int d0 = 0; d0 < 4; ++d0) { const float v = o[d0][r] * rli[r];
;             const float vn = dpp<0xB1>(v);
;             if ((r32 & 1) == 0) *(unsigned*)(Ow + (size_t)orow * RS + d0 * 32 + r32) = cvtpk(v, vn); } }
.LBB0_247:
	s_or_b64 exec, exec, s[6:7]
	s_waitcnt vmcnt(8)
	s_waitcnt vmcnt(0) lgkmcnt(0)
	ds_write_b128 v224, v[120:123] offset:32768
	ds_write_b128 v224, v[124:127] offset:40960
	v_cmp_gt_u32_e32 vcc, 32, v220
	s_mov_b64 s[4:5], exec
	s_and_b64 s[6:7], s[4:5], vcc
	v_mov_b32_e32 v1, v215
	s_mov_b64 exec, s[6:7]
	ds_write_b32 v226, v2
	s_or_b64 exec, exec, s[4:5]
	s_waitcnt lgkmcnt(0)
	ds_read_b128 v[80:83], v225
	s_ashr_i32 s89, s88, 31
	ds_read_b128 v[10:13], v225 offset:32
	ds_read_b128 v[6:9], v225 offset:64
	ds_read_b128 v[2:5], v225 offset:96
	s_lshl_b64 s[4:5], s[88:89], 11
	s_add_u32 s6, s86, s4
	s_waitcnt lgkmcnt(3)
	v_rcp_f32_e32 v80, v80
	v_and_b32_e32 v0, 1, v219
	s_addc_u32 s7, s87, s5
	v_cmp_eq_u32_e64 s[4:5], 0, v0
	v_lshlrev_b32_e32 v0, 1, v222
	v_lshl_add_u64 v[14:15], s[6:7], 0, v[0:1]
	v_lshlrev_b32_e32 v0, 13, v221
	v_lshl_add_u64 v[14:15], v[14:15], 0, v[0:1]
	v_mul_f32_e32 v0, v64, v80
	s_nop 1
	v_mov_b32_dpp v64, v0 quad_perm:[1,0,3,2] row_mask:0xf bank_mask:0xf bound_ctrl:1
	s_and_saveexec_b64 s[6:7], s[4:5]
	s_cbranch_execz .LBB0_251
	v_cvt_pk_bf16_f32 v0, v0, v64
	global_store_dword v[14:15], v0, off
.LBB0_251:
	s_or_b64 exec, exec, s[6:7]
	v_mul_f32_e32 v0, v48, v80
	s_nop 1
	v_mov_b32_dpp v48, v0 quad_perm:[1,0,3,2] row_mask:0xf bank_mask:0xf bound_ctrl:1
	s_and_saveexec_b64 s[6:7], s[4:5]
	s_cbranch_execz .LBB0_253
	v_cvt_pk_bf16_f32 v0, v0, v48
	global_store_dword v[14:15], v0, off offset:64
.LBB0_253:
	s_or_b64 exec, exec, s[6:7]
	v_mul_f32_e32 v0, v32, v80
	s_nop 1
	v_mov_b32_dpp v32, v0 quad_perm:[1,0,3,2] row_mask:0xf bank_mask:0xf bound_ctrl:1
	s_and_saveexec_b64 s[6:7], s[4:5]
	s_cbranch_execz .LBB0_255
	v_cvt_pk_bf16_f32 v0, v0, v32
	global_store_dword v[14:15], v0, off offset:128
.LBB0_255:
	s_or_b64 exec, exec, s[6:7]
	v_mul_f32_e32 v0, v16, v80
	s_nop 1
	v_mov_b32_dpp v16, v0 quad_perm:[1,0,3,2] row_mask:0xf bank_mask:0xf bound_ctrl:1
	s_and_saveexec_b64 s[6:7], s[4:5]
	s_cbranch_execz .LBB0_257
	v_cvt_pk_bf16_f32 v0, v0, v16
	global_store_dword v[14:15], v0, off offset:192
.LBB0_257:
	s_or_b64 exec, exec, s[6:7]
	v_rcp_f32_e32 v0, v81
	s_nop 0
	v_mul_f32_e32 v16, v65, v0
	s_nop 1
	v_mov_b32_dpp v32, v16 quad_perm:[1,0,3,2] row_mask:0xf bank_mask:0xf bound_ctrl:1
	s_and_saveexec_b64 s[6:7], s[4:5]
	s_cbranch_execz .LBB0_259
	v_cvt_pk_bf16_f32 v16, v16, v32
	global_store_dword v[14:15], v16, off offset:2048
.LBB0_259:
	s_or_b64 exec, exec, s[6:7]
	v_mul_f32_e32 v16, v49, v0
	s_nop 1
	v_mov_b32_dpp v32, v16 quad_perm:[1,0,3,2] row_mask:0xf bank_mask:0xf bound_ctrl:1
	s_and_saveexec_b64 s[6:7], s[4:5]
	s_cbranch_execz .LBB0_261
	v_cvt_pk_bf16_f32 v16, v16, v32
	global_store_dword v[14:15], v16, off offset:2112
.LBB0_261:
	s_or_b64 exec, exec, s[6:7]
	v_mul_f32_e32 v16, v33, v0
	s_nop 1
	v_mov_b32_dpp v32, v16 quad_perm:[1,0,3,2] row_mask:0xf bank_mask:0xf bound_ctrl:1
	s_and_saveexec_b64 s[6:7], s[4:5]
	s_cbranch_execz .LBB0_263
	v_cvt_pk_bf16_f32 v16, v16, v32
	global_store_dword v[14:15], v16, off offset:2176
.LBB0_263:
	s_or_b64 exec, exec, s[6:7]
	v_mul_f32_e32 v0, v17, v0
	s_nop 1
	v_mov_b32_dpp v16, v0 quad_perm:[1,0,3,2] row_mask:0xf bank_mask:0xf bound_ctrl:1
	s_and_saveexec_b64 s[6:7], s[4:5]
	s_cbranch_execz .LBB0_265
	v_cvt_pk_bf16_f32 v0, v0, v16
	global_store_dword v[14:15], v0, off offset:2240
.LBB0_265:
	s_or_b64 exec, exec, s[6:7]
	v_rcp_f32_e32 v0, v82
	s_nop 0
	v_mul_f32_e32 v16, v66, v0
	s_nop 1
	v_mov_b32_dpp v17, v16 quad_perm:[1,0,3,2] row_mask:0xf bank_mask:0xf bound_ctrl:1
	s_and_saveexec_b64 s[6:7], s[4:5]
	s_cbranch_execz .LBB0_267
	v_cvt_pk_bf16_f32 v32, v16, v17
	v_add_co_u32_e32 v16, vcc, 0x1000, v14
	s_nop 1
	v_addc_co_u32_e32 v17, vcc, 0, v15, vcc
	global_store_dword v[16:17], v32, off
.LBB0_267:
	s_or_b64 exec, exec, s[6:7]
	v_mul_f32_e32 v16, v50, v0
	s_nop 1
	v_mov_b32_dpp v17, v16 quad_perm:[1,0,3,2] row_mask:0xf bank_mask:0xf bound_ctrl:1
	s_and_saveexec_b64 s[6:7], s[4:5]
	s_cbranch_execz .LBB0_269
	v_cvt_pk_bf16_f32 v32, v16, v17
	v_add_co_u32_e32 v16, vcc, 0x1000, v14
	s_nop 1
	v_addc_co_u32_e32 v17, vcc, 0, v15, vcc
	global_store_dword v[16:17], v32, off offset:64
.LBB0_269:
	s_or_b64 exec, exec, s[6:7]
	v_mul_f32_e32 v16, v34, v0
	s_nop 1
	v_mov_b32_dpp v17, v16 quad_perm:[1,0,3,2] row_mask:0xf bank_mask:0xf bound_ctrl:1
	s_and_saveexec_b64 s[6:7], s[4:5]
	s_cbranch_execz .LBB0_271
	v_cvt_pk_bf16_f32 v32, v16, v17
	v_add_co_u32_e32 v16, vcc, 0x1000, v14
	s_nop 1
	v_addc_co_u32_e32 v17, vcc, 0, v15, vcc
	global_store_dword v[16:17], v32, off offset:128
.LBB0_271:
	s_or_b64 exec, exec, s[6:7]
	v_mul_f32_e32 v0, v18, v0
	s_nop 1
	v_mov_b32_dpp v16, v0 quad_perm:[1,0,3,2] row_mask:0xf bank_mask:0xf bound_ctrl:1
	s_and_saveexec_b64 s[6:7], s[4:5]
	s_cbranch_execz .LBB0_273
	v_cvt_pk_bf16_f32 v0, v0, v16
	v_add_co_u32_e32 v16, vcc, 0x1000, v14
	s_nop 1
	v_addc_co_u32_e32 v17, vcc, 0, v15, vcc
	global_store_dword v[16:17], v0, off offset:192
.LBB0_273:
	s_or_b64 exec, exec, s[6:7]
	v_rcp_f32_e32 v0, v83
	s_nop 0
	v_mul_f32_e32 v16, v67, v0
	s_nop 1
	v_mov_b32_dpp v17, v16 quad_perm:[1,0,3,2] row_mask:0xf bank_mask:0xf bound_ctrl:1
	s_and_saveexec_b64 s[6:7], s[4:5]
	s_cbranch_execz .LBB0_275
	v_cvt_pk_bf16_f32 v18, v16, v17
	v_add_co_u32_e32 v16, vcc, 0x1000, v14
	s_nop 1
	v_addc_co_u32_e32 v17, vcc, 0, v15, vcc
	global_store_dword v[16:17], v18, off offset:2048
.LBB0_275:
	s_or_b64 exec, exec, s[6:7]
	v_mul_f32_e32 v16, v51, v0
	s_nop 1
	v_mov_b32_dpp v17, v16 quad_perm:[1,0,3,2] row_mask:0xf bank_mask:0xf bound_ctrl:1
	s_and_saveexec_b64 s[6:7], s[4:5]
	s_cbranch_execz .LBB0_277
	v_cvt_pk_bf16_f32 v18, v16, v17
	v_add_co_u32_e32 v16, vcc, 0x1000, v14
	s_nop 1
	v_addc_co_u32_e32 v17, vcc, 0, v15, vcc
	global_store_dword v[16:17], v18, off offset:2112
; DEVI unsigned cvtpk(float lo, float hi) { unsigned r; asm volatile("v_cvt_pk_bf16_f32 %0, %1, %2" : "=v"(r) : "v"(lo), "v"(hi)); return r; }
; template <int CTRL> DEVI float dpp(float x) { return __builtin_bit_cast(float, __builtin_amdgcn_mov_dpp(__builtin_bit_cast(int, x), CTRL, 0xf, 0xf, true)); }
; DEVI int crow(int r, int hi) { return (r & 3) + 8 * (r >> 2) + 4 * hi; }
; DEVI void block(const BlockRef& cur, const BlockRef& nxt, char* lds, Seam& S, int wv) {
;     ...
;     for (int r = 0; r < 16; ++r) { const int orow = crow(r, hi);
; #pragma unroll
;         for (int d0 = 0; d0 < 4; ++d0) { const float v = o[d0][r] * rli[r];
;             const float vn = dpp<0xB1>(v);
;             if ((r32 & 1) == 0) *(unsigned*)(Ow + (size_t)orow * RS + d0 * 32 + r32) = cvtpk(v, vn); } }
.LBB0_277:
	s_or_b64 exec, exec, s[6:7]
	v_mul_f32_e32 v16, v35, v0
	s_nop 1
	v_mov_b32_dpp v17, v16 quad_perm:[1,0,3,2] row_mask:0xf bank_mask:0xf bound_ctrl:1
	s_and_saveexec_b64 s[6:7], s[4:5]
	s_cbranch_execz .LBB0_279
	v_cvt_pk_bf16_f32 v18, v16, v17
	v_add_co_u32_e32 v16, vcc, 0x1000, v14
	s_nop 1
	v_addc_co_u32_e32 v17, vcc, 0, v15, vcc
	global_store_dword v[16:17], v18, off offset:2176
.LBB0_279:
	s_or_b64 exec, exec, s[6:7]
	v_mul_f32_e32 v0, v19, v0
	s_nop 1
	v_mov_b32_dpp v16, v0 quad_perm:[1,0,3,2] row_mask:0xf bank_mask:0xf bound_ctrl:1
	s_and_saveexec_b64 s[6:7], s[4:5]
	s_cbranch_execz .LBB0_281
	v_cvt_pk_bf16_f32 v0, v0, v16
	v_add_co_u32_e32 v16, vcc, 0x1000, v14
	s_nop 1
	v_addc_co_u32_e32 v17, vcc, 0, v15, vcc
	global_store_dword v[16:17], v0, off offset:2240
.LBB0_281:
	s_or_b64 exec, exec, s[6:7]
	s_waitcnt lgkmcnt(0)
	v_rcp_f32_e32 v0, v10
	s_nop 0
	v_mul_f32_e32 v10, v68, v0
	s_nop 1
	v_mov_b32_dpp v16, v10 quad_perm:[1,0,3,2] row_mask:0xf bank_mask:0xf bound_ctrl:1
	s_and_saveexec_b64 s[6:7], s[4:5]
	s_cbranch_execz .LBB0_283
	v_cvt_pk_bf16_f32 v10, v10, v16
	v_add_co_u32_e32 v16, vcc, 0x4000, v14
	s_nop 1
	v_addc_co_u32_e32 v17, vcc, 0, v15, vcc
	global_store_dword v[16:17], v10, off
.LBB0_283:
	s_or_b64 exec, exec, s[6:7]
	v_mul_f32_e32 v10, v52, v0
	s_nop 1
	v_mov_b32_dpp v16, v10 quad_perm:[1,0,3,2] row_mask:0xf bank_mask:0xf bound_ctrl:1
	s_and_saveexec_b64 s[6:7], s[4:5]
	s_cbranch_execz .LBB0_285
	v_cvt_pk_bf16_f32 v10, v10, v16
	v_add_co_u32_e32 v16, vcc, 0x4000, v14
	s_nop 1
	v_addc_co_u32_e32 v17, vcc, 0, v15, vcc
	global_store_dword v[16:17], v10, off offset:64
.LBB0_285:
	s_or_b64 exec, exec, s[6:7]
	v_mul_f32_e32 v10, v36, v0
	s_nop 1
	v_mov_b32_dpp v16, v10 quad_perm:[1,0,3,2] row_mask:0xf bank_mask:0xf bound_ctrl:1
	s_and_saveexec_b64 s[6:7], s[4:5]
	s_cbranch_execz .LBB0_287
	v_cvt_pk_bf16_f32 v10, v10, v16
	v_add_co_u32_e32 v16, vcc, 0x4000, v14
	s_nop 1
	v_addc_co_u32_e32 v17, vcc, 0, v15, vcc
	global_store_dword v[16:17], v10, off offset:128
.LBB0_287:
	s_or_b64 exec, exec, s[6:7]
	v_mul_f32_e32 v0, v20, v0
	s_nop 1
	v_mov_b32_dpp v10, v0 quad_perm:[1,0,3,2] row_mask:0xf bank_mask:0xf bound_ctrl:1
	s_and_saveexec_b64 s[6:7], s[4:5]
	s_cbranch_execz .LBB0_289
	v_add_co_u32_e32 v16, vcc, 0x4000, v14
	v_cvt_pk_bf16_f32 v0, v0, v10
	s_nop 1
	v_addc_co_u32_e32 v17, vcc, 0, v15, vcc
	global_store_dword v[16:17], v0, off offset:192
.LBB0_289:
	s_or_b64 exec, exec, s[6:7]
	v_rcp_f32_e32 v0, v11
	s_nop 0
	v_mul_f32_e32 v10, v69, v0
	s_nop 1
	v_mov_b32_dpp v11, v10 quad_perm:[1,0,3,2] row_mask:0xf bank_mask:0xf bound_ctrl:1
	s_and_saveexec_b64 s[6:7], s[4:5]
	s_cbranch_execz .LBB0_291
	v_cvt_pk_bf16_f32 v16, v10, v11
	v_add_co_u32_e32 v10, vcc, 0x4000, v14
	s_nop 1
	v_addc_co_u32_e32 v11, vcc, 0, v15, vcc
	global_store_dword v[10:11], v16, off offset:2048
.LBB0_291:
	s_or_b64 exec, exec, s[6:7]
	v_mul_f32_e32 v10, v53, v0
	s_nop 1
	v_mov_b32_dpp v11, v10 quad_perm:[1,0,3,2] row_mask:0xf bank_mask:0xf bound_ctrl:1
	s_and_saveexec_b64 s[6:7], s[4:5]
	s_cbranch_execz .LBB0_293
	v_cvt_pk_bf16_f32 v16, v10, v11
	v_add_co_u32_e32 v10, vcc, 0x4000, v14
	s_nop 1
	v_addc_co_u32_e32 v11, vcc, 0, v15, vcc
	global_store_dword v[10:11], v16, off offset:2112
.LBB0_293:
	s_or_b64 exec, exec, s[6:7]
	v_mul_f32_e32 v10, v37, v0
	s_nop 1
	v_mov_b32_dpp v11, v10 quad_perm:[1,0,3,2] row_mask:0xf bank_mask:0xf bound_ctrl:1
	s_and_saveexec_b64 s[6:7], s[4:5]
	s_cbranch_execz .LBB0_295
	v_cvt_pk_bf16_f32 v16, v10, v11
	v_add_co_u32_e32 v10, vcc, 0x4000, v14
	s_nop 1
	v_addc_co_u32_e32 v11, vcc, 0, v15, vcc
	global_store_dword v[10:11], v16, off offset:2176
.LBB0_295:
	s_or_b64 exec, exec, s[6:7]
	v_mul_f32_e32 v0, v21, v0
	s_nop 1
	v_mov_b32_dpp v10, v0 quad_perm:[1,0,3,2] row_mask:0xf bank_mask:0xf bound_ctrl:1
	s_and_saveexec_b64 s[6:7], s[4:5]
	s_cbranch_execz .LBB0_297
	v_cvt_pk_bf16_f32 v0, v0, v10
	v_add_co_u32_e32 v10, vcc, 0x4000, v14
	s_nop 1
	v_addc_co_u32_e32 v11, vcc, 0, v15, vcc
	global_store_dword v[10:11], v0, off offset:2240
.LBB0_297:
	s_or_b64 exec, exec, s[6:7]
	v_rcp_f32_e32 v0, v12
	s_nop 0
	v_mul_f32_e32 v10, v70, v0
	s_nop 1
	v_mov_b32_dpp v11, v10 quad_perm:[1,0,3,2] row_mask:0xf bank_mask:0xf bound_ctrl:1
	s_and_saveexec_b64 s[6:7], s[4:5]
	s_cbranch_execz .LBB0_299
	v_cvt_pk_bf16_f32 v12, v10, v11
	v_add_co_u32_e32 v10, vcc, 0x5000, v14
	s_nop 1
	v_addc_co_u32_e32 v11, vcc, 0, v15, vcc
	global_store_dword v[10:11], v12, off
.LBB0_299:
	s_or_b64 exec, exec, s[6:7]
	v_mul_f32_e32 v10, v54, v0
	s_nop 1
	v_mov_b32_dpp v11, v10 quad_perm:[1,0,3,2] row_mask:0xf bank_mask:0xf bound_ctrl:1
	s_and_saveexec_b64 s[6:7], s[4:5]
	s_cbranch_execz .LBB0_301
	v_cvt_pk_bf16_f32 v12, v10, v11
	v_add_co_u32_e32 v10, vcc, 0x5000, v14
	s_nop 1
	v_addc_co_u32_e32 v11, vcc, 0, v15, vcc
	global_store_dword v[10:11], v12, off offset:64
.LBB0_301:
	s_or_b64 exec, exec, s[6:7]
	v_mul_f32_e32 v10, v38, v0
	s_nop 1
	v_mov_b32_dpp v11, v10 quad_perm:[1,0,3,2] row_mask:0xf bank_mask:0xf bound_ctrl:1
	s_and_saveexec_b64 s[6:7], s[4:5]
	s_cbranch_execz .LBB0_303
	v_cvt_pk_bf16_f32 v12, v10, v11
	v_add_co_u32_e32 v10, vcc, 0x5000, v14
	s_nop 1
	v_addc_co_u32_e32 v11, vcc, 0, v15, vcc
	global_store_dword v[10:11], v12, off offset:128
.LBB0_303:
	s_or_b64 exec, exec, s[6:7]
	v_mul_f32_e32 v0, v22, v0
	s_nop 1
	v_mov_b32_dpp v10, v0 quad_perm:[1,0,3,2] row_mask:0xf bank_mask:0xf bound_ctrl:1
	s_and_saveexec_b64 s[6:7], s[4:5]
	s_cbranch_execz .LBB0_305
	v_cvt_pk_bf16_f32 v0, v0, v10
	v_add_co_u32_e32 v10, vcc, 0x5000, v14
	s_nop 1
	v_addc_co_u32_e32 v11, vcc, 0, v15, vcc
	global_store_dword v[10:11], v0, off offset:192
; DEVI unsigned cvtpk(float lo, float hi) { unsigned r; asm volatile("v_cvt_pk_bf16_f32 %0, %1, %2" : "=v"(r) : "v"(lo), "v"(hi)); return r; }
; template <int CTRL> DEVI float dpp(float x) { return __builtin_bit_cast(float, __builtin_amdgcn_mov_dpp(__builtin_bit_cast(int, x), CTRL, 0xf, 0xf, true)); }
; DEVI int crow(int r, int hi) { return (r & 3) + 8 * (r >> 2) + 4 * hi; }
; DEVI void block(const BlockRef& cur, const BlockRef& nxt, char* lds, Seam& S, int wv) {
;     ...
;     for (int r = 0; r < 16; ++r) { const int orow = crow(r, hi);
; #pragma unroll
;         for (int d0 = 0; d0 < 4; ++d0) { const float v = o[d0][r] * rli[r];
;             const float vn = dpp<0xB1>(v);
;             if ((r32 & 1) == 0) *(unsigned*)(Ow + (size_t)orow * RS + d0 * 32 + r32) = cvtpk(v, vn); } }
.LBB0_305:
	s_or_b64 exec, exec, s[6:7]
	v_rcp_f32_e32 v0, v13
	s_nop 0
	v_mul_f32_e32 v10, v71, v0
	s_nop 1
	v_mov_b32_dpp v11, v10 quad_perm:[1,0,3,2] row_mask:0xf bank_mask:0xf bound_ctrl:1
	s_and_saveexec_b64 s[6:7], s[4:5]
	s_cbranch_execz .LBB0_307
	v_cvt_pk_bf16_f32 v12, v10, v11
	v_add_co_u32_e32 v10, vcc, 0x5000, v14
	s_nop 1
	v_addc_co_u32_e32 v11, vcc, 0, v15, vcc
	global_store_dword v[10:11], v12, off offset:2048
.LBB0_307:
	s_or_b64 exec, exec, s[6:7]
	v_mul_f32_e32 v10, v55, v0
	s_nop 1
	v_mov_b32_dpp v11, v10 quad_perm:[1,0,3,2] row_mask:0xf bank_mask:0xf bound_ctrl:1
	s_and_saveexec_b64 s[6:7], s[4:5]
	s_cbranch_execz .LBB0_309
	v_cvt_pk_bf16_f32 v12, v10, v11
	v_add_co_u32_e32 v10, vcc, 0x5000, v14
	s_nop 1
	v_addc_co_u32_e32 v11, vcc, 0, v15, vcc
	global_store_dword v[10:11], v12, off offset:2112
.LBB0_309:
	s_or_b64 exec, exec, s[6:7]
	v_mul_f32_e32 v10, v39, v0
	s_nop 1
	v_mov_b32_dpp v11, v10 quad_perm:[1,0,3,2] row_mask:0xf bank_mask:0xf bound_ctrl:1
	s_and_saveexec_b64 s[6:7], s[4:5]
	s_cbranch_execz .LBB0_311
	v_cvt_pk_bf16_f32 v12, v10, v11
	v_add_co_u32_e32 v10, vcc, 0x5000, v14
	s_nop 1
	v_addc_co_u32_e32 v11, vcc, 0, v15, vcc
	global_store_dword v[10:11], v12, off offset:2176
.LBB0_311:
	s_or_b64 exec, exec, s[6:7]
	v_mul_f32_e32 v0, v23, v0
	s_nop 1
	v_mov_b32_dpp v10, v0 quad_perm:[1,0,3,2] row_mask:0xf bank_mask:0xf bound_ctrl:1
	s_and_saveexec_b64 s[6:7], s[4:5]
	s_cbranch_execz .LBB0_313
	v_cvt_pk_bf16_f32 v0, v0, v10
	v_add_co_u32_e32 v10, vcc, 0x5000, v14
	s_nop 1
	v_addc_co_u32_e32 v11, vcc, 0, v15, vcc
	global_store_dword v[10:11], v0, off offset:2240
.LBB0_313:
	s_or_b64 exec, exec, s[6:7]
	v_rcp_f32_e32 v0, v6
	s_nop 0
	v_mul_f32_e32 v6, v72, v0
	s_nop 1
	v_mov_b32_dpp v10, v6 quad_perm:[1,0,3,2] row_mask:0xf bank_mask:0xf bound_ctrl:1
	s_and_saveexec_b64 s[6:7], s[4:5]
	s_cbranch_execz .LBB0_315
	v_cvt_pk_bf16_f32 v6, v6, v10
	v_add_co_u32_e32 v10, vcc, 0x8000, v14
	s_nop 1
	v_addc_co_u32_e32 v11, vcc, 0, v15, vcc
	global_store_dword v[10:11], v6, off
.LBB0_315:
	s_or_b64 exec, exec, s[6:7]
	v_mul_f32_e32 v6, v56, v0
	s_nop 1
	v_mov_b32_dpp v10, v6 quad_perm:[1,0,3,2] row_mask:0xf bank_mask:0xf bound_ctrl:1
	s_and_saveexec_b64 s[6:7], s[4:5]
	s_cbranch_execz .LBB0_317
	v_cvt_pk_bf16_f32 v6, v6, v10
	v_add_co_u32_e32 v10, vcc, 0x8000, v14
	s_nop 1
	v_addc_co_u32_e32 v11, vcc, 0, v15, vcc
	global_store_dword v[10:11], v6, off offset:64
.LBB0_317:
	s_or_b64 exec, exec, s[6:7]
	v_mul_f32_e32 v6, v40, v0
	s_nop 1
	v_mov_b32_dpp v10, v6 quad_perm:[1,0,3,2] row_mask:0xf bank_mask:0xf bound_ctrl:1
	s_and_saveexec_b64 s[6:7], s[4:5]
	s_cbranch_execz .LBB0_319
	v_cvt_pk_bf16_f32 v6, v6, v10
	v_add_co_u32_e32 v10, vcc, 0x8000, v14
	s_nop 1
	v_addc_co_u32_e32 v11, vcc, 0, v15, vcc
	global_store_dword v[10:11], v6, off offset:128
.LBB0_319:
	s_or_b64 exec, exec, s[6:7]
	v_mul_f32_e32 v0, v24, v0
	s_nop 1
	v_mov_b32_dpp v6, v0 quad_perm:[1,0,3,2] row_mask:0xf bank_mask:0xf bound_ctrl:1
	s_and_saveexec_b64 s[6:7], s[4:5]
	s_cbranch_execz .LBB0_321
	v_add_co_u32_e32 v10, vcc, 0x8000, v14
	v_cvt_pk_bf16_f32 v0, v0, v6
	s_nop 1
	v_addc_co_u32_e32 v11, vcc, 0, v15, vcc
	global_store_dword v[10:11], v0, off offset:192
.LBB0_321:
	s_or_b64 exec, exec, s[6:7]
	v_rcp_f32_e32 v0, v7
	s_nop 0
	v_mul_f32_e32 v6, v73, v0
	s_nop 1
	v_mov_b32_dpp v7, v6 quad_perm:[1,0,3,2] row_mask:0xf bank_mask:0xf bound_ctrl:1
	s_and_saveexec_b64 s[6:7], s[4:5]
	s_cbranch_execz .LBB0_323
	v_cvt_pk_bf16_f32 v10, v6, v7
	v_add_co_u32_e32 v6, vcc, 0x8000, v14
	s_nop 1
	v_addc_co_u32_e32 v7, vcc, 0, v15, vcc
	global_store_dword v[6:7], v10, off offset:2048
.LBB0_323:
	s_or_b64 exec, exec, s[6:7]
	v_mul_f32_e32 v6, v57, v0
	s_nop 1
	v_mov_b32_dpp v7, v6 quad_perm:[1,0,3,2] row_mask:0xf bank_mask:0xf bound_ctrl:1
	s_and_saveexec_b64 s[6:7], s[4:5]
	s_cbranch_execz .LBB0_325
	v_cvt_pk_bf16_f32 v10, v6, v7
	v_add_co_u32_e32 v6, vcc, 0x8000, v14
	s_nop 1
	v_addc_co_u32_e32 v7, vcc, 0, v15, vcc
	global_store_dword v[6:7], v10, off offset:2112
.LBB0_325:
	s_or_b64 exec, exec, s[6:7]
	v_mul_f32_e32 v6, v41, v0
	s_nop 1
	v_mov_b32_dpp v7, v6 quad_perm:[1,0,3,2] row_mask:0xf bank_mask:0xf bound_ctrl:1
	s_and_saveexec_b64 s[6:7], s[4:5]
	s_cbranch_execz .LBB0_327
	v_cvt_pk_bf16_f32 v10, v6, v7
	v_add_co_u32_e32 v6, vcc, 0x8000, v14
	s_nop 1
	v_addc_co_u32_e32 v7, vcc, 0, v15, vcc
	global_store_dword v[6:7], v10, off offset:2176
.LBB0_327:
	s_or_b64 exec, exec, s[6:7]
	v_mul_f32_e32 v0, v25, v0
	s_nop 1
	v_mov_b32_dpp v6, v0 quad_perm:[1,0,3,2] row_mask:0xf bank_mask:0xf bound_ctrl:1
	s_and_saveexec_b64 s[6:7], s[4:5]
	s_cbranch_execz .LBB0_329
	v_cvt_pk_bf16_f32 v0, v0, v6
	v_add_co_u32_e32 v6, vcc, 0x8000, v14
	s_nop 1
	v_addc_co_u32_e32 v7, vcc, 0, v15, vcc
	global_store_dword v[6:7], v0, off offset:2240
.LBB0_329:
	s_or_b64 exec, exec, s[6:7]
	v_rcp_f32_e32 v0, v8
	s_nop 0
	v_mul_f32_e32 v6, v74, v0
	s_nop 1
	v_mov_b32_dpp v7, v6 quad_perm:[1,0,3,2] row_mask:0xf bank_mask:0xf bound_ctrl:1
	s_and_saveexec_b64 s[6:7], s[4:5]
	s_cbranch_execz .LBB0_331
	v_cvt_pk_bf16_f32 v8, v6, v7
	v_add_co_u32_e32 v6, vcc, 0x9000, v14
	s_nop 1
	v_addc_co_u32_e32 v7, vcc, 0, v15, vcc
	global_store_dword v[6:7], v8, off
.LBB0_331:
	s_or_b64 exec, exec, s[6:7]
	v_mul_f32_e32 v6, v58, v0
	s_nop 1
	v_mov_b32_dpp v7, v6 quad_perm:[1,0,3,2] row_mask:0xf bank_mask:0xf bound_ctrl:1
	s_and_saveexec_b64 s[6:7], s[4:5]
	s_cbranch_execz .LBB0_333
	v_cvt_pk_bf16_f32 v8, v6, v7
	v_add_co_u32_e32 v6, vcc, 0x9000, v14
	s_nop 1
	v_addc_co_u32_e32 v7, vcc, 0, v15, vcc
	global_store_dword v[6:7], v8, off offset:64
; DEVI unsigned cvtpk(float lo, float hi) { unsigned r; asm volatile("v_cvt_pk_bf16_f32 %0, %1, %2" : "=v"(r) : "v"(lo), "v"(hi)); return r; }
; template <int CTRL> DEVI float dpp(float x) { return __builtin_bit_cast(float, __builtin_amdgcn_mov_dpp(__builtin_bit_cast(int, x), CTRL, 0xf, 0xf, true)); }
; DEVI int crow(int r, int hi) { return (r & 3) + 8 * (r >> 2) + 4 * hi; }
; DEVI void block(const BlockRef& cur, const BlockRef& nxt, char* lds, Seam& S, int wv) {
;     ...
;     for (int r = 0; r < 16; ++r) { const int orow = crow(r, hi);
; #pragma unroll
;         for (int d0 = 0; d0 < 4; ++d0) { const float v = o[d0][r] * rli[r];
;             const float vn = dpp<0xB1>(v);
;             if ((r32 & 1) == 0) *(unsigned*)(Ow + (size_t)orow * RS + d0 * 32 + r32) = cvtpk(v, vn); } }
.LBB0_333:
	s_or_b64 exec, exec, s[6:7]
	v_mul_f32_e32 v6, v42, v0
	s_nop 1
	v_mov_b32_dpp v7, v6 quad_perm:[1,0,3,2] row_mask:0xf bank_mask:0xf bound_ctrl:1
	s_and_saveexec_b64 s[6:7], s[4:5]
	s_cbranch_execz .LBB0_335
	v_cvt_pk_bf16_f32 v8, v6, v7
	v_add_co_u32_e32 v6, vcc, 0x9000, v14
	s_nop 1
	v_addc_co_u32_e32 v7, vcc, 0, v15, vcc
	global_store_dword v[6:7], v8, off offset:128
.LBB0_335:
	s_or_b64 exec, exec, s[6:7]
	v_mul_f32_e32 v0, v26, v0
	s_nop 1
	v_mov_b32_dpp v6, v0 quad_perm:[1,0,3,2] row_mask:0xf bank_mask:0xf bound_ctrl:1
	s_and_saveexec_b64 s[6:7], s[4:5]
	s_cbranch_execz .LBB0_337
	v_cvt_pk_bf16_f32 v0, v0, v6
	v_add_co_u32_e32 v6, vcc, 0x9000, v14
	s_nop 1
	v_addc_co_u32_e32 v7, vcc, 0, v15, vcc
	global_store_dword v[6:7], v0, off offset:192
.LBB0_337:
	s_or_b64 exec, exec, s[6:7]
	v_rcp_f32_e32 v0, v9
	s_nop 0
	v_mul_f32_e32 v6, v75, v0
	s_nop 1
	v_mov_b32_dpp v7, v6 quad_perm:[1,0,3,2] row_mask:0xf bank_mask:0xf bound_ctrl:1
	s_and_saveexec_b64 s[6:7], s[4:5]
	s_cbranch_execz .LBB0_339
	v_cvt_pk_bf16_f32 v8, v6, v7
	v_add_co_u32_e32 v6, vcc, 0x9000, v14
	s_nop 1
	v_addc_co_u32_e32 v7, vcc, 0, v15, vcc
	global_store_dword v[6:7], v8, off offset:2048
.LBB0_339:
	s_or_b64 exec, exec, s[6:7]
	v_mul_f32_e32 v6, v59, v0
	s_nop 1
	v_mov_b32_dpp v7, v6 quad_perm:[1,0,3,2] row_mask:0xf bank_mask:0xf bound_ctrl:1
	s_and_saveexec_b64 s[6:7], s[4:5]
	s_cbranch_execz .LBB0_341
	v_cvt_pk_bf16_f32 v8, v6, v7
	v_add_co_u32_e32 v6, vcc, 0x9000, v14
	s_nop 1
	v_addc_co_u32_e32 v7, vcc, 0, v15, vcc
	global_store_dword v[6:7], v8, off offset:2112
.LBB0_341:
	s_or_b64 exec, exec, s[6:7]
	v_mul_f32_e32 v6, v43, v0
	s_nop 1
	v_mov_b32_dpp v7, v6 quad_perm:[1,0,3,2] row_mask:0xf bank_mask:0xf bound_ctrl:1
	s_and_saveexec_b64 s[6:7], s[4:5]
	s_cbranch_execz .LBB0_343
	v_cvt_pk_bf16_f32 v8, v6, v7
	v_add_co_u32_e32 v6, vcc, 0x9000, v14
	s_nop 1
	v_addc_co_u32_e32 v7, vcc, 0, v15, vcc
	global_store_dword v[6:7], v8, off offset:2176
.LBB0_343:
	s_or_b64 exec, exec, s[6:7]
	v_mul_f32_e32 v0, v27, v0
	s_nop 1
	v_mov_b32_dpp v6, v0 quad_perm:[1,0,3,2] row_mask:0xf bank_mask:0xf bound_ctrl:1
	s_and_saveexec_b64 s[6:7], s[4:5]
	s_cbranch_execz .LBB0_345
	v_cvt_pk_bf16_f32 v0, v0, v6
	v_add_co_u32_e32 v6, vcc, 0x9000, v14
	s_nop 1
	v_addc_co_u32_e32 v7, vcc, 0, v15, vcc
	global_store_dword v[6:7], v0, off offset:2240
.LBB0_345:
	s_or_b64 exec, exec, s[6:7]
	v_rcp_f32_e32 v0, v2
	s_nop 0
	v_mul_f32_e32 v2, v76, v0
	s_nop 1
	v_mov_b32_dpp v6, v2 quad_perm:[1,0,3,2] row_mask:0xf bank_mask:0xf bound_ctrl:1
	s_and_saveexec_b64 s[6:7], s[4:5]
	s_cbranch_execz .LBB0_347
	v_cvt_pk_bf16_f32 v2, v2, v6
	v_add_co_u32_e32 v6, vcc, 0xc000, v14
	s_nop 1
	v_addc_co_u32_e32 v7, vcc, 0, v15, vcc
	global_store_dword v[6:7], v2, off
.LBB0_347:
	s_or_b64 exec, exec, s[6:7]
	v_mul_f32_e32 v2, v60, v0
	s_nop 1
	v_mov_b32_dpp v6, v2 quad_perm:[1,0,3,2] row_mask:0xf bank_mask:0xf bound_ctrl:1
	s_and_saveexec_b64 s[6:7], s[4:5]
	s_cbranch_execz .LBB0_349
	v_cvt_pk_bf16_f32 v2, v2, v6
	v_add_co_u32_e32 v6, vcc, 0xc000, v14
	s_nop 1
	v_addc_co_u32_e32 v7, vcc, 0, v15, vcc
	global_store_dword v[6:7], v2, off offset:64
.LBB0_349:
	s_or_b64 exec, exec, s[6:7]
	v_mul_f32_e32 v2, v44, v0
	s_nop 1
	v_mov_b32_dpp v6, v2 quad_perm:[1,0,3,2] row_mask:0xf bank_mask:0xf bound_ctrl:1
	s_and_saveexec_b64 s[6:7], s[4:5]
	s_cbranch_execz .LBB0_351
	v_cvt_pk_bf16_f32 v2, v2, v6
	v_add_co_u32_e32 v6, vcc, 0xc000, v14
	s_nop 1
	v_addc_co_u32_e32 v7, vcc, 0, v15, vcc
	global_store_dword v[6:7], v2, off offset:128
.LBB0_351:
	s_or_b64 exec, exec, s[6:7]
	v_mul_f32_e32 v0, v28, v0
	s_nop 1
	v_mov_b32_dpp v2, v0 quad_perm:[1,0,3,2] row_mask:0xf bank_mask:0xf bound_ctrl:1
	s_and_saveexec_b64 s[6:7], s[4:5]
	s_cbranch_execz .LBB0_353
	v_add_co_u32_e32 v6, vcc, 0xc000, v14
	v_cvt_pk_bf16_f32 v0, v0, v2
	s_nop 1
	v_addc_co_u32_e32 v7, vcc, 0, v15, vcc
	global_store_dword v[6:7], v0, off offset:192
.LBB0_353:
	s_or_b64 exec, exec, s[6:7]
	v_rcp_f32_e32 v0, v3
	s_nop 0
	v_mul_f32_e32 v2, v77, v0
	s_nop 1
	v_mov_b32_dpp v3, v2 quad_perm:[1,0,3,2] row_mask:0xf bank_mask:0xf bound_ctrl:1
	s_and_saveexec_b64 s[6:7], s[4:5]
	s_cbranch_execz .LBB0_355
	v_cvt_pk_bf16_f32 v6, v2, v3
	v_add_co_u32_e32 v2, vcc, 0xc000, v14
	s_nop 1
	v_addc_co_u32_e32 v3, vcc, 0, v15, vcc
	global_store_dword v[2:3], v6, off offset:2048
; DEVI unsigned cvtpk(float lo, float hi) { unsigned r; asm volatile("v_cvt_pk_bf16_f32 %0, %1, %2" : "=v"(r) : "v"(lo), "v"(hi)); return r; }
; template <int CTRL> DEVI float dpp(float x) { return __builtin_bit_cast(float, __builtin_amdgcn_mov_dpp(__builtin_bit_cast(int, x), CTRL, 0xf, 0xf, true)); }
; DEVI int crow(int r, int hi) { return (r & 3) + 8 * (r >> 2) + 4 * hi; }
; DEVI void block(const BlockRef& cur, const BlockRef& nxt, char* lds, Seam& S, int wv) {
;     ...
;     for (int r = 0; r < 16; ++r) { const int orow = crow(r, hi);
; #pragma unroll
;         for (int d0 = 0; d0 < 4; ++d0) { const float v = o[d0][r] * rli[r];
;             const float vn = dpp<0xB1>(v);
;             if ((r32 & 1) == 0) *(unsigned*)(Ow + (size_t)orow * RS + d0 * 32 + r32) = cvtpk(v, vn); } }
.LBB0_355:
	s_or_b64 exec, exec, s[6:7]
	v_mul_f32_e32 v2, v61, v0
	s_nop 1
	v_mov_b32_dpp v3, v2 quad_perm:[1,0,3,2] row_mask:0xf bank_mask:0xf bound_ctrl:1
	s_and_saveexec_b64 s[6:7], s[4:5]
	s_cbranch_execz .LBB0_357
	v_cvt_pk_bf16_f32 v6, v2, v3
	v_add_co_u32_e32 v2, vcc, 0xc000, v14
	s_nop 1
	v_addc_co_u32_e32 v3, vcc, 0, v15, vcc
	global_store_dword v[2:3], v6, off offset:2112
.LBB0_357:
	s_or_b64 exec, exec, s[6:7]
	v_mul_f32_e32 v2, v45, v0
	s_nop 1
	v_mov_b32_dpp v3, v2 quad_perm:[1,0,3,2] row_mask:0xf bank_mask:0xf bound_ctrl:1
	s_and_saveexec_b64 s[6:7], s[4:5]
	s_cbranch_execz .LBB0_359
	v_cvt_pk_bf16_f32 v6, v2, v3
	v_add_co_u32_e32 v2, vcc, 0xc000, v14
	s_nop 1
	v_addc_co_u32_e32 v3, vcc, 0, v15, vcc
	global_store_dword v[2:3], v6, off offset:2176
.LBB0_359:
	s_or_b64 exec, exec, s[6:7]
	v_mul_f32_e32 v0, v29, v0
	s_nop 1
	v_mov_b32_dpp v2, v0 quad_perm:[1,0,3,2] row_mask:0xf bank_mask:0xf bound_ctrl:1
	s_and_saveexec_b64 s[6:7], s[4:5]
	s_cbranch_execz .LBB0_361
	v_cvt_pk_bf16_f32 v0, v0, v2
	v_add_co_u32_e32 v2, vcc, 0xc000, v14
	s_nop 1
	v_addc_co_u32_e32 v3, vcc, 0, v15, vcc
	global_store_dword v[2:3], v0, off offset:2240
.LBB0_361:
	s_or_b64 exec, exec, s[6:7]
	v_rcp_f32_e32 v0, v4
	s_nop 0
	v_mul_f32_e32 v2, v78, v0
	s_nop 1
	v_mov_b32_dpp v3, v2 quad_perm:[1,0,3,2] row_mask:0xf bank_mask:0xf bound_ctrl:1
	s_and_saveexec_b64 s[6:7], s[4:5]
	s_cbranch_execz .LBB0_363
	v_cvt_pk_bf16_f32 v4, v2, v3
	v_add_co_u32_e32 v2, vcc, 0xd000, v14
	s_nop 1
	v_addc_co_u32_e32 v3, vcc, 0, v15, vcc
	global_store_dword v[2:3], v4, off
.LBB0_363:
	s_or_b64 exec, exec, s[6:7]
	v_mul_f32_e32 v2, v62, v0
	s_nop 1
	v_mov_b32_dpp v3, v2 quad_perm:[1,0,3,2] row_mask:0xf bank_mask:0xf bound_ctrl:1
	s_and_saveexec_b64 s[6:7], s[4:5]
	s_cbranch_execz .LBB0_365
	v_cvt_pk_bf16_f32 v4, v2, v3
	v_add_co_u32_e32 v2, vcc, 0xd000, v14
	s_nop 1
	v_addc_co_u32_e32 v3, vcc, 0, v15, vcc
	global_store_dword v[2:3], v4, off offset:64
.LBB0_365:
	s_or_b64 exec, exec, s[6:7]
	v_mul_f32_e32 v2, v46, v0
	s_nop 1
	v_mov_b32_dpp v3, v2 quad_perm:[1,0,3,2] row_mask:0xf bank_mask:0xf bound_ctrl:1
	s_and_saveexec_b64 s[6:7], s[4:5]
	s_cbranch_execz .LBB0_367
	v_cvt_pk_bf16_f32 v4, v2, v3
	v_add_co_u32_e32 v2, vcc, 0xd000, v14
	s_nop 1
	v_addc_co_u32_e32 v3, vcc, 0, v15, vcc
	global_store_dword v[2:3], v4, off offset:128
.LBB0_367:
	s_or_b64 exec, exec, s[6:7]
	v_mul_f32_e32 v0, v30, v0
	s_nop 1
	v_mov_b32_dpp v2, v0 quad_perm:[1,0,3,2] row_mask:0xf bank_mask:0xf bound_ctrl:1
	s_and_saveexec_b64 s[6:7], s[4:5]
	s_cbranch_execz .LBB0_369
	v_cvt_pk_bf16_f32 v0, v0, v2
	v_add_co_u32_e32 v2, vcc, 0xd000, v14
	s_nop 1
	v_addc_co_u32_e32 v3, vcc, 0, v15, vcc
	global_store_dword v[2:3], v0, off offset:192
.LBB0_369:
	s_or_b64 exec, exec, s[6:7]
	v_rcp_f32_e32 v0, v5
	s_nop 0
	v_mul_f32_e32 v2, v79, v0
	s_nop 1
	v_mov_b32_dpp v3, v2 quad_perm:[1,0,3,2] row_mask:0xf bank_mask:0xf bound_ctrl:1
	s_and_saveexec_b64 s[6:7], s[4:5]
	s_cbranch_execz .LBB0_371
	v_cvt_pk_bf16_f32 v4, v2, v3
	v_add_co_u32_e32 v2, vcc, 0xd000, v14
	s_nop 1
	v_addc_co_u32_e32 v3, vcc, 0, v15, vcc
	global_store_dword v[2:3], v4, off offset:2048
.LBB0_371:
	s_or_b64 exec, exec, s[6:7]
	v_mul_f32_e32 v2, v63, v0
	s_nop 1
	v_mov_b32_dpp v3, v2 quad_perm:[1,0,3,2] row_mask:0xf bank_mask:0xf bound_ctrl:1
	s_and_saveexec_b64 s[6:7], s[4:5]
	s_cbranch_execz .LBB0_373
	v_cvt_pk_bf16_f32 v4, v2, v3
	v_add_co_u32_e32 v2, vcc, 0xd000, v14
	s_nop 1
	v_addc_co_u32_e32 v3, vcc, 0, v15, vcc
	global_store_dword v[2:3], v4, off offset:2112
.LBB0_373:
	s_or_b64 exec, exec, s[6:7]
	v_mul_f32_e32 v2, v47, v0
	s_nop 1
	v_mov_b32_dpp v3, v2 quad_perm:[1,0,3,2] row_mask:0xf bank_mask:0xf bound_ctrl:1
	s_and_saveexec_b64 s[6:7], s[4:5]
	s_cbranch_execz .LBB0_375
	v_cvt_pk_bf16_f32 v4, v2, v3
	v_add_co_u32_e32 v2, vcc, 0xd000, v14
	s_nop 1
	v_addc_co_u32_e32 v3, vcc, 0, v15, vcc
	global_store_dword v[2:3], v4, off offset:2176
.LBB0_375:
	s_or_b64 exec, exec, s[6:7]
	v_mul_f32_e32 v0, v31, v0
	s_nop 1
	v_mov_b32_dpp v2, v0 quad_perm:[1,0,3,2] row_mask:0xf bank_mask:0xf bound_ctrl:1
	s_and_saveexec_b64 s[6:7], s[4:5]
	s_cbranch_execz .LBB0_201
	v_cvt_pk_bf16_f32 v0, v0, v2
	v_add_co_u32_e32 v2, vcc, 0xd000, v14
	s_nop 1
	v_addc_co_u32_e32 v3, vcc, 0, v15, vcc
	global_store_dword v[2:3], v0, off offset:2240
	s_branch .LBB0_201

; DEVI int ltid(int wv) { int t = (wv << 6) | (int)__builtin_amdgcn_mbcnt_hi(~0u, __builtin_amdgcn_mbcnt_lo(~0u, 0u)); asm volatile("" : "+v"(t)); return t; }
; DEVI int lbid() { int t = blockIdx.x; asm volatile("" : "+s"(t)); return t; }
; DEVI float wave_max(float v) { v = fmaxf(v, dpp<0xB1>(v)); v = fmaxf(v, dpp<0x4E>(v)); v = fmaxf(v, dpp<0x124>(v)); v = fmaxf(v, dpp<0x128>(v)); return xrow16_max(v); }
; DEVI void post_inproj_phase(const float* logf, float* cs, int* jlo, const float* qg, const float* kg, bf16_t* Qb, bf16_t* Kb, char* lds, int wv) {
;     const int tid = ltid(wv), lane = tid & 63, wave = tid >> 6;
;     if (lbid() < 16) {
;         const int bh = lbid(), b = bh >> 3, h = bh & 7;
;     ...
;         float* cL = (float*)lds;
;         double* wt = (double*)(lds + 69632);
;         float* sm = (float*)(lds + 69632 + 64);
;         const float* lf = logf + (size_t)bh * SEQ + (size_t)tid * 32;
;         float vals[32]; double tot = 0.0;
; #pragma unroll
;         for (int i = 0; i < 32; i += 4) { const f32x4 v4 = *(const f32x4*)(lf + i); vals[i] = v4[0]; vals[i + 1] = v4[1]; vals[i + 2] = v4[2]; vals[i + 3] = v4[3]; }
; #pragma unroll
;         for (int i = 0; i < 32; ++i) tot += (double)vals[i];
;         double* dt = (double*)(lds + 69632 + 128);
;         double* g1 = dt + 512;
;         double* g2 = g1 + 64;
;         dt[tid] = tot;
;         if (wave == 0) { float gq = fmaxf(fabsf(qg[lane]), fabsf(qg[lane + 64])), gk = fmaxf(fabsf(kg[lane]), fabsf(kg[lane + 64]));
;             gq = wave_max(gq); gk = wave_max(gk);
;             if (lane == 0) sm[0] = 2.f * 11.313708499f * gq * gk; }
.LBB0_378:
	s_andn2_b64 vcc, exec, s[4:5]
	s_cbranch_vccnz .LBB0_488
	s_add_u32 s14, s64, 0x21440000
	s_addc_u32 s15, s65, 0
	s_add_u32 s91, s64, 0x20000000
	s_addc_u32 s92, s65, 0
	s_mul_hi_i32 s77, s12, 0x7020
	s_mul_i32 s90, s12, 0x7020
	s_cmp_lt_i32 s57, 4
	s_mov_b64 s[4:5], -1
	s_cbranch_scc1 .LBB0_447
	s_cmp_eq_u32 s57, 4
	s_cbranch_scc0 .LBB0_446
	s_lshl_b32 s18, s12, 7
	s_ashr_i32 s19, s18, 31
	v_mov_b32_e32 v10, v217
	s_mov_b32 s4, s2
	s_cmp_gt_i32 s4, 15
	s_cbranch_scc1 .LBB0_398
	s_mov_b32 s6, s2
	s_ashr_i32 s7, s6, 31
	s_lshl_b64 s[20:21], s[6:7], 16
	s_add_u32 s4, s14, s20
	v_ashrrev_i32_e32 v11, 31, v10
	s_addc_u32 s5, s15, s21
	v_lshlrev_b64 v[2:3], 7, v[10:11]
	v_lshl_add_u64 v[2:3], s[4:5], 0, v[2:3]
	global_load_dwordx4 v[4:7], v[2:3], off
	global_load_dwordx4 v[12:15], v[2:3], off offset:16
	global_load_dwordx4 v[16:19], v[2:3], off offset:32
	global_load_dwordx4 v[20:23], v[2:3], off offset:48
	global_load_dwordx4 v[24:27], v[2:3], off offset:64
	global_load_dwordx4 v[28:31], v[2:3], off offset:80
	global_load_dwordx4 v[76:79], v[2:3], off offset:96
	global_load_dwordx4 v[80:83], v[2:3], off offset:112
	v_lshl_add_u32 v2, v10, 3, 0
	v_add_u32_e32 v0, 0x11080, v2
	v_cmp_gt_u32_e32 vcc, 64, v10
	s_waitcnt vmcnt(0) lgkmcnt(0)
	v_cvt_f64_f32_e32 v[72:73], v4
	v_cvt_f64_f32_e32 v[74:75], v5
	v_add_f64 v[4:5], v[72:73], 0
	v_cvt_f64_f32_e32 v[68:69], v6
	v_add_f64 v[4:5], v[4:5], v[74:75]
	v_cvt_f64_f32_e32 v[70:71], v7
	v_add_f64 v[4:5], v[4:5], v[68:69]
	v_cvt_f64_f32_e32 v[64:65], v12
	v_add_f64 v[4:5], v[4:5], v[70:71]
	v_cvt_f64_f32_e32 v[66:67], v13
	v_add_f64 v[4:5], v[4:5], v[64:65]
	v_cvt_f64_f32_e32 v[60:61], v14
	v_add_f64 v[4:5], v[4:5], v[66:67]
	v_cvt_f64_f32_e32 v[62:63], v15
	v_add_f64 v[4:5], v[4:5], v[60:61]
	v_cvt_f64_f32_e32 v[56:57], v16
	v_add_f64 v[4:5], v[4:5], v[62:63]
	v_cvt_f64_f32_e32 v[58:59], v17
	v_add_f64 v[4:5], v[4:5], v[56:57]
	v_cvt_f64_f32_e32 v[52:53], v18
	v_add_f64 v[4:5], v[4:5], v[58:59]
	v_cvt_f64_f32_e32 v[54:55], v19
	v_add_f64 v[4:5], v[4:5], v[52:53]
	v_cvt_f64_f32_e32 v[48:49], v20
	v_add_f64 v[4:5], v[4:5], v[54:55]
	v_cvt_f64_f32_e32 v[50:51], v21
	v_add_f64 v[4:5], v[4:5], v[48:49]
	v_cvt_f64_f32_e32 v[44:45], v22
	v_add_f64 v[4:5], v[4:5], v[50:51]
	v_cvt_f64_f32_e32 v[46:47], v23
	v_add_f64 v[4:5], v[4:5], v[44:45]
	v_cvt_f64_f32_e32 v[40:41], v24
	v_add_f64 v[4:5], v[4:5], v[46:47]
	v_cvt_f64_f32_e32 v[42:43], v25
	v_add_f64 v[4:5], v[4:5], v[40:41]
	v_cvt_f64_f32_e32 v[36:37], v26
	v_add_f64 v[4:5], v[4:5], v[42:43]
	v_cvt_f64_f32_e32 v[38:39], v27
	v_add_f64 v[4:5], v[4:5], v[36:37]
	v_cvt_f64_f32_e32 v[32:33], v28
	v_add_f64 v[4:5], v[4:5], v[38:39]
	v_cvt_f64_f32_e32 v[34:35], v29
	v_add_f64 v[4:5], v[4:5], v[32:33]
	v_cvt_f64_f32_e32 v[28:29], v30
	v_add_f64 v[4:5], v[4:5], v[34:35]
	v_cvt_f64_f32_e32 v[30:31], v31
	v_add_f64 v[4:5], v[4:5], v[28:29]
	v_cvt_f64_f32_e32 v[24:25], v76
	v_add_f64 v[4:5], v[4:5], v[30:31]
	v_cvt_f64_f32_e32 v[26:27], v77
	v_add_f64 v[4:5], v[4:5], v[24:25]
	v_cvt_f64_f32_e32 v[20:21], v78
	v_add_f64 v[4:5], v[4:5], v[26:27]
	v_cvt_f64_f32_e32 v[22:23], v79
	v_add_f64 v[4:5], v[4:5], v[20:21]
	v_cvt_f64_f32_e32 v[16:17], v80
	v_add_f64 v[4:5], v[4:5], v[22:23]
	v_cvt_f64_f32_e32 v[18:19], v81
	v_add_f64 v[4:5], v[4:5], v[16:17]
	v_cvt_f64_f32_e32 v[12:13], v82
	v_add_f64 v[4:5], v[4:5], v[18:19]
	v_cvt_f64_f32_e32 v[14:15], v83
	v_add_f64 v[4:5], v[4:5], v[12:13]
	v_add_f64 v[4:5], v[4:5], v[14:15]
	ds_write_b64 v0, v[4:5]
	s_and_saveexec_b64 s[4:5], vcc
	s_cbranch_execz .LBB0_385
	s_load_dwordx4 s[8:11], s[30:31], 0x40
	s_lshl_b64 s[22:23], s[18:19], 2
	v_and_b32_e32 v8, 63, v10
	v_mov_b32_e32 v0, v10
	v_lshlrev_b32_e32 v3, 2, v8
	s_waitcnt lgkmcnt(0)
	s_add_u32 s24, s8, s22
	s_addc_u32 s25, s9, s23
	s_add_u32 s22, s10, s22
	v_lshlrev_b64 v[4:5], 2, v[0:1]
	s_addc_u32 s23, s11, s23
	global_load_dword v9, v3, s[24:25]
	v_lshl_add_u64 v[6:7], s[24:25], 0, v[4:5]
	global_load_dword v0, v[6:7], off offset:256
	s_nop 0
	global_load_dword v3, v3, s[22:23]
	v_lshl_add_u64 v[4:5], s[22:23], 0, v[4:5]
	global_load_dword v4, v[4:5], off offset:256
	v_cmp_eq_u32_e32 vcc, 0, v8
	s_waitcnt vmcnt(3)
	v_max_f32_e64 v5, |v9|, |v9|
	s_waitcnt vmcnt(2)
	v_max_f32_e64 v0, |v0|, |v0|
	v_max_f32_e32 v0, v5, v0
	s_waitcnt vmcnt(1)
	v_max_f32_e64 v3, |v3|, |v3|
	s_waitcnt vmcnt(0)
	v_max_f32_e64 v4, |v4|, |v4|
	v_mov_b32_dpp v5, v0 quad_perm:[1,0,3,2] row_mask:0xf bank_mask:0xf bound_ctrl:1
	v_max_f32_e32 v3, v3, v4
	v_max_f32_e32 v4, v5, v5
	v_max_f32_e32 v0, v0, v4
	s_nop 0
	v_mov_b32_dpp v4, v3 quad_perm:[1,0,3,2] row_mask:0xf bank_mask:0xf bound_ctrl:1
	v_mov_b32_dpp v5, v0 quad_perm:[2,3,0,1] row_mask:0xf bank_mask:0xf bound_ctrl:1
	v_max_f32_e32 v4, v4, v4
	v_max_f32_e32 v5, v5, v5
	v_max_f32_e32 v3, v3, v4
	v_max_f32_e32 v0, v0, v5
	s_nop 0
	v_mov_b32_dpp v4, v3 quad_perm:[2,3,0,1] row_mask:0xf bank_mask:0xf bound_ctrl:1
	v_mov_b32_dpp v5, v0 row_ror:4 row_mask:0xf bank_mask:0xf bound_ctrl:1
	v_max_f32_e32 v4, v4, v4
	v_max_f32_e32 v5, v5, v5
	v_max_f32_e32 v3, v3, v4
	v_max_f32_e32 v0, v0, v5
	s_nop 0
	v_mov_b32_dpp v4, v3 row_ror:4 row_mask:0xf bank_mask:0xf bound_ctrl:1
	v_mov_b32_dpp v5, v0 row_ror:8 row_mask:0xf bank_mask:0xf bound_ctrl:1
	v_max_f32_e32 v4, v4, v4
	v_max_f32_e32 v5, v5, v5
	v_max_f32_e32 v3, v3, v4
	v_max_f32_e32 v0, v0, v5
	v_mov_b32_e32 v5, v0
	v_mov_b32_dpp v4, v3 row_ror:8 row_mask:0xf bank_mask:0xf bound_ctrl:1
	v_max_f32_e32 v4, v4, v4
	v_permlane16_swap_b32_e32 v0, v5
	v_max_f32_e32 v4, v3, v4
	v_max_f32_e32 v3, v5, v5
	v_mov_b32_e32 v5, v4
	s_nop 1
	v_permlane16_swap_b32_e32 v4, v5
	v_max_f32_e32 v0, v0, v0
	v_max_f32_e32 v5, v5, v5
	v_max_f32_e32 v4, v4, v4
	v_max_f32_e32 v0, v0, v3
	v_max_f32_e32 v4, v4, v5
	v_mov_b32_e32 v3, v0
	v_mov_b32_e32 v5, v4
	s_nop 0
	v_permlane32_swap_b32_e32 v0, v3
	v_permlane32_swap_b32_e32 v4, v5
	s_and_b64 exec, exec, vcc
	s_cbranch_execz .LBB0_385
	v_max_f32_e32 v0, v0, v0
	v_max_f32_e32 v3, v3, v3
	v_max_f32_e32 v0, v0, v3
	v_max_f32_e32 v3, v4, v4
	v_max_f32_e32 v4, v5, v5
	v_mul_f32_e32 v0, 0x41b504f3, v0
	v_max_f32_e32 v3, v3, v4
	v_readlane_b32 s8, v255, 8
	v_mul_f32_e32 v0, v0, v3
	s_nop 0
	v_mov_b32_e32 v3, s8
	ds_write_b32 v3, v0

; DEVI void post_inproj_phase(const float* logf, float* cs, int* jlo, const float* qg, const float* kg, bf16_t* Qb, bf16_t* Kb, char* lds, int wv) {
;     ...
; #pragma unroll 4
;         for (int j = 0; j < 32; ++j) { const int e = j * 512 + tid; cs[(size_t)bh * SEQ + e] = -cL[PADI(e)] * 11.313708499f; }
;         if (tid < 64) {
;             const int P0 = tid * 256, nj = P0 / 64; const float cP = cL[PADI(P0)], thr = -(104.f + sm[0]);
;             int lo = 0, hi = nj;
;             while (lo < hi) { const int mid = (lo + hi) >> 1; if (cP - cL[PADI(64 * mid + 63)] >= thr) hi = mid; else lo = mid + 1; }
.LBB0_390:
	v_add_u32_e32 v7, s7, v10
	v_ashrrev_i32_e32 v8, 5, v7
	v_lshl_add_u32 v8, v8, 2, v6
	ds_read_b32 v8, v8
	s_addk_i32 s7, 0x800
	s_cmpk_eq_i32 s7, 0x4000
	s_waitcnt lgkmcnt(0)
	v_mul_f32_e32 v11, 0xc13504f3, v8
	v_add_co_u32_e32 v8, vcc, 0xfffff800, v4
	s_nop 1
	v_addc_co_u32_e32 v9, vcc, -1, v5, vcc
	global_store_dword v[8:9], v11, off
	v_add_u32_e32 v8, 0x200, v7
	v_ashrrev_i32_e32 v8, 5, v8
	v_lshl_add_u32 v8, v8, 2, v6
	ds_read_b32 v8, v8 offset:2048
	s_waitcnt lgkmcnt(0)
	v_mul_f32_e32 v8, 0xc13504f3, v8
	global_store_dword v[4:5], v8, off
	v_add_u32_e32 v8, 0x400, v7
	v_ashrrev_i32_e32 v8, 5, v8
	v_lshl_add_u32 v8, v8, 2, v6
	ds_read_b32 v8, v8 offset:4096
	v_lshl_add_u64 v[4:5], v[4:5], 0, s[8:9]
	s_waitcnt lgkmcnt(0)
	v_mul_f32_e32 v8, 0xc13504f3, v8
	global_store_dword v[2:3], v8, off
	v_add_u32_e32 v8, 0x600, v7
	v_ashrrev_i32_e32 v7, 5, v8
	v_lshl_add_u32 v7, v7, 2, v6
	ds_read_b32 v7, v7 offset:6144
	v_ashrrev_i32_e32 v9, 31, v8
	v_lshl_add_u64 v[8:9], v[8:9], 2, s[22:23]
	v_lshl_add_u64 v[2:3], v[2:3], 0, s[8:9]
	v_add_u32_e32 v6, 0x2000, v6
	s_waitcnt lgkmcnt(0)
	v_mul_f32_e32 v7, 0xc13504f3, v7
	global_store_dword v[8:9], v7, off
	s_cbranch_scc0 .LBB0_390
	s_and_saveexec_b64 s[20:21], s[4:5]
	s_cbranch_execz .LBB0_397
	v_mov_b32_e32 v3, 0
	v_cmp_lt_i32_e32 vcc, 0, v10
	s_and_saveexec_b64 s[4:5], vcc
	s_cbranch_execz .LBB0_396
	s_movk_i32 s7, 0x420
	v_mul_lo_u32 v2, v10, s7
	v_readlane_b32 s7, v255, 8
	v_add_u32_e32 v2, 0, v2
	ds_read_b32 v2, v2
	v_mov_b32_e32 v3, s7
	ds_read_b32 v3, v3
	s_mov_b64 s[22:23], 0
	s_waitcnt lgkmcnt(0)
	v_add_f32_e32 v4, 0x42d00000, v3
	v_mov_b32_e32 v3, 0

; DEVI void post_inproj_phase(const float* logf, float* cs, int* jlo, const float* qg, const float* kg, bf16_t* Qb, bf16_t* Kb, char* lds, int wv) {
;     ...
;             jlo[bh * 64 + tid] = lo;
.LBB0_396:
	s_or_b64 exec, exec, s[4:5]
	v_lshl_add_u32 v4, s6, 6, v10
	v_ashrrev_i32_e32 v5, 31, v4
	v_lshl_add_u64 v[4:5], v[4:5], 2, s[16:17]
	global_store_dword v[4:5], v3, off

; DEVI unsigned cvtpk(float lo, float hi) { unsigned r; asm volatile("v_cvt_pk_bf16_f32 %0, %1, %2" : "=v"(r) : "v"(lo), "v"(hi)); return r; }
;     DEVI void operator()(AccRef acc, const pg8::Unit& u, int wr, int wc, int fr, int fq) const {
;     ...
; #pragma unroll
;         for (int ai = 0; ai < 2; ++ai)
; #pragma unroll
;             for (int m = 0; m < 4; ++m) { bf16_t* rowp = dst + (size_t)(row0 + ai * 128 + m * 16) * DM + col0;
; #pragma unroll
;                 for (int bj = 0; bj < 2; ++bj) { const f32x4 v0 = acc[ai][bj][m][0], v1 = acc[ai][bj][m][1];
;                     u32x4 w; w.x = cvtpk(v0[0], v0[1]); w.y = cvtpk(v0[2], v0[3]); w.z = cvtpk(v1[0], v1[1]); w.w = cvtpk(v1[2], v1[3]); __builtin_nontemporal_store(w, (u32x4*)(rowp + bj * 128)); } }
.LBB0_405:
	s_ashr_i32 s60, s24, 2
	s_ashr_i32 s61, s60, 31
	s_and_b32 s8, s21, 0x300
	s_lshl_b64 s[60:61], s[60:61], 26
	v_or_b32_e32 v0, s8, v160
	s_add_u32 s60, s64, s60
	v_lshl_add_u32 v8, s78, 8, v158
	s_addc_u32 s61, s65, s61
	v_lshlrev_b32_e32 v0, 1, v0
	v_lshl_add_u64 v[2:3], s[60:61], 0, v[0:1]
	s_mov_b64 s[60:61], 0x4000000
	v_ashrrev_i32_e32 v9, 31, v8
	v_lshl_add_u64 v[10:11], v[2:3], 0, s[60:61]
	v_lshlrev_b64 v[2:3], 11, v[8:9]
	v_lshl_add_u64 v[2:3], v[10:11], 0, v[2:3]
	v_cvt_pk_bf16_f32 v4, v126, v127
	v_cvt_pk_bf16_f32 v5, v128, v129
	v_cvt_pk_bf16_f32 v6, v144, v145
	v_cvt_pk_bf16_f32 v7, v142, v143
	global_store_dwordx4 v[2:3], v[4:7], off nt
	s_mov_b32 s8, 0x40000
	s_mov_b64 s[60:61], 0x40000
	v_cvt_pk_bf16_f32 v4, v152, v153
	v_cvt_pk_bf16_f32 v5, v150, v151
	v_cvt_pk_bf16_f32 v6, v156, v157
	v_cvt_pk_bf16_f32 v7, v154, v155
	global_store_dwordx4 v[2:3], v[4:7], off offset:256 nt
	s_mov_b32 s24, s20
	s_mov_b32 s78, s22
	v_or_b32_e32 v4, 16, v8
	v_ashrrev_i32_e32 v5, 31, v4
	v_lshlrev_b64 v[4:5], 11, v[4:5]
	v_lshl_add_u64 v[12:13], v[10:11], 0, v[4:5]
	v_cvt_pk_bf16_f32 v4, v122, v123
	v_cvt_pk_bf16_f32 v5, v124, v125
	v_cvt_pk_bf16_f32 v6, v120, v121
	v_cvt_pk_bf16_f32 v7, v118, v119
	global_store_dwordx4 v[12:13], v[4:7], off nt
	s_mov_b64 s[84:85], s[82:83]
	s_mov_b64 s[86:87], s[80:81]
	v_cvt_pk_bf16_f32 v4, v64, v65
	v_cvt_pk_bf16_f32 v5, v62, v63
	v_cvt_pk_bf16_f32 v6, v148, v149
	v_cvt_pk_bf16_f32 v7, v146, v147
	global_store_dwordx4 v[12:13], v[4:7], off offset:256 nt
	s_nop 1
	v_or_b32_e32 v4, 32, v8
	v_ashrrev_i32_e32 v5, 31, v4
	v_lshlrev_b64 v[4:5], 11, v[4:5]
	v_lshl_add_u64 v[12:13], v[10:11], 0, v[4:5]
	v_cvt_pk_bf16_f32 v4, v114, v115
	v_cvt_pk_bf16_f32 v5, v116, v117
	v_cvt_pk_bf16_f32 v6, v112, v113
	v_cvt_pk_bf16_f32 v7, v110, v111
	global_store_dwordx4 v[12:13], v[4:7], off nt
	s_nop 1
	v_cvt_pk_bf16_f32 v4, v60, v61
	v_cvt_pk_bf16_f32 v5, v58, v59
	v_cvt_pk_bf16_f32 v6, v56, v57
	v_cvt_pk_bf16_f32 v7, v54, v55
	global_store_dwordx4 v[12:13], v[4:7], off offset:256 nt
	s_nop 1
	v_or_b32_e32 v4, 48, v8
	v_ashrrev_i32_e32 v5, 31, v4
	v_lshlrev_b64 v[4:5], 11, v[4:5]
	v_lshl_add_u64 v[8:9], v[10:11], 0, v[4:5]
	v_cvt_pk_bf16_f32 v4, v106, v107
	v_cvt_pk_bf16_f32 v5, v108, v109
	v_cvt_pk_bf16_f32 v6, v104, v105
	v_cvt_pk_bf16_f32 v7, v102, v103
	global_store_dwordx4 v[8:9], v[4:7], off nt
	v_add_co_u32_e32 v10, vcc, s8, v2
	s_nop 0
	v_cvt_pk_bf16_f32 v4, v52, v53
	v_cvt_pk_bf16_f32 v5, v50, v51
	v_cvt_pk_bf16_f32 v6, v48, v49
	v_cvt_pk_bf16_f32 v7, v46, v47
	global_store_dwordx4 v[8:9], v[4:7], off offset:256 nt
	v_addc_co_u32_e32 v11, vcc, 0, v3, vcc
	s_nop 0
	v_cvt_pk_bf16_f32 v4, v94, v95
	v_cvt_pk_bf16_f32 v5, v96, v97
	v_cvt_pk_bf16_f32 v6, v100, v101
	v_cvt_pk_bf16_f32 v7, v98, v99
	s_mov_b32 s8, 0x48000
	v_lshl_add_u64 v[8:9], v[2:3], 0, s[60:61]
	global_store_dwordx4 v[10:11], v[4:7], off nt
	v_add_co_u32_e32 v10, vcc, s8, v2
	s_nop 0
	v_cvt_pk_bf16_f32 v4, v44, v45
	v_cvt_pk_bf16_f32 v5, v42, v43
	v_cvt_pk_bf16_f32 v6, v40, v41
	v_cvt_pk_bf16_f32 v7, v38, v39
	global_store_dwordx4 v[8:9], v[4:7], off offset:256 nt
	s_mov_b64 s[60:61], 0x48000
	v_addc_co_u32_e32 v11, vcc, 0, v3, vcc
	v_cvt_pk_bf16_f32 v4, v90, v91
	v_cvt_pk_bf16_f32 v5, v92, v93
	v_cvt_pk_bf16_f32 v6, v88, v89
	v_cvt_pk_bf16_f32 v7, v86, v87
	s_mov_b32 s8, 0x50000
	v_lshl_add_u64 v[8:9], v[2:3], 0, s[60:61]
	global_store_dwordx4 v[10:11], v[4:7], off nt
	s_mov_b64 s[60:61], 0x50000
	v_add_co_u32_e32 v10, vcc, s8, v2
	v_cvt_pk_bf16_f32 v4, v32, v33
	v_cvt_pk_bf16_f32 v5, v30, v31
	v_cvt_pk_bf16_f32 v6, v36, v37
	v_cvt_pk_bf16_f32 v7, v34, v35
	global_store_dwordx4 v[8:9], v[4:7], off offset:256 nt
	v_lshl_add_u64 v[8:9], v[2:3], 0, s[60:61]
	v_addc_co_u32_e32 v11, vcc, 0, v3, vcc
	v_cvt_pk_bf16_f32 v4, v82, v83
	v_cvt_pk_bf16_f32 v5, v84, v85
	v_cvt_pk_bf16_f32 v6, v80, v81
	v_cvt_pk_bf16_f32 v7, v78, v79
	s_mov_b64 s[60:61], 0x58000
	s_mov_b32 s8, 0x58000
	global_store_dwordx4 v[10:11], v[4:7], off nt
	s_nop 1
	v_cvt_pk_bf16_f32 v4, v28, v29
	v_cvt_pk_bf16_f32 v5, v26, v27
	v_cvt_pk_bf16_f32 v6, v24, v25
	v_cvt_pk_bf16_f32 v7, v22, v23
	global_store_dwordx4 v[8:9], v[4:7], off offset:256 nt
	v_lshl_add_u64 v[8:9], v[2:3], 0, s[60:61]
	v_add_co_u32_e32 v2, vcc, s8, v2
	v_cvt_pk_bf16_f32 v4, v74, v75
	v_cvt_pk_bf16_f32 v5, v76, v77
	v_cvt_pk_bf16_f32 v6, v72, v73
	v_cvt_pk_bf16_f32 v7, v70, v71
	s_nop 1
	v_addc_co_u32_e32 v3, vcc, 0, v3, vcc
	s_and_b64 vcc, exec, s[6:7]
	global_store_dwordx4 v[2:3], v[4:7], off nt
	v_cvt_pk_bf16_f32 v2, v20, v21
	v_cvt_pk_bf16_f32 v3, v18, v19
	s_nop 1
	v_cvt_pk_bf16_f32 v4, v16, v17
	v_cvt_pk_bf16_f32 v5, v14, v15
	global_store_dwordx4 v[8:9], v[2:5], off offset:256 nt
	s_cbranch_vccnz .LBB0_443

; DEVI unsigned cvtpk(float lo, float hi) { unsigned r; asm volatile("v_cvt_pk_bf16_f32 %0, %1, %2" : "=v"(r) : "v"(lo), "v"(hi)); return r; }
; DEVI int ltid(int wv) { int t = (wv << 6) | (int)__builtin_amdgcn_mbcnt_hi(~0u, __builtin_amdgcn_mbcnt_lo(~0u, 0u)); asm volatile("" : "+v"(t)); return t; }
; DEVI int lbid() { int t = blockIdx.x; asm volatile("" : "+s"(t)); return t; }
; template <int KT, class F> DEVI void cvt_tile(F colptr, int ldsrc, int k0, bf16_t* out, int ldo, int v0, float* tile, int wv) {
;     const int tid = ltid(wv);
;     constexpr int PITCH = KT * 64 + 1;
;     { const int vc = tid & 63, kk = tid >> 6; const float* cp = colptr(v0 + vc) + (size_t)k0 * ldsrc; float v[8 * KT];
; #pragma unroll
;       for (int r = 0; r < 8 * KT; ++r) v[r] = cp[(size_t)(r * 8 + kk) * ldsrc];
; #pragma unroll
;       for (int r = 0; r < 8 * KT; ++r) tile[vc * PITCH + r * 8 + kk] = v[r]; }
;     __syncthreads();
;     { const int vc = tid >> 3, k8 = (tid & 7) * 8;
; #pragma unroll
;       for (int q = 0; q < KT; ++q) { const float* tp = tile + vc * PITCH + q * 64 + k8;
;         u32x4 w = {cvtpk(tp[0], tp[1]), cvtpk(tp[2], tp[3]), cvtpk(tp[4], tp[5]), cvtpk(tp[6], tp[7])};
;         *(u32x4*)(out + (size_t)(v0 + vc) * ldo + k0 + q * 64 + k8) = w; } }
;     __syncthreads();
; }
; DEVI void cvt_mix_phase(const float* win, const float* woa, const float* wor, const float* wout, const float* lwa, const float* lwx, unsigned char* ws, char* lds, int wv) {
;     ...
;     for (int job = lbid(); job < 448 + 192 + 32; job += lgrid()) {
;         if (job < 448) { const int vt = job >> 2, kg = job & 3; cvt_tile<4>(ColIn{win}, NIN, kg * 256, (bf16_t*)(ws + WS_WIN), DM, vt * 64, tile, wv); }
;         else if (job < 448 + 192) { const int j = job - 448, m = j >> 6, jj = j & 63, vt = jj >> 2, kg = jj & 3;
;             const float* src = m == 0 ? woa : (m == 1 ? wor : wout);
;             if (m < 2) cvt_tile<4>(ColLin{src}, DM, kg * 256, (bf16_t*)(ws + WS_WOA) + m * DM, 2 * DM, vt * 64, tile, wv);
;             else cvt_tile<4>(ColLin{src}, DM, kg * 256, (bf16_t*)(ws + WS_WOUT), DM, vt * 64, tile, wv); }
;         else { const int j = job - 448 - 192, gate = j >> 4, n = j & 15; const float* src = (gate ? lwx : lwa) + n * 4096;
;             cvt_tile<1>(ColLin{src}, 64, 0, (bf16_t*)(ws + WS_LRU) + n * 8192 + gate * 4096, 64, 0, tile, wv); }
.LBB0_451:
	s_cmpk_gt_i32 s59, 0x1bf
	s_mov_b64 s[22:23], -1
	s_cbranch_scc0 .LBB0_460
	s_cmpk_gt_u32 s59, 0x27f
	s_cbranch_scc0 .LBB0_454
	s_add_i32 s24, s59, 0xfffffd80
	s_and_b32 s22, s59, 15
	s_cmp_lt_u32 s24, 16
	s_cselect_b32 s25, s16, s18
	s_cselect_b32 s23, s17, s19
	s_add_u32 s25, s25, s4
	s_addc_u32 s23, s23, s5
	s_lshl_b32 s46, s22, 14
	v_mov_b32_e32 v12, v217
	s_add_u32 s22, s25, s46
	s_addc_u32 s23, s23, 0
	v_and_b32_e32 v13, 63, v12
	v_ashrrev_i32_e32 v2, 6, v12
	v_lshlrev_b32_e32 v0, 2, v13
	v_ashrrev_i32_e32 v3, 31, v2
	v_lshl_add_u64 v[4:5], s[22:23], 0, v[0:1]
	v_lshlrev_b64 v[6:7], 8, v[2:3]
	v_lshl_add_u64 v[4:5], v[4:5], 0, v[6:7]
	s_movk_i32 s22, 0x1000
	v_add_co_u32_e32 v6, vcc, s22, v4
	s_movk_i32 s22, 0x2000
	s_nop 0
	v_addc_co_u32_e32 v7, vcc, 0, v5, vcc
	v_add_co_u32_e32 v8, vcc, s22, v4
	s_movk_i32 s22, 0x3000
	s_nop 0
	v_addc_co_u32_e32 v9, vcc, 0, v5, vcc
	v_add_co_u32_e32 v10, vcc, s22, v4
	s_movk_i32 s22, 0x104
	s_nop 0
	v_addc_co_u32_e32 v11, vcc, 0, v5, vcc
	global_load_dword v0, v[4:5], off
	global_load_dword v3, v[4:5], off offset:2048
	s_nop 0
	global_load_dword v5, v[8:9], off offset:-4096
	s_nop 0
	global_load_dword v6, v[6:7], off offset:2048
	s_nop 0
	global_load_dword v7, v[8:9], off
	s_nop 0
	global_load_dword v8, v[8:9], off offset:2048
	s_nop 0
	global_load_dword v9, v[10:11], off
	s_nop 0
	global_load_dword v10, v[10:11], off offset:2048
	v_ashrrev_i32_e32 v4, 3, v12
	v_lshlrev_b32_e32 v11, 3, v12
	v_mul_u32_u24_e32 v12, 0x104, v13
	v_lshlrev_b32_e32 v2, 2, v2
	v_and_b32_e32 v11, 56, v11
	v_mul_lo_u32 v13, v4, s22
	v_readlane_b32 s22, v255, 29
	v_add3_u32 v2, 0, v12, v2
	v_lshlrev_b32_e32 v12, 2, v11
	s_add_u32 s22, s22, s46
	v_readlane_b32 s23, v255, 30
	v_add3_u32 v12, 0, v12, v13
	s_addc_u32 s23, s23, 0
	s_lshl_b32 s24, s24, 9
	v_add_u32_e32 v2, 0x8000, v2
	v_add_u32_e32 v13, 0x8000, v12
	s_and_b32 s24, s24, 0xffffe000
	s_add_u32 s22, s22, s24
	s_addc_u32 s23, s23, 0
	s_waitcnt vmcnt(0)
	ds_write2_b32 v2, v0, v3 offset1:8
	ds_write2_b32 v2, v5, v6 offset0:16 offset1:24
	ds_write2_b32 v2, v7, v8 offset0:32 offset1:40
	ds_write2_b32 v2, v9, v10 offset0:48 offset1:56
	s_waitcnt lgkmcnt(0)
	s_barrier
	ds_read2_b32 v[2:3], v13 offset1:1
	v_ashrrev_i32_e32 v5, 31, v4
	v_add_u32_e32 v0, 0x8008, v12
	s_waitcnt lgkmcnt(0)
	v_cvt_pk_bf16_f32 v2, v2, v3
	ds_read2_b32 v[6:7], v0 offset1:1
	v_lshlrev_b64 v[8:9], 7, v[4:5]
	v_add_u32_e32 v0, 0x8010, v12
	s_waitcnt lgkmcnt(0)
	v_cvt_pk_bf16_f32 v3, v6, v7
	ds_read2_b32 v[4:5], v0 offset1:1
	v_lshlrev_b32_e32 v0, 1, v11
	v_lshl_add_u64 v[8:9], s[22:23], 0, v[8:9]
	v_add_u32_e32 v10, 0x8018, v12
	v_lshl_add_u64 v[8:9], v[8:9], 0, v[0:1]
	s_waitcnt lgkmcnt(0)
	v_cvt_pk_bf16_f32 v4, v4, v5
	ds_read2_b32 v[6:7], v10 offset1:1
	s_waitcnt lgkmcnt(0)
	v_cvt_pk_bf16_f32 v5, v6, v7
	global_store_dwordx4 v[8:9], v[2:5], off
	s_waitcnt lgkmcnt(0)
	s_barrier
	s_mov_b64 s[22:23], 0
.LBB0_454:
	s_andn2_b64 vcc, exec, s[22:23]
	s_cbranch_vccnz .LBB0_459
	s_add_i32 s80, s59, 0xfffffe40
	s_lshr_b32 s79, s80, 6
	s_bfe_u32 s78, s59, 0x40002
	s_and_b32 s76, s59, 3
	s_cmp_eq_u32 s79, 1
	s_cselect_b32 s22, s6, s20
	s_cselect_b32 s23, s7, s21
	s_add_u32 s22, s22, s12
	s_addc_u32 s23, s23, s13
	s_cmpk_gt_u32 s80, 0x7f
	s_mov_b64 s[24:25], -1
	s_cbranch_scc0 .LBB0_457
	v_mov_b32_e32 v8, v217
	s_lshl_b32 s24, s78, 6
	s_lshl_b32 s46, s76, 20
	v_and_b32_e32 v9, 63, v8
	v_or_b32_e32 v0, s24, v9
	v_ashrrev_i32_e32 v2, 6, v8
	v_lshlrev_b32_e32 v0, 2, v0
	v_lshl_add_u64 v[4:5], s[22:23], 0, v[0:1]
	v_ashrrev_i32_e32 v3, 31, v2
	v_lshl_add_u64 v[4:5], v[4:5], 0, s[46:47]
	v_lshlrev_b64 v[6:7], 12, v[2:3]
	v_lshl_add_u64 v[4:5], v[4:5], 0, v[6:7]
	v_add_co_u32_e32 v6, vcc, s33, v4
	global_load_dword v0, v[4:5], off
	s_nop 0
	v_addc_co_u32_e32 v7, vcc, 0, v5, vcc
	global_load_dword v3, v[6:7], off
	v_add_co_u32_e32 v6, vcc, s54, v4
	s_mov_b32 s25, 0x28000
	s_nop 0
	v_addc_co_u32_e32 v7, vcc, 0, v5, vcc
	global_load_dword v10, v[6:7], off
	v_add_co_u32_e32 v6, vcc, s27, v4
	v_lshlrev_b32_e32 v2, 2, v2
	s_nop 0
	v_addc_co_u32_e32 v7, vcc, 0, v5, vcc
	global_load_dword v11, v[6:7], off
	v_add_co_u32_e32 v6, vcc, s38, v4
	v_readlane_b32 s46, v255, 15
	s_nop 0
	v_addc_co_u32_e32 v7, vcc, 0, v5, vcc
	global_load_dword v12, v[6:7], off
	v_add_co_u32_e32 v6, vcc, s25, v4
	s_mov_b32 s25, 0x38000
	s_nop 0
	v_addc_co_u32_e32 v7, vcc, 0, v5, vcc
	global_load_dword v13, v[6:7], off
	v_add_co_u32_e32 v6, vcc, s39, v4
	s_nop 1
	v_addc_co_u32_e32 v7, vcc, 0, v5, vcc
	global_load_dword v14, v[6:7], off
	v_add_co_u32_e32 v6, vcc, s25, v4
	s_mov_b32 s25, 0x40000
	s_nop 0
	v_addc_co_u32_e32 v7, vcc, 0, v5, vcc
	global_load_dword v15, v[6:7], off
	v_add_co_u32_e32 v6, vcc, s25, v4
	s_mov_b32 s25, 0x48000
	s_nop 0
	v_addc_co_u32_e32 v7, vcc, 0, v5, vcc
	global_load_dword v16, v[6:7], off
	v_add_co_u32_e32 v6, vcc, s25, v4
	s_mov_b32 s25, 0x50000
	s_nop 0
	v_addc_co_u32_e32 v7, vcc, 0, v5, vcc
	global_load_dword v17, v[6:7], off
	v_add_co_u32_e32 v6, vcc, s25, v4
	s_mov_b32 s25, 0x58000
	s_nop 0
	v_addc_co_u32_e32 v7, vcc, 0, v5, vcc
	global_load_dword v18, v[6:7], off
	v_add_co_u32_e32 v6, vcc, s25, v4
	s_mov_b32 s25, 0x60000
	s_nop 0
	v_addc_co_u32_e32 v7, vcc, 0, v5, vcc
	global_load_dword v19, v[6:7], off
	v_add_co_u32_e32 v6, vcc, s25, v4
	s_mov_b32 s25, 0x68000
	s_nop 0
	v_addc_co_u32_e32 v7, vcc, 0, v5, vcc
	global_load_dword v20, v[6:7], off
	v_add_co_u32_e32 v6, vcc, s25, v4
	s_mov_b32 s25, 0x70000
	s_nop 0
	v_addc_co_u32_e32 v7, vcc, 0, v5, vcc
	global_load_dword v21, v[6:7], off
	v_add_co_u32_e32 v6, vcc, s25, v4
	s_mov_b32 s25, 0x78000
	s_nop 0
	v_addc_co_u32_e32 v7, vcc, 0, v5, vcc
; DEVI unsigned cvtpk(float lo, float hi) { unsigned r; asm volatile("v_cvt_pk_bf16_f32 %0, %1, %2" : "=v"(r) : "v"(lo), "v"(hi)); return r; }
; DEVI int ltid(int wv) { int t = (wv << 6) | (int)__builtin_amdgcn_mbcnt_hi(~0u, __builtin_amdgcn_mbcnt_lo(~0u, 0u)); asm volatile("" : "+v"(t)); return t; }
; template <int KT, class F> DEVI void cvt_tile(F colptr, int ldsrc, int k0, bf16_t* out, int ldo, int v0, float* tile, int wv) {
;     const int tid = ltid(wv);
;     constexpr int PITCH = KT * 64 + 1;
;     { const int vc = tid & 63, kk = tid >> 6; const float* cp = colptr(v0 + vc) + (size_t)k0 * ldsrc; float v[8 * KT];
; #pragma unroll
;       for (int r = 0; r < 8 * KT; ++r) v[r] = cp[(size_t)(r * 8 + kk) * ldsrc];
; #pragma unroll
;       for (int r = 0; r < 8 * KT; ++r) tile[vc * PITCH + r * 8 + kk] = v[r]; }
;     __syncthreads();
;     { const int vc = tid >> 3, k8 = (tid & 7) * 8;
; #pragma unroll
;       for (int q = 0; q < KT; ++q) { const float* tp = tile + vc * PITCH + q * 64 + k8;
;         u32x4 w = {cvtpk(tp[0], tp[1]), cvtpk(tp[2], tp[3]), cvtpk(tp[4], tp[5]), cvtpk(tp[6], tp[7])};
;         *(u32x4*)(out + (size_t)(v0 + vc) * ldo + k0 + q * 64 + k8) = w; } }
;     __syncthreads();
; }
; DEVI void cvt_mix_phase(const float* win, const float* woa, const float* wor, const float* wout, const float* lwa, const float* lwx, unsigned char* ws, char* lds, int wv) {
;     ...
;             else cvt_tile<4>(ColLin{src}, DM, kg * 256, (bf16_t*)(ws + WS_WOUT), DM, vt * 64, tile, wv); }
	global_load_dword v22, v[6:7], off
	v_add_co_u32_e32 v6, vcc, s25, v4
	s_mov_b32 s25, 0x80000
	s_nop 0
	v_addc_co_u32_e32 v7, vcc, 0, v5, vcc
	global_load_dword v23, v[6:7], off
	v_add_co_u32_e32 v6, vcc, s25, v4
	s_mov_b32 s25, 0x88000
	s_nop 0
	v_addc_co_u32_e32 v7, vcc, 0, v5, vcc
	global_load_dword v24, v[6:7], off
	v_add_co_u32_e32 v6, vcc, s25, v4
	s_mov_b32 s25, 0x90000
	s_nop 0
	v_addc_co_u32_e32 v7, vcc, 0, v5, vcc
	global_load_dword v25, v[6:7], off
	v_add_co_u32_e32 v6, vcc, s25, v4
	s_mov_b32 s25, 0x98000
	s_nop 0
	v_addc_co_u32_e32 v7, vcc, 0, v5, vcc
	global_load_dword v26, v[6:7], off
	v_add_co_u32_e32 v6, vcc, s25, v4
	s_mov_b32 s25, 0xa0000
	s_nop 0
	v_addc_co_u32_e32 v7, vcc, 0, v5, vcc
	global_load_dword v27, v[6:7], off
	v_add_co_u32_e32 v6, vcc, s25, v4
	s_mov_b32 s25, 0xa8000
	s_nop 0
	v_addc_co_u32_e32 v7, vcc, 0, v5, vcc
	global_load_dword v28, v[6:7], off
	v_add_co_u32_e32 v6, vcc, s25, v4
	s_mov_b32 s25, 0xb0000
	s_nop 0
	v_addc_co_u32_e32 v7, vcc, 0, v5, vcc
	global_load_dword v29, v[6:7], off
	v_add_co_u32_e32 v6, vcc, s25, v4
	s_mov_b32 s25, 0xb8000
	s_nop 0
	v_addc_co_u32_e32 v7, vcc, 0, v5, vcc
	global_load_dword v30, v[6:7], off
	v_add_co_u32_e32 v6, vcc, s25, v4
	s_mov_b32 s25, 0xc0000
	s_nop 0
	v_addc_co_u32_e32 v7, vcc, 0, v5, vcc
	global_load_dword v31, v[6:7], off
	v_add_co_u32_e32 v6, vcc, s25, v4
	s_mov_b32 s25, 0xc8000
	s_nop 0
	v_addc_co_u32_e32 v7, vcc, 0, v5, vcc
	global_load_dword v32, v[6:7], off
	v_add_co_u32_e32 v6, vcc, s25, v4
	s_mov_b32 s25, 0xd0000
	s_nop 0
	v_addc_co_u32_e32 v7, vcc, 0, v5, vcc
	global_load_dword v33, v[6:7], off
	v_add_co_u32_e32 v6, vcc, s25, v4
	s_mov_b32 s25, 0xd8000
	s_nop 0
	v_addc_co_u32_e32 v7, vcc, 0, v5, vcc
	global_load_dword v34, v[6:7], off
	v_add_co_u32_e32 v6, vcc, s25, v4
	s_mov_b32 s25, 0xe0000
	s_nop 0
	v_addc_co_u32_e32 v7, vcc, 0, v5, vcc
	global_load_dword v35, v[6:7], off
	v_add_co_u32_e32 v6, vcc, s25, v4
	s_mov_b32 s25, 0xe8000
	s_nop 0
	v_addc_co_u32_e32 v7, vcc, 0, v5, vcc
	global_load_dword v36, v[6:7], off
	v_add_co_u32_e32 v6, vcc, s25, v4
	s_mov_b32 s25, 0xf0000
	s_nop 0
	v_addc_co_u32_e32 v7, vcc, 0, v5, vcc
	global_load_dword v37, v[6:7], off
	v_add_co_u32_e32 v6, vcc, s25, v4
	s_mov_b32 s25, 0xf8000
	s_nop 0
	v_addc_co_u32_e32 v7, vcc, 0, v5, vcc
	v_add_co_u32_e32 v4, vcc, s25, v4
	global_load_dword v6, v[6:7], off
	s_nop 0
	v_addc_co_u32_e32 v5, vcc, 0, v5, vcc
	global_load_dword v4, v[4:5], off
	v_mul_u32_u24_e32 v5, 0x404, v9
	v_add3_u32 v2, 0, v5, v2
	v_add_u32_e32 v2, 0x8000, v2
	s_waitcnt vmcnt(0)
	ds_write2_b32 v2, v0, v3 offset1:8
	ds_write2_b32 v2, v10, v11 offset0:16 offset1:24
	ds_write2_b32 v2, v12, v13 offset0:32 offset1:40
	ds_write2_b32 v2, v14, v15 offset0:48 offset1:56
	ds_write2_b32 v2, v16, v17 offset0:64 offset1:72
	ds_write2_b32 v2, v18, v19 offset0:80 offset1:88
	ds_write2_b32 v2, v20, v21 offset0:96 offset1:104
	ds_write2_b32 v2, v22, v23 offset0:112 offset1:120
	ds_write2_b32 v2, v24, v25 offset0:128 offset1:136
	ds_write2_b32 v2, v26, v27 offset0:144 offset1:152
	ds_write2_b32 v2, v28, v29 offset0:160 offset1:168
	ds_write2_b32 v2, v30, v31 offset0:176 offset1:184
	ds_write2_b32 v2, v32, v33 offset0:192 offset1:200
	ds_write2_b32 v2, v34, v35 offset0:208 offset1:216
	ds_write2_b32 v2, v36, v37 offset0:224 offset1:232
	ds_write2_b32 v2, v6, v4 offset0:240 offset1:248
	v_lshlrev_b32_e32 v2, 3, v8
	v_ashrrev_i32_e32 v0, 3, v8
	v_and_b32_e32 v4, 56, v2
	v_mul_lo_u32 v2, v0, s43
	v_lshlrev_b32_e32 v3, 2, v4
	v_add3_u32 v10, 0, v2, v3
	s_lshl_b32 s25, s76, 9
	v_add_u32_e32 v2, s24, v0
	s_add_u32 s82, s46, s25
	v_readlane_b32 s25, v255, 16
	v_ashrrev_i32_e32 v3, 31, v2
	s_addc_u32 s83, s25, 0
	v_lshlrev_b64 v[2:3], 11, v[2:3]
	v_add_u32_e32 v5, 0x8000, v10
	v_lshl_add_u64 v[2:3], s[82:83], 0, v[2:3]
	v_lshlrev_b32_e32 v0, 1, v4
	s_waitcnt lgkmcnt(0)
	s_barrier
	v_lshl_add_u64 v[6:7], v[2:3], 0, v[0:1]
	ds_read2_b32 v[2:3], v5 offset1:1
	v_add_u32_e32 v0, 0x8008, v10
	s_waitcnt lgkmcnt(0)
	v_cvt_pk_bf16_f32 v2, v2, v3
	ds_read2_b32 v[4:5], v0 offset1:1
	v_add_u32_e32 v0, 0x8010, v10
	s_waitcnt lgkmcnt(0)
	v_cvt_pk_bf16_f32 v3, v4, v5
	ds_read2_b32 v[4:5], v0 offset1:1
	v_add_u32_e32 v0, 0x8018, v10
	s_waitcnt lgkmcnt(0)
	v_cvt_pk_bf16_f32 v4, v4, v5
	ds_read2_b32 v[8:9], v0 offset1:1
	s_waitcnt lgkmcnt(0)
	v_cvt_pk_bf16_f32 v5, v8, v9
	global_store_dwordx4 v[6:7], v[2:5], off
	v_add_u32_e32 v0, 0x8100, v10
	ds_read2_b32 v[2:3], v0 offset1:1
	v_add_u32_e32 v0, 0x8108, v10
	s_waitcnt lgkmcnt(0)
	v_cvt_pk_bf16_f32 v2, v2, v3
	ds_read2_b32 v[4:5], v0 offset1:1
	v_add_u32_e32 v0, 0x8110, v10
	s_waitcnt lgkmcnt(0)
	v_cvt_pk_bf16_f32 v3, v4, v5
	ds_read2_b32 v[4:5], v0 offset1:1
	v_add_u32_e32 v0, 0x8118, v10
	s_waitcnt lgkmcnt(0)
	v_cvt_pk_bf16_f32 v4, v4, v5
	ds_read2_b32 v[8:9], v0 offset1:1
	s_waitcnt lgkmcnt(0)
	v_cvt_pk_bf16_f32 v5, v8, v9
	global_store_dwordx4 v[6:7], v[2:5], off offset:128
	v_add_u32_e32 v0, 0x8200, v10
	ds_read2_b32 v[2:3], v0 offset1:1
	v_add_u32_e32 v0, 0x8208, v10
	s_waitcnt lgkmcnt(0)
	v_cvt_pk_bf16_f32 v2, v2, v3
	ds_read2_b32 v[4:5], v0 offset1:1
	v_add_u32_e32 v0, 0x8210, v10
	s_waitcnt lgkmcnt(0)
	v_cvt_pk_bf16_f32 v3, v4, v5
	ds_read2_b32 v[4:5], v0 offset1:1
	v_add_u32_e32 v0, 0x8218, v10
	s_waitcnt lgkmcnt(0)
	v_cvt_pk_bf16_f32 v4, v4, v5
	ds_read2_b32 v[8:9], v0 offset1:1
	s_waitcnt lgkmcnt(0)
	v_cvt_pk_bf16_f32 v5, v8, v9
	global_store_dwordx4 v[6:7], v[2:5], off offset:256
	v_add_u32_e32 v0, 0x8300, v10
	ds_read2_b32 v[2:3], v0 offset1:1
	v_add_u32_e32 v0, 0x8308, v10
	s_waitcnt lgkmcnt(0)
	v_cvt_pk_bf16_f32 v2, v2, v3
	ds_read2_b32 v[4:5], v0 offset1:1
	v_add_u32_e32 v0, 0x8310, v10
	s_waitcnt lgkmcnt(0)
	v_cvt_pk_bf16_f32 v3, v4, v5
	ds_read2_b32 v[4:5], v0 offset1:1
	v_add_u32_e32 v0, 0x8318, v10
	s_waitcnt lgkmcnt(0)
	v_cvt_pk_bf16_f32 v4, v4, v5
	ds_read2_b32 v[8:9], v0 offset1:1
	s_waitcnt lgkmcnt(0)
	v_cvt_pk_bf16_f32 v5, v8, v9
	global_store_dwordx4 v[6:7], v[2:5], off offset:384
	s_waitcnt lgkmcnt(0)
	s_barrier
	s_mov_b64 s[24:25], 0
; DEVI int ltid(int wv) { int t = (wv << 6) | (int)__builtin_amdgcn_mbcnt_hi(~0u, __builtin_amdgcn_mbcnt_lo(~0u, 0u)); asm volatile("" : "+v"(t)); return t; }
; template <int KT, class F> DEVI void cvt_tile(F colptr, int ldsrc, int k0, bf16_t* out, int ldo, int v0, float* tile, int wv) {
;     const int tid = ltid(wv);
;     constexpr int PITCH = KT * 64 + 1;
;     { const int vc = tid & 63, kk = tid >> 6; const float* cp = colptr(v0 + vc) + (size_t)k0 * ldsrc; float v[8 * KT];
; #pragma unroll
;       for (int r = 0; r < 8 * KT; ++r) v[r] = cp[(size_t)(r * 8 + kk) * ldsrc];
; #pragma unroll
;       for (int r = 0; r < 8 * KT; ++r) tile[vc * PITCH + r * 8 + kk] = v[r]; }
;     __syncthreads();
; DEVI void cvt_mix_phase(const float* win, const float* woa, const float* wor, const float* wout, const float* lwa, const float* lwx, unsigned char* ws, char* lds, int wv) {
;     ...
;             if (m < 2) cvt_tile<4>(ColLin{src}, DM, kg * 256, (bf16_t*)(ws + WS_WOA) + m * DM, 2 * DM, vt * 64, tile, wv);
.LBB0_457:
	s_andn2_b64 vcc, exec, s[24:25]
	s_cbranch_vccnz .LBB0_459
	s_cmp_lt_u32 s80, 64
	s_cselect_b32 s81, s61, s23
	s_cselect_b32 s80, s60, s22
	s_lshl_b32 s22, s79, 11
	v_readlane_b32 s23, v255, 21
	s_add_u32 s23, s23, s22
	v_readlane_b32 s22, v255, 22
	v_mov_b32_e32 v8, v217
	s_addc_u32 s24, s22, 0
	s_lshl_b32 s22, s78, 6
	s_lshl_b32 s46, s76, 20
	v_and_b32_e32 v9, 63, v8
	v_or_b32_e32 v0, s22, v9
	v_ashrrev_i32_e32 v2, 6, v8
	v_lshlrev_b32_e32 v0, 2, v0
	v_lshl_add_u64 v[4:5], s[80:81], 0, v[0:1]
	v_ashrrev_i32_e32 v3, 31, v2
	v_lshl_add_u64 v[4:5], v[4:5], 0, s[46:47]
	v_lshlrev_b64 v[6:7], 12, v[2:3]
	v_lshl_add_u64 v[4:5], v[4:5], 0, v[6:7]
	v_add_co_u32_e32 v6, vcc, s33, v4
	global_load_dword v0, v[4:5], off
	s_nop 0
	v_addc_co_u32_e32 v7, vcc, 0, v5, vcc
	global_load_dword v3, v[6:7], off
	v_add_co_u32_e32 v6, vcc, s54, v4
	s_mov_b32 s25, 0x28000
	s_nop 0
	v_addc_co_u32_e32 v7, vcc, 0, v5, vcc
	global_load_dword v10, v[6:7], off
	v_add_co_u32_e32 v6, vcc, s27, v4
	v_lshlrev_b32_e32 v2, 2, v2
	s_nop 0
	v_addc_co_u32_e32 v7, vcc, 0, v5, vcc
	global_load_dword v11, v[6:7], off
	v_add_co_u32_e32 v6, vcc, s38, v4
	s_nop 1
	v_addc_co_u32_e32 v7, vcc, 0, v5, vcc
	global_load_dword v12, v[6:7], off
	v_add_co_u32_e32 v6, vcc, s25, v4
	s_mov_b32 s25, 0x38000
	s_nop 0
	v_addc_co_u32_e32 v7, vcc, 0, v5, vcc
	global_load_dword v13, v[6:7], off
	v_add_co_u32_e32 v6, vcc, s39, v4
	s_nop 1
	v_addc_co_u32_e32 v7, vcc, 0, v5, vcc
	global_load_dword v14, v[6:7], off
	v_add_co_u32_e32 v6, vcc, s25, v4
	s_mov_b32 s25, 0x40000
	s_nop 0
	v_addc_co_u32_e32 v7, vcc, 0, v5, vcc
	global_load_dword v15, v[6:7], off
	v_add_co_u32_e32 v6, vcc, s25, v4
	s_mov_b32 s25, 0x48000
	s_nop 0
	v_addc_co_u32_e32 v7, vcc, 0, v5, vcc
	global_load_dword v16, v[6:7], off
	v_add_co_u32_e32 v6, vcc, s25, v4
	s_mov_b32 s25, 0x50000
	s_nop 0
	v_addc_co_u32_e32 v7, vcc, 0, v5, vcc
	global_load_dword v17, v[6:7], off
	v_add_co_u32_e32 v6, vcc, s25, v4
	s_mov_b32 s25, 0x58000
	s_nop 0
	v_addc_co_u32_e32 v7, vcc, 0, v5, vcc
	global_load_dword v18, v[6:7], off
	v_add_co_u32_e32 v6, vcc, s25, v4
	s_mov_b32 s25, 0x60000
	s_nop 0
	v_addc_co_u32_e32 v7, vcc, 0, v5, vcc
	global_load_dword v19, v[6:7], off
	v_add_co_u32_e32 v6, vcc, s25, v4
	s_mov_b32 s25, 0x68000
	s_nop 0
	v_addc_co_u32_e32 v7, vcc, 0, v5, vcc
	global_load_dword v20, v[6:7], off
	v_add_co_u32_e32 v6, vcc, s25, v4
	s_mov_b32 s25, 0x70000
	s_nop 0
	v_addc_co_u32_e32 v7, vcc, 0, v5, vcc
	global_load_dword v21, v[6:7], off
	v_add_co_u32_e32 v6, vcc, s25, v4
	s_mov_b32 s25, 0x78000
	s_nop 0
	v_addc_co_u32_e32 v7, vcc, 0, v5, vcc
	global_load_dword v22, v[6:7], off
	v_add_co_u32_e32 v6, vcc, s25, v4
	s_mov_b32 s25, 0x80000
	s_nop 0
	v_addc_co_u32_e32 v7, vcc, 0, v5, vcc
	global_load_dword v23, v[6:7], off
	v_add_co_u32_e32 v6, vcc, s25, v4
	s_mov_b32 s25, 0x88000
	s_nop 0
	v_addc_co_u32_e32 v7, vcc, 0, v5, vcc
	global_load_dword v24, v[6:7], off
	v_add_co_u32_e32 v6, vcc, s25, v4
	s_mov_b32 s25, 0x90000
	s_nop 0
	v_addc_co_u32_e32 v7, vcc, 0, v5, vcc
	global_load_dword v25, v[6:7], off
	v_add_co_u32_e32 v6, vcc, s25, v4
	s_mov_b32 s25, 0x98000
	s_nop 0
	v_addc_co_u32_e32 v7, vcc, 0, v5, vcc
	global_load_dword v26, v[6:7], off
	v_add_co_u32_e32 v6, vcc, s25, v4
	s_mov_b32 s25, 0xa0000
	s_nop 0
	v_addc_co_u32_e32 v7, vcc, 0, v5, vcc
	global_load_dword v27, v[6:7], off
	v_add_co_u32_e32 v6, vcc, s25, v4
	s_mov_b32 s25, 0xa8000
	s_nop 0
	v_addc_co_u32_e32 v7, vcc, 0, v5, vcc
	global_load_dword v28, v[6:7], off
	v_add_co_u32_e32 v6, vcc, s25, v4
	s_mov_b32 s25, 0xb0000
	s_nop 0
	v_addc_co_u32_e32 v7, vcc, 0, v5, vcc
	global_load_dword v29, v[6:7], off
	v_add_co_u32_e32 v6, vcc, s25, v4
	s_mov_b32 s25, 0xb8000
	s_nop 0
	v_addc_co_u32_e32 v7, vcc, 0, v5, vcc
	global_load_dword v30, v[6:7], off
	v_add_co_u32_e32 v6, vcc, s25, v4
	s_mov_b32 s25, 0xc0000
	s_nop 0
	v_addc_co_u32_e32 v7, vcc, 0, v5, vcc
	global_load_dword v31, v[6:7], off
	v_add_co_u32_e32 v6, vcc, s25, v4
	s_mov_b32 s25, 0xc8000
	s_nop 0
	v_addc_co_u32_e32 v7, vcc, 0, v5, vcc
	global_load_dword v32, v[6:7], off
	v_add_co_u32_e32 v6, vcc, s25, v4
	s_mov_b32 s25, 0xd0000
	s_nop 0
	v_addc_co_u32_e32 v7, vcc, 0, v5, vcc
	global_load_dword v33, v[6:7], off
	v_add_co_u32_e32 v6, vcc, s25, v4
	s_mov_b32 s25, 0xd8000
	s_nop 0
	v_addc_co_u32_e32 v7, vcc, 0, v5, vcc
	global_load_dword v34, v[6:7], off
	v_add_co_u32_e32 v6, vcc, s25, v4
	s_mov_b32 s25, 0xe0000
	s_nop 0
	v_addc_co_u32_e32 v7, vcc, 0, v5, vcc
	global_load_dword v35, v[6:7], off
	v_add_co_u32_e32 v6, vcc, s25, v4
	s_mov_b32 s25, 0xe8000
	s_nop 0
	v_addc_co_u32_e32 v7, vcc, 0, v5, vcc
	global_load_dword v36, v[6:7], off
	v_add_co_u32_e32 v6, vcc, s25, v4
	s_mov_b32 s25, 0xf0000
	s_nop 0
	v_addc_co_u32_e32 v7, vcc, 0, v5, vcc
	global_load_dword v37, v[6:7], off
	v_add_co_u32_e32 v6, vcc, s25, v4
	s_mov_b32 s25, 0xf8000
	s_nop 0
	v_addc_co_u32_e32 v7, vcc, 0, v5, vcc
	v_add_co_u32_e32 v4, vcc, s25, v4
	global_load_dword v6, v[6:7], off
	s_nop 0
	v_addc_co_u32_e32 v5, vcc, 0, v5, vcc
	global_load_dword v4, v[4:5], off
	v_mul_u32_u24_e32 v5, 0x404, v9
	v_add3_u32 v2, 0, v5, v2
	v_add_u32_e32 v2, 0x8000, v2
	s_waitcnt vmcnt(0)
	ds_write2_b32 v2, v0, v3 offset1:8
	ds_write2_b32 v2, v10, v11 offset0:16 offset1:24
	ds_write2_b32 v2, v12, v13 offset0:32 offset1:40
	ds_write2_b32 v2, v14, v15 offset0:48 offset1:56
	ds_write2_b32 v2, v16, v17 offset0:64 offset1:72
	ds_write2_b32 v2, v18, v19 offset0:80 offset1:88
	ds_write2_b32 v2, v20, v21 offset0:96 offset1:104
	ds_write2_b32 v2, v22, v23 offset0:112 offset1:120
	ds_write2_b32 v2, v24, v25 offset0:128 offset1:136
	ds_write2_b32 v2, v26, v27 offset0:144 offset1:152
	ds_write2_b32 v2, v28, v29 offset0:160 offset1:168
	ds_write2_b32 v2, v30, v31 offset0:176 offset1:184
	ds_write2_b32 v2, v32, v33 offset0:192 offset1:200
	ds_write2_b32 v2, v34, v35 offset0:208 offset1:216
	ds_write2_b32 v2, v36, v37 offset0:224 offset1:232
	ds_write2_b32 v2, v6, v4 offset0:240 offset1:248
	v_lshlrev_b32_e32 v2, 3, v8
	v_ashrrev_i32_e32 v0, 3, v8
	v_and_b32_e32 v4, 56, v2
	v_mul_lo_u32 v2, v0, s43
	v_lshlrev_b32_e32 v3, 2, v4
	v_add3_u32 v10, 0, v2, v3
	s_lshl_b32 s25, s76, 9
	v_add_u32_e32 v2, s22, v0
	s_add_u32 s78, s23, s25
	v_ashrrev_i32_e32 v3, 31, v2
	s_addc_u32 s79, s24, 0
	v_lshlrev_b64 v[2:3], 12, v[2:3]
	v_add_u32_e32 v5, 0x8000, v10
	v_lshl_add_u64 v[2:3], s[78:79], 0, v[2:3]
	v_lshlrev_b32_e32 v0, 1, v4
	s_waitcnt lgkmcnt(0)
	s_barrier
; DEVI unsigned cvtpk(float lo, float hi) { unsigned r; asm volatile("v_cvt_pk_bf16_f32 %0, %1, %2" : "=v"(r) : "v"(lo), "v"(hi)); return r; }
; template <int KT, class F> DEVI void cvt_tile(F colptr, int ldsrc, int k0, bf16_t* out, int ldo, int v0, float* tile, int wv) {
;     ...
;     { const int vc = tid >> 3, k8 = (tid & 7) * 8;
; #pragma unroll
;       for (int q = 0; q < KT; ++q) { const float* tp = tile + vc * PITCH + q * 64 + k8;
;         u32x4 w = {cvtpk(tp[0], tp[1]), cvtpk(tp[2], tp[3]), cvtpk(tp[4], tp[5]), cvtpk(tp[6], tp[7])};
;         *(u32x4*)(out + (size_t)(v0 + vc) * ldo + k0 + q * 64 + k8) = w; } }
;     __syncthreads();
; }
	v_lshl_add_u64 v[6:7], v[2:3], 0, v[0:1]
	ds_read2_b32 v[2:3], v5 offset1:1
	v_add_u32_e32 v0, 0x8008, v10
	s_waitcnt lgkmcnt(0)
	v_cvt_pk_bf16_f32 v2, v2, v3
	ds_read2_b32 v[4:5], v0 offset1:1
	v_add_u32_e32 v0, 0x8010, v10
	s_waitcnt lgkmcnt(0)
	v_cvt_pk_bf16_f32 v3, v4, v5
	ds_read2_b32 v[4:5], v0 offset1:1
	v_add_u32_e32 v0, 0x8018, v10
	s_waitcnt lgkmcnt(0)
	v_cvt_pk_bf16_f32 v4, v4, v5
	ds_read2_b32 v[8:9], v0 offset1:1
	s_waitcnt lgkmcnt(0)
	v_cvt_pk_bf16_f32 v5, v8, v9
	global_store_dwordx4 v[6:7], v[2:5], off
	v_add_u32_e32 v0, 0x8100, v10
	ds_read2_b32 v[2:3], v0 offset1:1
	v_add_u32_e32 v0, 0x8108, v10
	s_waitcnt lgkmcnt(0)
	v_cvt_pk_bf16_f32 v2, v2, v3
	ds_read2_b32 v[4:5], v0 offset1:1
	v_add_u32_e32 v0, 0x8110, v10
	s_waitcnt lgkmcnt(0)
	v_cvt_pk_bf16_f32 v3, v4, v5
	ds_read2_b32 v[4:5], v0 offset1:1
	v_add_u32_e32 v0, 0x8118, v10
	s_waitcnt lgkmcnt(0)
	v_cvt_pk_bf16_f32 v4, v4, v5
	ds_read2_b32 v[8:9], v0 offset1:1
	s_waitcnt lgkmcnt(0)
	v_cvt_pk_bf16_f32 v5, v8, v9
	global_store_dwordx4 v[6:7], v[2:5], off offset:128
	v_add_u32_e32 v0, 0x8200, v10
	ds_read2_b32 v[2:3], v0 offset1:1
	v_add_u32_e32 v0, 0x8208, v10
	s_waitcnt lgkmcnt(0)
	v_cvt_pk_bf16_f32 v2, v2, v3
	ds_read2_b32 v[4:5], v0 offset1:1
	v_add_u32_e32 v0, 0x8210, v10
	s_waitcnt lgkmcnt(0)
	v_cvt_pk_bf16_f32 v3, v4, v5
	ds_read2_b32 v[4:5], v0 offset1:1
	v_add_u32_e32 v0, 0x8218, v10
	s_waitcnt lgkmcnt(0)
	v_cvt_pk_bf16_f32 v4, v4, v5
	ds_read2_b32 v[8:9], v0 offset1:1
	s_waitcnt lgkmcnt(0)
	v_cvt_pk_bf16_f32 v5, v8, v9
	global_store_dwordx4 v[6:7], v[2:5], off offset:256
	v_add_u32_e32 v0, 0x8300, v10
	ds_read2_b32 v[2:3], v0 offset1:1
	v_add_u32_e32 v0, 0x8308, v10
	s_waitcnt lgkmcnt(0)
	v_cvt_pk_bf16_f32 v2, v2, v3
	ds_read2_b32 v[4:5], v0 offset1:1
	v_add_u32_e32 v0, 0x8310, v10
	s_waitcnt lgkmcnt(0)
	v_cvt_pk_bf16_f32 v3, v4, v5
	ds_read2_b32 v[4:5], v0 offset1:1
	v_add_u32_e32 v0, 0x8318, v10
	s_waitcnt lgkmcnt(0)
	v_cvt_pk_bf16_f32 v4, v4, v5
	ds_read2_b32 v[8:9], v0 offset1:1
	s_waitcnt lgkmcnt(0)
	v_cvt_pk_bf16_f32 v5, v8, v9
	global_store_dwordx4 v[6:7], v[2:5], off offset:384
	s_waitcnt lgkmcnt(0)
	s_barrier

; DEVI int ltid(int wv) { int t = (wv << 6) | (int)__builtin_amdgcn_mbcnt_hi(~0u, __builtin_amdgcn_mbcnt_lo(~0u, 0u)); asm volatile("" : "+v"(t)); return t; }
; template <int KT, class F> DEVI void cvt_tile(F colptr, int ldsrc, int k0, bf16_t* out, int ldo, int v0, float* tile, int wv) {
;     const int tid = ltid(wv);
;     constexpr int PITCH = KT * 64 + 1;
;     { const int vc = tid & 63, kk = tid >> 6; const float* cp = colptr(v0 + vc) + (size_t)k0 * ldsrc; float v[8 * KT];
; #pragma unroll
;       for (int r = 0; r < 8 * KT; ++r) v[r] = cp[(size_t)(r * 8 + kk) * ldsrc];
; #pragma unroll
;       for (int r = 0; r < 8 * KT; ++r) tile[vc * PITCH + r * 8 + kk] = v[r]; }
;     __syncthreads();
; DEVI void cvt_mix_phase(const float* win, const float* woa, const float* wor, const float* wout, const float* lwa, const float* lwx, unsigned char* ws, char* lds, int wv) {
;     ...
;         if (job < 448) { const int vt = job >> 2, kg = job & 3; cvt_tile<4>(ColIn{win}, NIN, kg * 256, (bf16_t*)(ws + WS_WIN), DM, vt * 64, tile, wv); }
.LBB0_460:
	s_andn2_b64 vcc, exec, s[22:23]
	s_cbranch_vccnz .LBB0_450
	s_lshl_b32 s22, s59, 8
	s_lshl_b32 s24, s59, 4
	v_mov_b32_e32 v0, v217
	s_and_b32 s23, s22, 0x300
	s_and_b32 s22, s24, 0xffffffc0
	s_mul_i32 s46, s23, 0x7020
	v_bfi_b32 v2, 63, v0, s24
	s_movk_i32 s24, 0xc00
	v_cmp_gt_i32_e32 vcc, s24, v2
	v_add_u32_e32 v3, 8, v2
	v_ashrrev_i32_e32 v7, 6, v0
	v_cndmask_b32_e32 v2, v3, v2, vcc
	v_ashrrev_i32_e32 v3, 31, v2
	v_lshl_add_u64 v[2:3], v[2:3], 2, s[8:9]
	v_lshl_add_u64 v[2:3], v[2:3], 0, s[46:47]
	v_mad_i64_i32 v[4:5], s[24:25], v7, s52, v[2:3]
	global_load_dword v8, v[4:5], off
	v_add_u32_e32 v4, 8, v7
	v_mad_i64_i32 v[4:5], s[24:25], v4, s52, v[2:3]
	global_load_dword v9, v[4:5], off
	v_add_u32_e32 v4, 16, v7
	v_mad_i64_i32 v[4:5], s[24:25], v4, s52, v[2:3]
	global_load_dword v10, v[4:5], off
	v_add_u32_e32 v4, 24, v7
	v_mad_i64_i32 v[4:5], s[24:25], v4, s52, v[2:3]
	global_load_dword v11, v[4:5], off
	v_add_u32_e32 v4, 32, v7
	v_mad_i64_i32 v[4:5], s[24:25], v4, s52, v[2:3]
	global_load_dword v12, v[4:5], off
	v_add_u32_e32 v4, 40, v7
	v_mad_i64_i32 v[4:5], s[24:25], v4, s52, v[2:3]
	global_load_dword v13, v[4:5], off
	v_add_u32_e32 v4, 48, v7
	v_mad_i64_i32 v[4:5], s[24:25], v4, s52, v[2:3]
	global_load_dword v14, v[4:5], off
	v_add_u32_e32 v4, 56, v7
	v_mad_i64_i32 v[4:5], s[24:25], v4, s52, v[2:3]
	global_load_dword v15, v[4:5], off
	v_add_u32_e32 v4, 64, v7
	v_mad_i64_i32 v[4:5], s[24:25], v4, s52, v[2:3]
	global_load_dword v16, v[4:5], off
	v_add_u32_e32 v4, 0x48, v7
	v_mad_i64_i32 v[4:5], s[24:25], v4, s52, v[2:3]
	global_load_dword v17, v[4:5], off
	v_add_u32_e32 v4, 0x50, v7
	v_mad_i64_i32 v[4:5], s[24:25], v4, s52, v[2:3]
	global_load_dword v18, v[4:5], off
	v_add_u32_e32 v4, 0x58, v7
	v_mad_i64_i32 v[4:5], s[24:25], v4, s52, v[2:3]
	global_load_dword v19, v[4:5], off
	v_add_u32_e32 v4, 0x60, v7
	v_mad_i64_i32 v[4:5], s[24:25], v4, s52, v[2:3]
	global_load_dword v20, v[4:5], off
	v_add_u32_e32 v4, 0x68, v7
	v_mad_i64_i32 v[4:5], s[24:25], v4, s52, v[2:3]
	global_load_dword v21, v[4:5], off
	v_add_u32_e32 v4, 0x70, v7
	v_mad_i64_i32 v[4:5], s[24:25], v4, s52, v[2:3]
	global_load_dword v22, v[4:5], off
	v_add_u32_e32 v4, 0x78, v7
	v_mad_i64_i32 v[4:5], s[24:25], v4, s52, v[2:3]
	global_load_dword v23, v[4:5], off
	v_add_u32_e32 v4, 0x80, v7
	v_mad_i64_i32 v[4:5], s[24:25], v4, s52, v[2:3]
	global_load_dword v24, v[4:5], off
	v_add_u32_e32 v4, 0x88, v7
	v_mad_i64_i32 v[4:5], s[24:25], v4, s52, v[2:3]
	global_load_dword v25, v[4:5], off
	v_add_u32_e32 v4, 0x90, v7
	v_mad_i64_i32 v[4:5], s[24:25], v4, s52, v[2:3]
	global_load_dword v26, v[4:5], off
	v_add_u32_e32 v4, 0x98, v7
	v_mad_i64_i32 v[4:5], s[24:25], v4, s52, v[2:3]
	global_load_dword v27, v[4:5], off
	v_add_u32_e32 v4, 0xa0, v7
	v_mad_i64_i32 v[4:5], s[24:25], v4, s52, v[2:3]
	global_load_dword v28, v[4:5], off
	v_add_u32_e32 v4, 0xa8, v7
	v_mad_i64_i32 v[4:5], s[24:25], v4, s52, v[2:3]
	global_load_dword v29, v[4:5], off
	v_add_u32_e32 v4, 0xb0, v7
	v_mad_i64_i32 v[4:5], s[24:25], v4, s52, v[2:3]
	global_load_dword v30, v[4:5], off
	v_add_u32_e32 v4, 0xb8, v7
	v_mad_i64_i32 v[4:5], s[24:25], v4, s52, v[2:3]
	global_load_dword v31, v[4:5], off
	v_add_u32_e32 v4, 0xc0, v7
	v_mad_i64_i32 v[4:5], s[24:25], v4, s52, v[2:3]
	global_load_dword v32, v[4:5], off
	v_add_u32_e32 v4, 0xc8, v7
	v_mad_i64_i32 v[4:5], s[24:25], v4, s52, v[2:3]
	global_load_dword v33, v[4:5], off
	v_add_u32_e32 v4, 0xd0, v7
	v_mad_i64_i32 v[4:5], s[24:25], v4, s52, v[2:3]
	global_load_dword v34, v[4:5], off
	v_add_u32_e32 v4, 0xd8, v7
	v_mad_i64_i32 v[4:5], s[24:25], v4, s52, v[2:3]
	global_load_dword v35, v[4:5], off
	v_add_u32_e32 v4, 0xe0, v7
	v_mad_i64_i32 v[4:5], s[24:25], v4, s52, v[2:3]
	global_load_dword v36, v[4:5], off
	v_add_u32_e32 v4, 0xe8, v7
	v_mad_i64_i32 v[4:5], s[24:25], v4, s52, v[2:3]
	global_load_dword v37, v[4:5], off
	v_add_u32_e32 v4, 0xf0, v7
	v_mad_i64_i32 v[4:5], s[24:25], v4, s52, v[2:3]
	global_load_dword v4, v[4:5], off
	v_add_u32_e32 v5, 0xf8, v7
	v_mad_i64_i32 v[2:3], s[24:25], v5, s52, v[2:3]
	global_load_dword v2, v[2:3], off
	v_and_b32_e32 v6, 63, v0
	v_mul_u32_u24_e32 v3, 0x404, v6
	v_lshlrev_b32_e32 v5, 2, v7
	v_add3_u32 v3, 0, v3, v5
	v_add_u32_e32 v3, 0x8000, v3
	s_waitcnt vmcnt(0)
	ds_write2_b32 v3, v8, v9 offset1:8
	ds_write2_b32 v3, v10, v11 offset0:16 offset1:24
	ds_write2_b32 v3, v12, v13 offset0:32 offset1:40
	ds_write2_b32 v3, v14, v15 offset0:48 offset1:56
	ds_write2_b32 v3, v16, v17 offset0:64 offset1:72
	ds_write2_b32 v3, v18, v19 offset0:80 offset1:88
	ds_write2_b32 v3, v20, v21 offset0:96 offset1:104
	ds_write2_b32 v3, v22, v23 offset0:112 offset1:120
	ds_write2_b32 v3, v24, v25 offset0:128 offset1:136
	ds_write2_b32 v3, v26, v27 offset0:144 offset1:152
	ds_write2_b32 v3, v28, v29 offset0:160 offset1:168
	ds_write2_b32 v3, v30, v31 offset0:176 offset1:184
	ds_write2_b32 v3, v32, v33 offset0:192 offset1:200
	ds_write2_b32 v3, v34, v35 offset0:208 offset1:216
	ds_write2_b32 v3, v36, v37 offset0:224 offset1:232
	ds_write2_b32 v3, v4, v2 offset0:240 offset1:248
	v_ashrrev_i32_e32 v2, 3, v0
	v_lshlrev_b32_e32 v0, 3, v0
	v_and_b32_e32 v0, 56, v0
	v_mul_lo_u32 v3, v2, s43
	v_lshlrev_b32_e32 v4, 2, v0
	s_lshl_b32 s23, s23, 1
	v_add_u32_e32 v2, s22, v2
	v_add3_u32 v10, 0, v3, v4
	s_add_u32 s24, s91, s23
	v_ashrrev_i32_e32 v3, 31, v2
	s_addc_u32 s25, s92, 0
	v_lshlrev_b64 v[2:3], 11, v[2:3]
	v_add_u32_e32 v4, 0x8000, v10
	v_lshl_add_u64 v[2:3], s[24:25], 0, v[2:3]
	v_lshlrev_b32_e32 v0, 1, v0
	s_waitcnt lgkmcnt(0)
	s_barrier
; DEVI unsigned cvtpk(float lo, float hi) { unsigned r; asm volatile("v_cvt_pk_bf16_f32 %0, %1, %2" : "=v"(r) : "v"(lo), "v"(hi)); return r; }
; template <int KT, class F> DEVI void cvt_tile(F colptr, int ldsrc, int k0, bf16_t* out, int ldo, int v0, float* tile, int wv) {
;     ...
;     { const int vc = tid >> 3, k8 = (tid & 7) * 8;
; #pragma unroll
;       for (int q = 0; q < KT; ++q) { const float* tp = tile + vc * PITCH + q * 64 + k8;
;         u32x4 w = {cvtpk(tp[0], tp[1]), cvtpk(tp[2], tp[3]), cvtpk(tp[4], tp[5]), cvtpk(tp[6], tp[7])};
;         *(u32x4*)(out + (size_t)(v0 + vc) * ldo + k0 + q * 64 + k8) = w; } }
;     __syncthreads();
	v_lshl_add_u64 v[6:7], v[2:3], 0, v[0:1]
	ds_read2_b32 v[2:3], v4 offset1:1
	v_add_u32_e32 v0, 0x8008, v10
	s_waitcnt lgkmcnt(0)
	v_cvt_pk_bf16_f32 v2, v2, v3
	ds_read2_b32 v[4:5], v0 offset1:1
	v_add_u32_e32 v0, 0x8010, v10
	s_waitcnt lgkmcnt(0)
	v_cvt_pk_bf16_f32 v3, v4, v5
	ds_read2_b32 v[4:5], v0 offset1:1
	v_add_u32_e32 v0, 0x8018, v10
	s_waitcnt lgkmcnt(0)
	v_cvt_pk_bf16_f32 v4, v4, v5
	ds_read2_b32 v[8:9], v0 offset1:1
	s_waitcnt lgkmcnt(0)
	v_cvt_pk_bf16_f32 v5, v8, v9
	global_store_dwordx4 v[6:7], v[2:5], off
	v_add_u32_e32 v0, 0x8100, v10
	ds_read2_b32 v[2:3], v0 offset1:1
	v_add_u32_e32 v0, 0x8108, v10
	s_waitcnt lgkmcnt(0)
	v_cvt_pk_bf16_f32 v2, v2, v3
	ds_read2_b32 v[4:5], v0 offset1:1
	v_add_u32_e32 v0, 0x8110, v10
	s_waitcnt lgkmcnt(0)
	v_cvt_pk_bf16_f32 v3, v4, v5
	ds_read2_b32 v[4:5], v0 offset1:1
	v_add_u32_e32 v0, 0x8118, v10
	s_waitcnt lgkmcnt(0)
	v_cvt_pk_bf16_f32 v4, v4, v5
	ds_read2_b32 v[8:9], v0 offset1:1
	s_waitcnt lgkmcnt(0)
	v_cvt_pk_bf16_f32 v5, v8, v9
	global_store_dwordx4 v[6:7], v[2:5], off offset:128
	v_add_u32_e32 v0, 0x8200, v10
	ds_read2_b32 v[2:3], v0 offset1:1
	v_add_u32_e32 v0, 0x8208, v10
	s_waitcnt lgkmcnt(0)
	v_cvt_pk_bf16_f32 v2, v2, v3
	ds_read2_b32 v[4:5], v0 offset1:1
	v_add_u32_e32 v0, 0x8210, v10
	s_waitcnt lgkmcnt(0)
	v_cvt_pk_bf16_f32 v3, v4, v5
	ds_read2_b32 v[4:5], v0 offset1:1
	v_add_u32_e32 v0, 0x8218, v10
	s_waitcnt lgkmcnt(0)
	v_cvt_pk_bf16_f32 v4, v4, v5
	ds_read2_b32 v[8:9], v0 offset1:1
	s_waitcnt lgkmcnt(0)
	v_cvt_pk_bf16_f32 v5, v8, v9
	global_store_dwordx4 v[6:7], v[2:5], off offset:256
	v_add_u32_e32 v0, 0x8300, v10
	ds_read2_b32 v[2:3], v0 offset1:1
	v_add_u32_e32 v0, 0x8308, v10
	s_waitcnt lgkmcnt(0)
	v_cvt_pk_bf16_f32 v2, v2, v3
	ds_read2_b32 v[4:5], v0 offset1:1
	v_add_u32_e32 v0, 0x8310, v10
	s_waitcnt lgkmcnt(0)
	v_cvt_pk_bf16_f32 v3, v4, v5
	ds_read2_b32 v[4:5], v0 offset1:1
	v_add_u32_e32 v0, 0x8318, v10
	s_waitcnt lgkmcnt(0)
	v_cvt_pk_bf16_f32 v4, v4, v5
	ds_read2_b32 v[8:9], v0 offset1:1
	s_waitcnt lgkmcnt(0)
	v_cvt_pk_bf16_f32 v5, v8, v9
	global_store_dwordx4 v[6:7], v[2:5], off offset:384
	s_waitcnt lgkmcnt(0)
	s_barrier
	s_branch .LBB0_450

; DEVI unsigned cvtpk(float lo, float hi) { unsigned r; asm volatile("v_cvt_pk_bf16_f32 %0, %1, %2" : "=v"(r) : "v"(lo), "v"(hi)); return r; }
; DEVI int lbid() { int t = blockIdx.x; asm volatile("" : "+s"(t)); return t; }
; DEVI float wave_sum(float v) { v += dpp<0xB1>(v); v += dpp<0x4E>(v); v += dpp<0x124>(v); v += dpp<0x128>(v); return xrow16_sum(v); }
; DEVI void norm_phase(const float* __restrict__ x, const float* __restrict__ gain, bf16_t* __restrict__ out,
;                      const float* wf_src, const float* bf_src, float* logf, char* lds, int wv) {
;     ...
;     for (int row0 = lbid() * 8 + wave; row0 < T_TOK; row0 += 2 * nw) {
;         f32x4 v[2][4]; float ss[2];
; #pragma unroll
;         for (int q = 0; q < 2; ++q) { const int row = row0 + q * nw < T_TOK ? row0 + q * nw : row0; const float* xr = x + (size_t)row * DM;
; #pragma unroll
;             for (int j = 0; j < 4; ++j) v[q][j] = *(const f32x4*)(xr + j * 256 + lane * 4); }
; #pragma unroll
;         for (int q = 0; q < 2; ++q) { float s_ = 0.f;
; #pragma unroll
;             for (int j = 0; j < 4; ++j) s_ += v[q][j][0] * v[q][j][0] + v[q][j][1] * v[q][j][1] + v[q][j][2] * v[q][j][2] + v[q][j][3] * v[q][j][3];
;             ss[q] = wave_sum(s_); }
; #pragma unroll
;         for (int q = 0; q < 2; ++q) { const int row = row0 + q * nw; if (row >= T_TOK) break;
;             const float rstd = __builtin_amdgcn_rsqf(ss[q] * (1.f / 1024.f) + 1e-6f);
; #pragma unroll
;             for (int j = 0; j < 4; ++j) { v[q][j] = v[q][j] * rstd * g[j]; u32x2 w; w.x = cvtpk(v[q][j][0], v[q][j][1]); w.y = cvtpk(v[q][j][2], v[q][j][3]); *(u32x2*)(out + (size_t)row * DM + j * 256 + lane * 4) = w; }
.LBB0_479:
	v_ashrrev_i32_e32 v47, 31, v46
	v_lshlrev_b64 v[18:19], 12, v[46:47]
	v_lshl_add_u64 v[18:19], v[36:37], 0, v[18:19]
	global_load_dwordx4 v[48:51], v[18:19], off
	global_load_dwordx4 v[52:55], v[18:19], off offset:1024
	global_load_dwordx4 v[64:67], v[18:19], off offset:2048
	global_load_dwordx4 v[68:71], v[18:19], off offset:3072
	v_add_u32_e32 v44, s46, v46
	v_cmp_gt_i32_e64 s[22:23], s33, v44
	s_andn2_b64 vcc, exec, s[78:79]
	s_waitcnt vmcnt(0) lgkmcnt(0)
	v_mul_f32_e32 v0, v49, v49
	v_cndmask_b32_e64 v18, v46, v44, s[22:23]
	v_ashrrev_i32_e32 v19, 31, v18
	v_lshlrev_b64 v[18:19], 12, v[18:19]
	v_lshl_add_u64 v[18:19], v[36:37], 0, v[18:19]
	global_load_dwordx4 v[30:33], v[18:19], off
	global_load_dwordx4 v[26:29], v[18:19], off offset:1024
	global_load_dwordx4 v[22:25], v[18:19], off offset:2048
	s_nop 0
	global_load_dwordx4 v[18:21], v[18:19], off offset:3072
	v_mul_f32_e32 v35, v53, v53
	v_fmac_f32_e32 v0, v48, v48
	v_fmac_f32_e32 v35, v52, v52
	v_fmac_f32_e32 v0, v50, v50
	v_fmac_f32_e32 v35, v54, v54
	v_fmac_f32_e32 v0, v51, v51
	v_fmac_f32_e32 v35, v55, v55
	v_add_f32_e32 v0, v0, v35
	v_mul_f32_e32 v35, v65, v65
	v_fmac_f32_e32 v35, v64, v64
	v_fmac_f32_e32 v35, v66, v66
	v_fmac_f32_e32 v35, v67, v67
	v_add_f32_e32 v0, v0, v35
	v_mul_f32_e32 v35, v69, v69
	v_fmac_f32_e32 v35, v68, v68
	v_fmac_f32_e32 v35, v70, v70
	v_fmac_f32_e32 v35, v71, v71
	v_add_f32_e32 v0, v0, v35
	s_waitcnt vmcnt(0) lgkmcnt(0)
	v_mul_f32_e32 v45, v27, v27
	v_add_f32_dpp v0, v0, v0 quad_perm:[1,0,3,2] row_mask:0xf bank_mask:0xf bound_ctrl:1
	v_fmac_f32_e32 v45, v26, v26
	v_fmac_f32_e32 v45, v28, v28
	v_add_f32_dpp v0, v0, v0 quad_perm:[2,3,0,1] row_mask:0xf bank_mask:0xf bound_ctrl:1
	v_fmac_f32_e32 v45, v29, v29
	s_nop 0
	v_add_f32_dpp v0, v0, v0 row_ror:4 row_mask:0xf bank_mask:0xf bound_ctrl:1
	s_nop 1
	v_add_f32_dpp v0, v0, v0 row_ror:8 row_mask:0xf bank_mask:0xf bound_ctrl:1
	v_mov_b32_e32 v35, v0
	s_nop 1
	v_permlane16_swap_b32_e32 v0, v35
	v_add_f32_e32 v0, v0, v35
	v_mul_f32_e32 v35, v31, v31
	v_fmac_f32_e32 v35, v30, v30
	v_fmac_f32_e32 v35, v32, v32
	v_fmac_f32_e32 v35, v33, v33
	v_add_f32_e32 v35, v35, v45
	v_mul_f32_e32 v45, v23, v23
	v_fmac_f32_e32 v45, v22, v22
	v_mov_b32_e32 v56, v0
	v_fmac_f32_e32 v45, v24, v24
	s_nop 0
	v_permlane32_swap_b32_e32 v0, v56
	v_fmac_f32_e32 v45, v25, v25
	v_add_f32_e32 v35, v35, v45
	v_mul_f32_e32 v45, v19, v19
	v_add_f32_e32 v0, v0, v56
	v_fmac_f32_e32 v45, v18, v18
	v_fmamk_f32 v0, v0, 0x3a800000, v216
	v_fmac_f32_e32 v45, v20, v20
	v_rsq_f32_e32 v0, v0
	v_fmac_f32_e32 v45, v21, v21
	v_add_f32_e32 v35, v35, v45
	v_lshlrev_b64 v[56:57], 11, v[46:47]
	v_pk_mul_f32 v[48:49], v[48:49], v[0:1] op_sel_hi:[1,0]
	v_add_f32_dpp v35, v35, v35 quad_perm:[1,0,3,2] row_mask:0xf bank_mask:0xf bound_ctrl:1
	v_pk_mul_f32 v[50:51], v[50:51], v[0:1] op_sel_hi:[1,0]
	v_lshl_add_u64 v[72:73], v[38:39], 0, v[56:57]
	v_add_f32_dpp v35, v35, v35 quad_perm:[2,3,0,1] row_mask:0xf bank_mask:0xf bound_ctrl:1
	v_pk_mul_f32 v[60:61], v[4:5], v[50:51]
	v_pk_mul_f32 v[62:63], v[2:3], v[48:49]
	v_add_f32_dpp v35, v35, v35 row_ror:4 row_mask:0xf bank_mask:0xf bound_ctrl:1
	v_cvt_pk_bf16_f32 v48, v62, v63
	v_cvt_pk_bf16_f32 v49, v60, v61
	global_store_dwordx2 v[72:73], v[48:49], off
	v_pk_mul_f32 v[48:49], v[52:53], v[0:1] op_sel_hi:[1,0]
	v_add_f32_dpp v35, v35, v35 row_ror:8 row_mask:0xf bank_mask:0xf bound_ctrl:1
	v_pk_mul_f32 v[50:51], v[54:55], v[0:1] op_sel_hi:[1,0]
	v_mov_b32_e32 v45, v35
	v_pk_mul_f32 v[56:57], v[8:9], v[50:51]
	v_pk_mul_f32 v[58:59], v[6:7], v[48:49]
	v_permlane16_swap_b32_e32 v35, v45
	v_cvt_pk_bf16_f32 v48, v58, v59
	v_cvt_pk_bf16_f32 v49, v56, v57
	global_store_dwordx2 v[72:73], v[48:49], off offset:512
	v_pk_mul_f32 v[48:49], v[64:65], v[0:1] op_sel_hi:[1,0]
	v_pk_mul_f32 v[50:51], v[66:67], v[0:1] op_sel_hi:[1,0]
	v_add_f32_e32 v35, v35, v45
	v_pk_mul_f32 v[52:53], v[12:13], v[50:51]
	v_pk_mul_f32 v[54:55], v[10:11], v[48:49]
	v_mov_b32_e32 v45, v35
	v_cvt_pk_bf16_f32 v48, v54, v55
	v_cvt_pk_bf16_f32 v49, v52, v53
	global_store_dwordx2 v[72:73], v[48:49], off offset:1024
	v_pk_mul_f32 v[50:51], v[68:69], v[0:1] op_sel_hi:[1,0]
	v_pk_mul_f32 v[48:49], v[70:71], v[0:1] op_sel_hi:[1,0]
	v_cndmask_b32_e64 v0, 0, 1, s[78:79]
	v_permlane32_swap_b32_e32 v35, v45
	v_pk_mul_f32 v[48:49], v[16:17], v[48:49]
	v_pk_mul_f32 v[50:51], v[14:15], v[50:51]
	v_cmp_ne_u32_e64 s[24:25], 1, v0
	v_cvt_pk_bf16_f32 v64, v50, v51
	v_cvt_pk_bf16_f32 v65, v48, v49
	global_store_dwordx2 v[72:73], v[64:65], off offset:1536
	s_cbranch_vccnz .LBB0_483
; DEVI float wave_sum(float v) { v += dpp<0xB1>(v); v += dpp<0x4E>(v); v += dpp<0x124>(v); v += dpp<0x128>(v); return xrow16_sum(v); }
; DEVI void norm_phase(const float* __restrict__ x, const float* __restrict__ gain, bf16_t* __restrict__ out,
;                      const float* wf_src, const float* bf_src, float* logf, char* lds, int wv) {
;     ...
;             if (wf_src) {
;                 float z = 0.f;
; #pragma unroll
;                 for (int h = 0; h < 8; ++h) { float d = 0.f;
; #pragma unroll
;                     for (int j = 0; j < 4; ++j) { const f32x4 w = *(const f32x4*)(wf + h * 1024 + j * 256 + lane * 4); d += v[q][j][0] * w[0] + v[q][j][1] * w[1] + v[q][j][2] * w[2] + v[q][j][3] * w[3]; }
;                     d = wave_sum(d); if (lane == h) z = d; }
	v_add_u32_e32 v0, 0, v34
	ds_read_b128 v[64:67], v0
	s_waitcnt lgkmcnt(0)
	v_mul_f32_e32 v47, v63, v65
	v_fmac_f32_e32 v47, v62, v64
	v_fmac_f32_e32 v47, v60, v66
	v_fmac_f32_e32 v47, v61, v67
	ds_read_b128 v[64:67], v0 offset:1024
	v_add_f32_e32 v47, 0, v47
	s_waitcnt lgkmcnt(0)
	v_mul_f32_e32 v65, v59, v65
	v_fmac_f32_e32 v65, v58, v64
	v_fmac_f32_e32 v65, v56, v66
	v_fmac_f32_e32 v65, v57, v67
	v_add_f32_e32 v47, v47, v65
	ds_read_b128 v[64:67], v0 offset:2048
	s_waitcnt lgkmcnt(0)
	v_mul_f32_e32 v65, v55, v65
	v_fmac_f32_e32 v65, v54, v64
	v_fmac_f32_e32 v65, v52, v66
	v_fmac_f32_e32 v65, v53, v67
	v_add_f32_e32 v47, v47, v65
	ds_read_b128 v[64:67], v0 offset:3072
	s_waitcnt lgkmcnt(0)
	v_mul_f32_e32 v65, v51, v65
	v_fmac_f32_e32 v65, v50, v64
	v_fmac_f32_e32 v65, v48, v66
	v_fmac_f32_e32 v65, v49, v67
	ds_read_b128 v[66:69], v0 offset:4096
	v_add_f32_e32 v47, v47, v65
	s_waitcnt lgkmcnt(0)
	v_mul_f32_e32 v65, v63, v67
	v_fmac_f32_e32 v65, v62, v66
	v_fmac_f32_e32 v65, v60, v68
	v_fmac_f32_e32 v65, v61, v69
	ds_read_b128 v[66:69], v0 offset:5120
	v_add_f32_e32 v65, 0, v65
	v_add_f32_dpp v47, v47, v47 quad_perm:[1,0,3,2] row_mask:0xf bank_mask:0xf bound_ctrl:1
	s_waitcnt lgkmcnt(0)
	v_mul_f32_e32 v67, v59, v67
	v_fmac_f32_e32 v67, v58, v66
	v_fmac_f32_e32 v67, v56, v68
	v_fmac_f32_e32 v67, v57, v69
	v_add_f32_e32 v65, v65, v67
	ds_read_b128 v[66:69], v0 offset:6144
	v_add_f32_dpp v47, v47, v47 quad_perm:[2,3,0,1] row_mask:0xf bank_mask:0xf bound_ctrl:1
	s_waitcnt lgkmcnt(0)
	v_mul_f32_e32 v67, v55, v67
	v_fmac_f32_e32 v67, v54, v66
	v_fmac_f32_e32 v67, v52, v68
	v_fmac_f32_e32 v67, v53, v69
	v_add_f32_e32 v65, v65, v67
	ds_read_b128 v[66:69], v0 offset:7168
	v_add_f32_dpp v47, v47, v47 row_ror:4 row_mask:0xf bank_mask:0xf bound_ctrl:1
	s_waitcnt lgkmcnt(0)
	v_mul_f32_e32 v67, v51, v67
	v_fmac_f32_e32 v67, v50, v66
	v_fmac_f32_e32 v67, v48, v68
	v_fmac_f32_e32 v67, v49, v69
	ds_read_b128 v[68:71], v0 offset:8192
	v_add_f32_e32 v65, v65, v67
	v_add_f32_dpp v47, v47, v47 row_ror:8 row_mask:0xf bank_mask:0xf bound_ctrl:1
	v_mov_b32_e32 v64, v47
	v_add_f32_dpp v65, v65, v65 quad_perm:[1,0,3,2] row_mask:0xf bank_mask:0xf bound_ctrl:1
	s_waitcnt lgkmcnt(0)
	v_mul_f32_e32 v67, v63, v69
	v_fmac_f32_e32 v67, v62, v68
	v_fmac_f32_e32 v67, v60, v70
	v_fmac_f32_e32 v67, v61, v71
	ds_read_b128 v[68:71], v0 offset:9216
	v_add_f32_e32 v67, 0, v67
	v_add_f32_dpp v65, v65, v65 quad_perm:[2,3,0,1] row_mask:0xf bank_mask:0xf bound_ctrl:1
	v_permlane16_swap_b32_e32 v47, v64
	s_waitcnt lgkmcnt(0)
	v_mul_f32_e32 v69, v59, v69
	v_fmac_f32_e32 v69, v58, v68
	v_fmac_f32_e32 v69, v56, v70
	v_fmac_f32_e32 v69, v57, v71
	v_add_f32_e32 v67, v67, v69
	ds_read_b128 v[68:71], v0 offset:10240
	v_add_f32_dpp v65, v65, v65 row_ror:4 row_mask:0xf bank_mask:0xf bound_ctrl:1
	v_add_f32_e32 v47, v47, v64
	v_mov_b32_e32 v64, v47
	v_add_f32_dpp v65, v65, v65 row_ror:8 row_mask:0xf bank_mask:0xf bound_ctrl:1
	s_waitcnt lgkmcnt(0)
	v_mul_f32_e32 v69, v55, v69
	v_fmac_f32_e32 v69, v54, v68
	v_fmac_f32_e32 v69, v52, v70
	v_fmac_f32_e32 v69, v53, v71
	v_add_f32_e32 v67, v67, v69
	ds_read_b128 v[68:71], v0 offset:11264
	v_mov_b32_e32 v66, v65
	s_nop 1
	v_permlane16_swap_b32_e32 v65, v66
	v_add_f32_e32 v65, v65, v66
	s_waitcnt lgkmcnt(0)
	v_mul_f32_e32 v69, v51, v69
	v_fmac_f32_e32 v69, v50, v68
	v_fmac_f32_e32 v69, v48, v70
	v_fmac_f32_e32 v69, v49, v71
	ds_read_b128 v[70:73], v0 offset:12288
	v_add_f32_e32 v67, v67, v69
	v_mov_b32_e32 v66, v65
	v_permlane32_swap_b32_e32 v47, v64
	s_waitcnt lgkmcnt(0)
	v_mul_f32_e32 v69, v63, v71
	v_fmac_f32_e32 v69, v62, v70
	v_fmac_f32_e32 v69, v60, v72
	v_fmac_f32_e32 v69, v61, v73
	ds_read_b128 v[70:73], v0 offset:13312
	v_add_f32_e32 v69, 0, v69
	v_add_f32_dpp v67, v67, v67 quad_perm:[1,0,3,2] row_mask:0xf bank_mask:0xf bound_ctrl:1
	v_permlane32_swap_b32_e32 v65, v66
	s_waitcnt lgkmcnt(0)
	v_mul_f32_e32 v71, v59, v71
	v_fmac_f32_e32 v71, v58, v70
	v_fmac_f32_e32 v71, v56, v72
	v_fmac_f32_e32 v71, v57, v73
	v_add_f32_e32 v69, v69, v71
	ds_read_b128 v[70:73], v0 offset:14336
	v_add_f32_dpp v67, v67, v67 quad_perm:[2,3,0,1] row_mask:0xf bank_mask:0xf bound_ctrl:1
	s_waitcnt lgkmcnt(0)
	v_mul_f32_e32 v71, v55, v71
	v_fmac_f32_e32 v71, v54, v70
	v_fmac_f32_e32 v71, v52, v72
	v_fmac_f32_e32 v71, v53, v73
	v_add_f32_e32 v69, v69, v71
	ds_read_b128 v[70:73], v0 offset:15360
	v_add_f32_dpp v67, v67, v67 row_ror:4 row_mask:0xf bank_mask:0xf bound_ctrl:1
	s_waitcnt lgkmcnt(0)
	v_mul_f32_e32 v71, v51, v71
	v_fmac_f32_e32 v71, v50, v70
	v_fmac_f32_e32 v71, v48, v72
	v_fmac_f32_e32 v71, v49, v73
	ds_read_b128 v[72:75], v0 offset:16384
	v_add_f32_e32 v69, v69, v71
	v_add_f32_dpp v67, v67, v67 row_ror:8 row_mask:0xf bank_mask:0xf bound_ctrl:1
	v_mov_b32_e32 v68, v67
	v_add_f32_dpp v69, v69, v69 quad_perm:[1,0,3,2] row_mask:0xf bank_mask:0xf bound_ctrl:1
	s_waitcnt lgkmcnt(0)
	v_mul_f32_e32 v71, v63, v73
	v_fmac_f32_e32 v71, v62, v72
	v_fmac_f32_e32 v71, v60, v74
	v_fmac_f32_e32 v71, v61, v75
	ds_read_b128 v[72:75], v0 offset:17408
	v_add_f32_e32 v71, 0, v71
	v_add_f32_dpp v69, v69, v69 quad_perm:[2,3,0,1] row_mask:0xf bank_mask:0xf bound_ctrl:1
	v_permlane16_swap_b32_e32 v67, v68
	s_waitcnt lgkmcnt(0)
	v_mul_f32_e32 v73, v59, v73
	v_fmac_f32_e32 v73, v58, v72
	v_fmac_f32_e32 v73, v56, v74
	v_fmac_f32_e32 v73, v57, v75
	v_add_f32_e32 v71, v71, v73
	ds_read_b128 v[72:75], v0 offset:18432
	v_add_f32_dpp v69, v69, v69 row_ror:4 row_mask:0xf bank_mask:0xf bound_ctrl:1
	v_add_f32_e32 v67, v67, v68
	v_mov_b32_e32 v68, v67
	v_add_f32_dpp v69, v69, v69 row_ror:8 row_mask:0xf bank_mask:0xf bound_ctrl:1
	s_waitcnt lgkmcnt(0)
; DEVI float wave_sum(float v) { v += dpp<0xB1>(v); v += dpp<0x4E>(v); v += dpp<0x124>(v); v += dpp<0x128>(v); return xrow16_sum(v); }
; DEVI void norm_phase(const float* __restrict__ x, const float* __restrict__ gain, bf16_t* __restrict__ out,
;                      const float* wf_src, const float* bf_src, float* logf, char* lds, int wv) {
;     ...
;                 for (int h = 0; h < 8; ++h) { float d = 0.f;
; #pragma unroll
;                     for (int j = 0; j < 4; ++j) { const f32x4 w = *(const f32x4*)(wf + h * 1024 + j * 256 + lane * 4); d += v[q][j][0] * w[0] + v[q][j][1] * w[1] + v[q][j][2] * w[2] + v[q][j][3] * w[3]; }
;                     d = wave_sum(d); if (lane == h) z = d; }
;                 if (lane < 8) { z += bf_src[lane]; logf[((size_t)(row >> 14) * 8 + lane) * SEQ + (row & (SEQ - 1))] = fminf(z, 0.f) - __logf(1.f + __expf(-fabsf(z))); }
	v_mul_f32_e32 v73, v55, v73
	v_fmac_f32_e32 v73, v54, v72
	v_fmac_f32_e32 v73, v52, v74
	v_fmac_f32_e32 v73, v53, v75
	v_add_f32_e32 v71, v71, v73
	ds_read_b128 v[72:75], v0 offset:19456
	v_mov_b32_e32 v70, v69
	s_nop 1
	v_permlane16_swap_b32_e32 v69, v70
	v_add_f32_e32 v69, v69, v70
	s_waitcnt lgkmcnt(0)
	v_mul_f32_e32 v73, v51, v73
	v_fmac_f32_e32 v73, v50, v72
	v_fmac_f32_e32 v73, v48, v74
	v_fmac_f32_e32 v73, v49, v75
	ds_read_b128 v[74:77], v0 offset:20480
	v_add_f32_e32 v71, v71, v73
	v_mov_b32_e32 v70, v69
	v_permlane32_swap_b32_e32 v67, v68
	s_waitcnt lgkmcnt(0)
	v_mul_f32_e32 v73, v63, v75
	v_fmac_f32_e32 v73, v62, v74
	v_fmac_f32_e32 v73, v60, v76
	v_fmac_f32_e32 v73, v61, v77
	ds_read_b128 v[74:77], v0 offset:21504
	v_add_f32_e32 v73, 0, v73
	v_add_f32_dpp v71, v71, v71 quad_perm:[1,0,3,2] row_mask:0xf bank_mask:0xf bound_ctrl:1
	v_permlane32_swap_b32_e32 v69, v70
	s_waitcnt lgkmcnt(0)
	v_mul_f32_e32 v75, v59, v75
	v_fmac_f32_e32 v75, v58, v74
	v_fmac_f32_e32 v75, v56, v76
	v_fmac_f32_e32 v75, v57, v77
	v_add_f32_e32 v73, v73, v75
	ds_read_b128 v[74:77], v0 offset:22528
	v_add_f32_dpp v71, v71, v71 quad_perm:[2,3,0,1] row_mask:0xf bank_mask:0xf bound_ctrl:1
	s_waitcnt lgkmcnt(0)
	v_mul_f32_e32 v75, v55, v75
	v_fmac_f32_e32 v75, v54, v74
	v_fmac_f32_e32 v75, v52, v76
	v_fmac_f32_e32 v75, v53, v77
	v_add_f32_e32 v73, v73, v75
	ds_read_b128 v[74:77], v0 offset:23552
	v_add_f32_dpp v71, v71, v71 row_ror:4 row_mask:0xf bank_mask:0xf bound_ctrl:1
	s_waitcnt lgkmcnt(0)
	v_mul_f32_e32 v75, v51, v75
	v_fmac_f32_e32 v75, v50, v74
	v_fmac_f32_e32 v75, v48, v76
	v_fmac_f32_e32 v75, v49, v77
	ds_read_b128 v[76:79], v0 offset:24576
	v_add_f32_e32 v73, v73, v75
	v_add_f32_dpp v71, v71, v71 row_ror:8 row_mask:0xf bank_mask:0xf bound_ctrl:1
	v_mov_b32_e32 v72, v71
	v_add_f32_dpp v73, v73, v73 quad_perm:[1,0,3,2] row_mask:0xf bank_mask:0xf bound_ctrl:1
	s_waitcnt lgkmcnt(0)
	v_mul_f32_e32 v75, v63, v77
	v_fmac_f32_e32 v75, v62, v76
	v_fmac_f32_e32 v75, v60, v78
	v_fmac_f32_e32 v75, v61, v79
	ds_read_b128 v[76:79], v0 offset:25600
	v_add_f32_e32 v75, 0, v75
	v_add_f32_dpp v73, v73, v73 quad_perm:[2,3,0,1] row_mask:0xf bank_mask:0xf bound_ctrl:1
	v_permlane16_swap_b32_e32 v71, v72
	s_waitcnt lgkmcnt(0)
	v_mul_f32_e32 v77, v59, v77
	v_fmac_f32_e32 v77, v58, v76
	v_fmac_f32_e32 v77, v56, v78
	v_fmac_f32_e32 v77, v57, v79
	v_add_f32_e32 v75, v75, v77
	ds_read_b128 v[76:79], v0 offset:26624
	v_add_f32_dpp v73, v73, v73 row_ror:4 row_mask:0xf bank_mask:0xf bound_ctrl:1
	v_add_f32_e32 v71, v71, v72
	v_mov_b32_e32 v72, v71
	v_add_f32_dpp v73, v73, v73 row_ror:8 row_mask:0xf bank_mask:0xf bound_ctrl:1
	s_waitcnt lgkmcnt(0)
	v_mul_f32_e32 v77, v55, v77
	v_fmac_f32_e32 v77, v54, v76
	v_fmac_f32_e32 v77, v52, v78
	v_fmac_f32_e32 v77, v53, v79
	v_add_f32_e32 v75, v75, v77
	ds_read_b128 v[76:79], v0 offset:27648
	v_mov_b32_e32 v74, v73
	s_nop 1
	v_permlane16_swap_b32_e32 v73, v74
	v_add_f32_e32 v73, v73, v74
	s_waitcnt lgkmcnt(0)
	v_mul_f32_e32 v77, v51, v77
	v_fmac_f32_e32 v77, v50, v76
	v_fmac_f32_e32 v77, v48, v78
	v_fmac_f32_e32 v77, v49, v79
	ds_read_b128 v[78:81], v0 offset:28672
	v_add_f32_e32 v75, v75, v77
	v_mov_b32_e32 v74, v73
	v_permlane32_swap_b32_e32 v71, v72
	s_waitcnt lgkmcnt(0)
	v_mul_f32_e32 v63, v63, v79
	v_fmac_f32_e32 v63, v62, v78
	v_fmac_f32_e32 v63, v60, v80
	v_fmac_f32_e32 v63, v61, v81
	v_add_f32_e32 v77, 0, v63
	ds_read_b128 v[60:63], v0 offset:29696
	v_add_f32_dpp v75, v75, v75 quad_perm:[1,0,3,2] row_mask:0xf bank_mask:0xf bound_ctrl:1
	v_permlane32_swap_b32_e32 v73, v74
	s_nop 0
	v_add_f32_dpp v75, v75, v75 quad_perm:[2,3,0,1] row_mask:0xf bank_mask:0xf bound_ctrl:1
	s_waitcnt lgkmcnt(0)
	v_mul_f32_e32 v59, v59, v61
	v_fmac_f32_e32 v59, v58, v60
	v_fmac_f32_e32 v59, v56, v62
	v_fmac_f32_e32 v59, v57, v63
	v_add_f32_e32 v60, v77, v59
	ds_read_b128 v[56:59], v0 offset:30720
	v_add_f32_dpp v75, v75, v75 row_ror:4 row_mask:0xf bank_mask:0xf bound_ctrl:1
	s_waitcnt lgkmcnt(0)
	v_mul_f32_e32 v55, v55, v57
	v_fmac_f32_e32 v55, v54, v56
	v_fmac_f32_e32 v55, v52, v58
	v_fmac_f32_e32 v55, v53, v59
	v_add_f32_e32 v56, v60, v55
	ds_read_b128 v[52:55], v0 offset:31744
	v_add_f32_dpp v75, v75, v75 row_ror:8 row_mask:0xf bank_mask:0xf bound_ctrl:1
	v_mov_b32_e32 v76, v75
	s_nop 1
	v_permlane16_swap_b32_e32 v75, v76
	s_waitcnt lgkmcnt(0)
	v_mul_f32_e32 v0, v51, v53
	v_fmac_f32_e32 v0, v50, v52
	v_fmac_f32_e32 v0, v48, v54
	v_fmac_f32_e32 v0, v49, v55
	v_add_f32_e32 v0, v56, v0
	v_add_f32_e32 v75, v75, v76
	v_mov_b32_e32 v76, v75
	v_add_f32_dpp v0, v0, v0 quad_perm:[1,0,3,2] row_mask:0xf bank_mask:0xf bound_ctrl:1
	s_nop 0
	v_permlane32_swap_b32_e32 v75, v76
	v_add_f32_dpp v0, v0, v0 quad_perm:[2,3,0,1] row_mask:0xf bank_mask:0xf bound_ctrl:1
	s_nop 1
	v_add_f32_dpp v0, v0, v0 row_ror:4 row_mask:0xf bank_mask:0xf bound_ctrl:1
	s_nop 1
	v_add_f32_dpp v0, v0, v0 row_ror:8 row_mask:0xf bank_mask:0xf bound_ctrl:1
	v_mov_b32_e32 v48, v0
	s_nop 1
	v_permlane16_swap_b32_e32 v0, v48
	v_add_f32_e32 v0, v0, v48
	v_mov_b32_e32 v48, v0
	s_nop 1
	v_permlane32_swap_b32_e32 v0, v48
	s_and_saveexec_b64 s[84:85], s[4:5]
	s_cbranch_execz .LBB0_482
	global_load_dword v49, v[40:41], off
	v_add_f32_e32 v47, v47, v64
	v_add_f32_e32 v55, v65, v66
	v_cndmask_b32_e64 v47, 0, v47, s[20:21]
	v_add_f32_e32 v54, v67, v68
	v_cndmask_b32_e64 v47, v47, v55, s[18:19]
	v_add_f32_e32 v53, v69, v70
	v_cndmask_b32_e64 v47, v47, v54, s[16:17]
	v_add_f32_e32 v52, v71, v72
	v_cndmask_b32_e64 v47, v47, v53, s[14:15]
	v_add_f32_e32 v51, v73, v74
	v_cndmask_b32_e64 v47, v47, v52, s[12:13]
	v_add_f32_e32 v50, v75, v76
	v_cndmask_b32_e64 v47, v47, v51, s[10:11]
	v_add_f32_e32 v0, v0, v48
	v_cndmask_b32_e64 v47, v47, v50, s[8:9]
	v_cndmask_b32_e64 v0, v47, v0, s[6:7]
	s_mov_b32 s59, 0xbfb8aa3b
	v_ashrrev_i32_e32 v48, 14, v46
	v_and_b32_e32 v46, 0x3fff, v46
	s_waitcnt vmcnt(0)
	v_add_f32_e32 v50, v0, v49
	v_mul_f32_e64 v0, |v50|, s59
	v_exp_f32_e32 v51, v0
	v_ashrrev_i32_e32 v49, 31, v48
	v_lshlrev_b32_e32 v0, 2, v46
	v_lshlrev_b64 v[46:47], 19, v[48:49]
	v_add_f32_e32 v48, 1.0, v51
	s_mov_b32 s59, 0x800000
	v_cmp_gt_f32_e32 vcc, s59, v48
	s_mov_b32 s59, 0x3f317217
	v_lshl_add_u64 v[46:47], v[42:43], 0, v[46:47]
	v_cndmask_b32_e64 v49, 0, 32, vcc
	v_ldexp_f32 v48, v48, v49
	v_log_f32_e32 v48, v48
	v_min_f32_e32 v49, 0, v50
	v_mov_b32_e32 v50, 0x41b17218
	v_cndmask_b32_e32 v50, 0, v50, vcc
	v_mul_f32_e32 v51, 0x3f317217, v48
	v_fma_f32 v51, v48, s59, -v51
	v_fmac_f32_e32 v51, 0x3377d1cf, v48
	s_mov_b32 s59, 0x7f800000
	v_fmac_f32_e32 v51, 0x3f317217, v48
	v_cmp_lt_f32_e64 vcc, |v48|, s59
	v_lshl_add_u64 v[46:47], v[46:47], 0, v[0:1]
	s_nop 0
	v_cndmask_b32_e32 v48, v48, v51, vcc
	v_sub_f32_e32 v48, v48, v50
	v_sub_f32_e32 v48, v49, v48
	global_store_dword v[46:47], v48, off

; DEVI unsigned cvtpk(float lo, float hi) { unsigned r; asm volatile("v_cvt_pk_bf16_f32 %0, %1, %2" : "=v"(r) : "v"(lo), "v"(hi)); return r; }
; DEVI float wave_sum(float v) { v += dpp<0xB1>(v); v += dpp<0x4E>(v); v += dpp<0x124>(v); v += dpp<0x128>(v); return xrow16_sum(v); }
; DEVI void norm_phase(const float* __restrict__ x, const float* __restrict__ gain, bf16_t* __restrict__ out,
;                      const float* wf_src, const float* bf_src, float* logf, char* lds, int wv) {
;     ...
;         for (int q = 0; q < 2; ++q) { const int row = row0 + q * nw; if (row >= T_TOK) break;
;             const float rstd = __builtin_amdgcn_rsqf(ss[q] * (1.f / 1024.f) + 1e-6f);
; #pragma unroll
;             for (int j = 0; j < 4; ++j) { v[q][j] = v[q][j] * rstd * g[j]; u32x2 w; w.x = cvtpk(v[q][j][0], v[q][j][1]); w.y = cvtpk(v[q][j][2], v[q][j][3]); *(u32x2*)(out + (size_t)row * DM + j * 256 + lane * 4) = w; }
;             if (wf_src) {
;                 float z = 0.f;
; #pragma unroll
;                 for (int h = 0; h < 8; ++h) { float d = 0.f;
; #pragma unroll
;                     for (int j = 0; j < 4; ++j) { const f32x4 w = *(const f32x4*)(wf + h * 1024 + j * 256 + lane * 4); d += v[q][j][0] * w[0] + v[q][j][1] * w[1] + v[q][j][2] * w[2] + v[q][j][3] * w[3]; }
;                     d = wave_sum(d); if (lane == h) z = d; }
.LBB0_483:
	s_and_saveexec_b64 s[84:85], s[22:23]
	s_cbranch_execz .LBB0_478
	v_add_f32_e32 v0, v35, v45
	v_fmamk_f32 v0, v0, 0x3a800000, v216
	v_rsq_f32_e32 v0, v0
	v_ashrrev_i32_e32 v45, 31, v44
	v_lshlrev_b64 v[46:47], 11, v[44:45]
	v_lshl_add_u64 v[46:47], v[38:39], 0, v[46:47]
	v_pk_mul_f32 v[32:33], v[32:33], v[0:1] op_sel_hi:[1,0]
	v_pk_mul_f32 v[48:49], v[30:31], v[0:1] op_sel_hi:[1,0]
	v_pk_mul_f32 v[30:31], v[4:5], v[32:33]
	v_pk_mul_f32 v[32:33], v[2:3], v[48:49]
	v_pk_mul_f32 v[28:29], v[28:29], v[0:1] op_sel_hi:[1,0]
	v_cvt_pk_bf16_f32 v48, v32, v33
	v_cvt_pk_bf16_f32 v49, v30, v31
	global_store_dwordx2 v[46:47], v[48:49], off
	v_pk_mul_f32 v[48:49], v[26:27], v[0:1] op_sel_hi:[1,0]
	v_pk_mul_f32 v[26:27], v[8:9], v[28:29]
	v_pk_mul_f32 v[28:29], v[6:7], v[48:49]
	v_pk_mul_f32 v[24:25], v[24:25], v[0:1] op_sel_hi:[1,0]
	v_cvt_pk_bf16_f32 v48, v28, v29
	v_cvt_pk_bf16_f32 v49, v26, v27
	global_store_dwordx2 v[46:47], v[48:49], off offset:512
	v_pk_mul_f32 v[48:49], v[22:23], v[0:1] op_sel_hi:[1,0]
	v_pk_mul_f32 v[22:23], v[12:13], v[24:25]
	v_pk_mul_f32 v[24:25], v[10:11], v[48:49]
	v_pk_mul_f32 v[20:21], v[20:21], v[0:1] op_sel_hi:[1,0]
	v_cvt_pk_bf16_f32 v48, v24, v25
	v_cvt_pk_bf16_f32 v49, v22, v23
	global_store_dwordx2 v[46:47], v[48:49], off offset:1024
	v_pk_mul_f32 v[48:49], v[18:19], v[0:1] op_sel_hi:[1,0]
	v_pk_mul_f32 v[18:19], v[16:17], v[20:21]
	v_pk_mul_f32 v[20:21], v[14:15], v[48:49]
	s_and_b64 vcc, exec, s[24:25]
	v_cvt_pk_bf16_f32 v48, v20, v21
	v_cvt_pk_bf16_f32 v49, v18, v19
	global_store_dwordx2 v[46:47], v[48:49], off offset:1536
	s_cbranch_vccnz .LBB0_478
	v_add_u32_e32 v0, 0, v34
	ds_read_b128 v[46:49], v0
	s_waitcnt lgkmcnt(0)
	v_mul_f32_e32 v35, v33, v47
	v_fmac_f32_e32 v35, v32, v46
	v_fmac_f32_e32 v35, v30, v48
	v_fmac_f32_e32 v35, v31, v49
	ds_read_b128 v[46:49], v0 offset:1024
	v_add_f32_e32 v35, 0, v35
	s_waitcnt lgkmcnt(0)
	v_mul_f32_e32 v45, v29, v47
	v_fmac_f32_e32 v45, v28, v46
	v_fmac_f32_e32 v45, v26, v48
	v_fmac_f32_e32 v45, v27, v49
	ds_read_b128 v[46:49], v0 offset:2048
	v_add_f32_e32 v35, v35, v45
	s_waitcnt lgkmcnt(0)
	v_mul_f32_e32 v45, v25, v47
	v_fmac_f32_e32 v45, v24, v46
	v_fmac_f32_e32 v45, v22, v48
	v_fmac_f32_e32 v45, v23, v49
	ds_read_b128 v[46:49], v0 offset:3072
	v_add_f32_e32 v35, v35, v45
	s_waitcnt lgkmcnt(0)
	v_mul_f32_e32 v45, v21, v47
	v_fmac_f32_e32 v45, v20, v46
	v_fmac_f32_e32 v45, v18, v48
	v_fmac_f32_e32 v45, v19, v49
	ds_read_b128 v[46:49], v0 offset:4096
	v_add_f32_e32 v35, v35, v45
	s_waitcnt lgkmcnt(0)
	v_mul_f32_e32 v47, v33, v47
	v_fmac_f32_e32 v47, v32, v46
	v_fmac_f32_e32 v47, v30, v48
	v_fmac_f32_e32 v47, v31, v49
	v_add_f32_e32 v50, 0, v47
	ds_read_b128 v[46:49], v0 offset:5120
	v_add_f32_dpp v35, v35, v35 quad_perm:[1,0,3,2] row_mask:0xf bank_mask:0xf bound_ctrl:1
	s_waitcnt lgkmcnt(0)
	v_mul_f32_e32 v47, v29, v47
	v_fmac_f32_e32 v47, v28, v46
	v_fmac_f32_e32 v47, v26, v48
	v_fmac_f32_e32 v47, v27, v49
	v_add_f32_e32 v50, v50, v47
	ds_read_b128 v[46:49], v0 offset:6144
	v_add_f32_dpp v35, v35, v35 quad_perm:[2,3,0,1] row_mask:0xf bank_mask:0xf bound_ctrl:1
	s_waitcnt lgkmcnt(0)
	v_mul_f32_e32 v47, v25, v47
	v_fmac_f32_e32 v47, v24, v46
	v_fmac_f32_e32 v47, v22, v48
	v_fmac_f32_e32 v47, v23, v49
	v_add_f32_e32 v50, v50, v47
	ds_read_b128 v[46:49], v0 offset:7168
	v_add_f32_dpp v35, v35, v35 row_ror:4 row_mask:0xf bank_mask:0xf bound_ctrl:1
	s_waitcnt lgkmcnt(0)
	v_mul_f32_e32 v47, v21, v47
	v_fmac_f32_e32 v47, v20, v46
	v_fmac_f32_e32 v47, v18, v48
	v_fmac_f32_e32 v47, v19, v49
	v_add_f32_e32 v46, v50, v47
	ds_read_b128 v[48:51], v0 offset:8192
	v_add_f32_dpp v35, v35, v35 row_ror:8 row_mask:0xf bank_mask:0xf bound_ctrl:1
	v_add_f32_dpp v46, v46, v46 quad_perm:[1,0,3,2] row_mask:0xf bank_mask:0xf bound_ctrl:1
	v_mov_b32_e32 v45, v35
	s_nop 1
	v_permlane16_swap_b32_e32 v35, v45
	s_waitcnt lgkmcnt(0)
	v_mul_f32_e32 v49, v33, v49
	v_fmac_f32_e32 v49, v32, v48
	v_fmac_f32_e32 v49, v30, v50
	v_fmac_f32_e32 v49, v31, v51
	v_add_f32_e32 v52, 0, v49
	ds_read_b128 v[48:51], v0 offset:9216
	v_add_f32_dpp v46, v46, v46 quad_perm:[2,3,0,1] row_mask:0xf bank_mask:0xf bound_ctrl:1
	v_add_f32_e32 v35, v35, v45
	v_mov_b32_e32 v45, v35
	v_add_f32_dpp v46, v46, v46 row_ror:4 row_mask:0xf bank_mask:0xf bound_ctrl:1
	s_waitcnt lgkmcnt(0)
	v_mul_f32_e32 v49, v29, v49
	v_fmac_f32_e32 v49, v28, v48
	v_fmac_f32_e32 v49, v26, v50
	v_fmac_f32_e32 v49, v27, v51
	v_add_f32_e32 v52, v52, v49
	ds_read_b128 v[48:51], v0 offset:10240
	v_add_f32_dpp v46, v46, v46 row_ror:8 row_mask:0xf bank_mask:0xf bound_ctrl:1
	v_mov_b32_e32 v47, v46
	s_nop 1
	v_permlane16_swap_b32_e32 v46, v47
	s_waitcnt lgkmcnt(0)
	v_mul_f32_e32 v49, v25, v49
	v_fmac_f32_e32 v49, v24, v48
	v_fmac_f32_e32 v49, v22, v50
	v_fmac_f32_e32 v49, v23, v51
	v_add_f32_e32 v52, v52, v49
	ds_read_b128 v[48:51], v0 offset:11264
	v_add_f32_e32 v46, v46, v47
	v_mov_b32_e32 v47, v46
	v_permlane32_swap_b32_e32 v35, v45
	s_waitcnt lgkmcnt(0)
	v_mul_f32_e32 v49, v21, v49
	v_fmac_f32_e32 v49, v20, v48
	v_fmac_f32_e32 v49, v18, v50
	v_fmac_f32_e32 v49, v19, v51
	v_add_f32_e32 v48, v52, v49
	ds_read_b128 v[50:53], v0 offset:12288
	v_permlane32_swap_b32_e32 v46, v47
	v_add_f32_dpp v48, v48, v48 quad_perm:[1,0,3,2] row_mask:0xf bank_mask:0xf bound_ctrl:1
	s_waitcnt lgkmcnt(0)
	v_mul_f32_e32 v51, v33, v51
	v_fmac_f32_e32 v51, v32, v50
	v_fmac_f32_e32 v51, v30, v52
	v_fmac_f32_e32 v51, v31, v53
	v_add_f32_e32 v54, 0, v51
	ds_read_b128 v[50:53], v0 offset:13312
	v_add_f32_dpp v48, v48, v48 quad_perm:[2,3,0,1] row_mask:0xf bank_mask:0xf bound_ctrl:1
	s_waitcnt lgkmcnt(0)
; DEVI float wave_sum(float v) { v += dpp<0xB1>(v); v += dpp<0x4E>(v); v += dpp<0x124>(v); v += dpp<0x128>(v); return xrow16_sum(v); }
; DEVI void norm_phase(const float* __restrict__ x, const float* __restrict__ gain, bf16_t* __restrict__ out,
;                      const float* wf_src, const float* bf_src, float* logf, char* lds, int wv) {
;     ...
;             if (wf_src) {
;                 float z = 0.f;
; #pragma unroll
;                 for (int h = 0; h < 8; ++h) { float d = 0.f;
; #pragma unroll
;                     for (int j = 0; j < 4; ++j) { const f32x4 w = *(const f32x4*)(wf + h * 1024 + j * 256 + lane * 4); d += v[q][j][0] * w[0] + v[q][j][1] * w[1] + v[q][j][2] * w[2] + v[q][j][3] * w[3]; }
;                     d = wave_sum(d); if (lane == h) z = d; }
	v_mul_f32_e32 v51, v29, v51
	v_fmac_f32_e32 v51, v28, v50
	v_fmac_f32_e32 v51, v26, v52
	v_fmac_f32_e32 v51, v27, v53
	v_add_f32_e32 v54, v54, v51
	ds_read_b128 v[50:53], v0 offset:14336
	v_add_f32_dpp v48, v48, v48 row_ror:4 row_mask:0xf bank_mask:0xf bound_ctrl:1
	s_waitcnt lgkmcnt(0)
	v_mul_f32_e32 v51, v25, v51
	v_fmac_f32_e32 v51, v24, v50
	v_fmac_f32_e32 v51, v22, v52
	v_fmac_f32_e32 v51, v23, v53
	v_add_f32_e32 v54, v54, v51
	ds_read_b128 v[50:53], v0 offset:15360
	v_add_f32_dpp v48, v48, v48 row_ror:8 row_mask:0xf bank_mask:0xf bound_ctrl:1
	v_mov_b32_e32 v49, v48
	s_nop 1
	v_permlane16_swap_b32_e32 v48, v49
	s_waitcnt lgkmcnt(0)
	v_mul_f32_e32 v51, v21, v51
	v_fmac_f32_e32 v51, v20, v50
	v_fmac_f32_e32 v51, v18, v52
	v_fmac_f32_e32 v51, v19, v53
	v_add_f32_e32 v50, v54, v51
	ds_read_b128 v[52:55], v0 offset:16384
	v_add_f32_e32 v48, v48, v49
	v_add_f32_dpp v50, v50, v50 quad_perm:[1,0,3,2] row_mask:0xf bank_mask:0xf bound_ctrl:1
	v_mov_b32_e32 v49, v48
	s_nop 1
	v_permlane32_swap_b32_e32 v48, v49
	s_waitcnt lgkmcnt(0)
	v_mul_f32_e32 v53, v33, v53
	v_fmac_f32_e32 v53, v32, v52
	v_fmac_f32_e32 v53, v30, v54
	v_fmac_f32_e32 v53, v31, v55
	v_add_f32_e32 v56, 0, v53
	ds_read_b128 v[52:55], v0 offset:17408
	v_add_f32_dpp v50, v50, v50 quad_perm:[2,3,0,1] row_mask:0xf bank_mask:0xf bound_ctrl:1
	s_waitcnt lgkmcnt(0)
	v_mul_f32_e32 v53, v29, v53
	v_fmac_f32_e32 v53, v28, v52
	v_fmac_f32_e32 v53, v26, v54
	v_fmac_f32_e32 v53, v27, v55
	v_add_f32_e32 v56, v56, v53
	ds_read_b128 v[52:55], v0 offset:18432
	v_add_f32_dpp v50, v50, v50 row_ror:4 row_mask:0xf bank_mask:0xf bound_ctrl:1
	s_waitcnt lgkmcnt(0)
	v_mul_f32_e32 v53, v25, v53
	v_fmac_f32_e32 v53, v24, v52
	v_fmac_f32_e32 v53, v22, v54
	v_fmac_f32_e32 v53, v23, v55
	v_add_f32_e32 v56, v56, v53
	ds_read_b128 v[52:55], v0 offset:19456
	v_add_f32_dpp v50, v50, v50 row_ror:8 row_mask:0xf bank_mask:0xf bound_ctrl:1
	v_mov_b32_e32 v51, v50
	s_nop 1
	v_permlane16_swap_b32_e32 v50, v51
	s_waitcnt lgkmcnt(0)
	v_mul_f32_e32 v53, v21, v53
	v_fmac_f32_e32 v53, v20, v52
	v_fmac_f32_e32 v53, v18, v54
	v_fmac_f32_e32 v53, v19, v55
	v_add_f32_e32 v52, v56, v53
	ds_read_b128 v[54:57], v0 offset:20480
	v_add_f32_e32 v50, v50, v51
	v_add_f32_dpp v52, v52, v52 quad_perm:[1,0,3,2] row_mask:0xf bank_mask:0xf bound_ctrl:1
	v_mov_b32_e32 v51, v50
	s_nop 1
	v_permlane32_swap_b32_e32 v50, v51
	s_waitcnt lgkmcnt(0)
	v_mul_f32_e32 v55, v33, v55
	v_fmac_f32_e32 v55, v32, v54
	v_fmac_f32_e32 v55, v30, v56
	v_fmac_f32_e32 v55, v31, v57
	v_add_f32_e32 v58, 0, v55
	ds_read_b128 v[54:57], v0 offset:21504
	v_add_f32_dpp v52, v52, v52 quad_perm:[2,3,0,1] row_mask:0xf bank_mask:0xf bound_ctrl:1
	s_waitcnt lgkmcnt(0)
	v_mul_f32_e32 v55, v29, v55
	v_fmac_f32_e32 v55, v28, v54
	v_fmac_f32_e32 v55, v26, v56
	v_fmac_f32_e32 v55, v27, v57
	v_add_f32_e32 v58, v58, v55
	ds_read_b128 v[54:57], v0 offset:22528
	v_add_f32_dpp v52, v52, v52 row_ror:4 row_mask:0xf bank_mask:0xf bound_ctrl:1
	s_waitcnt lgkmcnt(0)
	v_mul_f32_e32 v55, v25, v55
	v_fmac_f32_e32 v55, v24, v54
	v_fmac_f32_e32 v55, v22, v56
	v_fmac_f32_e32 v55, v23, v57
	v_add_f32_e32 v58, v58, v55
	ds_read_b128 v[54:57], v0 offset:23552
	v_add_f32_dpp v52, v52, v52 row_ror:8 row_mask:0xf bank_mask:0xf bound_ctrl:1
	v_mov_b32_e32 v53, v52
	s_nop 1
	v_permlane16_swap_b32_e32 v52, v53
	s_waitcnt lgkmcnt(0)
	v_mul_f32_e32 v55, v21, v55
	v_fmac_f32_e32 v55, v20, v54
	v_fmac_f32_e32 v55, v18, v56
	v_fmac_f32_e32 v55, v19, v57
	v_add_f32_e32 v54, v58, v55
	ds_read_b128 v[56:59], v0 offset:24576
	v_add_f32_e32 v52, v52, v53
	v_add_f32_dpp v54, v54, v54 quad_perm:[1,0,3,2] row_mask:0xf bank_mask:0xf bound_ctrl:1
	v_mov_b32_e32 v53, v52
	s_nop 1
	v_permlane32_swap_b32_e32 v52, v53
	s_waitcnt lgkmcnt(0)
	v_mul_f32_e32 v57, v33, v57
	v_fmac_f32_e32 v57, v32, v56
	v_fmac_f32_e32 v57, v30, v58
	v_fmac_f32_e32 v57, v31, v59
	v_add_f32_e32 v60, 0, v57
	ds_read_b128 v[56:59], v0 offset:25600
	v_add_f32_dpp v54, v54, v54 quad_perm:[2,3,0,1] row_mask:0xf bank_mask:0xf bound_ctrl:1
	s_waitcnt lgkmcnt(0)
	v_mul_f32_e32 v57, v29, v57
	v_fmac_f32_e32 v57, v28, v56
	v_fmac_f32_e32 v57, v26, v58
	v_fmac_f32_e32 v57, v27, v59
	v_add_f32_e32 v60, v60, v57
	ds_read_b128 v[56:59], v0 offset:26624
	v_add_f32_dpp v54, v54, v54 row_ror:4 row_mask:0xf bank_mask:0xf bound_ctrl:1
	s_waitcnt lgkmcnt(0)
	v_mul_f32_e32 v57, v25, v57
	v_fmac_f32_e32 v57, v24, v56
	v_fmac_f32_e32 v57, v22, v58
	v_fmac_f32_e32 v57, v23, v59
	v_add_f32_e32 v60, v60, v57
	ds_read_b128 v[56:59], v0 offset:27648
	v_add_f32_dpp v54, v54, v54 row_ror:8 row_mask:0xf bank_mask:0xf bound_ctrl:1
	v_mov_b32_e32 v55, v54
	s_nop 1
	v_permlane16_swap_b32_e32 v54, v55
	s_waitcnt lgkmcnt(0)
	v_mul_f32_e32 v57, v21, v57
	v_fmac_f32_e32 v57, v20, v56
	v_fmac_f32_e32 v57, v18, v58
	v_fmac_f32_e32 v57, v19, v59
	v_add_f32_e32 v56, v60, v57
	ds_read_b128 v[58:61], v0 offset:28672
	v_add_f32_e32 v54, v54, v55
	v_add_f32_dpp v56, v56, v56 quad_perm:[1,0,3,2] row_mask:0xf bank_mask:0xf bound_ctrl:1
	v_mov_b32_e32 v55, v54
	s_nop 1
	v_permlane32_swap_b32_e32 v54, v55
	s_waitcnt lgkmcnt(0)
	v_mul_f32_e32 v33, v33, v59
	v_fmac_f32_e32 v33, v32, v58
	v_fmac_f32_e32 v33, v30, v60
	v_fmac_f32_e32 v33, v31, v61
	v_add_f32_e32 v58, 0, v33
	ds_read_b128 v[30:33], v0 offset:29696
	v_add_f32_dpp v56, v56, v56 quad_perm:[2,3,0,1] row_mask:0xf bank_mask:0xf bound_ctrl:1
	s_waitcnt lgkmcnt(0)
	v_mul_f32_e32 v29, v29, v31
	v_fmac_f32_e32 v29, v28, v30
	v_fmac_f32_e32 v29, v26, v32
	v_fmac_f32_e32 v29, v27, v33
	v_add_f32_e32 v30, v58, v29
	ds_read_b128 v[26:29], v0 offset:30720
	v_add_f32_dpp v56, v56, v56 row_ror:4 row_mask:0xf bank_mask:0xf bound_ctrl:1
	s_waitcnt lgkmcnt(0)
	v_mul_f32_e32 v25, v25, v27
	v_fmac_f32_e32 v25, v24, v26
	v_fmac_f32_e32 v25, v22, v28
	v_fmac_f32_e32 v25, v23, v29
	v_add_f32_e32 v26, v30, v25
	ds_read_b128 v[22:25], v0 offset:31744
	v_add_f32_dpp v56, v56, v56 row_ror:8 row_mask:0xf bank_mask:0xf bound_ctrl:1
	v_mov_b32_e32 v57, v56
	s_nop 1
	v_permlane16_swap_b32_e32 v56, v57
	s_waitcnt lgkmcnt(0)
	v_mul_f32_e32 v0, v21, v23
	v_fmac_f32_e32 v0, v20, v22
	v_fmac_f32_e32 v0, v18, v24
	v_fmac_f32_e32 v0, v19, v25
	v_add_f32_e32 v0, v26, v0
	v_add_f32_e32 v56, v56, v57
	v_mov_b32_e32 v57, v56
	v_add_f32_dpp v0, v0, v0 quad_perm:[1,0,3,2] row_mask:0xf bank_mask:0xf bound_ctrl:1
	s_nop 0
	v_permlane32_swap_b32_e32 v56, v57
	v_add_f32_dpp v0, v0, v0 quad_perm:[2,3,0,1] row_mask:0xf bank_mask:0xf bound_ctrl:1
	s_nop 1
	v_add_f32_dpp v0, v0, v0 row_ror:4 row_mask:0xf bank_mask:0xf bound_ctrl:1
	s_nop 1
	v_add_f32_dpp v0, v0, v0 row_ror:8 row_mask:0xf bank_mask:0xf bound_ctrl:1
	v_mov_b32_e32 v18, v0
	s_nop 1
	v_permlane16_swap_b32_e32 v0, v18
	v_add_f32_e32 v0, v0, v18
	v_mov_b32_e32 v18, v0
	s_nop 1
	v_permlane32_swap_b32_e32 v0, v18
	s_and_b64 exec, exec, s[4:5]
	s_cbranch_execz .LBB0_478
; DEVI void norm_phase(const float* __restrict__ x, const float* __restrict__ gain, bf16_t* __restrict__ out,
;                      const float* wf_src, const float* bf_src, float* logf, char* lds, int wv) {
;     ...
;                 if (lane < 8) { z += bf_src[lane]; logf[((size_t)(row >> 14) * 8 + lane) * SEQ + (row & (SEQ - 1))] = fminf(z, 0.f) - __logf(1.f + __expf(-fabsf(z))); }
	global_load_dword v19, v[40:41], off
	v_add_f32_e32 v26, v35, v45
	v_add_f32_e32 v25, v46, v47
	v_cndmask_b32_e64 v26, 0, v26, s[20:21]
	v_add_f32_e32 v24, v48, v49
	v_cndmask_b32_e64 v25, v26, v25, s[18:19]
	v_add_f32_e32 v23, v50, v51
	v_cndmask_b32_e64 v24, v25, v24, s[16:17]
	v_add_f32_e32 v22, v52, v53
	v_cndmask_b32_e64 v23, v24, v23, s[14:15]
	v_add_f32_e32 v21, v54, v55
	v_cndmask_b32_e64 v22, v23, v22, s[12:13]
	v_add_f32_e32 v20, v56, v57
	v_cndmask_b32_e64 v21, v22, v21, s[10:11]
	v_add_f32_e32 v0, v0, v18
	v_cndmask_b32_e64 v20, v21, v20, s[8:9]
	v_cndmask_b32_e64 v0, v20, v0, s[6:7]
	s_mov_b32 s22, 0xbfb8aa3b
	v_ashrrev_i32_e32 v18, 14, v44
	v_and_b32_e32 v27, 0x3fff, v44
	s_waitcnt vmcnt(0)
	v_add_f32_e32 v20, v0, v19
	v_mul_f32_e64 v0, |v20|, s22
	v_exp_f32_e32 v21, v0
	s_mov_b32 s22, 0x800000
	v_ashrrev_i32_e32 v19, 31, v18
	v_lshlrev_b64 v[18:19], 19, v[18:19]
	v_add_f32_e32 v21, 1.0, v21
	v_cmp_gt_f32_e32 vcc, s22, v21
	s_mov_b32 s22, 0x3f317217
	v_lshlrev_b32_e32 v0, 2, v27
	v_cndmask_b32_e64 v22, 0, 32, vcc
	v_ldexp_f32 v21, v21, v22
	v_log_f32_e32 v21, v21
	v_mov_b32_e32 v22, 0x41b17218
	v_cndmask_b32_e32 v22, 0, v22, vcc
	v_lshl_add_u64 v[18:19], v[42:43], 0, v[18:19]
	v_mul_f32_e32 v23, 0x3f317217, v21
	v_fma_f32 v23, v21, s22, -v23
	v_fmac_f32_e32 v23, 0x3377d1cf, v21
	s_mov_b32 s22, 0x7f800000
	v_fmac_f32_e32 v23, 0x3f317217, v21
	v_cmp_lt_f32_e64 vcc, |v21|, s22
	v_min_f32_e32 v20, 0, v20
	v_lshl_add_u64 v[18:19], v[18:19], 0, v[0:1]
	v_cndmask_b32_e32 v21, v21, v23, vcc
	v_sub_f32_e32 v21, v21, v22
	v_sub_f32_e32 v20, v20, v21
	global_store_dword v[18:19], v20, off
	s_branch .LBB0_478

.LBB0_528:
	s_add_u32 s20, s81, s46
	s_addc_u32 s21, s82, 0
	s_add_u32 s83, s79, s46
	s_addc_u32 s84, s80, 0
	s_add_i32 s85, 0, 0x10000
	v_add_u32_e32 v0, s85, v147
	ds_read_b128 v[150:153], v0
	ds_read_b128 v[154:157], v0 offset:1024
	ds_read_b128 v[158:161], v0 offset:2048
	ds_read_b128 v[162:165], v0 offset:3072
	s_cmp_eq_u32 s46, s18
	s_cselect_b32 s23, s9, s21
	s_cselect_b32 s22, s76, s20
	s_cselect_b32 s21, s7, s84
	s_cselect_b32 s20, s77, s83
	s_add_i32 s84, s11, 0xc000
	v_lshl_add_u64 v[140:141], v[144:145], 0, s[46:47]
	s_mov_b32 m0, s84
	s_add_i32 s83, s11, 0xe000
	ds_read_b128 v[166:169], v149
	ds_read_b128 v[170:173], v149 offset:1024
	ds_read_b128 v[174:177], v149 offset:2048
	ds_read_b128 v[178:181], v149 offset:3072
	ds_read_b128 v[182:185], v149 offset:4096
	ds_read_b128 v[186:189], v149 offset:5120
	ds_read_b128 v[190:193], v149 offset:6144
	ds_read_b128 v[194:197], v149 offset:7168
	global_load_lds_dwordx4 v[140:141], off
	v_lshl_add_u64 v[140:141], v[2:3], 0, s[46:47]
	s_mov_b32 m0, s83
	s_nop 0
	global_load_lds_dwordx4 v[140:141], off
	s_waitcnt lgkmcnt(8)
	s_barrier
	s_waitcnt lgkmcnt(0)
	s_setprio 1
	s_waitcnt lgkmcnt(0)
	v_mfma_f32_16x16x32_bf16 v[124:127], v[150:153], v[166:169], v[124:127]
	v_mfma_f32_16x16x32_bf16 v[116:119], v[158:161], v[166:169], v[116:119]
	v_mfma_f32_16x16x32_bf16 v[108:111], v[150:153], v[174:177], v[108:111]
	v_mfma_f32_16x16x32_bf16 v[100:103], v[158:161], v[174:177], v[100:103]
	v_mfma_f32_16x16x32_bf16 v[92:95], v[150:153], v[182:185], v[92:95]
	v_mfma_f32_16x16x32_bf16 v[84:87], v[158:161], v[182:185], v[84:87]
	v_mfma_f32_16x16x32_bf16 v[76:79], v[150:153], v[190:193], v[76:79]
	v_mfma_f32_16x16x32_bf16 v[64:67], v[158:161], v[190:193], v[64:67]
	v_mfma_f32_16x16x32_bf16 v[124:127], v[154:157], v[170:173], v[124:127]
	v_mfma_f32_16x16x32_bf16 v[116:119], v[162:165], v[170:173], v[116:119]
	v_mfma_f32_16x16x32_bf16 v[108:111], v[154:157], v[178:181], v[108:111]
	v_mfma_f32_16x16x32_bf16 v[100:103], v[162:165], v[178:181], v[100:103]
	v_mfma_f32_16x16x32_bf16 v[92:95], v[154:157], v[186:189], v[92:95]
	v_mfma_f32_16x16x32_bf16 v[84:87], v[162:165], v[186:189], v[84:87]
	v_mfma_f32_16x16x32_bf16 v[76:79], v[154:157], v[194:197], v[76:79]
	v_mfma_f32_16x16x32_bf16 v[64:67], v[162:165], v[194:197], v[64:67]
	s_setprio 0
	s_barrier
	s_add_i32 s88, 0, 0x14000
	s_add_i32 s85, s85, s25
	v_add_u32_e32 v0, s88, v147
	v_lshl_add_u64 v[140:141], s[20:21], 0, v[136:137]
	s_mov_b32 m0, s85
	ds_read_b128 v[200:203], v0
	ds_read_b128 v[204:207], v0 offset:1024
	ds_read_b128 v[208:211], v0 offset:2048
	ds_read_b128 v[212:215], v0 offset:3072
	global_load_lds_dwordx4 v[140:141], off
	v_lshl_add_u64 v[142:143], s[20:21], 0, v[132:133]
	s_add_i32 m0, s85, 0x2000
	s_nop 0
	global_load_lds_dwordx4 v[142:143], off
	s_barrier
	s_waitcnt lgkmcnt(0)
	s_setprio 1
	s_waitcnt lgkmcnt(0)
	v_mfma_f32_16x16x32_bf16 v[128:131], v[200:203], v[166:169], v[128:131]
	v_mfma_f32_16x16x32_bf16 v[120:123], v[208:211], v[166:169], v[120:123]
	v_mfma_f32_16x16x32_bf16 v[112:115], v[200:203], v[174:177], v[112:115]
	v_mfma_f32_16x16x32_bf16 v[104:107], v[208:211], v[174:177], v[104:107]
	v_mfma_f32_16x16x32_bf16 v[96:99], v[200:203], v[182:185], v[96:99]
	v_mfma_f32_16x16x32_bf16 v[88:91], v[208:211], v[182:185], v[88:91]
	v_mfma_f32_16x16x32_bf16 v[80:83], v[200:203], v[190:193], v[80:83]
	v_mfma_f32_16x16x32_bf16 v[72:75], v[208:211], v[190:193], v[72:75]
	v_mfma_f32_16x16x32_bf16 v[128:131], v[204:207], v[170:173], v[128:131]
	v_mfma_f32_16x16x32_bf16 v[120:123], v[212:215], v[170:173], v[120:123]
	v_mfma_f32_16x16x32_bf16 v[112:115], v[204:207], v[178:181], v[112:115]
	v_mfma_f32_16x16x32_bf16 v[104:107], v[212:215], v[178:181], v[104:107]
	v_mfma_f32_16x16x32_bf16 v[96:99], v[204:207], v[186:189], v[96:99]
	v_mfma_f32_16x16x32_bf16 v[88:91], v[212:215], v[186:189], v[88:91]
	v_mfma_f32_16x16x32_bf16 v[80:83], v[204:207], v[194:197], v[80:83]
	v_mfma_f32_16x16x32_bf16 v[72:75], v[212:215], v[194:197], v[72:75]
	s_setprio 0
	s_mov_b32 m0, s11
	v_lshl_add_u64 v[198:199], s[22:23], 0, v[138:139]
	s_barrier
	ds_read_b128 v[166:169], v149 offset:16384
	ds_read_b128 v[170:173], v149 offset:17408
	ds_read_b128 v[174:177], v149 offset:18432
	ds_read_b128 v[178:181], v149 offset:19456
	ds_read_b128 v[182:185], v149 offset:20480
	ds_read_b128 v[186:189], v149 offset:21504
	ds_read_b128 v[190:193], v149 offset:22528
	ds_read_b128 v[194:197], v149 offset:23552
	global_load_lds_dwordx4 v[198:199], off
	v_lshl_add_u64 v[218:219], s[22:23], 0, v[134:135]
	s_mov_b32 m0, s57
	s_nop 0
	global_load_lds_dwordx4 v[218:219], off
	s_barrier
	s_waitcnt lgkmcnt(0)
	s_setprio 1
	s_waitcnt lgkmcnt(0)
	v_mfma_f32_16x16x32_bf16 v[60:63], v[150:153], v[166:169], v[60:63]
	v_mfma_f32_16x16x32_bf16 v[52:55], v[158:161], v[166:169], v[52:55]
	v_mfma_f32_16x16x32_bf16 v[44:47], v[150:153], v[174:177], v[44:47]
	v_mfma_f32_16x16x32_bf16 v[36:39], v[158:161], v[174:177], v[36:39]
	v_mfma_f32_16x16x32_bf16 v[28:31], v[150:153], v[182:185], v[28:31]
	v_mfma_f32_16x16x32_bf16 v[20:23], v[158:161], v[182:185], v[20:23]
	v_mfma_f32_16x16x32_bf16 v[12:15], v[150:153], v[190:193], v[12:15]
	v_mfma_f32_16x16x32_bf16 v[4:7], v[158:161], v[190:193], v[4:7]
	v_mfma_f32_16x16x32_bf16 v[60:63], v[154:157], v[170:173], v[60:63]
	v_mfma_f32_16x16x32_bf16 v[52:55], v[162:165], v[170:173], v[52:55]
	v_mfma_f32_16x16x32_bf16 v[44:47], v[154:157], v[178:181], v[44:47]
	v_mfma_f32_16x16x32_bf16 v[36:39], v[162:165], v[178:181], v[36:39]
	v_mfma_f32_16x16x32_bf16 v[28:31], v[154:157], v[186:189], v[28:31]
	v_mfma_f32_16x16x32_bf16 v[20:23], v[162:165], v[186:189], v[20:23]
	v_mfma_f32_16x16x32_bf16 v[12:15], v[154:157], v[194:197], v[12:15]
	v_mfma_f32_16x16x32_bf16 v[4:7], v[162:165], v[194:197], v[4:7]
	s_setprio 0
	s_barrier
	s_add_u32 s86, s20, 0x40000
	s_addc_u32 s87, s21, 0
	s_add_i32 s85, s88, s25
	v_lshl_add_u64 v[150:151], s[86:87], 0, v[136:137]
	s_mov_b32 m0, s85
	s_nop 0
	global_load_lds_dwordx4 v[150:151], off
	v_lshl_add_u64 v[150:151], s[86:87], 0, v[132:133]
	s_add_i32 m0, s85, 0x2000
	s_nop 0
	global_load_lds_dwordx4 v[150:151], off
	s_waitcnt vmcnt(6)
	s_barrier
	s_setprio 1
	v_mfma_f32_16x16x32_bf16 v[68:71], v[200:203], v[166:169], v[68:71]
	v_mfma_f32_16x16x32_bf16 v[56:59], v[208:211], v[166:169], v[56:59]
	v_mfma_f32_16x16x32_bf16 v[48:51], v[200:203], v[174:177], v[48:51]
	v_mfma_f32_16x16x32_bf16 v[40:43], v[208:211], v[174:177], v[40:43]
	v_mfma_f32_16x16x32_bf16 v[32:35], v[200:203], v[182:185], v[32:35]
	v_mfma_f32_16x16x32_bf16 v[24:27], v[208:211], v[182:185], v[24:27]
	v_mfma_f32_16x16x32_bf16 v[16:19], v[200:203], v[190:193], v[16:19]
	v_mfma_f32_16x16x32_bf16 v[8:11], v[208:211], v[190:193], v[8:11]
	v_mfma_f32_16x16x32_bf16 v[68:71], v[204:207], v[170:173], v[68:71]
	v_mfma_f32_16x16x32_bf16 v[56:59], v[212:215], v[170:173], v[56:59]
	v_mfma_f32_16x16x32_bf16 v[48:51], v[204:207], v[178:181], v[48:51]
	v_mfma_f32_16x16x32_bf16 v[40:43], v[212:215], v[178:181], v[40:43]
	v_mfma_f32_16x16x32_bf16 v[32:35], v[204:207], v[186:189], v[32:35]
	v_mfma_f32_16x16x32_bf16 v[24:27], v[212:215], v[186:189], v[24:27]
	v_mfma_f32_16x16x32_bf16 v[16:19], v[204:207], v[194:197], v[16:19]
	v_mfma_f32_16x16x32_bf16 v[8:11], v[212:215], v[194:197], v[8:11]
	s_setprio 0
	s_add_i32 s85, 0, 0x18000
	v_add_u32_e32 v0, s85, v147
	s_barrier
	ds_read_b128 v[150:153], v0
	ds_read_b128 v[154:157], v0 offset:1024
	ds_read_b128 v[158:161], v0 offset:2048
	ds_read_b128 v[162:165], v0 offset:3072
	s_add_u32 s22, s22, 0x40000
	s_addc_u32 s23, s23, 0
	s_mov_b32 m0, s58
	v_lshl_add_u64 v[200:201], s[22:23], 0, v[138:139]
	ds_read_b128 v[166:169], v149 offset:32768
	ds_read_b128 v[170:173], v149 offset:33792
	ds_read_b128 v[174:177], v149 offset:34816
	ds_read_b128 v[178:181], v149 offset:35840
	ds_read_b128 v[182:185], v149 offset:36864
	ds_read_b128 v[186:189], v149 offset:37888
	ds_read_b128 v[190:193], v149 offset:38912
	ds_read_b128 v[194:197], v149 offset:39936
	global_load_lds_dwordx4 v[200:201], off
	v_lshl_add_u64 v[200:201], s[22:23], 0, v[134:135]
	s_mov_b32 m0, s59
	s_nop 0
	global_load_lds_dwordx4 v[200:201], off
	s_waitcnt lgkmcnt(8)
	s_barrier
	s_waitcnt lgkmcnt(0)
	s_setprio 1
	s_waitcnt lgkmcnt(0)
	v_mfma_f32_16x16x32_bf16 v[124:127], v[150:153], v[166:169], v[124:127]
	v_mfma_f32_16x16x32_bf16 v[116:119], v[158:161], v[166:169], v[116:119]
	v_mfma_f32_16x16x32_bf16 v[108:111], v[150:153], v[174:177], v[108:111]
	v_mfma_f32_16x16x32_bf16 v[100:103], v[158:161], v[174:177], v[100:103]
	v_mfma_f32_16x16x32_bf16 v[92:95], v[150:153], v[182:185], v[92:95]
	v_mfma_f32_16x16x32_bf16 v[84:87], v[158:161], v[182:185], v[84:87]
	v_mfma_f32_16x16x32_bf16 v[76:79], v[150:153], v[190:193], v[76:79]
	v_mfma_f32_16x16x32_bf16 v[64:67], v[158:161], v[190:193], v[64:67]
	v_mfma_f32_16x16x32_bf16 v[124:127], v[154:157], v[170:173], v[124:127]
	v_mfma_f32_16x16x32_bf16 v[116:119], v[162:165], v[170:173], v[116:119]
	v_mfma_f32_16x16x32_bf16 v[108:111], v[154:157], v[178:181], v[108:111]
	v_mfma_f32_16x16x32_bf16 v[100:103], v[162:165], v[178:181], v[100:103]
	v_mfma_f32_16x16x32_bf16 v[92:95], v[154:157], v[186:189], v[92:95]
	v_mfma_f32_16x16x32_bf16 v[84:87], v[162:165], v[186:189], v[84:87]
	v_mfma_f32_16x16x32_bf16 v[76:79], v[154:157], v[194:197], v[76:79]
	v_mfma_f32_16x16x32_bf16 v[64:67], v[162:165], v[194:197], v[64:67]
	s_setprio 0
	s_barrier
	s_add_i32 s22, 0, 0x1c000
	s_add_i32 s23, s85, s25
	v_add_u32_e32 v0, s22, v147
	v_lshl_add_u64 v[140:141], v[140:141], 0, s[48:49]
	s_mov_b32 m0, s23
	ds_read_b128 v[200:203], v0
	ds_read_b128 v[204:207], v0 offset:1024
	ds_read_b128 v[208:211], v0 offset:2048
	ds_read_b128 v[212:215], v0 offset:3072
	global_load_lds_dwordx4 v[140:141], off
	v_lshl_add_u64 v[140:141], v[142:143], 0, s[48:49]
	s_add_i32 m0, s23, 0x2000
	s_nop 0
	global_load_lds_dwordx4 v[140:141], off
	s_barrier
	s_waitcnt lgkmcnt(0)
	s_setprio 1
	s_waitcnt lgkmcnt(0)
	v_mfma_f32_16x16x32_bf16 v[128:131], v[200:203], v[166:169], v[128:131]
	v_mfma_f32_16x16x32_bf16 v[120:123], v[208:211], v[166:169], v[120:123]
	v_mfma_f32_16x16x32_bf16 v[112:115], v[200:203], v[174:177], v[112:115]
	v_mfma_f32_16x16x32_bf16 v[104:107], v[208:211], v[174:177], v[104:107]
	v_mfma_f32_16x16x32_bf16 v[96:99], v[200:203], v[182:185], v[96:99]
	v_mfma_f32_16x16x32_bf16 v[88:91], v[208:211], v[182:185], v[88:91]
	v_mfma_f32_16x16x32_bf16 v[80:83], v[200:203], v[190:193], v[80:83]
	v_mfma_f32_16x16x32_bf16 v[72:75], v[208:211], v[190:193], v[72:75]
	v_mfma_f32_16x16x32_bf16 v[128:131], v[204:207], v[170:173], v[128:131]
	v_mfma_f32_16x16x32_bf16 v[120:123], v[212:215], v[170:173], v[120:123]
	v_mfma_f32_16x16x32_bf16 v[112:115], v[204:207], v[178:181], v[112:115]
	v_mfma_f32_16x16x32_bf16 v[104:107], v[212:215], v[178:181], v[104:107]
	v_mfma_f32_16x16x32_bf16 v[96:99], v[204:207], v[186:189], v[96:99]
	v_mfma_f32_16x16x32_bf16 v[88:91], v[212:215], v[186:189], v[88:91]
	v_mfma_f32_16x16x32_bf16 v[80:83], v[204:207], v[194:197], v[80:83]
	v_mfma_f32_16x16x32_bf16 v[72:75], v[212:215], v[194:197], v[72:75]
	s_setprio 0
	s_mov_b32 m0, s60
	v_lshl_add_u64 v[140:141], v[198:199], 0, s[48:49]
	s_barrier
	ds_read_b128 v[166:169], v149 offset:49152
	ds_read_b128 v[170:173], v149 offset:50176
	ds_read_b128 v[174:177], v149 offset:51200
	ds_read_b128 v[178:181], v149 offset:52224
	ds_read_b128 v[182:185], v149 offset:53248
	ds_read_b128 v[186:189], v149 offset:54272
	ds_read_b128 v[190:193], v149 offset:55296
	ds_read_b128 v[194:197], v149 offset:56320
	global_load_lds_dwordx4 v[140:141], off
	v_lshl_add_u64 v[140:141], v[218:219], 0, s[48:49]
	s_mov_b32 m0, s61
	s_nop 0
	global_load_lds_dwordx4 v[140:141], off
	s_barrier
; DEVI unsigned cvtpk(float lo, float hi) { unsigned r; asm volatile("v_cvt_pk_bf16_f32 %0, %1, %2" : "=v"(r) : "v"(lo), "v"(hi)); return r; }
; DEVI float sigmoidf_(float x) { return __builtin_amdgcn_rcpf(1.f + __expf(-x)); }
; #define PG8_STAGE(bufoff, gbase, voff) do { _Pragma("unroll") for (int _i = 0; _i < 2; ++_i) \
;         __builtin_amdgcn_global_load_lds((const unsigned*)((const char*)(gbase) + (voff)[_i]), (PG8_LAS unsigned*)(lds + (bufoff) + ldsw + _i * 8192), 16, 0, 0); } while (0)
; #define PG8_WAIT_V(n) asm volatile("s_waitcnt vmcnt(" #n ")" ::: "memory")
; #define PG8_BAR __builtin_amdgcn_s_barrier()
; template <class Epi, class Sched>
; __device__ __forceinline__ void gemm_phase(PG8_LAS unsigned char* lds, const Gemm g, const Sched& S, const Epi& E, int wv) {
;     ...
;         if constexpr (Epi::HOIST) PG8_STAGE(PG8_SA(1, 1), nA + kstep + hstepA, voffA);
;         E(acc, cur, wr, wc, fr, fq);
;         pre = true;
;         if (!has_next) break;
; #pragma unroll
;         for (int a = 0; a < 2; ++a)
; #pragma unroll
;             for (int b = 0; b < 2; ++b)
; #pragma unroll
;                 for (int m = 0; m < 4; ++m)
; #pragma unroll
;                     for (int n = 0; n < 2; ++n) acc[a][b][m][n] = (f32x4){0.f, 0.f, 0.f, 0.f};
;         cur = nxt; cA = nA; cB = nB; ++ui;
;     }
;     PG8_WAIT_V(0);
;     if (wr == 0) PG8_BAR;
;     PG8_BAR;
;     ...
; }
;     DEVI void operator()(AccRef acc, const pg8::Unit& u, int wr, int wc, int fr, int fq) const {
;         const int row0 = u.pm * 256 + wr * 64 + fr, col = u.pn * 128 + wc * 32 + 8 * fq;
; #pragma unroll
;         for (int ai = 0; ai < 2; ++ai)
; #pragma unroll
;             for (int m = 0; m < 4; ++m) { bf16_t* rowp = Hm + (size_t)(row0 + ai * 128 + m * 16) * DFF + col; float h[8];
; #pragma unroll
;                 for (int j = 0; j < 8; ++j) { const float gt = acc[ai][0][m][j >> 2][j & 3], up = acc[ai][1][m][j >> 2][j & 3]; h[j] = gt * sigmoidf_(gt) * up; }
;                 u32x4 w; w.x = cvtpk(h[0], h[1]); w.y = cvtpk(h[2], h[3]); w.z = cvtpk(h[4], h[5]); w.w = cvtpk(h[6], h[7]);
;                 if (ai == 0 && m == 0) asm volatile("s_waitcnt vmcnt(0)" ::: "memory");
;                 __builtin_nontemporal_store(w, (u32x4*)rowp); }
	s_waitcnt lgkmcnt(0)
	s_setprio 1
	s_waitcnt lgkmcnt(0)
	v_mfma_f32_16x16x32_bf16 v[60:63], v[150:153], v[166:169], v[60:63]
	v_mfma_f32_16x16x32_bf16 v[52:55], v[158:161], v[166:169], v[52:55]
	v_mfma_f32_16x16x32_bf16 v[44:47], v[150:153], v[174:177], v[44:47]
	v_mfma_f32_16x16x32_bf16 v[36:39], v[158:161], v[174:177], v[36:39]
	v_mfma_f32_16x16x32_bf16 v[28:31], v[150:153], v[182:185], v[28:31]
	v_mfma_f32_16x16x32_bf16 v[20:23], v[158:161], v[182:185], v[20:23]
	v_mfma_f32_16x16x32_bf16 v[12:15], v[150:153], v[190:193], v[12:15]
	v_mfma_f32_16x16x32_bf16 v[4:7], v[158:161], v[190:193], v[4:7]
	v_mfma_f32_16x16x32_bf16 v[60:63], v[154:157], v[170:173], v[60:63]
	v_mfma_f32_16x16x32_bf16 v[52:55], v[162:165], v[170:173], v[52:55]
	v_mfma_f32_16x16x32_bf16 v[44:47], v[154:157], v[178:181], v[44:47]
	v_mfma_f32_16x16x32_bf16 v[36:39], v[162:165], v[178:181], v[36:39]
	v_mfma_f32_16x16x32_bf16 v[28:31], v[154:157], v[186:189], v[28:31]
	v_mfma_f32_16x16x32_bf16 v[20:23], v[162:165], v[186:189], v[20:23]
	v_mfma_f32_16x16x32_bf16 v[12:15], v[154:157], v[194:197], v[12:15]
	v_mfma_f32_16x16x32_bf16 v[4:7], v[162:165], v[194:197], v[4:7]
	s_setprio 0
	s_barrier
	s_add_u32 s20, s20, 0x40080
	s_addc_u32 s21, s21, 0
	s_add_i32 s22, s22, s25
	v_lshl_add_u64 v[140:141], s[20:21], 0, v[136:137]
	s_mov_b32 m0, s22
	s_nop 0
	global_load_lds_dwordx4 v[140:141], off
	v_lshl_add_u64 v[140:141], s[20:21], 0, v[132:133]
	s_add_i32 m0, s22, 0x2000
	s_nop 0
	global_load_lds_dwordx4 v[140:141], off
	s_waitcnt vmcnt(6)
	s_barrier
	s_setprio 1
	v_mfma_f32_16x16x32_bf16 v[68:71], v[200:203], v[166:169], v[68:71]
	v_mfma_f32_16x16x32_bf16 v[56:59], v[208:211], v[166:169], v[56:59]
	v_mfma_f32_16x16x32_bf16 v[48:51], v[200:203], v[174:177], v[48:51]
	v_mfma_f32_16x16x32_bf16 v[40:43], v[208:211], v[174:177], v[40:43]
	v_mfma_f32_16x16x32_bf16 v[32:35], v[200:203], v[182:185], v[32:35]
	v_mfma_f32_16x16x32_bf16 v[24:27], v[208:211], v[182:185], v[24:27]
	v_mfma_f32_16x16x32_bf16 v[16:19], v[200:203], v[190:193], v[16:19]
	v_mfma_f32_16x16x32_bf16 v[8:11], v[208:211], v[190:193], v[8:11]
	v_mfma_f32_16x16x32_bf16 v[68:71], v[204:207], v[170:173], v[68:71]
	v_mfma_f32_16x16x32_bf16 v[56:59], v[212:215], v[170:173], v[56:59]
	v_mfma_f32_16x16x32_bf16 v[48:51], v[204:207], v[178:181], v[48:51]
	v_mfma_f32_16x16x32_bf16 v[40:43], v[212:215], v[178:181], v[40:43]
	v_mfma_f32_16x16x32_bf16 v[32:35], v[204:207], v[186:189], v[32:35]
	v_mfma_f32_16x16x32_bf16 v[24:27], v[212:215], v[186:189], v[24:27]
	v_mfma_f32_16x16x32_bf16 v[16:19], v[204:207], v[194:197], v[16:19]
	v_mfma_f32_16x16x32_bf16 v[8:11], v[212:215], v[194:197], v[8:11]
	s_setprio 0
	s_add_i32 s78, s78, 2
	s_add_u32 s79, s79, 0x100
	s_addc_u32 s80, s80, 0
	s_add_u32 s81, s81, 0x100
	s_addc_u32 s82, s82, 0
	s_add_u32 s18, s18, 0xffffff00
	s_addc_u32 s19, s19, -1
	v_lshl_add_u64 v[2:3], v[2:3], 0, s[50:51]
	s_cmp_gt_u32 s78, 13
	v_lshl_add_u64 v[144:145], v[144:145], 0, s[50:51]
	s_barrier
	s_cbranch_scc0 .LBB0_528
	s_add_u32 s18, s76, 0x40080
	s_addc_u32 s19, s9, 0
	s_mov_b32 m0, s84
	v_lshl_add_u64 v[2:3], s[18:19], 0, v[138:139]
	global_load_lds_dwordx4 v[2:3], off
	v_lshl_add_u64 v[2:3], s[18:19], 0, v[134:135]
	s_mov_b32 m0, s83
	v_lshl_or_b32 v140, s75, 7, v148
	global_load_lds_dwordx4 v[2:3], off
	v_mul_f32_e32 v2, 0xbfb8aa3b, v124
	v_exp_f32_e32 v142, v2
	v_mul_f32_e32 v2, 0xbfb8aa3b, v125
	v_exp_f32_e32 v143, v2
	v_lshl_add_u32 v0, s10, 8, v146
	v_add_f32_e32 v142, 1.0, v142
	v_rcp_f32_e32 v144, v142
	v_add_f32_e32 v142, 1.0, v143
	v_rcp_f32_e32 v145, v142
	v_ashrrev_i32_e32 v141, 31, v140
	v_mul_f32_e32 v124, v124, v144
	v_mul_f32_e32 v124, v124, v128
	v_mul_f32_e32 v128, 0xbfb8aa3b, v126
	v_mul_f32_e32 v144, 0xbfb8aa3b, v127
	v_exp_f32_e32 v128, v128
	v_exp_f32_e32 v144, v144
	v_mul_f32_e32 v125, v125, v145
	v_mul_f32_e32 v125, v125, v129
	v_add_f32_e32 v128, 1.0, v128
	v_add_f32_e32 v129, 1.0, v144
	v_mul_f32_e32 v144, 0xbfb8aa3b, v116
	v_rcp_f32_e32 v128, v128
	v_exp_f32_e32 v144, v144
	v_rcp_f32_e32 v129, v129
	v_mov_b64_e32 v[2:3], s[68:69]
	v_mul_f32_e32 v126, v126, v128
	v_add_f32_e32 v128, 1.0, v144
	v_mul_f32_e32 v127, v127, v129
	v_rcp_f32_e32 v128, v128
	v_mul_f32_e32 v129, 0xbfb8aa3b, v117
	v_exp_f32_e32 v129, v129
	v_mad_i64_i32 v[142:143], s[18:19], v0, s3, v[2:3]
	v_mul_f32_e32 v116, v116, v128
	v_mul_f32_e32 v120, v116, v120
	v_add_f32_e32 v116, 1.0, v129
	v_mul_f32_e32 v128, 0xbfb8aa3b, v118
	v_rcp_f32_e32 v116, v116
	v_exp_f32_e32 v128, v128
	v_mul_f32_e32 v129, 0xbfb8aa3b, v119
	v_exp_f32_e32 v129, v129
	v_mul_f32_e32 v116, v117, v116
	v_add_f32_e32 v117, 1.0, v128
	v_rcp_f32_e32 v117, v117
	v_mul_f32_e32 v121, v116, v121
	v_add_f32_e32 v128, 1.0, v129
	v_rcp_f32_e32 v128, v128
	v_mul_f32_e32 v116, v118, v117
	v_cvt_pk_bf16_f32 v118, v124, v125
	v_mul_f32_e32 v124, 0xbfb8aa3b, v108
	v_exp_f32_e32 v124, v124
	v_mul_f32_e32 v125, 0xbfb8aa3b, v109
	v_exp_f32_e32 v125, v125
	v_mul_f32_e32 v129, v116, v122
	v_add_f32_e32 v124, 1.0, v124
	v_rcp_f32_e32 v124, v124
	v_mul_f32_e32 v116, v119, v128
	v_mul_f32_e32 v128, v116, v123
	v_lshlrev_b64 v[116:117], 1, v[140:141]
	v_lshl_add_u64 v[122:123], v[142:143], 0, v[116:117]
	v_add_f32_e32 v125, 1.0, v125
	v_mul_f32_e32 v108, v108, v124
	v_mul_f32_e32 v126, v126, v130
	v_mul_f32_e32 v127, v127, v131
	v_cvt_pk_bf16_f32 v119, v126, v127
	v_cvt_pk_bf16_f32 v120, v120, v121
	v_cvt_pk_bf16_f32 v121, v129, v128
	s_waitcnt vmcnt(0)
; DEVI unsigned cvtpk(float lo, float hi) { unsigned r; asm volatile("v_cvt_pk_bf16_f32 %0, %1, %2" : "=v"(r) : "v"(lo), "v"(hi)); return r; }
; DEVI float sigmoidf_(float x) { return __builtin_amdgcn_rcpf(1.f + __expf(-x)); }
;     DEVI void operator()(AccRef acc, const pg8::Unit& u, int wr, int wc, int fr, int fq) const {
;         const int row0 = u.pm * 256 + wr * 64 + fr, col = u.pn * 128 + wc * 32 + 8 * fq;
; #pragma unroll
;         for (int ai = 0; ai < 2; ++ai)
; #pragma unroll
;             for (int m = 0; m < 4; ++m) { bf16_t* rowp = Hm + (size_t)(row0 + ai * 128 + m * 16) * DFF + col; float h[8];
; #pragma unroll
;                 for (int j = 0; j < 8; ++j) { const float gt = acc[ai][0][m][j >> 2][j & 3], up = acc[ai][1][m][j >> 2][j & 3]; h[j] = gt * sigmoidf_(gt) * up; }
;                 u32x4 w; w.x = cvtpk(h[0], h[1]); w.y = cvtpk(h[2], h[3]); w.z = cvtpk(h[4], h[5]); w.w = cvtpk(h[6], h[7]);
;                 if (ai == 0 && m == 0) asm volatile("s_waitcnt vmcnt(0)" ::: "memory");
;                 __builtin_nontemporal_store(w, (u32x4*)rowp); }
;     }
	v_rcp_f32_e32 v125, v125
	global_store_dwordx4 v[122:123], v[118:121], off
	v_mul_f32_e32 v108, v108, v112
	v_mul_f32_e32 v112, 0xbfb8aa3b, v110
	v_mul_f32_e32 v118, 0xbfb8aa3b, v111
	v_exp_f32_e32 v112, v112
	v_exp_f32_e32 v118, v118
	v_mul_f32_e32 v109, v109, v125
	v_mul_f32_e32 v109, v109, v113
	v_add_f32_e32 v112, 1.0, v112
	v_add_f32_e32 v113, 1.0, v118
	v_mul_f32_e32 v118, 0xbfb8aa3b, v100
	v_rcp_f32_e32 v112, v112
	v_exp_f32_e32 v118, v118
	v_rcp_f32_e32 v113, v113
	s_mov_b64 s[22:23], -1
	v_mul_f32_e32 v110, v110, v112
	v_add_f32_e32 v112, 1.0, v118
	v_mul_f32_e32 v111, v111, v113
	v_rcp_f32_e32 v112, v112
	v_mul_f32_e32 v113, 0xbfb8aa3b, v101
	v_exp_f32_e32 v113, v113
	v_mul_f32_e32 v110, v110, v114
	v_mul_f32_e32 v100, v100, v112
	v_mul_f32_e32 v104, v100, v104
	v_add_f32_e32 v100, 1.0, v113
	v_mul_f32_e32 v112, 0xbfb8aa3b, v102
	v_rcp_f32_e32 v100, v100
	v_exp_f32_e32 v112, v112
	v_mul_f32_e32 v113, 0xbfb8aa3b, v103
	v_exp_f32_e32 v113, v113
	v_mul_f32_e32 v100, v101, v100
	v_add_f32_e32 v101, 1.0, v112
	v_rcp_f32_e32 v101, v101
	v_add_f32_e32 v112, 1.0, v113
	v_rcp_f32_e32 v112, v112
	v_mul_f32_e32 v105, v100, v105
	v_mul_f32_e32 v100, v102, v101
	v_mul_f32_e32 v106, v100, v106
	v_mul_f32_e32 v100, v103, v112
	v_mul_f32_e32 v103, v100, v107
	v_mul_f32_e32 v111, v111, v115
	v_cvt_pk_bf16_f32 v100, v108, v109
	v_cvt_pk_bf16_f32 v101, v110, v111
	v_cvt_pk_bf16_f32 v102, v104, v105
	v_cvt_pk_bf16_f32 v103, v106, v103
	v_mul_f32_e32 v106, 0xbfb8aa3b, v92
	v_exp_f32_e32 v106, v106
	v_mul_f32_e32 v107, 0xbfb8aa3b, v93
	v_exp_f32_e32 v107, v107
	v_or_b32_e32 v104, 16, v0
	v_add_f32_e32 v106, 1.0, v106
	v_rcp_f32_e32 v106, v106
	v_mad_i64_i32 v[104:105], s[18:19], v104, s3, v[2:3]
	v_lshl_add_u64 v[104:105], v[104:105], 0, v[116:117]
	v_add_f32_e32 v107, 1.0, v107
	v_mul_f32_e32 v92, v92, v106
	v_rcp_f32_e32 v107, v107
	global_store_dwordx4 v[104:105], v[100:103], off
	v_mul_f32_e32 v92, v92, v96
	v_mul_f32_e32 v96, 0xbfb8aa3b, v94
	v_mul_f32_e32 v100, 0xbfb8aa3b, v95
	v_exp_f32_e32 v96, v96
	v_exp_f32_e32 v100, v100
	v_mul_f32_e32 v93, v93, v107
	v_mul_f32_e32 v93, v93, v97
	v_add_f32_e32 v96, 1.0, v96
	v_add_f32_e32 v97, 1.0, v100
	v_mul_f32_e32 v100, 0xbfb8aa3b, v84
	v_rcp_f32_e32 v96, v96
	v_exp_f32_e32 v100, v100
	v_rcp_f32_e32 v97, v97
	s_and_b64 vcc, exec, s[4:5]
	v_mul_f32_e32 v94, v94, v96
	v_add_f32_e32 v96, 1.0, v100
	v_mul_f32_e32 v95, v95, v97
	v_rcp_f32_e32 v96, v96
	v_mul_f32_e32 v97, 0xbfb8aa3b, v85
	v_exp_f32_e32 v97, v97
	v_mul_f32_e32 v94, v94, v98
	v_mul_f32_e32 v84, v84, v96
	v_mul_f32_e32 v88, v84, v88
	v_add_f32_e32 v84, 1.0, v97
	v_mul_f32_e32 v96, 0xbfb8aa3b, v86
	v_rcp_f32_e32 v84, v84
	v_exp_f32_e32 v96, v96
	v_mul_f32_e32 v97, 0xbfb8aa3b, v87
	v_exp_f32_e32 v97, v97
	v_mul_f32_e32 v84, v85, v84
	v_add_f32_e32 v85, 1.0, v96
	v_rcp_f32_e32 v85, v85
	v_add_f32_e32 v96, 1.0, v97
	v_rcp_f32_e32 v96, v96
	v_mul_f32_e32 v89, v84, v89
	v_mul_f32_e32 v84, v86, v85
	v_mul_f32_e32 v90, v84, v90
	v_mul_f32_e32 v84, v87, v96
	v_mul_f32_e32 v87, v84, v91
	v_mul_f32_e32 v95, v95, v99
	v_cvt_pk_bf16_f32 v84, v92, v93
	v_cvt_pk_bf16_f32 v85, v94, v95
	v_cvt_pk_bf16_f32 v86, v88, v89
	v_cvt_pk_bf16_f32 v87, v90, v87
	v_mul_f32_e32 v90, 0xbfb8aa3b, v76
	v_exp_f32_e32 v90, v90
	v_mul_f32_e32 v91, 0xbfb8aa3b, v77
	v_exp_f32_e32 v91, v91
	v_or_b32_e32 v88, 32, v0
	v_add_f32_e32 v90, 1.0, v90
	v_rcp_f32_e32 v90, v90
	v_mad_i64_i32 v[88:89], s[18:19], v88, s3, v[2:3]
	v_lshl_add_u64 v[88:89], v[88:89], 0, v[116:117]
	v_add_f32_e32 v91, 1.0, v91
	v_mul_f32_e32 v76, v76, v90
	v_rcp_f32_e32 v91, v91
	global_store_dwordx4 v[88:89], v[84:87], off
	v_mul_f32_e32 v76, v76, v80
	v_mul_f32_e32 v80, 0xbfb8aa3b, v78
	v_mul_f32_e32 v84, 0xbfb8aa3b, v79
	v_exp_f32_e32 v80, v80
	v_exp_f32_e32 v84, v84
	v_mul_f32_e32 v77, v77, v91
	v_mul_f32_e32 v77, v77, v81
	v_add_f32_e32 v80, 1.0, v80
	v_add_f32_e32 v81, 1.0, v84
	v_mul_f32_e32 v84, 0xbfb8aa3b, v64
	v_rcp_f32_e32 v80, v80
	v_exp_f32_e32 v84, v84
	v_rcp_f32_e32 v81, v81
	s_mov_b32 s75, s6
	v_mul_f32_e32 v78, v78, v80
	v_add_f32_e32 v80, 1.0, v84
	v_mul_f32_e32 v79, v79, v81
	v_rcp_f32_e32 v80, v80
	v_mul_f32_e32 v81, 0xbfb8aa3b, v65
	v_exp_f32_e32 v81, v81
	v_mul_f32_e32 v78, v78, v82
	v_mul_f32_e32 v64, v64, v80
	v_mul_f32_e32 v72, v64, v72
	v_add_f32_e32 v64, 1.0, v81
	v_mul_f32_e32 v80, 0xbfb8aa3b, v66
	v_rcp_f32_e32 v64, v64
	v_exp_f32_e32 v80, v80
	v_mul_f32_e32 v81, 0xbfb8aa3b, v67
	v_exp_f32_e32 v81, v81
	v_mul_f32_e32 v64, v65, v64
	v_add_f32_e32 v65, 1.0, v80
	v_rcp_f32_e32 v65, v65
	v_add_f32_e32 v80, 1.0, v81
	v_rcp_f32_e32 v80, v80
	v_mul_f32_e32 v73, v64, v73
	v_mul_f32_e32 v64, v66, v65
	v_mul_f32_e32 v74, v64, v74
	v_mul_f32_e32 v64, v67, v80
	v_mul_f32_e32 v79, v79, v83
	v_mul_f32_e32 v67, v64, v75
	v_cvt_pk_bf16_f32 v64, v76, v77
	v_cvt_pk_bf16_f32 v65, v78, v79
	v_cvt_pk_bf16_f32 v66, v72, v73
	v_or_b32_e32 v72, 48, v0
	v_mad_i64_i32 v[72:73], s[18:19], v72, s3, v[2:3]
	v_lshl_add_u64 v[72:73], v[72:73], 0, v[116:117]
	v_cvt_pk_bf16_f32 v67, v74, v67
	global_store_dwordx4 v[72:73], v[64:67], off
	v_mul_f32_e32 v74, 0xbfb8aa3b, v60
	v_mul_f32_e32 v75, 0xbfb8aa3b, v61
	v_mul_f32_e32 v64, 0xbfb8aa3b, v62
	v_exp_f32_e32 v64, v64
	v_mul_f32_e32 v65, 0xbfb8aa3b, v63
	v_exp_f32_e32 v65, v65
	v_mul_f32_e32 v66, 0xbfb8aa3b, v52
	v_add_f32_e32 v64, 1.0, v64
	v_rcp_f32_e32 v64, v64
	v_add_f32_e32 v65, 1.0, v65
	v_exp_f32_e32 v66, v66
	v_rcp_f32_e32 v65, v65
	v_mul_f32_e32 v62, v62, v64
	v_exp_f32_e32 v74, v74
	v_add_f32_e32 v64, 1.0, v66
	v_mul_f32_e32 v63, v63, v65
	v_rcp_f32_e32 v64, v64
	v_mul_f32_e32 v65, 0xbfb8aa3b, v53
	v_exp_f32_e32 v65, v65
	v_exp_f32_e32 v75, v75
; DEVI unsigned cvtpk(float lo, float hi) { unsigned r; asm volatile("v_cvt_pk_bf16_f32 %0, %1, %2" : "=v"(r) : "v"(lo), "v"(hi)); return r; }
; DEVI float sigmoidf_(float x) { return __builtin_amdgcn_rcpf(1.f + __expf(-x)); }
; #define PG8_WAIT_V(n) asm volatile("s_waitcnt vmcnt(" #n ")" ::: "memory")
; #define PG8_BAR __builtin_amdgcn_s_barrier()
; template <class Epi, class Sched>
; __device__ __forceinline__ void gemm_phase(PG8_LAS unsigned char* lds, const Gemm g, const Sched& S, const Epi& E, int wv) {
;     ...
;     PG8_WAIT_V(0);
;     if (wr == 0) PG8_BAR;
;     PG8_BAR;
;     DEVI void operator()(AccRef acc, const pg8::Unit& u, int wr, int wc, int fr, int fq) const {
;         const int row0 = u.pm * 256 + wr * 64 + fr, col = u.pn * 128 + wc * 32 + 8 * fq;
; #pragma unroll
;         for (int ai = 0; ai < 2; ++ai)
; #pragma unroll
;             for (int m = 0; m < 4; ++m) { bf16_t* rowp = Hm + (size_t)(row0 + ai * 128 + m * 16) * DFF + col; float h[8];
; #pragma unroll
;                 for (int j = 0; j < 8; ++j) { const float gt = acc[ai][0][m][j >> 2][j & 3], up = acc[ai][1][m][j >> 2][j & 3]; h[j] = gt * sigmoidf_(gt) * up; }
;                 u32x4 w; w.x = cvtpk(h[0], h[1]); w.y = cvtpk(h[2], h[3]); w.z = cvtpk(h[4], h[5]); w.w = cvtpk(h[6], h[7]);
;                 if (ai == 0 && m == 0) asm volatile("s_waitcnt vmcnt(0)" ::: "memory");
;                 __builtin_nontemporal_store(w, (u32x4*)rowp); }
;     }
	v_mul_f32_e32 v52, v52, v64
	v_mul_f32_e32 v56, v52, v56
	v_add_f32_e32 v52, 1.0, v65
	v_mul_f32_e32 v64, 0xbfb8aa3b, v54
	v_rcp_f32_e32 v52, v52
	v_exp_f32_e32 v64, v64
	v_mul_f32_e32 v65, 0xbfb8aa3b, v55
	v_exp_f32_e32 v65, v65
	v_mul_f32_e32 v52, v53, v52
	v_add_f32_e32 v53, 1.0, v64
	v_rcp_f32_e32 v53, v53
	v_add_f32_e32 v64, 1.0, v65
	v_add_f32_e32 v74, 1.0, v74
	v_add_f32_e32 v75, 1.0, v75
	v_rcp_f32_e32 v64, v64
	v_rcp_f32_e32 v74, v74
	v_rcp_f32_e32 v75, v75
	v_mul_f32_e32 v57, v52, v57
	v_mul_f32_e32 v52, v54, v53
	v_mul_f32_e32 v58, v52, v58
	v_mul_f32_e32 v52, v55, v64
	v_mul_f32_e32 v60, v60, v74
	v_mul_f32_e32 v61, v61, v75
	v_mul_f32_e32 v55, v52, v59
	v_mul_f32_e32 v60, v60, v68
	v_mul_f32_e32 v61, v61, v69
	v_mul_f32_e32 v62, v62, v70
	v_mul_f32_e32 v63, v63, v71
	v_cvt_pk_bf16_f32 v52, v60, v61
	v_cvt_pk_bf16_f32 v53, v62, v63
	v_cvt_pk_bf16_f32 v54, v56, v57
	v_cvt_pk_bf16_f32 v55, v58, v55
	v_mul_f32_e32 v58, 0xbfb8aa3b, v44
	v_exp_f32_e32 v58, v58
	v_mul_f32_e32 v59, 0xbfb8aa3b, v45
	v_exp_f32_e32 v59, v59
	v_add_u32_e32 v56, 0x80, v0
	v_add_f32_e32 v58, 1.0, v58
	v_rcp_f32_e32 v58, v58
	v_mad_i64_i32 v[56:57], s[18:19], v56, s3, v[2:3]
	v_lshl_add_u64 v[56:57], v[56:57], 0, v[116:117]
	v_add_f32_e32 v59, 1.0, v59
	v_mul_f32_e32 v44, v44, v58
	v_rcp_f32_e32 v59, v59
	global_store_dwordx4 v[56:57], v[52:55], off
	v_mul_f32_e32 v44, v44, v48
	v_mul_f32_e32 v48, 0xbfb8aa3b, v46
	v_mul_f32_e32 v52, 0xbfb8aa3b, v47
	v_exp_f32_e32 v48, v48
	v_exp_f32_e32 v52, v52
	v_mul_f32_e32 v45, v45, v59
	v_mul_f32_e32 v45, v45, v49
	v_add_f32_e32 v48, 1.0, v48
	v_add_f32_e32 v49, 1.0, v52
	v_mul_f32_e32 v52, 0xbfb8aa3b, v36
	v_rcp_f32_e32 v48, v48
	v_exp_f32_e32 v52, v52
	v_rcp_f32_e32 v49, v49
	s_mov_b32 s10, s8
	v_mul_f32_e32 v46, v46, v48
	v_add_f32_e32 v48, 1.0, v52
	v_mul_f32_e32 v47, v47, v49
	v_rcp_f32_e32 v48, v48
	v_mul_f32_e32 v49, 0xbfb8aa3b, v37
	v_exp_f32_e32 v49, v49
	v_mul_f32_e32 v46, v46, v50
	v_mul_f32_e32 v36, v36, v48
	v_mul_f32_e32 v40, v36, v40
	v_add_f32_e32 v36, 1.0, v49
	v_mul_f32_e32 v48, 0xbfb8aa3b, v38
	v_rcp_f32_e32 v36, v36
	v_exp_f32_e32 v48, v48
	v_mul_f32_e32 v49, 0xbfb8aa3b, v39
	v_exp_f32_e32 v49, v49
	v_mul_f32_e32 v36, v37, v36
	v_add_f32_e32 v37, 1.0, v48
	v_rcp_f32_e32 v37, v37
	v_add_f32_e32 v48, 1.0, v49
	v_rcp_f32_e32 v48, v48
	v_mul_f32_e32 v41, v36, v41
	v_mul_f32_e32 v36, v38, v37
	v_mul_f32_e32 v42, v36, v42
	v_mul_f32_e32 v36, v39, v48
	v_mul_f32_e32 v39, v36, v43
	v_mul_f32_e32 v47, v47, v51
	v_cvt_pk_bf16_f32 v36, v44, v45
	v_cvt_pk_bf16_f32 v37, v46, v47
	v_cvt_pk_bf16_f32 v38, v40, v41
	v_cvt_pk_bf16_f32 v39, v42, v39
	v_mul_f32_e32 v42, 0xbfb8aa3b, v28
	v_exp_f32_e32 v42, v42
	v_mul_f32_e32 v43, 0xbfb8aa3b, v29
	v_exp_f32_e32 v43, v43
	v_add_u32_e32 v40, 0x90, v0
	v_add_f32_e32 v42, 1.0, v42
	v_rcp_f32_e32 v42, v42
	v_mad_i64_i32 v[40:41], s[18:19], v40, s3, v[2:3]
	v_lshl_add_u64 v[40:41], v[40:41], 0, v[116:117]
	v_add_f32_e32 v43, 1.0, v43
	v_mul_f32_e32 v28, v28, v42
	v_rcp_f32_e32 v43, v43
	global_store_dwordx4 v[40:41], v[36:39], off
	v_mul_f32_e32 v28, v28, v32
	v_mul_f32_e32 v32, 0xbfb8aa3b, v30
	v_mul_f32_e32 v36, 0xbfb8aa3b, v31
	v_exp_f32_e32 v32, v32
	v_exp_f32_e32 v36, v36
	v_mul_f32_e32 v29, v29, v43
	v_mul_f32_e32 v29, v29, v33
	v_add_f32_e32 v32, 1.0, v32
	v_add_f32_e32 v33, 1.0, v36
	v_mul_f32_e32 v36, 0xbfb8aa3b, v20
	v_rcp_f32_e32 v32, v32
	v_exp_f32_e32 v36, v36
	v_rcp_f32_e32 v33, v33
	s_mov_b64 s[20:21], s[12:13]
	v_mul_f32_e32 v30, v30, v32
	v_add_f32_e32 v32, 1.0, v36
	v_mul_f32_e32 v31, v31, v33
	v_rcp_f32_e32 v32, v32
	v_mul_f32_e32 v33, 0xbfb8aa3b, v21
	v_exp_f32_e32 v33, v33
	v_mul_f32_e32 v30, v30, v34
	v_mul_f32_e32 v20, v20, v32
	v_mul_f32_e32 v24, v20, v24
	v_add_f32_e32 v20, 1.0, v33
	v_mul_f32_e32 v32, 0xbfb8aa3b, v22
	v_rcp_f32_e32 v20, v20
	v_exp_f32_e32 v32, v32
	v_mul_f32_e32 v33, 0xbfb8aa3b, v23
	v_exp_f32_e32 v33, v33
	v_mul_f32_e32 v20, v21, v20
	v_add_f32_e32 v21, 1.0, v32
	v_rcp_f32_e32 v21, v21
	v_add_f32_e32 v32, 1.0, v33
	v_rcp_f32_e32 v32, v32
	v_mul_f32_e32 v25, v20, v25
	v_mul_f32_e32 v20, v22, v21
	v_mul_f32_e32 v26, v20, v26
	v_mul_f32_e32 v20, v23, v32
	v_mul_f32_e32 v23, v20, v27
	v_mul_f32_e32 v31, v31, v35
	v_cvt_pk_bf16_f32 v20, v28, v29
	v_cvt_pk_bf16_f32 v21, v30, v31
	v_cvt_pk_bf16_f32 v22, v24, v25
	v_cvt_pk_bf16_f32 v23, v26, v23
	v_mul_f32_e32 v26, 0xbfb8aa3b, v12
	v_exp_f32_e32 v26, v26
	v_mul_f32_e32 v27, 0xbfb8aa3b, v13
	v_exp_f32_e32 v27, v27
	v_add_u32_e32 v24, 0xa0, v0
	v_add_f32_e32 v26, 1.0, v26
	v_rcp_f32_e32 v26, v26
	v_mad_i64_i32 v[24:25], s[18:19], v24, s3, v[2:3]
	v_lshl_add_u64 v[24:25], v[24:25], 0, v[116:117]
	v_add_f32_e32 v27, 1.0, v27
	v_mul_f32_e32 v12, v12, v26
	v_rcp_f32_e32 v27, v27
	global_store_dwordx4 v[24:25], v[20:23], off
	v_mul_f32_e32 v12, v12, v16
	v_mul_f32_e32 v16, 0xbfb8aa3b, v14
	v_mul_f32_e32 v20, 0xbfb8aa3b, v15
	v_exp_f32_e32 v16, v16
	v_exp_f32_e32 v20, v20
	v_mul_f32_e32 v13, v13, v27
	v_mul_f32_e32 v13, v13, v17
	v_add_f32_e32 v16, 1.0, v16
	v_add_f32_e32 v17, 1.0, v20
	v_mul_f32_e32 v20, 0xbfb8aa3b, v4
	v_rcp_f32_e32 v16, v16
	v_exp_f32_e32 v20, v20
	v_rcp_f32_e32 v17, v17
	v_add_u32_e32 v0, 0xb0, v0
	v_mul_f32_e32 v14, v14, v16
	v_add_f32_e32 v16, 1.0, v20
	v_mul_f32_e32 v15, v15, v17
	v_rcp_f32_e32 v16, v16
	v_mul_f32_e32 v17, 0xbfb8aa3b, v5
	v_exp_f32_e32 v17, v17
	v_mad_i64_i32 v[2:3], s[18:19], v0, s3, v[2:3]
	v_mul_f32_e32 v4, v4, v16
	v_mul_f32_e32 v8, v4, v8
	v_add_f32_e32 v4, 1.0, v17
	v_mul_f32_e32 v16, 0xbfb8aa3b, v6
	v_rcp_f32_e32 v4, v4
	v_exp_f32_e32 v16, v16
	v_mul_f32_e32 v17, 0xbfb8aa3b, v7
	v_exp_f32_e32 v17, v17
	v_mul_f32_e32 v4, v5, v4
	v_add_f32_e32 v5, 1.0, v16
	v_rcp_f32_e32 v5, v5
	v_add_f32_e32 v16, 1.0, v17
	v_rcp_f32_e32 v16, v16
	v_mul_f32_e32 v9, v4, v9
	v_mul_f32_e32 v4, v6, v5
	v_mul_f32_e32 v10, v4, v10
	v_mul_f32_e32 v4, v7, v16
	v_mul_f32_e32 v7, v4, v11
	v_lshl_add_u64 v[2:3], v[2:3], 0, v[116:117]
	s_mov_b64 s[18:19], s[14:15]
	v_mul_f32_e32 v14, v14, v18
	v_mul_f32_e32 v15, v15, v19
	v_cvt_pk_bf16_f32 v4, v12, v13
	v_cvt_pk_bf16_f32 v5, v14, v15
	v_cvt_pk_bf16_f32 v6, v8, v9
	v_cvt_pk_bf16_f32 v7, v10, v7
	global_store_dwordx4 v[2:3], v[4:7], off
	s_cbranch_vccz .LBB0_522
	s_waitcnt vmcnt(0)
	s_cmpk_gt_u32 s24, 0xff
	s_cbranch_scc1 .LBB0_532
	s_barrier

; DEVI int ltid(int wv) { int t = (wv << 6) | (int)__builtin_amdgcn_mbcnt_hi(~0u, __builtin_amdgcn_mbcnt_lo(~0u, 0u)); asm volatile("" : "+v"(t)); return t; }
; template <int KT, class F> DEVI void cvt_tile(F colptr, int ldsrc, int k0, bf16_t* out, int ldo, int v0, float* tile, int wv) {
;     const int tid = ltid(wv);
;     constexpr int PITCH = KT * 64 + 1;
;     { const int vc = tid & 63, kk = tid >> 6; const float* cp = colptr(v0 + vc) + (size_t)k0 * ldsrc; float v[8 * KT];
; #pragma unroll
;       for (int r = 0; r < 8 * KT; ++r) v[r] = cp[(size_t)(r * 8 + kk) * ldsrc];
; #pragma unroll
;       for (int r = 0; r < 8 * KT; ++r) tile[vc * PITCH + r * 8 + kk] = v[r]; }
;     __syncthreads();
; DEVI void cvt_ffn_phase(const float* wg, const float* wu, const float* wd, unsigned char* ws, char* lds, int j0, int jstride, int wv) {
;     ...
;     for (int job = j0; job < 352 + 176; job += jstride) {
;         if (job < 352) { const int vt = job >> 2, kg = job & 3; cvt_tile<4>(ColGU{wg, (long)((const char*)wu - (const char*)wg)}, DFF, kg * 256, Wgu, DM, vt * 64, tile, wv); }
;         else { const int j = job - 352, vt = j / 11, kg = j % 11; cvt_tile<4>(ColLin{wd}, DM, kg * 256, Wd, DFF, vt * 64, tile, wv); }
.LBB0_537:
	s_cmpk_gt_i32 s67, 0x15f
	s_mov_b64 s[6:7], -1
	s_cbranch_scc0 .LBB0_539
	s_add_i32 s6, s67, 0xffa0
	s_and_b32 s7, s6, 0xff
	s_mulk_i32 s7, 0x75
	s_lshr_b32 s18, s7, 8
	s_sub_i32 s18, s6, s18
	s_bfe_u32 s18, s18, 0x70001
	s_bfe_u32 s7, s7, 0x80008
	s_add_i32 s18, s18, s7
	s_bfe_u32 s7, s18, 0x50003
	s_mul_i32 s18, s7, 11
	v_mov_b32_e32 v22, v217
	s_sub_i32 s18, s6, s18
	s_lshl_b32 s6, s7, 6
	s_and_b32 s7, s18, 0xff
	v_and_b32_e32 v23, 63, v22
	v_or_b32_e32 v0, s6, v23
	v_ashrrev_i32_e32 v2, 6, v22
	v_lshlrev_b32_e32 v0, 2, v0
	v_lshl_add_u64 v[4:5], s[4:5], 0, v[0:1]
	s_lshl_b32 s46, s7, 20
	v_ashrrev_i32_e32 v3, 31, v2
	v_lshl_add_u64 v[4:5], v[4:5], 0, s[46:47]
	v_lshlrev_b64 v[6:7], 12, v[2:3]
	v_lshl_add_u64 v[4:5], v[4:5], 0, v[6:7]
	v_add_co_u32_e32 v6, vcc, s33, v4
	s_mov_b32 s18, 0x60000
	s_nop 0
	v_addc_co_u32_e32 v7, vcc, 0, v5, vcc
	v_add_co_u32_e32 v8, vcc, s54, v4
	v_lshlrev_b32_e32 v2, 2, v2
	s_nop 0
	v_addc_co_u32_e32 v9, vcc, 0, v5, vcc
	v_add_co_u32_e32 v10, vcc, s27, v4
	s_lshl_b32 s7, s7, 9
	s_nop 0
	v_addc_co_u32_e32 v11, vcc, 0, v5, vcc
	v_add_co_u32_e32 v12, vcc, s38, v4
	s_nop 1
	v_addc_co_u32_e32 v13, vcc, 0, v5, vcc
	v_add_co_u32_e32 v14, vcc, s24, v4
	s_nop 1
	v_addc_co_u32_e32 v15, vcc, 0, v5, vcc
	v_add_co_u32_e32 v16, vcc, s39, v4
	s_nop 1
	v_addc_co_u32_e32 v17, vcc, 0, v5, vcc
	v_add_co_u32_e32 v18, vcc, s25, v4
	s_nop 1
	v_addc_co_u32_e32 v19, vcc, 0, v5, vcc
	global_load_dword v0, v[4:5], off
	global_load_dword v3, v[6:7], off
	global_load_dword v24, v[8:9], off
	global_load_dword v25, v[10:11], off
	global_load_dword v26, v[12:13], off
	global_load_dword v27, v[14:15], off
	global_load_dword v28, v[16:17], off
	global_load_dword v29, v[18:19], off
	v_add_co_u32_e32 v6, vcc, s23, v4
	s_nop 1
	v_addc_co_u32_e32 v7, vcc, 0, v5, vcc
	v_add_co_u32_e32 v8, vcc, s26, v4
	s_nop 1
	v_addc_co_u32_e32 v9, vcc, 0, v5, vcc
	v_add_co_u32_e32 v10, vcc, s42, v4
	s_nop 1
	v_addc_co_u32_e32 v11, vcc, 0, v5, vcc
	v_add_co_u32_e32 v12, vcc, s57, v4
	s_nop 1
	v_addc_co_u32_e32 v13, vcc, 0, v5, vcc
	v_add_co_u32_e32 v14, vcc, s18, v4
	s_mov_b32 s18, 0x68000
	s_nop 0
	v_addc_co_u32_e32 v15, vcc, 0, v5, vcc
	v_add_co_u32_e32 v16, vcc, s18, v4
	s_mov_b32 s18, 0x70000
	s_nop 0
	v_addc_co_u32_e32 v17, vcc, 0, v5, vcc
	v_add_co_u32_e32 v18, vcc, s18, v4
	s_mov_b32 s18, 0x78000
	s_nop 0
	v_addc_co_u32_e32 v19, vcc, 0, v5, vcc
	v_add_co_u32_e32 v20, vcc, s18, v4
	s_mov_b32 s18, 0x88000
	s_nop 0
	v_addc_co_u32_e32 v21, vcc, 0, v5, vcc
	global_load_dword v30, v[6:7], off
	global_load_dword v31, v[8:9], off
	global_load_dword v32, v[10:11], off
	global_load_dword v33, v[12:13], off
	global_load_dword v34, v[14:15], off
	global_load_dword v35, v[16:17], off
	global_load_dword v36, v[18:19], off
	global_load_dword v37, v[20:21], off
	v_add_co_u32_e32 v6, vcc, s22, v4
	s_nop 1
	v_addc_co_u32_e32 v7, vcc, 0, v5, vcc
	v_add_co_u32_e32 v8, vcc, s18, v4
	s_mov_b32 s18, 0x90000
	s_nop 0
	v_addc_co_u32_e32 v9, vcc, 0, v5, vcc
	v_add_co_u32_e32 v10, vcc, s18, v4
	s_mov_b32 s18, 0x98000
	s_nop 0
	v_addc_co_u32_e32 v11, vcc, 0, v5, vcc
	v_add_co_u32_e32 v12, vcc, s18, v4
	s_mov_b32 s18, 0xa0000
	s_nop 0
	v_addc_co_u32_e32 v13, vcc, 0, v5, vcc
	v_add_co_u32_e32 v14, vcc, s18, v4
	s_mov_b32 s18, 0xa8000
	s_nop 0
	v_addc_co_u32_e32 v15, vcc, 0, v5, vcc
	v_add_co_u32_e32 v16, vcc, s18, v4
	s_mov_b32 s18, 0xb0000
	s_nop 0
	v_addc_co_u32_e32 v17, vcc, 0, v5, vcc
	v_add_co_u32_e32 v18, vcc, s18, v4
	s_mov_b32 s18, 0xb8000
	s_nop 0
	v_addc_co_u32_e32 v19, vcc, 0, v5, vcc
	v_add_co_u32_e32 v20, vcc, s18, v4
	s_mov_b32 s18, 0xc0000
	s_nop 0
	v_addc_co_u32_e32 v21, vcc, 0, v5, vcc
	global_load_dword v38, v[6:7], off
	global_load_dword v39, v[8:9], off
	global_load_dword v40, v[10:11], off
	global_load_dword v41, v[12:13], off
	global_load_dword v42, v[14:15], off
	global_load_dword v43, v[16:17], off
	global_load_dword v44, v[18:19], off
	s_nop 0
	global_load_dword v20, v[20:21], off
	v_add_co_u32_e32 v6, vcc, s18, v4
	s_mov_b32 s18, 0xc8000
	s_nop 0
	v_addc_co_u32_e32 v7, vcc, 0, v5, vcc
	v_add_co_u32_e32 v8, vcc, s18, v4
	s_mov_b32 s18, 0xd0000
	s_nop 0
	v_addc_co_u32_e32 v9, vcc, 0, v5, vcc
	v_add_co_u32_e32 v10, vcc, s18, v4
	s_mov_b32 s18, 0xd8000
	s_nop 0
	v_addc_co_u32_e32 v11, vcc, 0, v5, vcc
	v_add_co_u32_e32 v12, vcc, s18, v4
	s_mov_b32 s18, 0xe0000
	s_nop 0
	v_addc_co_u32_e32 v13, vcc, 0, v5, vcc
	v_add_co_u32_e32 v14, vcc, s18, v4
	s_mov_b32 s18, 0xe8000
	s_nop 0
	v_addc_co_u32_e32 v15, vcc, 0, v5, vcc
	v_add_co_u32_e32 v16, vcc, s18, v4
	s_mov_b32 s18, 0xf0000
	s_nop 0
	v_addc_co_u32_e32 v17, vcc, 0, v5, vcc
	v_add_co_u32_e32 v18, vcc, s18, v4
	s_mov_b32 s18, 0xf8000
	s_nop 0
	v_addc_co_u32_e32 v19, vcc, 0, v5, vcc
	v_add_co_u32_e32 v4, vcc, s18, v4
	s_add_u32 s18, s70, s7
	s_nop 0
	v_addc_co_u32_e32 v5, vcc, 0, v5, vcc
	global_load_dword v6, v[6:7], off
	s_nop 0
	global_load_dword v7, v[8:9], off
	s_nop 0
	global_load_dword v8, v[10:11], off
	global_load_dword v9, v[12:13], off
	s_nop 0
	global_load_dword v10, v[14:15], off
	global_load_dword v11, v[16:17], off
	global_load_dword v12, v[18:19], off
	s_nop 0
	global_load_dword v4, v[4:5], off
	v_mul_u32_u24_e32 v5, 0x404, v23
	v_add3_u32 v2, 0, v5, v2
	v_add_u32_e32 v2, 0x8000, v2
	s_waitcnt vmcnt(0)
	ds_write2_b32 v2, v0, v3 offset1:8
	ds_write2_b32 v2, v24, v25 offset0:16 offset1:24
	ds_write2_b32 v2, v26, v27 offset0:32 offset1:40
	ds_write2_b32 v2, v28, v29 offset0:48 offset1:56
	ds_write2_b32 v2, v30, v31 offset0:64 offset1:72
	ds_write2_b32 v2, v32, v33 offset0:80 offset1:88
	ds_write2_b32 v2, v34, v35 offset0:96 offset1:104
	ds_write2_b32 v2, v36, v37 offset0:112 offset1:120
	ds_write2_b32 v2, v38, v39 offset0:128 offset1:136
	ds_write2_b32 v2, v40, v41 offset0:144 offset1:152
	ds_write2_b32 v2, v42, v43 offset0:160 offset1:168
	ds_write2_b32 v2, v44, v20 offset0:176 offset1:184
	ds_write2_b32 v2, v6, v7 offset0:192 offset1:200
	ds_write2_b32 v2, v8, v9 offset0:208 offset1:216
	ds_write2_b32 v2, v10, v11 offset0:224 offset1:232
	ds_write2_b32 v2, v12, v4 offset0:240 offset1:248
	v_lshlrev_b32_e32 v2, 3, v22
	v_ashrrev_i32_e32 v0, 3, v22
	v_and_b32_e32 v10, 56, v2
	v_mul_lo_u32 v2, v0, s43
	v_lshlrev_b32_e32 v3, 2, v10
	v_add3_u32 v11, 0, v2, v3
	v_add_u32_e32 v2, 0x8000, v11
	s_waitcnt lgkmcnt(0)
	s_barrier
; DEVI unsigned cvtpk(float lo, float hi) { unsigned r; asm volatile("v_cvt_pk_bf16_f32 %0, %1, %2" : "=v"(r) : "v"(lo), "v"(hi)); return r; }
; template <int KT, class F> DEVI void cvt_tile(F colptr, int ldsrc, int k0, bf16_t* out, int ldo, int v0, float* tile, int wv) {
;     ...
;     { const int vc = tid >> 3, k8 = (tid & 7) * 8;
; #pragma unroll
;       for (int q = 0; q < KT; ++q) { const float* tp = tile + vc * PITCH + q * 64 + k8;
;         u32x4 w = {cvtpk(tp[0], tp[1]), cvtpk(tp[2], tp[3]), cvtpk(tp[4], tp[5]), cvtpk(tp[6], tp[7])};
;         *(u32x4*)(out + (size_t)(v0 + vc) * ldo + k0 + q * 64 + k8) = w; } }
;     __syncthreads();
; DEVI void cvt_ffn_phase(const float* wg, const float* wu, const float* wd, unsigned char* ws, char* lds, int j0, int jstride, int wv) {
;     ...
;         if (job < 352) { const int vt = job >> 2, kg = job & 3; cvt_tile<4>(ColGU{wg, (long)((const char*)wu - (const char*)wg)}, DFF, kg * 256, Wgu, DM, vt * 64, tile, wv); }
	ds_read2_b32 v[2:3], v2 offset1:1
	s_waitcnt lgkmcnt(0)
	v_cvt_pk_bf16_f32 v2, v2, v3
	v_add_u32_e32 v3, 0x8008, v11
	ds_read2_b32 v[4:5], v3 offset1:1
	s_addc_u32 s19, s71, 0
	s_waitcnt lgkmcnt(0)
	v_cvt_pk_bf16_f32 v3, v4, v5
	v_add_u32_e32 v4, 0x8010, v11
	v_add_u32_e32 v0, s6, v0
	v_mov_b64_e32 v[6:7], s[18:19]
	ds_read2_b32 v[4:5], v4 offset1:1
	v_mad_i64_i32 v[6:7], s[6:7], v0, s3, v[6:7]
	v_lshlrev_b32_e32 v0, 1, v10
	s_waitcnt lgkmcnt(0)
	v_cvt_pk_bf16_f32 v4, v4, v5
	v_add_u32_e32 v5, 0x8018, v11
	v_lshl_add_u64 v[6:7], v[6:7], 0, v[0:1]
	ds_read2_b32 v[8:9], v5 offset1:1
	s_waitcnt lgkmcnt(0)
	v_cvt_pk_bf16_f32 v5, v8, v9
	global_store_dwordx4 v[6:7], v[2:5], off
	v_add_u32_e32 v0, 0x8100, v11
	ds_read2_b32 v[2:3], v0 offset1:1
	v_add_u32_e32 v0, 0x8108, v11
	s_waitcnt lgkmcnt(0)
	v_cvt_pk_bf16_f32 v2, v2, v3
	ds_read2_b32 v[4:5], v0 offset1:1
	v_add_u32_e32 v0, 0x8110, v11
	s_waitcnt lgkmcnt(0)
	v_cvt_pk_bf16_f32 v3, v4, v5
	ds_read2_b32 v[4:5], v0 offset1:1
	v_add_u32_e32 v0, 0x8118, v11
	s_waitcnt lgkmcnt(0)
	v_cvt_pk_bf16_f32 v4, v4, v5
	ds_read2_b32 v[8:9], v0 offset1:1
	s_waitcnt lgkmcnt(0)
	v_cvt_pk_bf16_f32 v5, v8, v9
	global_store_dwordx4 v[6:7], v[2:5], off offset:128
	v_add_u32_e32 v0, 0x8200, v11
	ds_read2_b32 v[2:3], v0 offset1:1
	v_add_u32_e32 v0, 0x8208, v11
	s_waitcnt lgkmcnt(0)
	v_cvt_pk_bf16_f32 v2, v2, v3
	ds_read2_b32 v[4:5], v0 offset1:1
	v_add_u32_e32 v0, 0x8210, v11
	s_waitcnt lgkmcnt(0)
	v_cvt_pk_bf16_f32 v3, v4, v5
	ds_read2_b32 v[4:5], v0 offset1:1
	v_add_u32_e32 v0, 0x8218, v11
	s_waitcnt lgkmcnt(0)
	v_cvt_pk_bf16_f32 v4, v4, v5
	ds_read2_b32 v[8:9], v0 offset1:1
	s_waitcnt lgkmcnt(0)
	v_cvt_pk_bf16_f32 v5, v8, v9
	global_store_dwordx4 v[6:7], v[2:5], off offset:256
	v_add_u32_e32 v0, 0x8300, v11
	ds_read2_b32 v[2:3], v0 offset1:1
	v_add_u32_e32 v0, 0x8308, v11
	s_waitcnt lgkmcnt(0)
	v_cvt_pk_bf16_f32 v2, v2, v3
	ds_read2_b32 v[4:5], v0 offset1:1
	v_add_u32_e32 v0, 0x8310, v11
	s_waitcnt lgkmcnt(0)
	v_cvt_pk_bf16_f32 v3, v4, v5
	ds_read2_b32 v[4:5], v0 offset1:1
	v_add_u32_e32 v0, 0x8318, v11
	s_waitcnt lgkmcnt(0)
	v_cvt_pk_bf16_f32 v4, v4, v5
	ds_read2_b32 v[8:9], v0 offset1:1
	s_waitcnt lgkmcnt(0)
	v_cvt_pk_bf16_f32 v5, v8, v9
	global_store_dwordx4 v[6:7], v[2:5], off offset:384
	s_waitcnt lgkmcnt(0)
	s_barrier
	s_mov_b64 s[6:7], 0
.LBB0_539:
	s_andn2_b64 vcc, exec, s[6:7]
	s_cbranch_vccnz .LBB0_536
	s_and_b32 s7, s12, 0x300
	s_and_b32 s6, s14, 0xffffffc0
	s_bitcmp1_b32 s67, 3
	s_cselect_b32 s19, s10, 0
	s_cselect_b32 s18, s11, 0
	s_add_u32 s20, s8, s19
	s_addc_u32 s21, s9, s18
	s_and_b32 s18, s16, 0xffffff80
	v_mov_b32_e32 v20, v217
	s_ashr_i32 s19, s18, 31
	s_lshl_b64 s[18:19], s[18:19], 2
	v_and_b32_e32 v21, 63, v20
	s_add_u32 s18, s20, s18
	v_and_or_b32 v0, s14, 64, v21
	s_addc_u32 s19, s21, s19
	v_lshlrev_b32_e32 v0, 2, v0
	v_ashrrev_i32_e32 v22, 6, v20
	v_lshl_add_u64 v[2:3], s[18:19], 0, v[0:1]
	s_mul_i32 s46, s7, 0x2c00
	v_lshl_add_u64 v[2:3], v[2:3], 0, s[46:47]
	v_add_u32_e32 v0, 8, v22
	v_mad_i64_i32 v[6:7], s[18:19], v0, s44, v[2:3]
	v_add_u32_e32 v0, 16, v22
	v_mad_i64_i32 v[8:9], s[18:19], v0, s44, v[2:3]
	v_add_u32_e32 v0, 24, v22
	v_mad_i64_i32 v[10:11], s[18:19], v0, s44, v[2:3]
	v_add_u32_e32 v0, 32, v22
	v_mad_i64_i32 v[12:13], s[18:19], v0, s44, v[2:3]
	v_add_u32_e32 v0, 40, v22
	v_mad_i64_i32 v[14:15], s[18:19], v0, s44, v[2:3]
	v_add_u32_e32 v0, 48, v22
	v_mad_i64_i32 v[16:17], s[18:19], v0, s44, v[2:3]
	v_add_u32_e32 v0, 56, v22
	v_mad_i64_i32 v[4:5], s[18:19], v22, s44, v[2:3]
	v_mad_i64_i32 v[18:19], s[18:19], v0, s44, v[2:3]
	global_load_dword v0, v[4:5], off
	global_load_dword v23, v[6:7], off
	global_load_dword v24, v[8:9], off
	global_load_dword v25, v[10:11], off
	global_load_dword v26, v[12:13], off
	global_load_dword v27, v[14:15], off
	global_load_dword v28, v[16:17], off
	global_load_dword v29, v[18:19], off
	v_add_u32_e32 v4, 64, v22
	v_add_u32_e32 v6, 0x48, v22
	v_add_u32_e32 v8, 0x50, v22
	v_add_u32_e32 v10, 0x58, v22
	v_add_u32_e32 v12, 0x60, v22
	v_add_u32_e32 v14, 0x68, v22
	v_add_u32_e32 v16, 0x70, v22
	v_add_u32_e32 v18, 0x78, v22
	v_mad_i64_i32 v[4:5], s[18:19], v4, s44, v[2:3]
	v_mad_i64_i32 v[6:7], s[18:19], v6, s44, v[2:3]
	v_mad_i64_i32 v[8:9], s[18:19], v8, s44, v[2:3]
	v_mad_i64_i32 v[10:11], s[18:19], v10, s44, v[2:3]
	v_mad_i64_i32 v[12:13], s[18:19], v12, s44, v[2:3]
	v_mad_i64_i32 v[14:15], s[18:19], v14, s44, v[2:3]
	v_mad_i64_i32 v[16:17], s[18:19], v16, s44, v[2:3]
	v_mad_i64_i32 v[18:19], s[18:19], v18, s44, v[2:3]
	global_load_dword v30, v[4:5], off
	global_load_dword v31, v[6:7], off
	global_load_dword v32, v[8:9], off
	global_load_dword v33, v[10:11], off
	global_load_dword v34, v[12:13], off
	global_load_dword v35, v[14:15], off
	global_load_dword v36, v[16:17], off
	global_load_dword v37, v[18:19], off
	v_add_u32_e32 v4, 0x80, v22
	v_add_u32_e32 v6, 0x88, v22
	v_add_u32_e32 v8, 0x90, v22
	v_add_u32_e32 v10, 0x98, v22
	v_add_u32_e32 v12, 0xa0, v22
	v_add_u32_e32 v14, 0xa8, v22
	v_add_u32_e32 v16, 0xb0, v22
	v_add_u32_e32 v18, 0xb8, v22
	v_mad_i64_i32 v[4:5], s[18:19], v4, s44, v[2:3]
	v_mad_i64_i32 v[6:7], s[18:19], v6, s44, v[2:3]
	v_mad_i64_i32 v[8:9], s[18:19], v8, s44, v[2:3]
	v_mad_i64_i32 v[10:11], s[18:19], v10, s44, v[2:3]
	v_mad_i64_i32 v[12:13], s[18:19], v12, s44, v[2:3]
	v_mad_i64_i32 v[14:15], s[18:19], v14, s44, v[2:3]
	v_mad_i64_i32 v[16:17], s[18:19], v16, s44, v[2:3]
	v_mad_i64_i32 v[18:19], s[18:19], v18, s44, v[2:3]
	global_load_dword v38, v[4:5], off
	global_load_dword v39, v[6:7], off
	global_load_dword v40, v[8:9], off
	global_load_dword v41, v[10:11], off
	global_load_dword v42, v[12:13], off
	global_load_dword v43, v[14:15], off
	global_load_dword v44, v[16:17], off
	s_nop 0
	global_load_dword v18, v[18:19], off
	v_add_u32_e32 v4, 0xc0, v22
	v_add_u32_e32 v6, 0xc8, v22
	v_add_u32_e32 v8, 0xd0, v22
	v_add_u32_e32 v10, 0xd8, v22
	v_add_u32_e32 v12, 0xe0, v22
	v_add_u32_e32 v14, 0xe8, v22
	v_add_u32_e32 v16, 0xf0, v22
	v_add_u32_e32 v19, 0xf8, v22
	v_mad_i64_i32 v[4:5], s[18:19], v4, s44, v[2:3]
	v_mad_i64_i32 v[6:7], s[18:19], v6, s44, v[2:3]
	v_mad_i64_i32 v[8:9], s[18:19], v8, s44, v[2:3]
	v_mad_i64_i32 v[10:11], s[18:19], v10, s44, v[2:3]
	v_mad_i64_i32 v[12:13], s[18:19], v12, s44, v[2:3]
	v_mad_i64_i32 v[14:15], s[18:19], v14, s44, v[2:3]
	v_mad_i64_i32 v[16:17], s[18:19], v16, s44, v[2:3]
	v_mad_i64_i32 v[2:3], s[18:19], v19, s44, v[2:3]
	global_load_dword v4, v[4:5], off
	s_nop 0
	global_load_dword v5, v[6:7], off
	s_nop 0
	global_load_dword v6, v[8:9], off
	global_load_dword v7, v[10:11], off
	s_nop 0
	global_load_dword v8, v[12:13], off
	global_load_dword v9, v[14:15], off
	global_load_dword v10, v[16:17], off
	s_nop 0
	global_load_dword v2, v[2:3], off
	v_mul_u32_u24_e32 v3, 0x404, v21
	v_lshlrev_b32_e32 v11, 2, v22
	v_add3_u32 v3, 0, v3, v11
	v_add_u32_e32 v3, 0x8000, v3
	s_waitcnt vmcnt(0)
; DEVI unsigned cvtpk(float lo, float hi) { unsigned r; asm volatile("v_cvt_pk_bf16_f32 %0, %1, %2" : "=v"(r) : "v"(lo), "v"(hi)); return r; }
; template <int KT, class F> DEVI void cvt_tile(F colptr, int ldsrc, int k0, bf16_t* out, int ldo, int v0, float* tile, int wv) {
;     ...
;       for (int r = 0; r < 8 * KT; ++r) tile[vc * PITCH + r * 8 + kk] = v[r]; }
;     __syncthreads();
;     { const int vc = tid >> 3, k8 = (tid & 7) * 8;
; #pragma unroll
;       for (int q = 0; q < KT; ++q) { const float* tp = tile + vc * PITCH + q * 64 + k8;
;         u32x4 w = {cvtpk(tp[0], tp[1]), cvtpk(tp[2], tp[3]), cvtpk(tp[4], tp[5]), cvtpk(tp[6], tp[7])};
;         *(u32x4*)(out + (size_t)(v0 + vc) * ldo + k0 + q * 64 + k8) = w; } }
;     __syncthreads();
	ds_write2_b32 v3, v0, v23 offset1:8
	ds_write2_b32 v3, v24, v25 offset0:16 offset1:24
	ds_write2_b32 v3, v26, v27 offset0:32 offset1:40
	ds_write2_b32 v3, v28, v29 offset0:48 offset1:56
	ds_write2_b32 v3, v30, v31 offset0:64 offset1:72
	ds_write2_b32 v3, v32, v33 offset0:80 offset1:88
	ds_write2_b32 v3, v34, v35 offset0:96 offset1:104
	ds_write2_b32 v3, v36, v37 offset0:112 offset1:120
	ds_write2_b32 v3, v38, v39 offset0:128 offset1:136
	ds_write2_b32 v3, v40, v41 offset0:144 offset1:152
	ds_write2_b32 v3, v42, v43 offset0:160 offset1:168
	ds_write2_b32 v3, v44, v18 offset0:176 offset1:184
	ds_write2_b32 v3, v4, v5 offset0:192 offset1:200
	ds_write2_b32 v3, v6, v7 offset0:208 offset1:216
	ds_write2_b32 v3, v8, v9 offset0:224 offset1:232
	ds_write2_b32 v3, v10, v2 offset0:240 offset1:248
	v_lshlrev_b32_e32 v2, 3, v20
	v_ashrrev_i32_e32 v0, 3, v20
	v_and_b32_e32 v10, 56, v2
	v_mul_lo_u32 v2, v0, s43
	v_lshlrev_b32_e32 v3, 2, v10
	v_add3_u32 v11, 0, v2, v3
	v_add_u32_e32 v2, 0x8000, v11
	s_waitcnt lgkmcnt(0)
	s_barrier
	ds_read2_b32 v[2:3], v2 offset1:1
	s_waitcnt lgkmcnt(0)
	v_cvt_pk_bf16_f32 v2, v2, v3
	v_add_u32_e32 v3, 0x8008, v11
	ds_read2_b32 v[4:5], v3 offset1:1
	s_lshl_b32 s7, s7, 1
	v_add_u32_e32 v6, s6, v0
	s_waitcnt lgkmcnt(0)
	v_cvt_pk_bf16_f32 v3, v4, v5
	v_add_u32_e32 v4, 0x8010, v11
	s_add_u32 s18, s72, s7
	v_ashrrev_i32_e32 v7, 31, v6
	ds_read2_b32 v[4:5], v4 offset1:1
	s_addc_u32 s19, s73, 0
	v_add_u32_e32 v0, 0x8018, v11
	v_lshlrev_b64 v[6:7], 11, v[6:7]
	s_waitcnt lgkmcnt(0)
	v_cvt_pk_bf16_f32 v4, v4, v5
	ds_read2_b32 v[8:9], v0 offset1:1
	v_lshl_add_u64 v[6:7], s[18:19], 0, v[6:7]
	v_lshlrev_b32_e32 v0, 1, v10
	v_lshl_add_u64 v[6:7], v[6:7], 0, v[0:1]
	s_waitcnt lgkmcnt(0)
	v_cvt_pk_bf16_f32 v5, v8, v9
	global_store_dwordx4 v[6:7], v[2:5], off
	v_add_u32_e32 v0, 0x8100, v11
	ds_read2_b32 v[2:3], v0 offset1:1
	v_add_u32_e32 v0, 0x8108, v11
	s_waitcnt lgkmcnt(0)
	v_cvt_pk_bf16_f32 v2, v2, v3
	ds_read2_b32 v[4:5], v0 offset1:1
	v_add_u32_e32 v0, 0x8110, v11
	s_waitcnt lgkmcnt(0)
	v_cvt_pk_bf16_f32 v3, v4, v5
	ds_read2_b32 v[4:5], v0 offset1:1
	v_add_u32_e32 v0, 0x8118, v11
	s_waitcnt lgkmcnt(0)
	v_cvt_pk_bf16_f32 v4, v4, v5
	ds_read2_b32 v[8:9], v0 offset1:1
	s_waitcnt lgkmcnt(0)
	v_cvt_pk_bf16_f32 v5, v8, v9
	global_store_dwordx4 v[6:7], v[2:5], off offset:128
	v_add_u32_e32 v0, 0x8200, v11
	ds_read2_b32 v[2:3], v0 offset1:1
	v_add_u32_e32 v0, 0x8208, v11
	s_waitcnt lgkmcnt(0)
	v_cvt_pk_bf16_f32 v2, v2, v3
	ds_read2_b32 v[4:5], v0 offset1:1
	v_add_u32_e32 v0, 0x8210, v11
	s_waitcnt lgkmcnt(0)
	v_cvt_pk_bf16_f32 v3, v4, v5
	ds_read2_b32 v[4:5], v0 offset1:1
	v_add_u32_e32 v0, 0x8218, v11
	s_waitcnt lgkmcnt(0)
	v_cvt_pk_bf16_f32 v4, v4, v5
	ds_read2_b32 v[8:9], v0 offset1:1
	s_waitcnt lgkmcnt(0)
	v_cvt_pk_bf16_f32 v5, v8, v9
	global_store_dwordx4 v[6:7], v[2:5], off offset:256
	v_add_u32_e32 v0, 0x8300, v11
	ds_read2_b32 v[2:3], v0 offset1:1
	v_add_u32_e32 v0, 0x8308, v11
	s_waitcnt lgkmcnt(0)
	v_cvt_pk_bf16_f32 v2, v2, v3
	ds_read2_b32 v[4:5], v0 offset1:1
	v_add_u32_e32 v0, 0x8310, v11
	s_waitcnt lgkmcnt(0)
	v_cvt_pk_bf16_f32 v3, v4, v5
	ds_read2_b32 v[4:5], v0 offset1:1
	v_add_u32_e32 v0, 0x8318, v11
	s_waitcnt lgkmcnt(0)
	v_cvt_pk_bf16_f32 v4, v4, v5
	ds_read2_b32 v[8:9], v0 offset1:1
	s_waitcnt lgkmcnt(0)
	v_cvt_pk_bf16_f32 v5, v8, v9
	global_store_dwordx4 v[6:7], v[2:5], off offset:384
	s_waitcnt lgkmcnt(0)
	s_barrier
	s_branch .LBB0_536
